# GEMM K-loops (8 instances) rewritten: LDS-DMA global_load_lds staging with source swizzle, rolling fragment prefetch, one mid-k-tile barrier; bit-identical
# speedup vs baseline: 1.0685x; 1.0685x over previous
; #define G_LOAD(KT) do { _Pragma("unroll") for (int i = 0; i < 4; ++i) { ra[i] = *(const u32x4*)(Ag + (size_t)i * 64 * lda + (KT) * 64); rb[i] = *(const u32x4*)(Bg + (size_t)i * 64 * K + (KT) * 64); } } while (0)
; #define G_STORE(BUF) do { u16* ad = As + (BUF) * 256 * 64 + sto; u16* bd = Bs + (BUF) * 256 * 64 + sto; _Pragma("unroll") for (int i = 0; i < 4; ++i) { *(u32x4*)(ad + i * 64 * 64) = ra[i]; *(u32x4*)(bd + i * 64 * 64) = rb[i]; } } while (0)
; template <int EPI>
; DI void gemm_phase(const u16* __restrict__ A, int lda, const u16* __restrict__ Bt, int K, int N, u16* outb, int ldo,
;                    const float* r0, const float* r1, float* outf, char* lds, int bid, int nb) {
;     ...
;     const u16* Ag = A + (size_t)(tm * 256 + lrow) * lda + lch * 8;
;     const u16* Bg = Bt + (size_t)(tn * 256 + lrow) * K + lch * 8;
;     f32x4 acc[8][4];
; #pragma unroll
;     for (int i = 0; i < 8; ++i)
; #pragma unroll
;       for (int j = 0; j < 4; ++j) acc[i][j] = (f32x4){0.f, 0.f, 0.f, 0.f};
;     u32x4 ra[4], rb[4];
;     ...
;     G_LOAD(0);
;     G_STORE(0);
;     __syncthreads();
.LBB0_287:
	s_lshl_b32 s56, s56, 8
	v_or_b32_e32 v0, s56, v138
	s_lshl_b32 s57, s57, 8
	v_ashrrev_i32_e32 v1, 31, v0
	v_or_b32_e32 v2, s57, v138
	v_ashrrev_i32_e32 v3, 31, v2
	v_lshlrev_b64 v[64:65], 11, v[0:1]
	v_lshl_add_u64 v[0:1], v[130:131], 0, v[64:65]
	v_lshlrev_b64 v[2:3], 11, v[2:3]
	v_lshl_add_u64 v[134:135], v[128:129], 0, v[2:3]
	v_add_co_u32_e32 v2, vcc, s19, v0
	s_nop 1
	v_readfirstlane_b32 s98, v0
	v_readfirstlane_b32 s99, v1
	s_nop 1
	v_readfirstlane_b32 s100, v134
	v_readfirstlane_b32 s101, v135
	v_addc_co_u32_e32 v3, vcc, 0, v1, vcc
	v_add_co_u32_e32 v4, vcc, s19, v134
	s_mov_b32 s62, 0
	s_nop 0
	v_addc_co_u32_e32 v5, vcc, 0, v135, vcc
	v_add_co_u32_e32 v2, vcc, s20, v0
	s_mov_b64 s[12:13], 0
	s_nop 0
	v_addc_co_u32_e32 v3, vcc, 0, v1, vcc
	v_add_co_u32_e32 v4, vcc, s20, v134
	v_lshl_add_u64 v[136:137], v[132:133], 0, v[64:65]
	s_nop 0
	v_addc_co_u32_e32 v5, vcc, 0, v135, vcc
	v_add_co_u32_e32 v0, vcc, s21, v0
	v_addc_co_u32_e32 v1, vcc, 0, v1, vcc
	v_add_co_u32_e32 v2, vcc, s21, v134
	s_nop 1
	v_addc_co_u32_e32 v3, vcc, 0, v135, vcc
	v_mov_b32_e32 v0, 0
	v_mov_b32_e32 v1, v0
	v_mov_b32_e32 v2, v0
	v_mov_b32_e32 v3, v0
	v_mov_b32_e32 v4, v0
	v_mov_b32_e32 v5, v0
	v_mov_b32_e32 v6, v0
	v_mov_b32_e32 v7, v0
	v_mov_b32_e32 v8, v0
	v_mov_b32_e32 v9, v0
	v_mov_b32_e32 v10, v0
	v_mov_b32_e32 v11, v0
	v_mov_b32_e32 v12, v0
	v_mov_b32_e32 v13, v0
	v_mov_b32_e32 v14, v0
	v_mov_b32_e32 v15, v0
	v_mov_b32_e32 v16, v0
	v_mov_b32_e32 v17, v0
	v_mov_b32_e32 v18, v0
	v_mov_b32_e32 v19, v0
	v_mov_b32_e32 v20, v0
	v_mov_b32_e32 v21, v0
	v_mov_b32_e32 v22, v0
	v_mov_b32_e32 v23, v0
	v_mov_b32_e32 v24, v0
	v_mov_b32_e32 v25, v0
	v_mov_b32_e32 v26, v0
	v_mov_b32_e32 v27, v0
	v_mov_b32_e32 v28, v0
	v_mov_b32_e32 v29, v0
	v_mov_b32_e32 v30, v0
	v_mov_b32_e32 v31, v0
	v_mov_b32_e32 v64, v0
	v_mov_b32_e32 v65, v0
	v_mov_b32_e32 v66, v0
	v_mov_b32_e32 v67, v0
	v_mov_b32_e32 v68, v0
	v_mov_b32_e32 v69, v0
	v_mov_b32_e32 v70, v0
	v_mov_b32_e32 v71, v0
	v_mov_b32_e32 v72, v0
	v_mov_b32_e32 v73, v0
	v_mov_b32_e32 v74, v0
	v_mov_b32_e32 v75, v0
	v_mov_b32_e32 v76, v0
	v_mov_b32_e32 v77, v0
	v_mov_b32_e32 v78, v0
	v_mov_b32_e32 v79, v0
	v_mov_b32_e32 v80, v0
	v_mov_b32_e32 v81, v0
	v_mov_b32_e32 v82, v0
	v_mov_b32_e32 v83, v0
	v_mov_b32_e32 v84, v0
	v_mov_b32_e32 v85, v0
	v_mov_b32_e32 v32, v0
	v_mov_b32_e32 v33, v0
	v_mov_b32_e32 v34, v0
	v_mov_b32_e32 v35, v0
	v_mov_b32_e32 v36, v0
	v_mov_b32_e32 v37, v0
	v_mov_b32_e32 v38, v0
	v_mov_b32_e32 v39, v0
	v_mov_b32_e32 v40, v0
	v_mov_b32_e32 v41, v0
	v_mov_b32_e32 v42, v0
	v_mov_b32_e32 v43, v0
	v_mov_b32_e32 v44, v0
	v_mov_b32_e32 v45, v0
	v_mov_b32_e32 v46, v0
	v_mov_b32_e32 v47, v0
	v_mov_b32_e32 v48, v0
	v_mov_b32_e32 v49, v0
	v_mov_b32_e32 v50, v0
	v_mov_b32_e32 v51, v0
	v_mov_b32_e32 v52, v0
	v_mov_b32_e32 v53, v0
	v_mov_b32_e32 v54, v0
	v_mov_b32_e32 v55, v0
	v_mov_b32_e32 v56, v0
	v_mov_b32_e32 v57, v0
	v_mov_b32_e32 v58, v0
	v_mov_b32_e32 v59, v0
	v_mov_b32_e32 v60, v0
	v_mov_b32_e32 v61, v0
	v_mov_b32_e32 v62, v0
	v_mov_b32_e32 v63, v0
	v_mov_b32_e32 v86, v0
	v_mov_b32_e32 v87, v0
	v_mov_b32_e32 v88, v0
	v_mov_b32_e32 v89, v0
	v_mov_b32_e32 v90, v0
	v_mov_b32_e32 v91, v0
	v_mov_b32_e32 v92, v0
	v_mov_b32_e32 v93, v0
	v_mov_b32_e32 v94, v0
	v_mov_b32_e32 v95, v0
	v_mov_b32_e32 v96, v0
	v_mov_b32_e32 v97, v0
	v_mov_b32_e32 v98, v0
	v_mov_b32_e32 v99, v0
	v_mov_b32_e32 v100, v0
	v_mov_b32_e32 v101, v0
	v_mov_b32_e32 v102, v0
	v_mov_b32_e32 v103, v0
	v_mov_b32_e32 v104, v0
	v_mov_b32_e32 v105, v0
	v_mov_b32_e32 v106, v0
	v_mov_b32_e32 v107, v0
	v_mov_b32_e32 v108, v0
	v_mov_b32_e32 v109, v0
	v_mov_b32_e32 v110, v0
	v_mov_b32_e32 v111, v0
	v_mov_b32_e32 v112, v0
	v_mov_b32_e32 v113, v0
	v_mov_b32_e32 v114, v0
	v_mov_b32_e32 v115, v0
	v_mov_b32_e32 v116, v0
	v_mov_b32_e32 v117, v0
	v_mov_b32_e32 v118, v0
	v_mov_b32_e32 v119, v0
	v_mov_b32_e32 v120, v0
	v_mov_b32_e32 v121, v0
	v_mov_b32_e32 v122, v0
	v_mov_b32_e32 v123, v0
	v_mov_b32_e32 v124, v0
	v_mov_b32_e32 v125, v0
	v_mov_b32_e32 v126, v0
	v_mov_b32_e32 v127, v0
	v_and_b32_e32 v229, 63, v174
	v_lshrrev_b32_e32 v230, 3, v229
	v_mov_b32_e32 v233, 0x800
	v_mul_u32_u24_e32 v224, v230, v233
	v_bfe_u32 v231, v174, 4, 2
	v_bfe_u32 v232, v174, 6, 1
	v_lshl_or_b32 v232, v232, 2, v231
	v_and_b32_e32 v233, 7, v174
	v_xor_b32_e32 v232, v232, v233
	v_lshl_add_u32 v224, v232, 4, v224
	v_and_b32_e32 v229, 15, v174
	v_bfe_u32 v230, v174, 1, 3
	v_xor_b32_e32 v230, v230, v231
	v_lshlrev_b32_e32 v230, 4, v230
	v_lshl_or_b32 v230, v229, 7, v230
	v_lshrrev_b32_e32 v229, 8, v174
	v_lshl_or_b32 v225, v229, 14, v230
	v_bfe_u32 v229, v174, 6, 2
	v_lshl_or_b32 v227, v229, 13, v230
	v_or_b32_e32 v227, 0x10000, v227
	v_xor_b32_e32 v226, 64, v225
	v_xor_b32_e32 v228, 64, v227
	v_readfirstlane_b32 s97, v174
	s_lshl_b32 s97, s97, 4
	s_mov_b32 s28, 14
	s_add_u32 s12, s98, 0x0
	s_addc_u32 s13, s99, 0
	s_add_u32 m0, s97, 0x0
	s_nop 0
	global_load_lds_dwordx4 v224, s[12:13]
	s_add_u32 s12, s100, 0x0
	s_addc_u32 s13, s101, 0
	s_add_u32 m0, s97, 0x10000
	s_nop 0
	global_load_lds_dwordx4 v224, s[12:13]
	s_add_u32 s12, s98, 0x20000
	s_addc_u32 s13, s99, 0
	s_add_u32 m0, s97, 0x2000
	s_nop 0
	global_load_lds_dwordx4 v224, s[12:13]
	s_add_u32 s12, s100, 0x20000
	s_addc_u32 s13, s101, 0
	s_add_u32 m0, s97, 0x12000
	s_nop 0
	global_load_lds_dwordx4 v224, s[12:13]
	s_add_u32 s12, s98, 0x40000
	s_addc_u32 s13, s99, 0
	s_add_u32 m0, s97, 0x4000
	s_nop 0
	global_load_lds_dwordx4 v224, s[12:13]
	s_add_u32 s12, s100, 0x40000
	s_addc_u32 s13, s101, 0
	s_add_u32 m0, s97, 0x14000
	s_nop 0
	global_load_lds_dwordx4 v224, s[12:13]
	s_add_u32 s12, s98, 0x60000
	s_addc_u32 s13, s99, 0
	s_add_u32 m0, s97, 0x6000
	s_nop 0
	global_load_lds_dwordx4 v224, s[12:13]
	s_add_u32 s12, s100, 0x60000
	s_addc_u32 s13, s101, 0
	s_add_u32 m0, s97, 0x16000
	s_nop 0
	global_load_lds_dwordx4 v224, s[12:13]
	s_add_u32 s12, s98, 0x80
	s_addc_u32 s13, s99, 0
	s_add_u32 m0, s97, 0x8000
	s_nop 0
	global_load_lds_dwordx4 v224, s[12:13]
	s_add_u32 s12, s100, 0x80
	s_addc_u32 s13, s101, 0
	s_add_u32 m0, s97, 0x18000
	s_nop 0
	global_load_lds_dwordx4 v224, s[12:13]
	s_add_u32 s12, s98, 0x20080
	s_addc_u32 s13, s99, 0
	s_add_u32 m0, s97, 0xa000
	s_nop 0
	global_load_lds_dwordx4 v224, s[12:13]
	s_add_u32 s12, s100, 0x20080
	s_addc_u32 s13, s101, 0
	s_add_u32 m0, s97, 0x1a000
	s_nop 0
	global_load_lds_dwordx4 v224, s[12:13]
	s_add_u32 s12, s98, 0x40080
	s_addc_u32 s13, s99, 0
	s_add_u32 m0, s97, 0xc000
	s_nop 0
	global_load_lds_dwordx4 v224, s[12:13]
	s_add_u32 s12, s100, 0x40080
	s_addc_u32 s13, s101, 0
	s_add_u32 m0, s97, 0x1c000
	s_nop 0
	global_load_lds_dwordx4 v224, s[12:13]
	s_add_u32 s12, s98, 0x60080
	s_addc_u32 s13, s99, 0
	s_add_u32 m0, s97, 0xe000
	s_nop 0
	global_load_lds_dwordx4 v224, s[12:13]
	s_add_u32 s12, s100, 0x60080
	s_addc_u32 s13, s101, 0
	s_add_u32 m0, s97, 0x1e000
	s_nop 0
	global_load_lds_dwordx4 v224, s[12:13]
	s_add_u32 s98, s98, 0x100
	s_addc_u32 s99, s99, 0
	s_add_u32 s100, s100, 0x100
	s_addc_u32 s101, s101, 0
	s_waitcnt vmcnt(8)
	s_barrier
; #define G_LOAD(KT) do { _Pragma("unroll") for (int i = 0; i < 4; ++i) { ra[i] = *(const u32x4*)(Ag + (size_t)i * 64 * lda + (KT) * 64); rb[i] = *(const u32x4*)(Bg + (size_t)i * 64 * K + (KT) * 64); } } while (0)
; #define G_STORE(BUF) do { u16* ad = As + (BUF) * 256 * 64 + sto; u16* bd = Bs + (BUF) * 256 * 64 + sto; _Pragma("unroll") for (int i = 0; i < 4; ++i) { *(u32x4*)(ad + i * 64 * 64) = ra[i]; *(u32x4*)(bd + i * 64 * 64) = rb[i]; } } while (0)
; template <int EPI>
; DI void gemm_phase(const u16* __restrict__ A, int lda, const u16* __restrict__ Bt, int K, int N, u16* outb, int ldo,
;                    const float* r0, const float* r1, float* outf, char* lds, int bid, int nb) {
;     ...
;     G_LOAD(0);
;     G_STORE(0);
;     __syncthreads();
;     for (int kt = 0; kt < nk; ++kt) {
;       const int cur = kt & 1;
;       if (kt + 1 < nk) G_LOAD(kt + 1);
;       G_MMA(cur, fo0);
;       G_MMA(cur, fo1);
;       if (kt + 1 < nk) G_STORE(cur ^ 1);
;       __syncthreads();
;     }
	ds_read_b128 v[152:155], v227 offset:0
	ds_read_b128 v[156:159], v227 offset:2048
	ds_read_b128 v[160:163], v227 offset:4096
	ds_read_b128 v[164:167], v227 offset:6144
	ds_read_b128 v[188:191], v225 offset:0
	ds_read_b128 v[192:195], v225 offset:2048
	ds_read_b128 v[196:199], v225 offset:4096
	ds_read_b128 v[200:203], v225 offset:6144
	ds_read_b128 v[204:207], v225 offset:8192
	ds_read_b128 v[208:211], v225 offset:10240
	ds_read_b128 v[212:215], v225 offset:12288
	ds_read_b128 v[216:219], v225 offset:14336
	v_xor_b32_e32 v225, 0x8000, v225
	v_xor_b32_e32 v227, 0x8000, v227
	s_waitcnt lgkmcnt(0)
.Lgm0_loop:
	s_waitcnt lgkmcnt(4)
	v_mfma_f32_16x16x32_bf16 v[124:127], v[188:191], v[152:155], v[124:127]
	v_mfma_f32_16x16x32_bf16 v[120:123], v[188:191], v[156:159], v[120:123]
	v_mfma_f32_16x16x32_bf16 v[116:119], v[188:191], v[160:163], v[116:119]
	v_mfma_f32_16x16x32_bf16 v[112:115], v[188:191], v[164:167], v[112:115]
	ds_read_b128 v[188:191], v226 offset:0
	ds_read_b128 v[168:171], v228 offset:0
	v_mfma_f32_16x16x32_bf16 v[108:111], v[192:195], v[152:155], v[108:111]
	v_mfma_f32_16x16x32_bf16 v[104:107], v[192:195], v[156:159], v[104:107]
	v_mfma_f32_16x16x32_bf16 v[100:103], v[192:195], v[160:163], v[100:103]
	v_mfma_f32_16x16x32_bf16 v[96:99], v[192:195], v[164:167], v[96:99]
	ds_read_b128 v[192:195], v226 offset:2048
	ds_read_b128 v[176:179], v228 offset:2048
	v_mfma_f32_16x16x32_bf16 v[92:95], v[196:199], v[152:155], v[92:95]
	v_mfma_f32_16x16x32_bf16 v[88:91], v[196:199], v[156:159], v[88:91]
	v_mfma_f32_16x16x32_bf16 v[84:87], v[196:199], v[160:163], v[84:87]
	v_mfma_f32_16x16x32_bf16 v[80:83], v[196:199], v[164:167], v[80:83]
	ds_read_b128 v[196:199], v226 offset:4096
	ds_read_b128 v[180:183], v228 offset:4096
	v_mfma_f32_16x16x32_bf16 v[76:79], v[200:203], v[152:155], v[76:79]
	v_mfma_f32_16x16x32_bf16 v[72:75], v[200:203], v[156:159], v[72:75]
	v_mfma_f32_16x16x32_bf16 v[68:71], v[200:203], v[160:163], v[68:71]
	v_mfma_f32_16x16x32_bf16 v[64:67], v[200:203], v[164:167], v[64:67]
	ds_read_b128 v[200:203], v226 offset:6144
	ds_read_b128 v[184:187], v228 offset:6144
	s_waitcnt lgkmcnt(11)
	v_mfma_f32_16x16x32_bf16 v[60:63], v[204:207], v[152:155], v[60:63]
	v_mfma_f32_16x16x32_bf16 v[56:59], v[204:207], v[156:159], v[56:59]
	v_mfma_f32_16x16x32_bf16 v[52:55], v[204:207], v[160:163], v[52:55]
	v_mfma_f32_16x16x32_bf16 v[48:51], v[204:207], v[164:167], v[48:51]
	ds_read_b128 v[204:207], v226 offset:8192
	ds_read_b128 v[220:223], v226 offset:14336
	s_waitcnt lgkmcnt(11)
	v_mfma_f32_16x16x32_bf16 v[44:47], v[208:211], v[152:155], v[44:47]
	v_mfma_f32_16x16x32_bf16 v[40:43], v[208:211], v[156:159], v[40:43]
	v_mfma_f32_16x16x32_bf16 v[36:39], v[208:211], v[160:163], v[36:39]
	v_mfma_f32_16x16x32_bf16 v[32:35], v[208:211], v[164:167], v[32:35]
	ds_read_b128 v[208:211], v226 offset:10240
	s_waitcnt lgkmcnt(11)
	v_mfma_f32_16x16x32_bf16 v[28:31], v[212:215], v[152:155], v[28:31]
	v_mfma_f32_16x16x32_bf16 v[24:27], v[212:215], v[156:159], v[24:27]
	v_mfma_f32_16x16x32_bf16 v[20:23], v[212:215], v[160:163], v[20:23]
	v_mfma_f32_16x16x32_bf16 v[16:19], v[212:215], v[164:167], v[16:19]
	ds_read_b128 v[212:215], v226 offset:12288
	v_mfma_f32_16x16x32_bf16 v[12:15], v[216:219], v[152:155], v[12:15]
	v_mfma_f32_16x16x32_bf16 v[8:11], v[216:219], v[156:159], v[8:11]
	v_mfma_f32_16x16x32_bf16 v[4:7], v[216:219], v[160:163], v[4:7]
	v_mfma_f32_16x16x32_bf16 v[0:3], v[216:219], v[164:167], v[0:3]
	s_waitcnt vmcnt(0) lgkmcnt(0)
	s_barrier
	v_mfma_f32_16x16x32_bf16 v[124:127], v[188:191], v[168:171], v[124:127]
	v_mfma_f32_16x16x32_bf16 v[120:123], v[188:191], v[176:179], v[120:123]
	v_mfma_f32_16x16x32_bf16 v[116:119], v[188:191], v[180:183], v[116:119]
	v_mfma_f32_16x16x32_bf16 v[112:115], v[188:191], v[184:187], v[112:115]
	ds_read_b128 v[188:191], v225 offset:0
	ds_read_b128 v[152:155], v227 offset:0
	s_add_u32 s12, s98, 0x0
	s_addc_u32 s13, s99, 0
	s_add_u32 m0, s97, 0x0
	s_nop 0
	global_load_lds_dwordx4 v224, s[12:13]
	v_mfma_f32_16x16x32_bf16 v[108:111], v[192:195], v[168:171], v[108:111]
	v_mfma_f32_16x16x32_bf16 v[104:107], v[192:195], v[176:179], v[104:107]
	v_mfma_f32_16x16x32_bf16 v[100:103], v[192:195], v[180:183], v[100:103]
	v_mfma_f32_16x16x32_bf16 v[96:99], v[192:195], v[184:187], v[96:99]
	ds_read_b128 v[192:195], v225 offset:2048
	ds_read_b128 v[156:159], v227 offset:2048
	s_add_u32 s12, s100, 0x0
	s_addc_u32 s13, s101, 0
	s_add_u32 m0, s97, 0x10000
	s_nop 0
	global_load_lds_dwordx4 v224, s[12:13]
	v_mfma_f32_16x16x32_bf16 v[92:95], v[196:199], v[168:171], v[92:95]
	v_mfma_f32_16x16x32_bf16 v[88:91], v[196:199], v[176:179], v[88:91]
	v_mfma_f32_16x16x32_bf16 v[84:87], v[196:199], v[180:183], v[84:87]
	v_mfma_f32_16x16x32_bf16 v[80:83], v[196:199], v[184:187], v[80:83]
	ds_read_b128 v[196:199], v225 offset:4096
	ds_read_b128 v[160:163], v227 offset:4096
	s_add_u32 s12, s98, 0x20000
	s_addc_u32 s13, s99, 0
	s_add_u32 m0, s97, 0x2000
	s_nop 0
	global_load_lds_dwordx4 v224, s[12:13]
	v_mfma_f32_16x16x32_bf16 v[76:79], v[200:203], v[168:171], v[76:79]
	v_mfma_f32_16x16x32_bf16 v[72:75], v[200:203], v[176:179], v[72:75]
	v_mfma_f32_16x16x32_bf16 v[68:71], v[200:203], v[180:183], v[68:71]
	v_mfma_f32_16x16x32_bf16 v[64:67], v[200:203], v[184:187], v[64:67]
	ds_read_b128 v[200:203], v225 offset:6144
	ds_read_b128 v[164:167], v227 offset:6144
	s_add_u32 s12, s100, 0x20000
	s_addc_u32 s13, s101, 0
	s_add_u32 m0, s97, 0x12000
	s_nop 0
	global_load_lds_dwordx4 v224, s[12:13]
	v_mfma_f32_16x16x32_bf16 v[60:63], v[204:207], v[168:171], v[60:63]
	v_mfma_f32_16x16x32_bf16 v[56:59], v[204:207], v[176:179], v[56:59]
; #define G_LOAD(KT) do { _Pragma("unroll") for (int i = 0; i < 4; ++i) { ra[i] = *(const u32x4*)(Ag + (size_t)i * 64 * lda + (KT) * 64); rb[i] = *(const u32x4*)(Bg + (size_t)i * 64 * K + (KT) * 64); } } while (0)
; #define G_STORE(BUF) do { u16* ad = As + (BUF) * 256 * 64 + sto; u16* bd = Bs + (BUF) * 256 * 64 + sto; _Pragma("unroll") for (int i = 0; i < 4; ++i) { *(u32x4*)(ad + i * 64 * 64) = ra[i]; *(u32x4*)(bd + i * 64 * 64) = rb[i]; } } while (0)
; template <int EPI>
; DI void gemm_phase(const u16* __restrict__ A, int lda, const u16* __restrict__ Bt, int K, int N, u16* outb, int ldo,
;                    const float* r0, const float* r1, float* outf, char* lds, int bid, int nb) {
;     ...
;     G_LOAD(0);
;     G_STORE(0);
;     __syncthreads();
;     for (int kt = 0; kt < nk; ++kt) {
;       const int cur = kt & 1;
;       if (kt + 1 < nk) G_LOAD(kt + 1);
;       G_MMA(cur, fo0);
;       G_MMA(cur, fo1);
;       if (kt + 1 < nk) G_STORE(cur ^ 1);
;       __syncthreads();
;     }
	v_mfma_f32_16x16x32_bf16 v[52:55], v[204:207], v[180:183], v[52:55]
	v_mfma_f32_16x16x32_bf16 v[48:51], v[204:207], v[184:187], v[48:51]
	ds_read_b128 v[204:207], v225 offset:8192
	ds_read_b128 v[216:219], v225 offset:14336
	s_add_u32 s12, s98, 0x40000
	s_addc_u32 s13, s99, 0
	s_add_u32 m0, s97, 0x4000
	s_nop 0
	global_load_lds_dwordx4 v224, s[12:13]
	v_mfma_f32_16x16x32_bf16 v[44:47], v[208:211], v[168:171], v[44:47]
	v_mfma_f32_16x16x32_bf16 v[40:43], v[208:211], v[176:179], v[40:43]
	v_mfma_f32_16x16x32_bf16 v[36:39], v[208:211], v[180:183], v[36:39]
	v_mfma_f32_16x16x32_bf16 v[32:35], v[208:211], v[184:187], v[32:35]
	ds_read_b128 v[208:211], v225 offset:10240
	s_add_u32 s12, s100, 0x40000
	s_addc_u32 s13, s101, 0
	s_add_u32 m0, s97, 0x14000
	s_nop 0
	global_load_lds_dwordx4 v224, s[12:13]
	v_mfma_f32_16x16x32_bf16 v[28:31], v[212:215], v[168:171], v[28:31]
	v_mfma_f32_16x16x32_bf16 v[24:27], v[212:215], v[176:179], v[24:27]
	v_mfma_f32_16x16x32_bf16 v[20:23], v[212:215], v[180:183], v[20:23]
	v_mfma_f32_16x16x32_bf16 v[16:19], v[212:215], v[184:187], v[16:19]
	ds_read_b128 v[212:215], v225 offset:12288
	s_add_u32 s12, s98, 0x60000
	s_addc_u32 s13, s99, 0
	s_add_u32 m0, s97, 0x6000
	s_nop 0
	global_load_lds_dwordx4 v224, s[12:13]
	v_mfma_f32_16x16x32_bf16 v[12:15], v[220:223], v[168:171], v[12:15]
	v_mfma_f32_16x16x32_bf16 v[8:11], v[220:223], v[176:179], v[8:11]
	v_mfma_f32_16x16x32_bf16 v[4:7], v[220:223], v[180:183], v[4:7]
	v_mfma_f32_16x16x32_bf16 v[0:3], v[220:223], v[184:187], v[0:3]
	s_add_u32 s12, s100, 0x60000
	s_addc_u32 s13, s101, 0
	s_add_u32 m0, s97, 0x16000
	s_nop 0
	global_load_lds_dwordx4 v224, s[12:13]
	v_xor_b32_e32 v225, 0x8000, v225
	v_xor_b32_e32 v227, 0x8000, v227
	v_xor_b32_e32 v226, 0x8000, v226
	v_xor_b32_e32 v228, 0x8000, v228
	s_xor_b32 s97, s97, 0x8000
	s_add_u32 s98, s98, 0x80
	s_addc_u32 s99, s99, 0
	s_add_u32 s100, s100, 0x80
	s_addc_u32 s101, s101, 0
	s_sub_u32 s28, s28, 1
	s_cmp_lg_u32 s28, 0
	s_cbranch_scc1 .Lgm0_loop
	s_waitcnt lgkmcnt(4)
	v_mfma_f32_16x16x32_bf16 v[124:127], v[188:191], v[152:155], v[124:127]
	v_mfma_f32_16x16x32_bf16 v[120:123], v[188:191], v[156:159], v[120:123]
	v_mfma_f32_16x16x32_bf16 v[116:119], v[188:191], v[160:163], v[116:119]
	v_mfma_f32_16x16x32_bf16 v[112:115], v[188:191], v[164:167], v[112:115]
	ds_read_b128 v[188:191], v226 offset:0
	ds_read_b128 v[168:171], v228 offset:0
	v_mfma_f32_16x16x32_bf16 v[108:111], v[192:195], v[152:155], v[108:111]
	v_mfma_f32_16x16x32_bf16 v[104:107], v[192:195], v[156:159], v[104:107]
	v_mfma_f32_16x16x32_bf16 v[100:103], v[192:195], v[160:163], v[100:103]
	v_mfma_f32_16x16x32_bf16 v[96:99], v[192:195], v[164:167], v[96:99]
	ds_read_b128 v[192:195], v226 offset:2048
	ds_read_b128 v[176:179], v228 offset:2048
	v_mfma_f32_16x16x32_bf16 v[92:95], v[196:199], v[152:155], v[92:95]
	v_mfma_f32_16x16x32_bf16 v[88:91], v[196:199], v[156:159], v[88:91]
	v_mfma_f32_16x16x32_bf16 v[84:87], v[196:199], v[160:163], v[84:87]
	v_mfma_f32_16x16x32_bf16 v[80:83], v[196:199], v[164:167], v[80:83]
	ds_read_b128 v[196:199], v226 offset:4096
	ds_read_b128 v[180:183], v228 offset:4096
	v_mfma_f32_16x16x32_bf16 v[76:79], v[200:203], v[152:155], v[76:79]
	v_mfma_f32_16x16x32_bf16 v[72:75], v[200:203], v[156:159], v[72:75]
	v_mfma_f32_16x16x32_bf16 v[68:71], v[200:203], v[160:163], v[68:71]
	v_mfma_f32_16x16x32_bf16 v[64:67], v[200:203], v[164:167], v[64:67]
	ds_read_b128 v[200:203], v226 offset:6144
	ds_read_b128 v[184:187], v228 offset:6144
	s_waitcnt lgkmcnt(11)
	v_mfma_f32_16x16x32_bf16 v[60:63], v[204:207], v[152:155], v[60:63]
	v_mfma_f32_16x16x32_bf16 v[56:59], v[204:207], v[156:159], v[56:59]
	v_mfma_f32_16x16x32_bf16 v[52:55], v[204:207], v[160:163], v[52:55]
	v_mfma_f32_16x16x32_bf16 v[48:51], v[204:207], v[164:167], v[48:51]
	ds_read_b128 v[204:207], v226 offset:8192
	ds_read_b128 v[220:223], v226 offset:14336
	s_waitcnt lgkmcnt(11)
	v_mfma_f32_16x16x32_bf16 v[44:47], v[208:211], v[152:155], v[44:47]
	v_mfma_f32_16x16x32_bf16 v[40:43], v[208:211], v[156:159], v[40:43]
	v_mfma_f32_16x16x32_bf16 v[36:39], v[208:211], v[160:163], v[36:39]
	v_mfma_f32_16x16x32_bf16 v[32:35], v[208:211], v[164:167], v[32:35]
	ds_read_b128 v[208:211], v226 offset:10240
	s_waitcnt lgkmcnt(11)
	v_mfma_f32_16x16x32_bf16 v[28:31], v[212:215], v[152:155], v[28:31]
	v_mfma_f32_16x16x32_bf16 v[24:27], v[212:215], v[156:159], v[24:27]
	v_mfma_f32_16x16x32_bf16 v[20:23], v[212:215], v[160:163], v[20:23]
	v_mfma_f32_16x16x32_bf16 v[16:19], v[212:215], v[164:167], v[16:19]
	ds_read_b128 v[212:215], v226 offset:12288
	v_mfma_f32_16x16x32_bf16 v[12:15], v[216:219], v[152:155], v[12:15]
	v_mfma_f32_16x16x32_bf16 v[8:11], v[216:219], v[156:159], v[8:11]
	v_mfma_f32_16x16x32_bf16 v[4:7], v[216:219], v[160:163], v[4:7]
	v_mfma_f32_16x16x32_bf16 v[0:3], v[216:219], v[164:167], v[0:3]
	s_waitcnt vmcnt(0) lgkmcnt(0)
	s_barrier
; #define G_LOAD(KT) do { _Pragma("unroll") for (int i = 0; i < 4; ++i) { ra[i] = *(const u32x4*)(Ag + (size_t)i * 64 * lda + (KT) * 64); rb[i] = *(const u32x4*)(Bg + (size_t)i * 64 * K + (KT) * 64); } } while (0)
; #define G_STORE(BUF) do { u16* ad = As + (BUF) * 256 * 64 + sto; u16* bd = Bs + (BUF) * 256 * 64 + sto; _Pragma("unroll") for (int i = 0; i < 4; ++i) { *(u32x4*)(ad + i * 64 * 64) = ra[i]; *(u32x4*)(bd + i * 64 * 64) = rb[i]; } } while (0)
; template <int EPI>
; DI void gemm_phase(const u16* __restrict__ A, int lda, const u16* __restrict__ Bt, int K, int N, u16* outb, int ldo,
;                    const float* r0, const float* r1, float* outf, char* lds, int bid, int nb) {
;     ...
;     G_LOAD(0);
;     G_STORE(0);
;     __syncthreads();
;     for (int kt = 0; kt < nk; ++kt) {
;       const int cur = kt & 1;
;       if (kt + 1 < nk) G_LOAD(kt + 1);
;       G_MMA(cur, fo0);
;       G_MMA(cur, fo1);
;       if (kt + 1 < nk) G_STORE(cur ^ 1);
;       __syncthreads();
;     }
	v_mfma_f32_16x16x32_bf16 v[124:127], v[188:191], v[168:171], v[124:127]
	v_mfma_f32_16x16x32_bf16 v[120:123], v[188:191], v[176:179], v[120:123]
	v_mfma_f32_16x16x32_bf16 v[116:119], v[188:191], v[180:183], v[116:119]
	v_mfma_f32_16x16x32_bf16 v[112:115], v[188:191], v[184:187], v[112:115]
	ds_read_b128 v[188:191], v225 offset:0
	ds_read_b128 v[152:155], v227 offset:0
	v_mfma_f32_16x16x32_bf16 v[108:111], v[192:195], v[168:171], v[108:111]
	v_mfma_f32_16x16x32_bf16 v[104:107], v[192:195], v[176:179], v[104:107]
	v_mfma_f32_16x16x32_bf16 v[100:103], v[192:195], v[180:183], v[100:103]
	v_mfma_f32_16x16x32_bf16 v[96:99], v[192:195], v[184:187], v[96:99]
	ds_read_b128 v[192:195], v225 offset:2048
	ds_read_b128 v[156:159], v227 offset:2048
	v_mfma_f32_16x16x32_bf16 v[92:95], v[196:199], v[168:171], v[92:95]
	v_mfma_f32_16x16x32_bf16 v[88:91], v[196:199], v[176:179], v[88:91]
	v_mfma_f32_16x16x32_bf16 v[84:87], v[196:199], v[180:183], v[84:87]
	v_mfma_f32_16x16x32_bf16 v[80:83], v[196:199], v[184:187], v[80:83]
	ds_read_b128 v[196:199], v225 offset:4096
	ds_read_b128 v[160:163], v227 offset:4096
	v_mfma_f32_16x16x32_bf16 v[76:79], v[200:203], v[168:171], v[76:79]
	v_mfma_f32_16x16x32_bf16 v[72:75], v[200:203], v[176:179], v[72:75]
	v_mfma_f32_16x16x32_bf16 v[68:71], v[200:203], v[180:183], v[68:71]
	v_mfma_f32_16x16x32_bf16 v[64:67], v[200:203], v[184:187], v[64:67]
	ds_read_b128 v[200:203], v225 offset:6144
	ds_read_b128 v[164:167], v227 offset:6144
	v_mfma_f32_16x16x32_bf16 v[60:63], v[204:207], v[168:171], v[60:63]
	v_mfma_f32_16x16x32_bf16 v[56:59], v[204:207], v[176:179], v[56:59]
	v_mfma_f32_16x16x32_bf16 v[52:55], v[204:207], v[180:183], v[52:55]
	v_mfma_f32_16x16x32_bf16 v[48:51], v[204:207], v[184:187], v[48:51]
	ds_read_b128 v[204:207], v225 offset:8192
	ds_read_b128 v[216:219], v225 offset:14336
	v_mfma_f32_16x16x32_bf16 v[44:47], v[208:211], v[168:171], v[44:47]
	v_mfma_f32_16x16x32_bf16 v[40:43], v[208:211], v[176:179], v[40:43]
	v_mfma_f32_16x16x32_bf16 v[36:39], v[208:211], v[180:183], v[36:39]
	v_mfma_f32_16x16x32_bf16 v[32:35], v[208:211], v[184:187], v[32:35]
	ds_read_b128 v[208:211], v225 offset:10240
	v_mfma_f32_16x16x32_bf16 v[28:31], v[212:215], v[168:171], v[28:31]
	v_mfma_f32_16x16x32_bf16 v[24:27], v[212:215], v[176:179], v[24:27]
	v_mfma_f32_16x16x32_bf16 v[20:23], v[212:215], v[180:183], v[20:23]
	v_mfma_f32_16x16x32_bf16 v[16:19], v[212:215], v[184:187], v[16:19]
	ds_read_b128 v[212:215], v225 offset:12288
	v_mfma_f32_16x16x32_bf16 v[12:15], v[220:223], v[168:171], v[12:15]
	v_mfma_f32_16x16x32_bf16 v[8:11], v[220:223], v[176:179], v[8:11]
	v_mfma_f32_16x16x32_bf16 v[4:7], v[220:223], v[180:183], v[4:7]
	v_mfma_f32_16x16x32_bf16 v[0:3], v[220:223], v[184:187], v[0:3]
	v_xor_b32_e32 v226, 0x8000, v226
	v_xor_b32_e32 v228, 0x8000, v228
	s_waitcnt lgkmcnt(4)
	v_mfma_f32_16x16x32_bf16 v[124:127], v[188:191], v[152:155], v[124:127]
	v_mfma_f32_16x16x32_bf16 v[120:123], v[188:191], v[156:159], v[120:123]
	v_mfma_f32_16x16x32_bf16 v[116:119], v[188:191], v[160:163], v[116:119]
	v_mfma_f32_16x16x32_bf16 v[112:115], v[188:191], v[164:167], v[112:115]
	ds_read_b128 v[188:191], v226 offset:0
	ds_read_b128 v[168:171], v228 offset:0
	v_mfma_f32_16x16x32_bf16 v[108:111], v[192:195], v[152:155], v[108:111]
	v_mfma_f32_16x16x32_bf16 v[104:107], v[192:195], v[156:159], v[104:107]
	v_mfma_f32_16x16x32_bf16 v[100:103], v[192:195], v[160:163], v[100:103]
	v_mfma_f32_16x16x32_bf16 v[96:99], v[192:195], v[164:167], v[96:99]
	ds_read_b128 v[192:195], v226 offset:2048
	ds_read_b128 v[176:179], v228 offset:2048
	v_mfma_f32_16x16x32_bf16 v[92:95], v[196:199], v[152:155], v[92:95]
	v_mfma_f32_16x16x32_bf16 v[88:91], v[196:199], v[156:159], v[88:91]
	v_mfma_f32_16x16x32_bf16 v[84:87], v[196:199], v[160:163], v[84:87]
	v_mfma_f32_16x16x32_bf16 v[80:83], v[196:199], v[164:167], v[80:83]
	ds_read_b128 v[196:199], v226 offset:4096
	ds_read_b128 v[180:183], v228 offset:4096
	v_mfma_f32_16x16x32_bf16 v[76:79], v[200:203], v[152:155], v[76:79]
	v_mfma_f32_16x16x32_bf16 v[72:75], v[200:203], v[156:159], v[72:75]
	v_mfma_f32_16x16x32_bf16 v[68:71], v[200:203], v[160:163], v[68:71]
	v_mfma_f32_16x16x32_bf16 v[64:67], v[200:203], v[164:167], v[64:67]
	ds_read_b128 v[200:203], v226 offset:6144
	ds_read_b128 v[184:187], v228 offset:6144
	s_waitcnt lgkmcnt(11)
	v_mfma_f32_16x16x32_bf16 v[60:63], v[204:207], v[152:155], v[60:63]
	v_mfma_f32_16x16x32_bf16 v[56:59], v[204:207], v[156:159], v[56:59]
	v_mfma_f32_16x16x32_bf16 v[52:55], v[204:207], v[160:163], v[52:55]
	v_mfma_f32_16x16x32_bf16 v[48:51], v[204:207], v[164:167], v[48:51]
	ds_read_b128 v[204:207], v226 offset:8192
	ds_read_b128 v[220:223], v226 offset:14336
	s_waitcnt lgkmcnt(11)
	v_mfma_f32_16x16x32_bf16 v[44:47], v[208:211], v[152:155], v[44:47]
	v_mfma_f32_16x16x32_bf16 v[40:43], v[208:211], v[156:159], v[40:43]
	v_mfma_f32_16x16x32_bf16 v[36:39], v[208:211], v[160:163], v[36:39]
	v_mfma_f32_16x16x32_bf16 v[32:35], v[208:211], v[164:167], v[32:35]
	ds_read_b128 v[208:211], v226 offset:10240
	s_waitcnt lgkmcnt(11)
	v_mfma_f32_16x16x32_bf16 v[28:31], v[212:215], v[152:155], v[28:31]
	v_mfma_f32_16x16x32_bf16 v[24:27], v[212:215], v[156:159], v[24:27]
	v_mfma_f32_16x16x32_bf16 v[20:23], v[212:215], v[160:163], v[20:23]
	v_mfma_f32_16x16x32_bf16 v[16:19], v[212:215], v[164:167], v[16:19]
	ds_read_b128 v[212:215], v226 offset:12288
	v_mfma_f32_16x16x32_bf16 v[12:15], v[216:219], v[152:155], v[12:15]
	v_mfma_f32_16x16x32_bf16 v[8:11], v[216:219], v[156:159], v[8:11]
	v_mfma_f32_16x16x32_bf16 v[4:7], v[216:219], v[160:163], v[4:7]
	v_mfma_f32_16x16x32_bf16 v[0:3], v[216:219], v[164:167], v[0:3]
	s_waitcnt vmcnt(0) lgkmcnt(0)
	s_barrier
; DI u16 f2bf(float a) { return (u16)(pk2(a, 0.f) & 0xffffu); }
; template <int EPI>
; DI void gemm_phase(const u16* __restrict__ A, int lda, const u16* __restrict__ Bt, int K, int N, u16* outb, int ldo,
;                    const float* r0, const float* r1, float* outf, char* lds, int bid, int nb) {
;     ...
;     const int mrow = tm * 256 + wr * 128 + quad * 4;
;     if constexpr (EPI == EPI_BF16) {
;       const int col = tn * 256 + wc * 64 + l15;
; #pragma unroll
;       for (int i = 0; i < 8; ++i)
; #pragma unroll
;         for (int r = 0; r < 4; ++r) {
;           u16* o0 = outb + (size_t)(mrow + i * 16 + r) * ldo + col;
;           o0[0] = f2bf(acc[i][0][r]); o0[16] = f2bf(acc[i][1][r]); o0[32] = f2bf(acc[i][2][r]); o0[48] = f2bf(acc[i][3][r]);
;         }
	v_mfma_f32_16x16x32_bf16 v[124:127], v[188:191], v[168:171], v[124:127]
	v_mfma_f32_16x16x32_bf16 v[120:123], v[188:191], v[176:179], v[120:123]
	v_mfma_f32_16x16x32_bf16 v[116:119], v[188:191], v[180:183], v[116:119]
	v_mfma_f32_16x16x32_bf16 v[112:115], v[188:191], v[184:187], v[112:115]
	v_mfma_f32_16x16x32_bf16 v[108:111], v[192:195], v[168:171], v[108:111]
	v_mfma_f32_16x16x32_bf16 v[104:107], v[192:195], v[176:179], v[104:107]
	v_mfma_f32_16x16x32_bf16 v[100:103], v[192:195], v[180:183], v[100:103]
	v_mfma_f32_16x16x32_bf16 v[96:99], v[192:195], v[184:187], v[96:99]
	v_mfma_f32_16x16x32_bf16 v[92:95], v[196:199], v[168:171], v[92:95]
	v_mfma_f32_16x16x32_bf16 v[88:91], v[196:199], v[176:179], v[88:91]
	v_mfma_f32_16x16x32_bf16 v[84:87], v[196:199], v[180:183], v[84:87]
	v_mfma_f32_16x16x32_bf16 v[80:83], v[196:199], v[184:187], v[80:83]
	v_mfma_f32_16x16x32_bf16 v[76:79], v[200:203], v[168:171], v[76:79]
	v_mfma_f32_16x16x32_bf16 v[72:75], v[200:203], v[176:179], v[72:75]
	v_mfma_f32_16x16x32_bf16 v[68:71], v[200:203], v[180:183], v[68:71]
	v_mfma_f32_16x16x32_bf16 v[64:67], v[200:203], v[184:187], v[64:67]
	v_mfma_f32_16x16x32_bf16 v[60:63], v[204:207], v[168:171], v[60:63]
	v_mfma_f32_16x16x32_bf16 v[56:59], v[204:207], v[176:179], v[56:59]
	v_mfma_f32_16x16x32_bf16 v[52:55], v[204:207], v[180:183], v[52:55]
	v_mfma_f32_16x16x32_bf16 v[48:51], v[204:207], v[184:187], v[48:51]
	v_mfma_f32_16x16x32_bf16 v[44:47], v[208:211], v[168:171], v[44:47]
	v_mfma_f32_16x16x32_bf16 v[40:43], v[208:211], v[176:179], v[40:43]
	v_mfma_f32_16x16x32_bf16 v[36:39], v[208:211], v[180:183], v[36:39]
	v_mfma_f32_16x16x32_bf16 v[32:35], v[208:211], v[184:187], v[32:35]
	v_mfma_f32_16x16x32_bf16 v[28:31], v[212:215], v[168:171], v[28:31]
	v_mfma_f32_16x16x32_bf16 v[24:27], v[212:215], v[176:179], v[24:27]
	v_mfma_f32_16x16x32_bf16 v[20:23], v[212:215], v[180:183], v[20:23]
	v_mfma_f32_16x16x32_bf16 v[16:19], v[212:215], v[184:187], v[16:19]
	v_mfma_f32_16x16x32_bf16 v[12:15], v[220:223], v[168:171], v[12:15]
	v_mfma_f32_16x16x32_bf16 v[8:11], v[220:223], v[176:179], v[8:11]
	v_mfma_f32_16x16x32_bf16 v[4:7], v[220:223], v[180:183], v[4:7]
	v_mfma_f32_16x16x32_bf16 v[0:3], v[220:223], v[184:187], v[0:3]
	s_nop 7
	s_nop 3
	v_mov_b32_e32 v164, v48
	v_mov_b32_e32 v165, v49
	v_mov_b32_e32 v166, v50
	v_mov_b32_e32 v167, v51
	v_or_b32_e32 v48, s57, v144
	v_ashrrev_i32_e32 v49, 31, v48
	v_add_u32_e32 v134, s56, v143
	v_lshl_add_u64 v[48:49], v[48:49], 1, s[8:9]
	v_mad_i64_i32 v[50:51], s[12:13], v134, s53, v[48:49]
	v_cvt_pk_bf16_f32 v124, v124, s0
	v_cvt_pk_bf16_f32 v120, v120, s0
	v_cvt_pk_bf16_f32 v116, v116, s0
	v_cvt_pk_bf16_f32 v112, v112, s0
	global_store_short v[50:51], v124, off
	global_store_short v[50:51], v120, off offset:32
	global_store_short v[50:51], v116, off offset:64
	global_store_short v[50:51], v112, off offset:96
	v_or_b32_e32 v50, 1, v134
	v_mad_i64_i32 v[50:51], s[12:13], v50, s53, v[48:49]
	v_cvt_pk_bf16_f32 v112, v125, s0
	global_store_short v[50:51], v112, off
	v_cvt_pk_bf16_f32 v112, v121, s0
	global_store_short v[50:51], v112, off offset:32
	v_cvt_pk_bf16_f32 v112, v117, s0
	global_store_short v[50:51], v112, off offset:64
	v_cvt_pk_bf16_f32 v112, v113, s0
	global_store_short v[50:51], v112, off offset:96
	v_or_b32_e32 v50, 2, v134
	v_mad_i64_i32 v[50:51], s[12:13], v50, s53, v[48:49]
	v_cvt_pk_bf16_f32 v112, v126, s0
	global_store_short v[50:51], v112, off
	v_cvt_pk_bf16_f32 v112, v122, s0
	global_store_short v[50:51], v112, off offset:32
	v_cvt_pk_bf16_f32 v112, v118, s0
	global_store_short v[50:51], v112, off offset:64
	v_cvt_pk_bf16_f32 v112, v114, s0
	global_store_short v[50:51], v112, off offset:96
	v_or_b32_e32 v50, 3, v134
	v_mad_i64_i32 v[50:51], s[12:13], v50, s53, v[48:49]
	v_cvt_pk_bf16_f32 v112, v127, s0
	global_store_short v[50:51], v112, off
	v_cvt_pk_bf16_f32 v112, v123, s0
	global_store_short v[50:51], v112, off offset:32
	v_cvt_pk_bf16_f32 v112, v119, s0
	global_store_short v[50:51], v112, off offset:64
	v_cvt_pk_bf16_f32 v112, v115, s0
	global_store_short v[50:51], v112, off offset:96
	v_or_b32_e32 v50, 16, v134
	v_mad_i64_i32 v[50:51], s[12:13], v50, s53, v[48:49]
	v_cvt_pk_bf16_f32 v108, v108, s0
	v_cvt_pk_bf16_f32 v104, v104, s0
	v_cvt_pk_bf16_f32 v100, v100, s0
	v_cvt_pk_bf16_f32 v96, v96, s0
	global_store_short v[50:51], v108, off
	global_store_short v[50:51], v104, off offset:32
	global_store_short v[50:51], v100, off offset:64
	global_store_short v[50:51], v96, off offset:96
	v_or_b32_e32 v50, 17, v134
	v_mad_i64_i32 v[50:51], s[12:13], v50, s53, v[48:49]
	v_cvt_pk_bf16_f32 v96, v109, s0
	global_store_short v[50:51], v96, off
	v_cvt_pk_bf16_f32 v96, v105, s0
	global_store_short v[50:51], v96, off offset:32
	v_cvt_pk_bf16_f32 v96, v101, s0
	global_store_short v[50:51], v96, off offset:64
	v_cvt_pk_bf16_f32 v96, v97, s0
	global_store_short v[50:51], v96, off offset:96
	v_or_b32_e32 v50, 18, v134
	v_mad_i64_i32 v[50:51], s[12:13], v50, s53, v[48:49]
	v_cvt_pk_bf16_f32 v96, v110, s0
	global_store_short v[50:51], v96, off
	v_cvt_pk_bf16_f32 v96, v106, s0
	global_store_short v[50:51], v96, off offset:32
	v_cvt_pk_bf16_f32 v96, v102, s0
	global_store_short v[50:51], v96, off offset:64
	v_cvt_pk_bf16_f32 v96, v98, s0
	global_store_short v[50:51], v96, off offset:96
	v_or_b32_e32 v50, 19, v134
	v_mad_i64_i32 v[50:51], s[12:13], v50, s53, v[48:49]
	v_cvt_pk_bf16_f32 v96, v111, s0
	global_store_short v[50:51], v96, off
	v_cvt_pk_bf16_f32 v96, v107, s0
	global_store_short v[50:51], v96, off offset:32
	v_cvt_pk_bf16_f32 v96, v103, s0
	global_store_short v[50:51], v96, off offset:64
	v_cvt_pk_bf16_f32 v96, v99, s0
; DI u16 f2bf(float a) { return (u16)(pk2(a, 0.f) & 0xffffu); }
; template <int EPI>
; DI void gemm_phase(const u16* __restrict__ A, int lda, const u16* __restrict__ Bt, int K, int N, u16* outb, int ldo,
;                    const float* r0, const float* r1, float* outf, char* lds, int bid, int nb) {
;     ...
;       for (int i = 0; i < 8; ++i)
; #pragma unroll
;         for (int r = 0; r < 4; ++r) {
;           u16* o0 = outb + (size_t)(mrow + i * 16 + r) * ldo + col;
;           o0[0] = f2bf(acc[i][0][r]); o0[16] = f2bf(acc[i][1][r]); o0[32] = f2bf(acc[i][2][r]); o0[48] = f2bf(acc[i][3][r]);
;         }
	global_store_short v[50:51], v96, off offset:96
	v_or_b32_e32 v50, 32, v134
	v_mad_i64_i32 v[50:51], s[12:13], v50, s53, v[48:49]
	v_cvt_pk_bf16_f32 v92, v92, s0
	v_cvt_pk_bf16_f32 v88, v88, s0
	v_cvt_pk_bf16_f32 v84, v84, s0
	v_cvt_pk_bf16_f32 v80, v80, s0
	global_store_short v[50:51], v92, off
	global_store_short v[50:51], v88, off offset:32
	global_store_short v[50:51], v84, off offset:64
	global_store_short v[50:51], v80, off offset:96
	v_or_b32_e32 v50, 33, v134
	v_mad_i64_i32 v[50:51], s[12:13], v50, s53, v[48:49]
	v_cvt_pk_bf16_f32 v80, v93, s0
	global_store_short v[50:51], v80, off
	v_cvt_pk_bf16_f32 v80, v89, s0
	global_store_short v[50:51], v80, off offset:32
	v_cvt_pk_bf16_f32 v80, v85, s0
	global_store_short v[50:51], v80, off offset:64
	v_cvt_pk_bf16_f32 v80, v81, s0
	global_store_short v[50:51], v80, off offset:96
	v_or_b32_e32 v50, 34, v134
	v_mad_i64_i32 v[50:51], s[12:13], v50, s53, v[48:49]
	v_cvt_pk_bf16_f32 v80, v94, s0
	global_store_short v[50:51], v80, off
	v_cvt_pk_bf16_f32 v80, v90, s0
	global_store_short v[50:51], v80, off offset:32
	v_cvt_pk_bf16_f32 v80, v86, s0
	global_store_short v[50:51], v80, off offset:64
	v_cvt_pk_bf16_f32 v80, v82, s0
	global_store_short v[50:51], v80, off offset:96
	v_or_b32_e32 v50, 35, v134
	v_mad_i64_i32 v[50:51], s[12:13], v50, s53, v[48:49]
	v_cvt_pk_bf16_f32 v80, v95, s0
	global_store_short v[50:51], v80, off
	v_cvt_pk_bf16_f32 v80, v91, s0
	global_store_short v[50:51], v80, off offset:32
	v_cvt_pk_bf16_f32 v80, v87, s0
	global_store_short v[50:51], v80, off offset:64
	v_cvt_pk_bf16_f32 v80, v83, s0
	global_store_short v[50:51], v80, off offset:96
	v_or_b32_e32 v50, 48, v134
	v_mad_i64_i32 v[50:51], s[12:13], v50, s53, v[48:49]
	v_cvt_pk_bf16_f32 v76, v76, s0
	v_cvt_pk_bf16_f32 v72, v72, s0
	v_cvt_pk_bf16_f32 v68, v68, s0
	v_cvt_pk_bf16_f32 v64, v64, s0
	global_store_short v[50:51], v76, off
	global_store_short v[50:51], v72, off offset:32
	global_store_short v[50:51], v68, off offset:64
	global_store_short v[50:51], v64, off offset:96
	v_or_b32_e32 v50, 49, v134
	v_mad_i64_i32 v[50:51], s[12:13], v50, s53, v[48:49]
	v_cvt_pk_bf16_f32 v64, v77, s0
	global_store_short v[50:51], v64, off
	v_cvt_pk_bf16_f32 v64, v73, s0
	global_store_short v[50:51], v64, off offset:32
	v_cvt_pk_bf16_f32 v64, v69, s0
	global_store_short v[50:51], v64, off offset:64
	v_cvt_pk_bf16_f32 v64, v65, s0
	global_store_short v[50:51], v64, off offset:96
	v_or_b32_e32 v50, 50, v134
	v_mad_i64_i32 v[50:51], s[12:13], v50, s53, v[48:49]
	v_cvt_pk_bf16_f32 v64, v78, s0
	global_store_short v[50:51], v64, off
	v_cvt_pk_bf16_f32 v64, v74, s0
	global_store_short v[50:51], v64, off offset:32
	v_cvt_pk_bf16_f32 v64, v70, s0
	global_store_short v[50:51], v64, off offset:64
	v_cvt_pk_bf16_f32 v64, v66, s0
	global_store_short v[50:51], v64, off offset:96
	v_or_b32_e32 v50, 51, v134
	v_mad_i64_i32 v[50:51], s[12:13], v50, s53, v[48:49]
	v_cvt_pk_bf16_f32 v64, v79, s0
	global_store_short v[50:51], v64, off
	v_cvt_pk_bf16_f32 v64, v75, s0
	global_store_short v[50:51], v64, off offset:32
	v_cvt_pk_bf16_f32 v64, v71, s0
	global_store_short v[50:51], v64, off offset:64
	v_cvt_pk_bf16_f32 v64, v67, s0
	global_store_short v[50:51], v64, off offset:96
	v_or_b32_e32 v50, 64, v134
	v_mad_i64_i32 v[50:51], s[12:13], v50, s53, v[48:49]
	v_cvt_pk_bf16_f32 v52, v52, s0
	v_cvt_pk_bf16_f32 v60, v60, s0
	v_cvt_pk_bf16_f32 v56, v56, s0
	global_store_short v[50:51], v52, off offset:64
	v_cvt_pk_bf16_f32 v52, v164, s0
	global_store_short v[50:51], v60, off
	global_store_short v[50:51], v56, off offset:32
	global_store_short v[50:51], v52, off offset:96
	v_or_b32_e32 v50, 0x41, v134
	v_mad_i64_i32 v[50:51], s[12:13], v50, s53, v[48:49]
	v_cvt_pk_bf16_f32 v52, v61, s0
	global_store_short v[50:51], v52, off
	v_cvt_pk_bf16_f32 v52, v57, s0
	global_store_short v[50:51], v52, off offset:32
	v_cvt_pk_bf16_f32 v52, v53, s0
	global_store_short v[50:51], v52, off offset:64
	v_cvt_pk_bf16_f32 v52, v165, s0
	global_store_short v[50:51], v52, off offset:96
	v_or_b32_e32 v50, 0x42, v134
	v_mad_i64_i32 v[50:51], s[12:13], v50, s53, v[48:49]
	v_cvt_pk_bf16_f32 v52, v62, s0
	global_store_short v[50:51], v52, off
	v_cvt_pk_bf16_f32 v52, v58, s0
	global_store_short v[50:51], v52, off offset:32
	v_cvt_pk_bf16_f32 v52, v54, s0
	global_store_short v[50:51], v52, off offset:64
	v_cvt_pk_bf16_f32 v52, v166, s0
	global_store_short v[50:51], v52, off offset:96
	v_or_b32_e32 v50, 0x43, v134
	v_mad_i64_i32 v[50:51], s[12:13], v50, s53, v[48:49]
	v_cvt_pk_bf16_f32 v52, v63, s0
	global_store_short v[50:51], v52, off
	v_cvt_pk_bf16_f32 v52, v59, s0
	global_store_short v[50:51], v52, off offset:32
	v_cvt_pk_bf16_f32 v52, v55, s0
	global_store_short v[50:51], v52, off offset:64
	v_cvt_pk_bf16_f32 v52, v167, s0
	global_store_short v[50:51], v52, off offset:96
; DI u16 f2bf(float a) { return (u16)(pk2(a, 0.f) & 0xffffu); }
; template <int EPI>
; DI void gemm_phase(const u16* __restrict__ A, int lda, const u16* __restrict__ Bt, int K, int N, u16* outb, int ldo,
;                    const float* r0, const float* r1, float* outf, char* lds, int bid, int nb) {
;     ...
;       for (int i = 0; i < 8; ++i)
; #pragma unroll
;         for (int r = 0; r < 4; ++r) {
;           u16* o0 = outb + (size_t)(mrow + i * 16 + r) * ldo + col;
;           o0[0] = f2bf(acc[i][0][r]); o0[16] = f2bf(acc[i][1][r]); o0[32] = f2bf(acc[i][2][r]); o0[48] = f2bf(acc[i][3][r]);
;         }
	v_or_b32_e32 v50, 0x50, v134
	v_mad_i64_i32 v[50:51], s[12:13], v50, s53, v[48:49]
	v_cvt_pk_bf16_f32 v32, v32, s0
	v_cvt_pk_bf16_f32 v44, v44, s0
	v_cvt_pk_bf16_f32 v40, v40, s0
	v_cvt_pk_bf16_f32 v36, v36, s0
	global_store_short v[50:51], v32, off offset:96
	v_or_b32_e32 v32, 0x51, v134
	global_store_short v[50:51], v44, off
	global_store_short v[50:51], v40, off offset:32
	global_store_short v[50:51], v36, off offset:64
	v_mad_i64_i32 v[50:51], s[12:13], v32, s53, v[48:49]
	v_cvt_pk_bf16_f32 v32, v45, s0
	global_store_short v[50:51], v32, off
	v_cvt_pk_bf16_f32 v32, v41, s0
	global_store_short v[50:51], v32, off offset:32
	v_cvt_pk_bf16_f32 v32, v37, s0
	global_store_short v[50:51], v32, off offset:64
	v_cvt_pk_bf16_f32 v32, v33, s0
	global_store_short v[50:51], v32, off offset:96
	v_or_b32_e32 v32, 0x52, v134
	v_mad_i64_i32 v[32:33], s[12:13], v32, s53, v[48:49]
	v_cvt_pk_bf16_f32 v36, v46, s0
	global_store_short v[32:33], v36, off
	v_cvt_pk_bf16_f32 v36, v42, s0
	global_store_short v[32:33], v36, off offset:32
	v_cvt_pk_bf16_f32 v36, v38, s0
	v_cvt_pk_bf16_f32 v34, v34, s0
	global_store_short v[32:33], v36, off offset:64
	global_store_short v[32:33], v34, off offset:96
	v_or_b32_e32 v32, 0x53, v134
	v_mad_i64_i32 v[32:33], s[12:13], v32, s53, v[48:49]
	v_cvt_pk_bf16_f32 v34, v47, s0
	global_store_short v[32:33], v34, off
	v_cvt_pk_bf16_f32 v34, v43, s0
	global_store_short v[32:33], v34, off offset:32
	v_cvt_pk_bf16_f32 v34, v39, s0
	global_store_short v[32:33], v34, off offset:64
	v_cvt_pk_bf16_f32 v34, v35, s0
	global_store_short v[32:33], v34, off offset:96
	v_or_b32_e32 v32, 0x60, v134
	v_mad_i64_i32 v[32:33], s[12:13], v32, s53, v[48:49]
	v_cvt_pk_bf16_f32 v16, v16, s0
	v_cvt_pk_bf16_f32 v28, v28, s0
	v_cvt_pk_bf16_f32 v24, v24, s0
	v_cvt_pk_bf16_f32 v20, v20, s0
	global_store_short v[32:33], v16, off offset:96
	v_or_b32_e32 v16, 0x61, v134
	global_store_short v[32:33], v28, off
	global_store_short v[32:33], v24, off offset:32
	global_store_short v[32:33], v20, off offset:64
	v_mad_i64_i32 v[32:33], s[12:13], v16, s53, v[48:49]
	v_cvt_pk_bf16_f32 v16, v29, s0
	global_store_short v[32:33], v16, off
	v_cvt_pk_bf16_f32 v16, v25, s0
	global_store_short v[32:33], v16, off offset:32
	v_cvt_pk_bf16_f32 v16, v21, s0
	global_store_short v[32:33], v16, off offset:64
	v_cvt_pk_bf16_f32 v16, v17, s0
	global_store_short v[32:33], v16, off offset:96
	v_or_b32_e32 v16, 0x62, v134
	v_mad_i64_i32 v[16:17], s[12:13], v16, s53, v[48:49]
	v_cvt_pk_bf16_f32 v20, v30, s0
	global_store_short v[16:17], v20, off
	v_cvt_pk_bf16_f32 v20, v26, s0
	global_store_short v[16:17], v20, off offset:32
	v_cvt_pk_bf16_f32 v20, v22, s0
	v_cvt_pk_bf16_f32 v18, v18, s0
	global_store_short v[16:17], v20, off offset:64
	global_store_short v[16:17], v18, off offset:96
	v_or_b32_e32 v16, 0x63, v134
	v_mad_i64_i32 v[16:17], s[12:13], v16, s53, v[48:49]
	v_cvt_pk_bf16_f32 v18, v31, s0
	global_store_short v[16:17], v18, off
	v_cvt_pk_bf16_f32 v18, v27, s0
	global_store_short v[16:17], v18, off offset:32
	v_cvt_pk_bf16_f32 v18, v23, s0
	global_store_short v[16:17], v18, off offset:64
	v_cvt_pk_bf16_f32 v18, v19, s0
	global_store_short v[16:17], v18, off offset:96
	v_or_b32_e32 v16, 0x70, v134
	v_mad_i64_i32 v[16:17], s[12:13], v16, s53, v[48:49]
	v_cvt_pk_bf16_f32 v0, v0, s0
	v_cvt_pk_bf16_f32 v12, v12, s0
	v_cvt_pk_bf16_f32 v8, v8, s0
	v_cvt_pk_bf16_f32 v4, v4, s0
	global_store_short v[16:17], v0, off offset:96
	v_or_b32_e32 v0, 0x71, v134
	global_store_short v[16:17], v12, off
	global_store_short v[16:17], v8, off offset:32
	global_store_short v[16:17], v4, off offset:64
	v_mad_i64_i32 v[16:17], s[12:13], v0, s53, v[48:49]
	v_cvt_pk_bf16_f32 v0, v13, s0
	global_store_short v[16:17], v0, off
	v_cvt_pk_bf16_f32 v0, v9, s0
	global_store_short v[16:17], v0, off offset:32
	v_cvt_pk_bf16_f32 v0, v5, s0
	global_store_short v[16:17], v0, off offset:64
	v_cvt_pk_bf16_f32 v0, v1, s0
	global_store_short v[16:17], v0, off offset:96
	v_or_b32_e32 v0, 0x72, v134
	v_mad_i64_i32 v[0:1], s[12:13], v0, s53, v[48:49]
	v_cvt_pk_bf16_f32 v4, v14, s0
	global_store_short v[0:1], v4, off
	v_cvt_pk_bf16_f32 v4, v10, s0
	global_store_short v[0:1], v4, off offset:32
	v_cvt_pk_bf16_f32 v4, v6, s0
	v_cvt_pk_bf16_f32 v2, v2, s0
	global_store_short v[0:1], v4, off offset:64
	global_store_short v[0:1], v2, off offset:96
	v_or_b32_e32 v0, 0x73, v134
	v_mad_i64_i32 v[0:1], s[12:13], v0, s53, v[48:49]
	v_cvt_pk_bf16_f32 v2, v15, s0
	global_store_short v[0:1], v2, off
	v_cvt_pk_bf16_f32 v2, v11, s0
	global_store_short v[0:1], v2, off offset:32
	v_cvt_pk_bf16_f32 v2, v7, s0
	s_add_i32 s18, s18, 1
	global_store_short v[0:1], v2, off offset:64
	v_cvt_pk_bf16_f32 v2, v3, s0
	s_cmp_eq_u32 s18, s14
	global_store_short v[0:1], v2, off offset:96
	s_cbranch_scc0 .LBB0_283

; #define G_LOAD(KT) do { _Pragma("unroll") for (int i = 0; i < 4; ++i) { ra[i] = *(const u32x4*)(Ag + (size_t)i * 64 * lda + (KT) * 64); rb[i] = *(const u32x4*)(Bg + (size_t)i * 64 * K + (KT) * 64); } } while (0)
; #define G_STORE(BUF) do { u16* ad = As + (BUF) * 256 * 64 + sto; u16* bd = Bs + (BUF) * 256 * 64 + sto; _Pragma("unroll") for (int i = 0; i < 4; ++i) { *(u32x4*)(ad + i * 64 * 64) = ra[i]; *(u32x4*)(bd + i * 64 * 64) = rb[i]; } } while (0)
; template <int EPI>
; DI void gemm_phase(const u16* __restrict__ A, int lda, const u16* __restrict__ Bt, int K, int N, u16* outb, int ldo,
;                    const float* r0, const float* r1, float* outf, char* lds, int bid, int nb) {
;     ...
;     const u16* Ag = A + (size_t)(tm * 256 + lrow) * lda + lch * 8;
;     const u16* Bg = Bt + (size_t)(tn * 256 + lrow) * K + lch * 8;
;     f32x4 acc[8][4];
; #pragma unroll
;     for (int i = 0; i < 8; ++i)
; #pragma unroll
;       for (int j = 0; j < 4; ++j) acc[i][j] = (f32x4){0.f, 0.f, 0.f, 0.f};
;     u32x4 ra[4], rb[4];
;     ...
;     G_LOAD(0);
;     G_STORE(0);
;     __syncthreads();
.LBB0_581:
	s_lshl_b32 s52, s51, 8
	v_or_b32_e32 v0, s52, v138
	v_ashrrev_i32_e32 v1, 31, v0
	s_lshl_b32 s53, s53, 8
	v_or_b32_e32 v2, s53, v138
	v_lshlrev_b64 v[62:63], 11, v[0:1]
	v_ashrrev_i32_e32 v3, 31, v2
	v_lshl_add_u64 v[0:1], v[128:129], 0, v[62:63]
	v_lshlrev_b64 v[64:65], 11, v[2:3]
	v_add_co_u32_e32 v4, vcc, s19, v0
	v_lshl_add_u64 v[2:3], v[130:131], 0, v[64:65]
	s_nop 0
	v_addc_co_u32_e32 v5, vcc, 0, v1, vcc
	v_add_co_u32_e32 v6, vcc, s19, v2
	s_nop 1
	v_readfirstlane_b32 s98, v0
	v_readfirstlane_b32 s99, v1
	s_nop 1
	v_readfirstlane_b32 s100, v2
	v_readfirstlane_b32 s101, v3
	v_addc_co_u32_e32 v7, vcc, 0, v3, vcc
	v_add_co_u32_e32 v4, vcc, s20, v0
	s_mov_b32 s54, 0
	s_nop 0
	v_addc_co_u32_e32 v5, vcc, 0, v1, vcc
	v_add_co_u32_e32 v6, vcc, s20, v2
	s_mov_b64 s[8:9], 0
	s_nop 0
	v_addc_co_u32_e32 v7, vcc, 0, v3, vcc
	v_add_co_u32_e32 v0, vcc, s21, v0
	v_addc_co_u32_e32 v1, vcc, 0, v1, vcc
	v_add_co_u32_e32 v2, vcc, s21, v2
	v_lshl_add_u64 v[134:135], v[132:133], 0, v[62:63]
	s_nop 0
	v_addc_co_u32_e32 v3, vcc, 0, v3, vcc
	v_mov_b32_e32 v0, 0
	v_mov_b32_e32 v1, v0
	v_mov_b32_e32 v2, v0
	v_mov_b32_e32 v3, v0
	v_mov_b32_e32 v4, v0
	v_mov_b32_e32 v5, v0
	v_mov_b32_e32 v6, v0
	v_mov_b32_e32 v7, v0
	v_mov_b32_e32 v8, v0
	v_mov_b32_e32 v9, v0
	v_mov_b32_e32 v10, v0
	v_mov_b32_e32 v11, v0
	v_mov_b32_e32 v12, v0
	v_mov_b32_e32 v13, v0
	v_mov_b32_e32 v14, v0
	v_mov_b32_e32 v15, v0
	v_mov_b32_e32 v16, v0
	v_mov_b32_e32 v17, v0
	v_mov_b32_e32 v18, v0
	v_mov_b32_e32 v19, v0
	v_mov_b32_e32 v20, v0
	v_mov_b32_e32 v21, v0
	v_mov_b32_e32 v22, v0
	v_mov_b32_e32 v23, v0
	v_mov_b32_e32 v24, v0
	v_mov_b32_e32 v25, v0
	v_mov_b32_e32 v26, v0
	v_mov_b32_e32 v27, v0
	v_mov_b32_e32 v28, v0
	v_mov_b32_e32 v29, v0
	v_lshl_add_u64 v[136:137], v[132:133], 0, v[64:65]
	v_mov_b32_e32 v62, v0
	v_mov_b32_e32 v63, v0
	v_mov_b32_e32 v64, v0
	v_mov_b32_e32 v65, v0
	v_mov_b32_e32 v66, v0
	v_mov_b32_e32 v67, v0
	v_mov_b32_e32 v68, v0
	v_mov_b32_e32 v69, v0
	v_mov_b32_e32 v70, v0
	v_mov_b32_e32 v71, v0
	v_mov_b32_e32 v72, v0
	v_mov_b32_e32 v73, v0
	v_mov_b32_e32 v74, v0
	v_mov_b32_e32 v75, v0
	v_mov_b32_e32 v76, v0
	v_mov_b32_e32 v77, v0
	v_mov_b32_e32 v78, v0
	v_mov_b32_e32 v79, v0
	v_mov_b32_e32 v80, v0
	v_mov_b32_e32 v81, v0
	v_mov_b32_e32 v82, v0
	v_mov_b32_e32 v83, v0
	v_mov_b32_e32 v84, v0
	v_mov_b32_e32 v85, v0
	v_mov_b32_e32 v30, v0
	v_mov_b32_e32 v31, v0
	v_mov_b32_e32 v32, v0
	v_mov_b32_e32 v33, v0
	v_mov_b32_e32 v34, v0
	v_mov_b32_e32 v35, v0
	v_mov_b32_e32 v36, v0
	v_mov_b32_e32 v37, v0
	v_mov_b32_e32 v38, v0
	v_mov_b32_e32 v39, v0
	v_mov_b32_e32 v40, v0
	v_mov_b32_e32 v41, v0
	v_mov_b32_e32 v42, v0
	v_mov_b32_e32 v43, v0
	v_mov_b32_e32 v44, v0
	v_mov_b32_e32 v45, v0
	v_mov_b32_e32 v46, v0
	v_mov_b32_e32 v47, v0
	v_mov_b32_e32 v48, v0
	v_mov_b32_e32 v49, v0
	v_mov_b32_e32 v50, v0
	v_mov_b32_e32 v51, v0
	v_mov_b32_e32 v52, v0
	v_mov_b32_e32 v53, v0
	v_mov_b32_e32 v54, v0
	v_mov_b32_e32 v55, v0
	v_mov_b32_e32 v56, v0
	v_mov_b32_e32 v57, v0
	v_mov_b32_e32 v58, v0
	v_mov_b32_e32 v59, v0
	v_mov_b32_e32 v60, v0
	v_mov_b32_e32 v61, v0
	v_mov_b32_e32 v86, v0
	v_mov_b32_e32 v87, v0
	v_mov_b32_e32 v88, v0
	v_mov_b32_e32 v89, v0
	v_mov_b32_e32 v90, v0
	v_mov_b32_e32 v91, v0
	v_mov_b32_e32 v92, v0
	v_mov_b32_e32 v93, v0
	v_mov_b32_e32 v94, v0
	v_mov_b32_e32 v95, v0
	v_mov_b32_e32 v96, v0
	v_mov_b32_e32 v97, v0
	v_mov_b32_e32 v98, v0
	v_mov_b32_e32 v99, v0
	v_mov_b32_e32 v100, v0
	v_mov_b32_e32 v101, v0
	v_mov_b32_e32 v102, v0
	v_mov_b32_e32 v103, v0
	v_mov_b32_e32 v104, v0
	v_mov_b32_e32 v105, v0
	v_mov_b32_e32 v106, v0
	v_mov_b32_e32 v107, v0
	v_mov_b32_e32 v108, v0
	v_mov_b32_e32 v109, v0
	v_mov_b32_e32 v110, v0
	v_mov_b32_e32 v111, v0
	v_mov_b32_e32 v112, v0
	v_mov_b32_e32 v113, v0
	v_mov_b32_e32 v114, v0
	v_mov_b32_e32 v115, v0
	v_mov_b32_e32 v116, v0
	v_mov_b32_e32 v117, v0
	v_mov_b32_e32 v118, v0
	v_mov_b32_e32 v119, v0
	v_mov_b32_e32 v120, v0
	v_mov_b32_e32 v121, v0
	v_mov_b32_e32 v122, v0
	v_mov_b32_e32 v123, v0
	v_mov_b32_e32 v124, v0
	v_mov_b32_e32 v125, v0
	v_mov_b32_e32 v126, v0
	v_mov_b32_e32 v127, v0
	v_and_b32_e32 v229, 63, v174
	v_lshrrev_b32_e32 v230, 3, v229
	v_mov_b32_e32 v233, 0x800
	v_mul_u32_u24_e32 v224, v230, v233
	v_bfe_u32 v231, v174, 4, 2
	v_bfe_u32 v232, v174, 6, 1
	v_lshl_or_b32 v232, v232, 2, v231
	v_and_b32_e32 v233, 7, v174
	v_xor_b32_e32 v232, v232, v233
	v_lshl_add_u32 v224, v232, 4, v224
	v_and_b32_e32 v229, 15, v174
	v_bfe_u32 v230, v174, 1, 3
	v_xor_b32_e32 v230, v230, v231
	v_lshlrev_b32_e32 v230, 4, v230
	v_lshl_or_b32 v230, v229, 7, v230
	v_lshrrev_b32_e32 v229, 8, v174
	v_lshl_or_b32 v225, v229, 14, v230
	v_bfe_u32 v229, v174, 6, 2
	v_lshl_or_b32 v227, v229, 13, v230
	v_or_b32_e32 v227, 0x10000, v227
	v_xor_b32_e32 v226, 64, v225
	v_xor_b32_e32 v228, 64, v227
	v_readfirstlane_b32 s97, v174
	s_lshl_b32 s97, s97, 4
	s_mov_b32 s28, 14
	s_add_u32 s8, s98, 0x0
	s_addc_u32 s9, s99, 0
	s_add_u32 m0, s97, 0x0
	s_nop 0
	global_load_lds_dwordx4 v224, s[8:9]
	s_add_u32 s8, s100, 0x0
	s_addc_u32 s9, s101, 0
	s_add_u32 m0, s97, 0x10000
	s_nop 0
	global_load_lds_dwordx4 v224, s[8:9]
	s_add_u32 s8, s98, 0x20000
	s_addc_u32 s9, s99, 0
	s_add_u32 m0, s97, 0x2000
	s_nop 0
	global_load_lds_dwordx4 v224, s[8:9]
	s_add_u32 s8, s100, 0x20000
	s_addc_u32 s9, s101, 0
	s_add_u32 m0, s97, 0x12000
	s_nop 0
	global_load_lds_dwordx4 v224, s[8:9]
	s_add_u32 s8, s98, 0x40000
	s_addc_u32 s9, s99, 0
	s_add_u32 m0, s97, 0x4000
	s_nop 0
	global_load_lds_dwordx4 v224, s[8:9]
	s_add_u32 s8, s100, 0x40000
	s_addc_u32 s9, s101, 0
	s_add_u32 m0, s97, 0x14000
	s_nop 0
	global_load_lds_dwordx4 v224, s[8:9]
	s_add_u32 s8, s98, 0x60000
	s_addc_u32 s9, s99, 0
	s_add_u32 m0, s97, 0x6000
	s_nop 0
	global_load_lds_dwordx4 v224, s[8:9]
	s_add_u32 s8, s100, 0x60000
	s_addc_u32 s9, s101, 0
	s_add_u32 m0, s97, 0x16000
	s_nop 0
	global_load_lds_dwordx4 v224, s[8:9]
	s_add_u32 s8, s98, 0x80
	s_addc_u32 s9, s99, 0
	s_add_u32 m0, s97, 0x8000
	s_nop 0
	global_load_lds_dwordx4 v224, s[8:9]
	s_add_u32 s8, s100, 0x80
	s_addc_u32 s9, s101, 0
	s_add_u32 m0, s97, 0x18000
	s_nop 0
	global_load_lds_dwordx4 v224, s[8:9]
	s_add_u32 s8, s98, 0x20080
	s_addc_u32 s9, s99, 0
	s_add_u32 m0, s97, 0xa000
	s_nop 0
	global_load_lds_dwordx4 v224, s[8:9]
	s_add_u32 s8, s100, 0x20080
	s_addc_u32 s9, s101, 0
	s_add_u32 m0, s97, 0x1a000
	s_nop 0
	global_load_lds_dwordx4 v224, s[8:9]
	s_add_u32 s8, s98, 0x40080
	s_addc_u32 s9, s99, 0
	s_add_u32 m0, s97, 0xc000
	s_nop 0
	global_load_lds_dwordx4 v224, s[8:9]
	s_add_u32 s8, s100, 0x40080
	s_addc_u32 s9, s101, 0
	s_add_u32 m0, s97, 0x1c000
	s_nop 0
	global_load_lds_dwordx4 v224, s[8:9]
	s_add_u32 s8, s98, 0x60080
	s_addc_u32 s9, s99, 0
	s_add_u32 m0, s97, 0xe000
	s_nop 0
	global_load_lds_dwordx4 v224, s[8:9]
	s_add_u32 s8, s100, 0x60080
	s_addc_u32 s9, s101, 0
	s_add_u32 m0, s97, 0x1e000
	s_nop 0
	global_load_lds_dwordx4 v224, s[8:9]
	s_add_u32 s98, s98, 0x100
	s_addc_u32 s99, s99, 0
	s_add_u32 s100, s100, 0x100
	s_addc_u32 s101, s101, 0
	s_waitcnt vmcnt(8)
	s_barrier
; #define G_LOAD(KT) do { _Pragma("unroll") for (int i = 0; i < 4; ++i) { ra[i] = *(const u32x4*)(Ag + (size_t)i * 64 * lda + (KT) * 64); rb[i] = *(const u32x4*)(Bg + (size_t)i * 64 * K + (KT) * 64); } } while (0)
; #define G_STORE(BUF) do { u16* ad = As + (BUF) * 256 * 64 + sto; u16* bd = Bs + (BUF) * 256 * 64 + sto; _Pragma("unroll") for (int i = 0; i < 4; ++i) { *(u32x4*)(ad + i * 64 * 64) = ra[i]; *(u32x4*)(bd + i * 64 * 64) = rb[i]; } } while (0)
; template <int EPI>
; DI void gemm_phase(const u16* __restrict__ A, int lda, const u16* __restrict__ Bt, int K, int N, u16* outb, int ldo,
;                    const float* r0, const float* r1, float* outf, char* lds, int bid, int nb) {
;     ...
;     G_LOAD(0);
;     G_STORE(0);
;     __syncthreads();
;     for (int kt = 0; kt < nk; ++kt) {
;       const int cur = kt & 1;
;       if (kt + 1 < nk) G_LOAD(kt + 1);
;       G_MMA(cur, fo0);
;       G_MMA(cur, fo1);
;       if (kt + 1 < nk) G_STORE(cur ^ 1);
;       __syncthreads();
;     }
	ds_read_b128 v[152:155], v227 offset:0
	ds_read_b128 v[156:159], v227 offset:2048
	ds_read_b128 v[160:163], v227 offset:4096
	ds_read_b128 v[164:167], v227 offset:6144
	ds_read_b128 v[188:191], v225 offset:0
	ds_read_b128 v[192:195], v225 offset:2048
	ds_read_b128 v[196:199], v225 offset:4096
	ds_read_b128 v[200:203], v225 offset:6144
	ds_read_b128 v[204:207], v225 offset:8192
	ds_read_b128 v[208:211], v225 offset:10240
	ds_read_b128 v[212:215], v225 offset:12288
	ds_read_b128 v[216:219], v225 offset:14336
	v_xor_b32_e32 v225, 0x8000, v225
	v_xor_b32_e32 v227, 0x8000, v227
	s_waitcnt lgkmcnt(0)
.Lgm1_loop:
	s_waitcnt lgkmcnt(4)
	v_mfma_f32_16x16x32_bf16 v[124:127], v[188:191], v[152:155], v[124:127]
	v_mfma_f32_16x16x32_bf16 v[120:123], v[188:191], v[156:159], v[120:123]
	v_mfma_f32_16x16x32_bf16 v[116:119], v[188:191], v[160:163], v[116:119]
	v_mfma_f32_16x16x32_bf16 v[112:115], v[188:191], v[164:167], v[112:115]
	ds_read_b128 v[188:191], v226 offset:0
	ds_read_b128 v[168:171], v228 offset:0
	v_mfma_f32_16x16x32_bf16 v[108:111], v[192:195], v[152:155], v[108:111]
	v_mfma_f32_16x16x32_bf16 v[104:107], v[192:195], v[156:159], v[104:107]
	v_mfma_f32_16x16x32_bf16 v[100:103], v[192:195], v[160:163], v[100:103]
	v_mfma_f32_16x16x32_bf16 v[96:99], v[192:195], v[164:167], v[96:99]
	ds_read_b128 v[192:195], v226 offset:2048
	ds_read_b128 v[176:179], v228 offset:2048
	v_mfma_f32_16x16x32_bf16 v[92:95], v[196:199], v[152:155], v[92:95]
	v_mfma_f32_16x16x32_bf16 v[88:91], v[196:199], v[156:159], v[88:91]
	v_mfma_f32_16x16x32_bf16 v[84:87], v[196:199], v[160:163], v[84:87]
	v_mfma_f32_16x16x32_bf16 v[80:83], v[196:199], v[164:167], v[80:83]
	ds_read_b128 v[196:199], v226 offset:4096
	ds_read_b128 v[180:183], v228 offset:4096
	v_mfma_f32_16x16x32_bf16 v[76:79], v[200:203], v[152:155], v[76:79]
	v_mfma_f32_16x16x32_bf16 v[72:75], v[200:203], v[156:159], v[72:75]
	v_mfma_f32_16x16x32_bf16 v[68:71], v[200:203], v[160:163], v[68:71]
	v_mfma_f32_16x16x32_bf16 v[64:67], v[200:203], v[164:167], v[64:67]
	ds_read_b128 v[200:203], v226 offset:6144
	ds_read_b128 v[184:187], v228 offset:6144
	s_waitcnt lgkmcnt(11)
	v_mfma_f32_16x16x32_bf16 v[60:63], v[204:207], v[152:155], v[60:63]
	v_mfma_f32_16x16x32_bf16 v[56:59], v[204:207], v[156:159], v[56:59]
	v_mfma_f32_16x16x32_bf16 v[52:55], v[204:207], v[160:163], v[52:55]
	v_mfma_f32_16x16x32_bf16 v[48:51], v[204:207], v[164:167], v[48:51]
	ds_read_b128 v[204:207], v226 offset:8192
	ds_read_b128 v[220:223], v226 offset:14336
	s_waitcnt lgkmcnt(11)
	v_mfma_f32_16x16x32_bf16 v[44:47], v[208:211], v[152:155], v[44:47]
	v_mfma_f32_16x16x32_bf16 v[40:43], v[208:211], v[156:159], v[40:43]
	v_mfma_f32_16x16x32_bf16 v[36:39], v[208:211], v[160:163], v[36:39]
	v_mfma_f32_16x16x32_bf16 v[32:35], v[208:211], v[164:167], v[32:35]
	ds_read_b128 v[208:211], v226 offset:10240
	s_waitcnt lgkmcnt(11)
	v_mfma_f32_16x16x32_bf16 v[28:31], v[212:215], v[152:155], v[28:31]
	v_mfma_f32_16x16x32_bf16 v[24:27], v[212:215], v[156:159], v[24:27]
	v_mfma_f32_16x16x32_bf16 v[20:23], v[212:215], v[160:163], v[20:23]
	v_mfma_f32_16x16x32_bf16 v[16:19], v[212:215], v[164:167], v[16:19]
	ds_read_b128 v[212:215], v226 offset:12288
	v_mfma_f32_16x16x32_bf16 v[12:15], v[216:219], v[152:155], v[12:15]
	v_mfma_f32_16x16x32_bf16 v[8:11], v[216:219], v[156:159], v[8:11]
	v_mfma_f32_16x16x32_bf16 v[4:7], v[216:219], v[160:163], v[4:7]
	v_mfma_f32_16x16x32_bf16 v[0:3], v[216:219], v[164:167], v[0:3]
	s_waitcnt vmcnt(0) lgkmcnt(0)
	s_barrier
	v_mfma_f32_16x16x32_bf16 v[124:127], v[188:191], v[168:171], v[124:127]
	v_mfma_f32_16x16x32_bf16 v[120:123], v[188:191], v[176:179], v[120:123]
	v_mfma_f32_16x16x32_bf16 v[116:119], v[188:191], v[180:183], v[116:119]
	v_mfma_f32_16x16x32_bf16 v[112:115], v[188:191], v[184:187], v[112:115]
	ds_read_b128 v[188:191], v225 offset:0
	ds_read_b128 v[152:155], v227 offset:0
	s_add_u32 s8, s98, 0x0
	s_addc_u32 s9, s99, 0
	s_add_u32 m0, s97, 0x0
	s_nop 0
	global_load_lds_dwordx4 v224, s[8:9]
	v_mfma_f32_16x16x32_bf16 v[108:111], v[192:195], v[168:171], v[108:111]
	v_mfma_f32_16x16x32_bf16 v[104:107], v[192:195], v[176:179], v[104:107]
	v_mfma_f32_16x16x32_bf16 v[100:103], v[192:195], v[180:183], v[100:103]
	v_mfma_f32_16x16x32_bf16 v[96:99], v[192:195], v[184:187], v[96:99]
	ds_read_b128 v[192:195], v225 offset:2048
	ds_read_b128 v[156:159], v227 offset:2048
	s_add_u32 s8, s100, 0x0
	s_addc_u32 s9, s101, 0
	s_add_u32 m0, s97, 0x10000
	s_nop 0
	global_load_lds_dwordx4 v224, s[8:9]
	v_mfma_f32_16x16x32_bf16 v[92:95], v[196:199], v[168:171], v[92:95]
	v_mfma_f32_16x16x32_bf16 v[88:91], v[196:199], v[176:179], v[88:91]
	v_mfma_f32_16x16x32_bf16 v[84:87], v[196:199], v[180:183], v[84:87]
	v_mfma_f32_16x16x32_bf16 v[80:83], v[196:199], v[184:187], v[80:83]
	ds_read_b128 v[196:199], v225 offset:4096
	ds_read_b128 v[160:163], v227 offset:4096
	s_add_u32 s8, s98, 0x20000
	s_addc_u32 s9, s99, 0
	s_add_u32 m0, s97, 0x2000
	s_nop 0
	global_load_lds_dwordx4 v224, s[8:9]
	v_mfma_f32_16x16x32_bf16 v[76:79], v[200:203], v[168:171], v[76:79]
	v_mfma_f32_16x16x32_bf16 v[72:75], v[200:203], v[176:179], v[72:75]
	v_mfma_f32_16x16x32_bf16 v[68:71], v[200:203], v[180:183], v[68:71]
	v_mfma_f32_16x16x32_bf16 v[64:67], v[200:203], v[184:187], v[64:67]
	ds_read_b128 v[200:203], v225 offset:6144
	ds_read_b128 v[164:167], v227 offset:6144
	s_add_u32 s8, s100, 0x20000
	s_addc_u32 s9, s101, 0
	s_add_u32 m0, s97, 0x12000
	s_nop 0
	global_load_lds_dwordx4 v224, s[8:9]
	v_mfma_f32_16x16x32_bf16 v[60:63], v[204:207], v[168:171], v[60:63]
	v_mfma_f32_16x16x32_bf16 v[56:59], v[204:207], v[176:179], v[56:59]
	v_mfma_f32_16x16x32_bf16 v[52:55], v[204:207], v[180:183], v[52:55]
; #define G_LOAD(KT) do { _Pragma("unroll") for (int i = 0; i < 4; ++i) { ra[i] = *(const u32x4*)(Ag + (size_t)i * 64 * lda + (KT) * 64); rb[i] = *(const u32x4*)(Bg + (size_t)i * 64 * K + (KT) * 64); } } while (0)
; #define G_STORE(BUF) do { u16* ad = As + (BUF) * 256 * 64 + sto; u16* bd = Bs + (BUF) * 256 * 64 + sto; _Pragma("unroll") for (int i = 0; i < 4; ++i) { *(u32x4*)(ad + i * 64 * 64) = ra[i]; *(u32x4*)(bd + i * 64 * 64) = rb[i]; } } while (0)
; template <int EPI>
; DI void gemm_phase(const u16* __restrict__ A, int lda, const u16* __restrict__ Bt, int K, int N, u16* outb, int ldo,
;                    const float* r0, const float* r1, float* outf, char* lds, int bid, int nb) {
;     ...
;     G_LOAD(0);
;     G_STORE(0);
;     __syncthreads();
;     for (int kt = 0; kt < nk; ++kt) {
;       const int cur = kt & 1;
;       if (kt + 1 < nk) G_LOAD(kt + 1);
;       G_MMA(cur, fo0);
;       G_MMA(cur, fo1);
;       if (kt + 1 < nk) G_STORE(cur ^ 1);
;       __syncthreads();
;     }
	v_mfma_f32_16x16x32_bf16 v[48:51], v[204:207], v[184:187], v[48:51]
	ds_read_b128 v[204:207], v225 offset:8192
	ds_read_b128 v[216:219], v225 offset:14336
	s_add_u32 s8, s98, 0x40000
	s_addc_u32 s9, s99, 0
	s_add_u32 m0, s97, 0x4000
	s_nop 0
	global_load_lds_dwordx4 v224, s[8:9]
	v_mfma_f32_16x16x32_bf16 v[44:47], v[208:211], v[168:171], v[44:47]
	v_mfma_f32_16x16x32_bf16 v[40:43], v[208:211], v[176:179], v[40:43]
	v_mfma_f32_16x16x32_bf16 v[36:39], v[208:211], v[180:183], v[36:39]
	v_mfma_f32_16x16x32_bf16 v[32:35], v[208:211], v[184:187], v[32:35]
	ds_read_b128 v[208:211], v225 offset:10240
	s_add_u32 s8, s100, 0x40000
	s_addc_u32 s9, s101, 0
	s_add_u32 m0, s97, 0x14000
	s_nop 0
	global_load_lds_dwordx4 v224, s[8:9]
	v_mfma_f32_16x16x32_bf16 v[28:31], v[212:215], v[168:171], v[28:31]
	v_mfma_f32_16x16x32_bf16 v[24:27], v[212:215], v[176:179], v[24:27]
	v_mfma_f32_16x16x32_bf16 v[20:23], v[212:215], v[180:183], v[20:23]
	v_mfma_f32_16x16x32_bf16 v[16:19], v[212:215], v[184:187], v[16:19]
	ds_read_b128 v[212:215], v225 offset:12288
	s_add_u32 s8, s98, 0x60000
	s_addc_u32 s9, s99, 0
	s_add_u32 m0, s97, 0x6000
	s_nop 0
	global_load_lds_dwordx4 v224, s[8:9]
	v_mfma_f32_16x16x32_bf16 v[12:15], v[220:223], v[168:171], v[12:15]
	v_mfma_f32_16x16x32_bf16 v[8:11], v[220:223], v[176:179], v[8:11]
	v_mfma_f32_16x16x32_bf16 v[4:7], v[220:223], v[180:183], v[4:7]
	v_mfma_f32_16x16x32_bf16 v[0:3], v[220:223], v[184:187], v[0:3]
	s_add_u32 s8, s100, 0x60000
	s_addc_u32 s9, s101, 0
	s_add_u32 m0, s97, 0x16000
	s_nop 0
	global_load_lds_dwordx4 v224, s[8:9]
	v_xor_b32_e32 v225, 0x8000, v225
	v_xor_b32_e32 v227, 0x8000, v227
	v_xor_b32_e32 v226, 0x8000, v226
	v_xor_b32_e32 v228, 0x8000, v228
	s_xor_b32 s97, s97, 0x8000
	s_add_u32 s98, s98, 0x80
	s_addc_u32 s99, s99, 0
	s_add_u32 s100, s100, 0x80
	s_addc_u32 s101, s101, 0
	s_sub_u32 s28, s28, 1
	s_cmp_lg_u32 s28, 0
	s_cbranch_scc1 .Lgm1_loop
	s_waitcnt lgkmcnt(4)
	v_mfma_f32_16x16x32_bf16 v[124:127], v[188:191], v[152:155], v[124:127]
	v_mfma_f32_16x16x32_bf16 v[120:123], v[188:191], v[156:159], v[120:123]
	v_mfma_f32_16x16x32_bf16 v[116:119], v[188:191], v[160:163], v[116:119]
	v_mfma_f32_16x16x32_bf16 v[112:115], v[188:191], v[164:167], v[112:115]
	ds_read_b128 v[188:191], v226 offset:0
	ds_read_b128 v[168:171], v228 offset:0
	v_mfma_f32_16x16x32_bf16 v[108:111], v[192:195], v[152:155], v[108:111]
	v_mfma_f32_16x16x32_bf16 v[104:107], v[192:195], v[156:159], v[104:107]
	v_mfma_f32_16x16x32_bf16 v[100:103], v[192:195], v[160:163], v[100:103]
	v_mfma_f32_16x16x32_bf16 v[96:99], v[192:195], v[164:167], v[96:99]
	ds_read_b128 v[192:195], v226 offset:2048
	ds_read_b128 v[176:179], v228 offset:2048
	v_mfma_f32_16x16x32_bf16 v[92:95], v[196:199], v[152:155], v[92:95]
	v_mfma_f32_16x16x32_bf16 v[88:91], v[196:199], v[156:159], v[88:91]
	v_mfma_f32_16x16x32_bf16 v[84:87], v[196:199], v[160:163], v[84:87]
	v_mfma_f32_16x16x32_bf16 v[80:83], v[196:199], v[164:167], v[80:83]
	ds_read_b128 v[196:199], v226 offset:4096
	ds_read_b128 v[180:183], v228 offset:4096
	v_mfma_f32_16x16x32_bf16 v[76:79], v[200:203], v[152:155], v[76:79]
	v_mfma_f32_16x16x32_bf16 v[72:75], v[200:203], v[156:159], v[72:75]
	v_mfma_f32_16x16x32_bf16 v[68:71], v[200:203], v[160:163], v[68:71]
	v_mfma_f32_16x16x32_bf16 v[64:67], v[200:203], v[164:167], v[64:67]
	ds_read_b128 v[200:203], v226 offset:6144
	ds_read_b128 v[184:187], v228 offset:6144
	s_waitcnt lgkmcnt(11)
	v_mfma_f32_16x16x32_bf16 v[60:63], v[204:207], v[152:155], v[60:63]
	v_mfma_f32_16x16x32_bf16 v[56:59], v[204:207], v[156:159], v[56:59]
	v_mfma_f32_16x16x32_bf16 v[52:55], v[204:207], v[160:163], v[52:55]
	v_mfma_f32_16x16x32_bf16 v[48:51], v[204:207], v[164:167], v[48:51]
	ds_read_b128 v[204:207], v226 offset:8192
	ds_read_b128 v[220:223], v226 offset:14336
	s_waitcnt lgkmcnt(11)
	v_mfma_f32_16x16x32_bf16 v[44:47], v[208:211], v[152:155], v[44:47]
	v_mfma_f32_16x16x32_bf16 v[40:43], v[208:211], v[156:159], v[40:43]
	v_mfma_f32_16x16x32_bf16 v[36:39], v[208:211], v[160:163], v[36:39]
	v_mfma_f32_16x16x32_bf16 v[32:35], v[208:211], v[164:167], v[32:35]
	ds_read_b128 v[208:211], v226 offset:10240
	s_waitcnt lgkmcnt(11)
	v_mfma_f32_16x16x32_bf16 v[28:31], v[212:215], v[152:155], v[28:31]
	v_mfma_f32_16x16x32_bf16 v[24:27], v[212:215], v[156:159], v[24:27]
	v_mfma_f32_16x16x32_bf16 v[20:23], v[212:215], v[160:163], v[20:23]
	v_mfma_f32_16x16x32_bf16 v[16:19], v[212:215], v[164:167], v[16:19]
	ds_read_b128 v[212:215], v226 offset:12288
	v_mfma_f32_16x16x32_bf16 v[12:15], v[216:219], v[152:155], v[12:15]
	v_mfma_f32_16x16x32_bf16 v[8:11], v[216:219], v[156:159], v[8:11]
	v_mfma_f32_16x16x32_bf16 v[4:7], v[216:219], v[160:163], v[4:7]
	v_mfma_f32_16x16x32_bf16 v[0:3], v[216:219], v[164:167], v[0:3]
	s_waitcnt vmcnt(0) lgkmcnt(0)
	s_barrier
; #define G_LOAD(KT) do { _Pragma("unroll") for (int i = 0; i < 4; ++i) { ra[i] = *(const u32x4*)(Ag + (size_t)i * 64 * lda + (KT) * 64); rb[i] = *(const u32x4*)(Bg + (size_t)i * 64 * K + (KT) * 64); } } while (0)
; #define G_STORE(BUF) do { u16* ad = As + (BUF) * 256 * 64 + sto; u16* bd = Bs + (BUF) * 256 * 64 + sto; _Pragma("unroll") for (int i = 0; i < 4; ++i) { *(u32x4*)(ad + i * 64 * 64) = ra[i]; *(u32x4*)(bd + i * 64 * 64) = rb[i]; } } while (0)
; template <int EPI>
; DI void gemm_phase(const u16* __restrict__ A, int lda, const u16* __restrict__ Bt, int K, int N, u16* outb, int ldo,
;                    const float* r0, const float* r1, float* outf, char* lds, int bid, int nb) {
;     ...
;     G_LOAD(0);
;     G_STORE(0);
;     __syncthreads();
;     for (int kt = 0; kt < nk; ++kt) {
;       const int cur = kt & 1;
;       if (kt + 1 < nk) G_LOAD(kt + 1);
;       G_MMA(cur, fo0);
;       G_MMA(cur, fo1);
;       if (kt + 1 < nk) G_STORE(cur ^ 1);
;       __syncthreads();
;     }
	v_mfma_f32_16x16x32_bf16 v[124:127], v[188:191], v[168:171], v[124:127]
	v_mfma_f32_16x16x32_bf16 v[120:123], v[188:191], v[176:179], v[120:123]
	v_mfma_f32_16x16x32_bf16 v[116:119], v[188:191], v[180:183], v[116:119]
	v_mfma_f32_16x16x32_bf16 v[112:115], v[188:191], v[184:187], v[112:115]
	ds_read_b128 v[188:191], v225 offset:0
	ds_read_b128 v[152:155], v227 offset:0
	v_mfma_f32_16x16x32_bf16 v[108:111], v[192:195], v[168:171], v[108:111]
	v_mfma_f32_16x16x32_bf16 v[104:107], v[192:195], v[176:179], v[104:107]
	v_mfma_f32_16x16x32_bf16 v[100:103], v[192:195], v[180:183], v[100:103]
	v_mfma_f32_16x16x32_bf16 v[96:99], v[192:195], v[184:187], v[96:99]
	ds_read_b128 v[192:195], v225 offset:2048
	ds_read_b128 v[156:159], v227 offset:2048
	v_mfma_f32_16x16x32_bf16 v[92:95], v[196:199], v[168:171], v[92:95]
	v_mfma_f32_16x16x32_bf16 v[88:91], v[196:199], v[176:179], v[88:91]
	v_mfma_f32_16x16x32_bf16 v[84:87], v[196:199], v[180:183], v[84:87]
	v_mfma_f32_16x16x32_bf16 v[80:83], v[196:199], v[184:187], v[80:83]
	ds_read_b128 v[196:199], v225 offset:4096
	ds_read_b128 v[160:163], v227 offset:4096
	v_mfma_f32_16x16x32_bf16 v[76:79], v[200:203], v[168:171], v[76:79]
	v_mfma_f32_16x16x32_bf16 v[72:75], v[200:203], v[176:179], v[72:75]
	v_mfma_f32_16x16x32_bf16 v[68:71], v[200:203], v[180:183], v[68:71]
	v_mfma_f32_16x16x32_bf16 v[64:67], v[200:203], v[184:187], v[64:67]
	ds_read_b128 v[200:203], v225 offset:6144
	ds_read_b128 v[164:167], v227 offset:6144
	v_mfma_f32_16x16x32_bf16 v[60:63], v[204:207], v[168:171], v[60:63]
	v_mfma_f32_16x16x32_bf16 v[56:59], v[204:207], v[176:179], v[56:59]
	v_mfma_f32_16x16x32_bf16 v[52:55], v[204:207], v[180:183], v[52:55]
	v_mfma_f32_16x16x32_bf16 v[48:51], v[204:207], v[184:187], v[48:51]
	ds_read_b128 v[204:207], v225 offset:8192
	ds_read_b128 v[216:219], v225 offset:14336
	v_mfma_f32_16x16x32_bf16 v[44:47], v[208:211], v[168:171], v[44:47]
	v_mfma_f32_16x16x32_bf16 v[40:43], v[208:211], v[176:179], v[40:43]
	v_mfma_f32_16x16x32_bf16 v[36:39], v[208:211], v[180:183], v[36:39]
	v_mfma_f32_16x16x32_bf16 v[32:35], v[208:211], v[184:187], v[32:35]
	ds_read_b128 v[208:211], v225 offset:10240
	v_mfma_f32_16x16x32_bf16 v[28:31], v[212:215], v[168:171], v[28:31]
	v_mfma_f32_16x16x32_bf16 v[24:27], v[212:215], v[176:179], v[24:27]
	v_mfma_f32_16x16x32_bf16 v[20:23], v[212:215], v[180:183], v[20:23]
	v_mfma_f32_16x16x32_bf16 v[16:19], v[212:215], v[184:187], v[16:19]
	ds_read_b128 v[212:215], v225 offset:12288
	v_mfma_f32_16x16x32_bf16 v[12:15], v[220:223], v[168:171], v[12:15]
	v_mfma_f32_16x16x32_bf16 v[8:11], v[220:223], v[176:179], v[8:11]
	v_mfma_f32_16x16x32_bf16 v[4:7], v[220:223], v[180:183], v[4:7]
	v_mfma_f32_16x16x32_bf16 v[0:3], v[220:223], v[184:187], v[0:3]
	v_xor_b32_e32 v226, 0x8000, v226
	v_xor_b32_e32 v228, 0x8000, v228
	s_waitcnt lgkmcnt(4)
	v_mfma_f32_16x16x32_bf16 v[124:127], v[188:191], v[152:155], v[124:127]
	v_mfma_f32_16x16x32_bf16 v[120:123], v[188:191], v[156:159], v[120:123]
	v_mfma_f32_16x16x32_bf16 v[116:119], v[188:191], v[160:163], v[116:119]
	v_mfma_f32_16x16x32_bf16 v[112:115], v[188:191], v[164:167], v[112:115]
	ds_read_b128 v[188:191], v226 offset:0
	ds_read_b128 v[168:171], v228 offset:0
	v_mfma_f32_16x16x32_bf16 v[108:111], v[192:195], v[152:155], v[108:111]
	v_mfma_f32_16x16x32_bf16 v[104:107], v[192:195], v[156:159], v[104:107]
	v_mfma_f32_16x16x32_bf16 v[100:103], v[192:195], v[160:163], v[100:103]
	v_mfma_f32_16x16x32_bf16 v[96:99], v[192:195], v[164:167], v[96:99]
	ds_read_b128 v[192:195], v226 offset:2048
	ds_read_b128 v[176:179], v228 offset:2048
	v_mfma_f32_16x16x32_bf16 v[92:95], v[196:199], v[152:155], v[92:95]
	v_mfma_f32_16x16x32_bf16 v[88:91], v[196:199], v[156:159], v[88:91]
	v_mfma_f32_16x16x32_bf16 v[84:87], v[196:199], v[160:163], v[84:87]
	v_mfma_f32_16x16x32_bf16 v[80:83], v[196:199], v[164:167], v[80:83]
	ds_read_b128 v[196:199], v226 offset:4096
	ds_read_b128 v[180:183], v228 offset:4096
	v_mfma_f32_16x16x32_bf16 v[76:79], v[200:203], v[152:155], v[76:79]
	v_mfma_f32_16x16x32_bf16 v[72:75], v[200:203], v[156:159], v[72:75]
	v_mfma_f32_16x16x32_bf16 v[68:71], v[200:203], v[160:163], v[68:71]
	v_mfma_f32_16x16x32_bf16 v[64:67], v[200:203], v[164:167], v[64:67]
	ds_read_b128 v[200:203], v226 offset:6144
	ds_read_b128 v[184:187], v228 offset:6144
	s_waitcnt lgkmcnt(11)
	v_mfma_f32_16x16x32_bf16 v[60:63], v[204:207], v[152:155], v[60:63]
	v_mfma_f32_16x16x32_bf16 v[56:59], v[204:207], v[156:159], v[56:59]
	v_mfma_f32_16x16x32_bf16 v[52:55], v[204:207], v[160:163], v[52:55]
	v_mfma_f32_16x16x32_bf16 v[48:51], v[204:207], v[164:167], v[48:51]
	ds_read_b128 v[204:207], v226 offset:8192
	ds_read_b128 v[220:223], v226 offset:14336
	s_waitcnt lgkmcnt(11)
	v_mfma_f32_16x16x32_bf16 v[44:47], v[208:211], v[152:155], v[44:47]
	v_mfma_f32_16x16x32_bf16 v[40:43], v[208:211], v[156:159], v[40:43]
	v_mfma_f32_16x16x32_bf16 v[36:39], v[208:211], v[160:163], v[36:39]
	v_mfma_f32_16x16x32_bf16 v[32:35], v[208:211], v[164:167], v[32:35]
	ds_read_b128 v[208:211], v226 offset:10240
	s_waitcnt lgkmcnt(11)
	v_mfma_f32_16x16x32_bf16 v[28:31], v[212:215], v[152:155], v[28:31]
	v_mfma_f32_16x16x32_bf16 v[24:27], v[212:215], v[156:159], v[24:27]
	v_mfma_f32_16x16x32_bf16 v[20:23], v[212:215], v[160:163], v[20:23]
	v_mfma_f32_16x16x32_bf16 v[16:19], v[212:215], v[164:167], v[16:19]
	ds_read_b128 v[212:215], v226 offset:12288
	v_mfma_f32_16x16x32_bf16 v[12:15], v[216:219], v[152:155], v[12:15]
	v_mfma_f32_16x16x32_bf16 v[8:11], v[216:219], v[156:159], v[8:11]
	v_mfma_f32_16x16x32_bf16 v[4:7], v[216:219], v[160:163], v[4:7]
	v_mfma_f32_16x16x32_bf16 v[0:3], v[216:219], v[164:167], v[0:3]
	s_waitcnt vmcnt(0) lgkmcnt(0)
	s_barrier
; template <int EPI>
; DI void gemm_phase(const u16* __restrict__ A, int lda, const u16* __restrict__ Bt, int K, int N, u16* outb, int ldo,
;                    const float* r0, const float* r1, float* outf, char* lds, int bid, int nb) {
;     ...
;     } else if constexpr (EPI == EPI_RESID) {
;       const int col = tn * 256 + wc * 64 + l15;
;       const float* rb_ = (tm * 256 < M_P) ? r0 : (r1 - (size_t)M_P * DM);
; #pragma unroll
;       for (int i = 0; i < 8; ++i)
; #pragma unroll
;         for (int r = 0; r < 4; ++r) {
;           const size_t i0 = (size_t)(mrow + i * 16 + r) * DM + col;
;           const float x0 = rb_[i0], x1 = rb_[i0 + 16], x2 = rb_[i0 + 32], x3 = rb_[i0 + 48];
;           outf[i0] = x0 + acc[i][0][r]; outf[i0 + 16] = x1 + acc[i][1][r]; outf[i0 + 32] = x2 + acc[i][2][r]; outf[i0 + 48] = x3 + acc[i][3][r];
	v_mfma_f32_16x16x32_bf16 v[124:127], v[188:191], v[168:171], v[124:127]
	v_mfma_f32_16x16x32_bf16 v[120:123], v[188:191], v[176:179], v[120:123]
	v_mfma_f32_16x16x32_bf16 v[116:119], v[188:191], v[180:183], v[116:119]
	v_mfma_f32_16x16x32_bf16 v[112:115], v[188:191], v[184:187], v[112:115]
	v_mfma_f32_16x16x32_bf16 v[108:111], v[192:195], v[168:171], v[108:111]
	v_mfma_f32_16x16x32_bf16 v[104:107], v[192:195], v[176:179], v[104:107]
	v_mfma_f32_16x16x32_bf16 v[100:103], v[192:195], v[180:183], v[100:103]
	v_mfma_f32_16x16x32_bf16 v[96:99], v[192:195], v[184:187], v[96:99]
	v_mfma_f32_16x16x32_bf16 v[92:95], v[196:199], v[168:171], v[92:95]
	v_mfma_f32_16x16x32_bf16 v[88:91], v[196:199], v[176:179], v[88:91]
	v_mfma_f32_16x16x32_bf16 v[84:87], v[196:199], v[180:183], v[84:87]
	v_mfma_f32_16x16x32_bf16 v[80:83], v[196:199], v[184:187], v[80:83]
	v_mfma_f32_16x16x32_bf16 v[76:79], v[200:203], v[168:171], v[76:79]
	v_mfma_f32_16x16x32_bf16 v[72:75], v[200:203], v[176:179], v[72:75]
	v_mfma_f32_16x16x32_bf16 v[68:71], v[200:203], v[180:183], v[68:71]
	v_mfma_f32_16x16x32_bf16 v[64:67], v[200:203], v[184:187], v[64:67]
	v_mfma_f32_16x16x32_bf16 v[60:63], v[204:207], v[168:171], v[60:63]
	v_mfma_f32_16x16x32_bf16 v[56:59], v[204:207], v[176:179], v[56:59]
	v_mfma_f32_16x16x32_bf16 v[52:55], v[204:207], v[180:183], v[52:55]
	v_mfma_f32_16x16x32_bf16 v[48:51], v[204:207], v[184:187], v[48:51]
	v_mfma_f32_16x16x32_bf16 v[44:47], v[208:211], v[168:171], v[44:47]
	v_mfma_f32_16x16x32_bf16 v[40:43], v[208:211], v[176:179], v[40:43]
	v_mfma_f32_16x16x32_bf16 v[36:39], v[208:211], v[180:183], v[36:39]
	v_mfma_f32_16x16x32_bf16 v[32:35], v[208:211], v[184:187], v[32:35]
	v_mfma_f32_16x16x32_bf16 v[28:31], v[212:215], v[168:171], v[28:31]
	v_mfma_f32_16x16x32_bf16 v[24:27], v[212:215], v[176:179], v[24:27]
	v_mfma_f32_16x16x32_bf16 v[20:23], v[212:215], v[180:183], v[20:23]
	v_mfma_f32_16x16x32_bf16 v[16:19], v[212:215], v[184:187], v[16:19]
	v_mfma_f32_16x16x32_bf16 v[12:15], v[220:223], v[168:171], v[12:15]
	v_mfma_f32_16x16x32_bf16 v[8:11], v[220:223], v[176:179], v[8:11]
	v_mfma_f32_16x16x32_bf16 v[4:7], v[220:223], v[180:183], v[4:7]
	v_mfma_f32_16x16x32_bf16 v[0:3], v[220:223], v[184:187], v[0:3]
	s_nop 7
	s_nop 3
	v_mov_b32_e32 v232, v112
	v_mov_b32_e32 v233, v113
	v_mov_b32_e32 v234, v114
	v_mov_b32_e32 v235, v115
	v_mov_b32_e32 v172, v96
	v_mov_b32_e32 v96, v108
	v_mov_b32_e32 v108, v172
	v_mov_b32_e32 v172, v97
	v_mov_b32_e32 v97, v109
	v_mov_b32_e32 v109, v172
	v_mov_b32_e32 v172, v98
	v_mov_b32_e32 v98, v110
	v_mov_b32_e32 v110, v172
	v_mov_b32_e32 v172, v99
	v_mov_b32_e32 v99, v111
	v_mov_b32_e32 v111, v172
	v_mov_b32_e32 v172, v100
	v_mov_b32_e32 v100, v104
	v_mov_b32_e32 v104, v172
	v_mov_b32_e32 v172, v101
	v_mov_b32_e32 v101, v105
	v_mov_b32_e32 v105, v172
	v_mov_b32_e32 v172, v102
	v_mov_b32_e32 v102, v106
	v_mov_b32_e32 v106, v172
	v_mov_b32_e32 v172, v103
	v_mov_b32_e32 v103, v107
	v_mov_b32_e32 v107, v172
	v_mov_b32_e32 v172, v80
	v_mov_b32_e32 v80, v92
	v_mov_b32_e32 v92, v172
	v_mov_b32_e32 v172, v81
	v_mov_b32_e32 v81, v93
	v_mov_b32_e32 v93, v172
	v_mov_b32_e32 v172, v82
	v_mov_b32_e32 v82, v94
	v_mov_b32_e32 v94, v172
	v_mov_b32_e32 v172, v83
	v_mov_b32_e32 v83, v95
	v_mov_b32_e32 v95, v172
	v_mov_b32_e32 v172, v84
	v_mov_b32_e32 v84, v88
	v_mov_b32_e32 v88, v172
	v_mov_b32_e32 v172, v85
	v_mov_b32_e32 v85, v89
	v_mov_b32_e32 v89, v172
	v_mov_b32_e32 v172, v86
	v_mov_b32_e32 v86, v90
	v_mov_b32_e32 v90, v172
	v_mov_b32_e32 v172, v87
	v_mov_b32_e32 v87, v91
	v_mov_b32_e32 v91, v172
	v_mov_b32_e32 v172, v64
	v_mov_b32_e32 v64, v76
	v_mov_b32_e32 v76, v172
	v_mov_b32_e32 v172, v65
	v_mov_b32_e32 v65, v77
	v_mov_b32_e32 v77, v172
	v_mov_b32_e32 v172, v66
	v_mov_b32_e32 v66, v78
	v_mov_b32_e32 v78, v172
	v_mov_b32_e32 v172, v67
	v_mov_b32_e32 v67, v79
	v_mov_b32_e32 v79, v172
	v_mov_b32_e32 v172, v68
	v_mov_b32_e32 v68, v72
	v_mov_b32_e32 v72, v172
	v_mov_b32_e32 v172, v69
	v_mov_b32_e32 v69, v73
	v_mov_b32_e32 v73, v172
	v_mov_b32_e32 v172, v70
	v_mov_b32_e32 v70, v74
	v_mov_b32_e32 v74, v172
	v_mov_b32_e32 v172, v71
	v_mov_b32_e32 v71, v75
	v_mov_b32_e32 v75, v172
	v_mov_b32_e32 v172, v48
	v_mov_b32_e32 v48, v60
	v_mov_b32_e32 v60, v172
	v_mov_b32_e32 v172, v49
	v_mov_b32_e32 v49, v61
	v_mov_b32_e32 v61, v172
	v_mov_b32_e32 v172, v50
	v_mov_b32_e32 v50, v62
	v_mov_b32_e32 v62, v172
	v_mov_b32_e32 v172, v51
	v_mov_b32_e32 v51, v63
	v_mov_b32_e32 v63, v172
	v_mov_b32_e32 v172, v52
	v_mov_b32_e32 v52, v56
	v_mov_b32_e32 v56, v172
	v_mov_b32_e32 v172, v53
	v_mov_b32_e32 v53, v57
	v_mov_b32_e32 v57, v172
	v_mov_b32_e32 v172, v54
	v_mov_b32_e32 v54, v58
	v_mov_b32_e32 v58, v172
	v_mov_b32_e32 v172, v55
	v_mov_b32_e32 v55, v59
	v_mov_b32_e32 v59, v172
	v_mov_b32_e32 v172, v32
	v_mov_b32_e32 v32, v44
	v_mov_b32_e32 v44, v172
	v_mov_b32_e32 v172, v33
	v_mov_b32_e32 v33, v45
	v_mov_b32_e32 v45, v172
	v_mov_b32_e32 v172, v34
	v_mov_b32_e32 v34, v46
	v_mov_b32_e32 v46, v172
	v_mov_b32_e32 v172, v35
	v_mov_b32_e32 v35, v47
	v_mov_b32_e32 v47, v172
	v_mov_b32_e32 v172, v36
	v_mov_b32_e32 v36, v40
	v_mov_b32_e32 v40, v172
	v_mov_b32_e32 v172, v37
	v_mov_b32_e32 v37, v41
	v_mov_b32_e32 v41, v172
	v_mov_b32_e32 v172, v38
	v_mov_b32_e32 v38, v42
	v_mov_b32_e32 v42, v172
	v_mov_b32_e32 v172, v39
	v_mov_b32_e32 v39, v43
	v_mov_b32_e32 v43, v172
	v_mov_b32_e32 v172, v16
	v_mov_b32_e32 v16, v28
	v_mov_b32_e32 v28, v172
	v_mov_b32_e32 v172, v17
	v_mov_b32_e32 v17, v29
	v_mov_b32_e32 v29, v172
	v_mov_b32_e32 v172, v18
	v_mov_b32_e32 v18, v30
	v_mov_b32_e32 v30, v172
	v_mov_b32_e32 v172, v19
	v_mov_b32_e32 v19, v31
	v_mov_b32_e32 v31, v172
; template <int EPI>
; DI void gemm_phase(const u16* __restrict__ A, int lda, const u16* __restrict__ Bt, int K, int N, u16* outb, int ldo,
;                    const float* r0, const float* r1, float* outf, char* lds, int bid, int nb) {
;     ...
;     } else if constexpr (EPI == EPI_RESID) {
;       const int col = tn * 256 + wc * 64 + l15;
;       const float* rb_ = (tm * 256 < M_P) ? r0 : (r1 - (size_t)M_P * DM);
; #pragma unroll
;       for (int i = 0; i < 8; ++i)
; #pragma unroll
;         for (int r = 0; r < 4; ++r) {
;           const size_t i0 = (size_t)(mrow + i * 16 + r) * DM + col;
;           const float x0 = rb_[i0], x1 = rb_[i0 + 16], x2 = rb_[i0 + 32], x3 = rb_[i0 + 48];
;           outf[i0] = x0 + acc[i][0][r]; outf[i0 + 16] = x1 + acc[i][1][r]; outf[i0 + 32] = x2 + acc[i][2][r]; outf[i0 + 48] = x3 + acc[i][3][r];
	v_mov_b32_e32 v172, v20
	v_mov_b32_e32 v20, v24
	v_mov_b32_e32 v24, v172
	v_mov_b32_e32 v172, v21
	v_mov_b32_e32 v21, v25
	v_mov_b32_e32 v25, v172
	v_mov_b32_e32 v172, v22
	v_mov_b32_e32 v22, v26
	v_mov_b32_e32 v26, v172
	v_mov_b32_e32 v172, v23
	v_mov_b32_e32 v23, v27
	v_mov_b32_e32 v27, v172
	v_mov_b32_e32 v172, v0
	v_mov_b32_e32 v0, v12
	v_mov_b32_e32 v12, v172
	v_mov_b32_e32 v172, v1
	v_mov_b32_e32 v1, v13
	v_mov_b32_e32 v13, v172
	v_mov_b32_e32 v172, v2
	v_mov_b32_e32 v2, v14
	v_mov_b32_e32 v14, v172
	v_mov_b32_e32 v172, v3
	v_mov_b32_e32 v3, v15
	v_mov_b32_e32 v15, v172
	v_mov_b32_e32 v172, v4
	v_mov_b32_e32 v4, v8
	v_mov_b32_e32 v8, v172
	v_mov_b32_e32 v172, v5
	v_mov_b32_e32 v5, v9
	v_mov_b32_e32 v9, v172
	v_mov_b32_e32 v172, v6
	v_mov_b32_e32 v6, v10
	v_mov_b32_e32 v10, v172
	v_mov_b32_e32 v172, v7
	v_mov_b32_e32 v7, v11
	v_mov_b32_e32 v11, v172
	v_add_u32_e32 v114, s52, v143
	v_or_b32_e32 v112, s53, v144
	v_ashrrev_i32_e32 v115, 31, v114
	v_ashrrev_i32_e32 v113, 31, v112
	v_lshlrev_b64 v[134:135], 10, v[114:115]
	s_cmpk_lt_i32 s51, 0x80
	v_lshl_add_u64 v[134:135], v[134:135], 0, v[112:113]
	s_cselect_b32 s9, s37, s17
	s_cselect_b32 s8, s36, s16
	v_lshlrev_b64 v[134:135], 2, v[134:135]
	v_lshl_add_u64 v[136:137], s[8:9], 0, v[134:135]
	global_load_dword v115, v[136:137], off
	global_load_dword v151, v[136:137], off offset:64
	global_load_dword v154, v[136:137], off offset:128
	global_load_dword v155, v[136:137], off offset:192
	v_or_b32_e32 v136, 1, v114
	v_ashrrev_i32_e32 v137, 31, v136
	v_lshlrev_b64 v[136:137], 10, v[136:137]
	v_lshl_add_u64 v[136:137], v[136:137], 0, v[112:113]
	v_lshl_add_u64 v[134:135], s[22:23], 0, v[134:135]
	v_lshlrev_b64 v[136:137], 2, v[136:137]
	v_lshl_add_u64 v[152:153], s[8:9], 0, v[136:137]
	v_lshl_add_u64 v[136:137], s[22:23], 0, v[136:137]
	s_add_i32 s18, s18, 1
	s_cmp_eq_u32 s18, s3
	s_waitcnt vmcnt(3)
	v_add_f32_e32 v115, v124, v115
	s_waitcnt vmcnt(2)
	v_add_f32_e32 v120, v120, v151
	s_waitcnt vmcnt(1)
	v_add_f32_e32 v116, v116, v154
	s_waitcnt vmcnt(0)
	v_add_f32_e32 v124, v232, v155
	global_store_dword v[134:135], v115, off
	global_store_dword v[134:135], v120, off offset:64
	global_store_dword v[134:135], v116, off offset:128
	global_store_dword v[134:135], v124, off offset:192
	global_load_dword v115, v[152:153], off
	s_nop 0
	global_load_dword v116, v[152:153], off offset:64
	global_load_dword v120, v[152:153], off offset:128
	global_load_dword v124, v[152:153], off offset:192
	v_or_b32_e32 v134, 2, v114
	v_ashrrev_i32_e32 v135, 31, v134
	v_lshlrev_b64 v[134:135], 10, v[134:135]
	v_lshl_add_u64 v[134:135], v[134:135], 0, v[112:113]
	v_lshlrev_b64 v[134:135], 2, v[134:135]
	v_lshl_add_u64 v[152:153], s[8:9], 0, v[134:135]
	s_waitcnt vmcnt(3)
	v_add_f32_e32 v115, v125, v115
	s_waitcnt vmcnt(2)
	v_add_f32_e32 v116, v121, v116
	s_waitcnt vmcnt(1)
	v_add_f32_e32 v117, v117, v120
	s_waitcnt vmcnt(0)
	v_add_f32_e32 v120, v233, v124
	global_store_dword v[136:137], v115, off
	global_store_dword v[136:137], v116, off offset:64
	global_store_dword v[136:137], v117, off offset:128
	global_store_dword v[136:137], v120, off offset:192
	global_load_dword v115, v[152:153], off
	s_nop 0
	global_load_dword v136, v[152:153], off offset:64
	global_load_dword v137, v[152:153], off offset:128
	global_load_dword v151, v[152:153], off offset:192
	v_or_b32_e32 v116, 3, v114
	v_ashrrev_i32_e32 v117, 31, v116
	v_lshlrev_b64 v[116:117], 10, v[116:117]
	v_lshl_add_u64 v[116:117], v[116:117], 0, v[112:113]
	v_lshlrev_b64 v[116:117], 2, v[116:117]
	v_lshl_add_u64 v[120:121], s[22:23], 0, v[134:135]
	v_lshl_add_u64 v[124:125], s[8:9], 0, v[116:117]
	v_lshl_add_u64 v[116:117], s[22:23], 0, v[116:117]
	s_waitcnt vmcnt(3)
	v_add_f32_e32 v115, v126, v115
	s_waitcnt vmcnt(2)
	v_add_f32_e32 v122, v122, v136
	s_waitcnt vmcnt(1)
	v_add_f32_e32 v118, v118, v137
	s_waitcnt vmcnt(0)
	v_add_f32_e32 v126, v234, v151
	global_store_dword v[120:121], v115, off
	global_store_dword v[120:121], v122, off offset:64
	global_store_dword v[120:121], v118, off offset:128
	global_store_dword v[120:121], v126, off offset:192
	global_load_dword v115, v[124:125], off
	s_nop 0
	global_load_dword v118, v[124:125], off offset:64
	global_load_dword v122, v[124:125], off offset:128
	global_load_dword v126, v[124:125], off offset:192
	v_or_b32_e32 v120, 16, v114
	v_ashrrev_i32_e32 v121, 31, v120
	v_lshlrev_b64 v[120:121], 10, v[120:121]
	v_lshl_add_u64 v[120:121], v[120:121], 0, v[112:113]
	v_lshlrev_b64 v[120:121], 2, v[120:121]
	v_lshl_add_u64 v[124:125], s[8:9], 0, v[120:121]
	s_waitcnt vmcnt(3)
	v_add_f32_e32 v115, v127, v115
	s_waitcnt vmcnt(2)
	v_add_f32_e32 v118, v123, v118
	s_waitcnt vmcnt(1)
	v_add_f32_e32 v119, v119, v122
	s_waitcnt vmcnt(0)
	v_add_f32_e32 v122, v235, v126
	global_store_dword v[116:117], v115, off
	global_store_dword v[116:117], v118, off offset:64
	global_store_dword v[116:117], v119, off offset:128
	global_store_dword v[116:117], v122, off offset:192
	global_load_dword v115, v[124:125], off
	s_nop 0
	global_load_dword v122, v[124:125], off offset:64
	global_load_dword v123, v[124:125], off offset:128
	s_nop 0
	global_load_dword v124, v[124:125], off offset:192
	v_or_b32_e32 v116, 17, v114
	v_ashrrev_i32_e32 v117, 31, v116
	v_lshlrev_b64 v[116:117], 10, v[116:117]
	v_lshl_add_u64 v[116:117], v[116:117], 0, v[112:113]
	v_lshlrev_b64 v[116:117], 2, v[116:117]
	v_lshl_add_u64 v[118:119], s[22:23], 0, v[120:121]
	v_lshl_add_u64 v[120:121], s[8:9], 0, v[116:117]
	v_lshl_add_u64 v[116:117], s[22:23], 0, v[116:117]
	s_waitcnt vmcnt(3)
	v_add_f32_e32 v96, v96, v115
	s_waitcnt vmcnt(2)
	v_add_f32_e32 v100, v100, v122
	s_waitcnt vmcnt(1)
; template <int EPI>
; DI void gemm_phase(const u16* __restrict__ A, int lda, const u16* __restrict__ Bt, int K, int N, u16* outb, int ldo,
;                    const float* r0, const float* r1, float* outf, char* lds, int bid, int nb) {
;     ...
;       for (int i = 0; i < 8; ++i)
; #pragma unroll
;         for (int r = 0; r < 4; ++r) {
;           const size_t i0 = (size_t)(mrow + i * 16 + r) * DM + col;
;           const float x0 = rb_[i0], x1 = rb_[i0 + 16], x2 = rb_[i0 + 32], x3 = rb_[i0 + 48];
;           outf[i0] = x0 + acc[i][0][r]; outf[i0 + 16] = x1 + acc[i][1][r]; outf[i0 + 32] = x2 + acc[i][2][r]; outf[i0 + 48] = x3 + acc[i][3][r];
;         }
	v_add_f32_e32 v104, v104, v123
	s_waitcnt vmcnt(0)
	v_add_f32_e32 v108, v108, v124
	global_store_dword v[118:119], v96, off
	global_store_dword v[118:119], v100, off offset:64
	global_store_dword v[118:119], v104, off offset:128
	global_store_dword v[118:119], v108, off offset:192
	global_load_dword v96, v[120:121], off
	s_nop 0
	global_load_dword v100, v[120:121], off offset:64
	global_load_dword v104, v[120:121], off offset:128
	global_load_dword v108, v[120:121], off offset:192
	v_or_b32_e32 v118, 18, v114
	v_ashrrev_i32_e32 v119, 31, v118
	v_lshlrev_b64 v[118:119], 10, v[118:119]
	v_lshl_add_u64 v[118:119], v[118:119], 0, v[112:113]
	v_lshlrev_b64 v[118:119], 2, v[118:119]
	v_lshl_add_u64 v[120:121], s[8:9], 0, v[118:119]
	s_waitcnt vmcnt(3)
	v_add_f32_e32 v96, v97, v96
	s_waitcnt vmcnt(2)
	v_add_f32_e32 v97, v101, v100
	s_waitcnt vmcnt(1)
	v_add_f32_e32 v100, v105, v104
	s_waitcnt vmcnt(0)
	v_add_f32_e32 v101, v109, v108
	global_store_dword v[116:117], v96, off
	global_store_dword v[116:117], v97, off offset:64
	global_store_dword v[116:117], v100, off offset:128
	global_store_dword v[116:117], v101, off offset:192
	global_load_dword v108, v[120:121], off
	global_load_dword v109, v[120:121], off offset:64
	global_load_dword v115, v[120:121], off offset:128
	s_nop 0
	global_load_dword v116, v[120:121], off offset:192
	v_or_b32_e32 v96, 19, v114
	v_ashrrev_i32_e32 v97, 31, v96
	v_lshlrev_b64 v[96:97], 10, v[96:97]
	v_lshl_add_u64 v[96:97], v[96:97], 0, v[112:113]
	v_lshlrev_b64 v[96:97], 2, v[96:97]
	v_lshl_add_u64 v[100:101], s[22:23], 0, v[118:119]
	v_lshl_add_u64 v[104:105], s[8:9], 0, v[96:97]
	v_lshl_add_u64 v[96:97], s[22:23], 0, v[96:97]
	s_waitcnt vmcnt(3)
	v_add_f32_e32 v98, v98, v108
	s_waitcnt vmcnt(2)
	v_add_f32_e32 v102, v102, v109
	s_waitcnt vmcnt(1)
	v_add_f32_e32 v106, v106, v115
	s_waitcnt vmcnt(0)
	v_add_f32_e32 v108, v110, v116
	global_store_dword v[100:101], v98, off
	global_store_dword v[100:101], v102, off offset:64
	global_store_dword v[100:101], v106, off offset:128
	global_store_dword v[100:101], v108, off offset:192
	global_load_dword v98, v[104:105], off
	s_nop 0
	global_load_dword v102, v[104:105], off offset:64
	global_load_dword v106, v[104:105], off offset:128
	global_load_dword v108, v[104:105], off offset:192
	v_or_b32_e32 v100, 32, v114
	v_ashrrev_i32_e32 v101, 31, v100
	v_lshlrev_b64 v[100:101], 10, v[100:101]
	v_lshl_add_u64 v[100:101], v[100:101], 0, v[112:113]
	v_lshlrev_b64 v[100:101], 2, v[100:101]
	v_lshl_add_u64 v[104:105], s[8:9], 0, v[100:101]
	s_waitcnt vmcnt(3)
	v_add_f32_e32 v98, v99, v98
	s_waitcnt vmcnt(2)
	v_add_f32_e32 v99, v103, v102
	s_waitcnt vmcnt(1)
	v_add_f32_e32 v102, v107, v106
	s_waitcnt vmcnt(0)
	v_add_f32_e32 v103, v111, v108
	global_store_dword v[96:97], v98, off
	global_store_dword v[96:97], v99, off offset:64
	global_store_dword v[96:97], v102, off offset:128
	global_store_dword v[96:97], v103, off offset:192
	global_load_dword v102, v[104:105], off
	s_nop 0
	global_load_dword v103, v[104:105], off offset:64
	global_load_dword v106, v[104:105], off offset:128
	s_nop 0
	global_load_dword v104, v[104:105], off offset:192
	v_or_b32_e32 v96, 33, v114
	v_ashrrev_i32_e32 v97, 31, v96
	v_lshlrev_b64 v[96:97], 10, v[96:97]
	v_lshl_add_u64 v[96:97], v[96:97], 0, v[112:113]
	v_lshlrev_b64 v[96:97], 2, v[96:97]
	v_lshl_add_u64 v[98:99], s[22:23], 0, v[100:101]
	v_lshl_add_u64 v[100:101], s[8:9], 0, v[96:97]
	v_lshl_add_u64 v[96:97], s[22:23], 0, v[96:97]
	s_waitcnt vmcnt(3)
	v_add_f32_e32 v80, v80, v102
	s_waitcnt vmcnt(2)
	v_add_f32_e32 v84, v84, v103
	s_waitcnt vmcnt(1)
	v_add_f32_e32 v88, v88, v106
	s_waitcnt vmcnt(0)
	v_add_f32_e32 v92, v92, v104
	global_store_dword v[98:99], v80, off
	global_store_dword v[98:99], v84, off offset:64
	global_store_dword v[98:99], v88, off offset:128
	global_store_dword v[98:99], v92, off offset:192
	global_load_dword v80, v[100:101], off
	s_nop 0
	global_load_dword v84, v[100:101], off offset:64
	global_load_dword v88, v[100:101], off offset:128
	global_load_dword v92, v[100:101], off offset:192
	v_or_b32_e32 v98, 34, v114
	v_ashrrev_i32_e32 v99, 31, v98
	v_lshlrev_b64 v[98:99], 10, v[98:99]
	v_lshl_add_u64 v[98:99], v[98:99], 0, v[112:113]
	v_lshlrev_b64 v[98:99], 2, v[98:99]
	v_lshl_add_u64 v[100:101], s[8:9], 0, v[98:99]
	s_waitcnt vmcnt(3)
	v_add_f32_e32 v80, v81, v80
	s_waitcnt vmcnt(2)
	v_add_f32_e32 v81, v85, v84
	s_waitcnt vmcnt(1)
	v_add_f32_e32 v84, v89, v88
	s_waitcnt vmcnt(0)
	v_add_f32_e32 v85, v93, v92
	global_store_dword v[96:97], v80, off
	global_store_dword v[96:97], v81, off offset:64
	global_store_dword v[96:97], v84, off offset:128
	global_store_dword v[96:97], v85, off offset:192
	global_load_dword v92, v[100:101], off
	global_load_dword v93, v[100:101], off offset:64
	s_nop 0
	global_load_dword v96, v[100:101], off offset:128
	global_load_dword v97, v[100:101], off offset:192
	v_or_b32_e32 v80, 35, v114
	v_ashrrev_i32_e32 v81, 31, v80
	v_lshlrev_b64 v[80:81], 10, v[80:81]
	v_lshl_add_u64 v[80:81], v[80:81], 0, v[112:113]
	v_lshlrev_b64 v[80:81], 2, v[80:81]
	v_lshl_add_u64 v[84:85], s[22:23], 0, v[98:99]
	v_lshl_add_u64 v[88:89], s[8:9], 0, v[80:81]
	v_lshl_add_u64 v[80:81], s[22:23], 0, v[80:81]
	s_waitcnt vmcnt(3)
	v_add_f32_e32 v82, v82, v92
	s_waitcnt vmcnt(2)
	v_add_f32_e32 v86, v86, v93
	s_waitcnt vmcnt(1)
	v_add_f32_e32 v90, v90, v96
	s_waitcnt vmcnt(0)
; template <int EPI>
; DI void gemm_phase(const u16* __restrict__ A, int lda, const u16* __restrict__ Bt, int K, int N, u16* outb, int ldo,
;                    const float* r0, const float* r1, float* outf, char* lds, int bid, int nb) {
;     ...
;       for (int i = 0; i < 8; ++i)
; #pragma unroll
;         for (int r = 0; r < 4; ++r) {
;           const size_t i0 = (size_t)(mrow + i * 16 + r) * DM + col;
;           const float x0 = rb_[i0], x1 = rb_[i0 + 16], x2 = rb_[i0 + 32], x3 = rb_[i0 + 48];
;           outf[i0] = x0 + acc[i][0][r]; outf[i0 + 16] = x1 + acc[i][1][r]; outf[i0 + 32] = x2 + acc[i][2][r]; outf[i0 + 48] = x3 + acc[i][3][r];
;         }
	v_add_f32_e32 v92, v94, v97
	global_store_dword v[84:85], v82, off
	global_store_dword v[84:85], v86, off offset:64
	global_store_dword v[84:85], v90, off offset:128
	global_store_dword v[84:85], v92, off offset:192
	global_load_dword v82, v[88:89], off
	s_nop 0
	global_load_dword v86, v[88:89], off offset:64
	global_load_dword v90, v[88:89], off offset:128
	global_load_dword v92, v[88:89], off offset:192
	v_or_b32_e32 v84, 48, v114
	v_ashrrev_i32_e32 v85, 31, v84
	v_lshlrev_b64 v[84:85], 10, v[84:85]
	v_lshl_add_u64 v[84:85], v[84:85], 0, v[112:113]
	v_lshlrev_b64 v[84:85], 2, v[84:85]
	v_lshl_add_u64 v[88:89], s[8:9], 0, v[84:85]
	s_waitcnt vmcnt(3)
	v_add_f32_e32 v82, v83, v82
	s_waitcnt vmcnt(2)
	v_add_f32_e32 v83, v87, v86
	s_waitcnt vmcnt(1)
	v_add_f32_e32 v86, v91, v90
	s_waitcnt vmcnt(0)
	v_add_f32_e32 v87, v95, v92
	global_store_dword v[80:81], v82, off
	global_store_dword v[80:81], v83, off offset:64
	global_store_dword v[80:81], v86, off offset:128
	global_store_dword v[80:81], v87, off offset:192
	global_load_dword v86, v[88:89], off
	s_nop 0
	global_load_dword v87, v[88:89], off offset:64
	global_load_dword v90, v[88:89], off offset:128
	s_nop 0
	global_load_dword v88, v[88:89], off offset:192
	v_or_b32_e32 v80, 49, v114
	v_ashrrev_i32_e32 v81, 31, v80
	v_lshlrev_b64 v[80:81], 10, v[80:81]
	v_lshl_add_u64 v[80:81], v[80:81], 0, v[112:113]
	v_lshlrev_b64 v[80:81], 2, v[80:81]
	v_lshl_add_u64 v[82:83], s[22:23], 0, v[84:85]
	v_lshl_add_u64 v[84:85], s[8:9], 0, v[80:81]
	v_lshl_add_u64 v[80:81], s[22:23], 0, v[80:81]
	s_waitcnt vmcnt(3)
	v_add_f32_e32 v64, v64, v86
	s_waitcnt vmcnt(2)
	v_add_f32_e32 v68, v68, v87
	s_waitcnt vmcnt(1)
	v_add_f32_e32 v72, v72, v90
	s_waitcnt vmcnt(0)
	v_add_f32_e32 v76, v76, v88
	global_store_dword v[82:83], v64, off
	global_store_dword v[82:83], v68, off offset:64
	global_store_dword v[82:83], v72, off offset:128
	global_store_dword v[82:83], v76, off offset:192
	global_load_dword v64, v[84:85], off
	s_nop 0
	global_load_dword v68, v[84:85], off offset:64
	global_load_dword v72, v[84:85], off offset:128
	global_load_dword v76, v[84:85], off offset:192
	v_or_b32_e32 v82, 50, v114
	v_ashrrev_i32_e32 v83, 31, v82
	v_lshlrev_b64 v[82:83], 10, v[82:83]
	v_lshl_add_u64 v[82:83], v[82:83], 0, v[112:113]
	v_lshlrev_b64 v[82:83], 2, v[82:83]
	v_lshl_add_u64 v[84:85], s[8:9], 0, v[82:83]
	s_waitcnt vmcnt(3)
	v_add_f32_e32 v64, v65, v64
	s_waitcnt vmcnt(2)
	v_add_f32_e32 v65, v69, v68
	s_waitcnt vmcnt(1)
	v_add_f32_e32 v68, v73, v72
	s_waitcnt vmcnt(0)
	v_add_f32_e32 v69, v77, v76
	global_store_dword v[80:81], v64, off
	global_store_dword v[80:81], v65, off offset:64
	global_store_dword v[80:81], v68, off offset:128
	global_store_dword v[80:81], v69, off offset:192
	global_load_dword v76, v[84:85], off
	global_load_dword v77, v[84:85], off offset:64
	s_nop 0
	global_load_dword v80, v[84:85], off offset:128
	global_load_dword v81, v[84:85], off offset:192
	v_or_b32_e32 v64, 51, v114
	v_ashrrev_i32_e32 v65, 31, v64
	v_lshlrev_b64 v[64:65], 10, v[64:65]
	v_lshl_add_u64 v[64:65], v[64:65], 0, v[112:113]
	v_lshlrev_b64 v[64:65], 2, v[64:65]
	v_lshl_add_u64 v[68:69], s[22:23], 0, v[82:83]
	v_lshl_add_u64 v[72:73], s[8:9], 0, v[64:65]
	v_lshl_add_u64 v[64:65], s[22:23], 0, v[64:65]
	s_waitcnt vmcnt(3)
	v_add_f32_e32 v66, v66, v76
	s_waitcnt vmcnt(2)
	v_add_f32_e32 v70, v70, v77
	s_waitcnt vmcnt(1)
	v_add_f32_e32 v74, v74, v80
	s_waitcnt vmcnt(0)
	v_add_f32_e32 v76, v78, v81
	global_store_dword v[68:69], v66, off
	global_store_dword v[68:69], v70, off offset:64
	global_store_dword v[68:69], v74, off offset:128
	global_store_dword v[68:69], v76, off offset:192
	global_load_dword v66, v[72:73], off
	s_nop 0
	global_load_dword v70, v[72:73], off offset:64
	global_load_dword v74, v[72:73], off offset:128
	global_load_dword v76, v[72:73], off offset:192
	v_or_b32_e32 v68, 64, v114
	v_ashrrev_i32_e32 v69, 31, v68
	v_lshlrev_b64 v[68:69], 10, v[68:69]
	v_lshl_add_u64 v[68:69], v[68:69], 0, v[112:113]
	v_lshlrev_b64 v[68:69], 2, v[68:69]
	v_lshl_add_u64 v[72:73], s[8:9], 0, v[68:69]
	s_waitcnt vmcnt(3)
	v_add_f32_e32 v66, v67, v66
	s_waitcnt vmcnt(2)
	v_add_f32_e32 v67, v71, v70
	s_waitcnt vmcnt(1)
	v_add_f32_e32 v70, v75, v74
	s_waitcnt vmcnt(0)
	v_add_f32_e32 v71, v79, v76
	global_store_dword v[64:65], v66, off
	global_store_dword v[64:65], v67, off offset:64
	global_store_dword v[64:65], v70, off offset:128
	global_store_dword v[64:65], v71, off offset:192
	global_load_dword v70, v[72:73], off
	s_nop 0
	global_load_dword v71, v[72:73], off offset:64
	global_load_dword v74, v[72:73], off offset:128
	s_nop 0
	global_load_dword v72, v[72:73], off offset:192
	v_or_b32_e32 v64, 0x41, v114
	v_ashrrev_i32_e32 v65, 31, v64
	v_lshlrev_b64 v[64:65], 10, v[64:65]
	v_lshl_add_u64 v[64:65], v[64:65], 0, v[112:113]
	v_lshlrev_b64 v[64:65], 2, v[64:65]
	v_lshl_add_u64 v[66:67], s[22:23], 0, v[68:69]
	v_lshl_add_u64 v[68:69], s[8:9], 0, v[64:65]
	v_lshl_add_u64 v[64:65], s[22:23], 0, v[64:65]
	s_waitcnt vmcnt(3)
	v_add_f32_e32 v48, v48, v70
	s_waitcnt vmcnt(2)
	v_add_f32_e32 v52, v52, v71
	s_waitcnt vmcnt(1)
	v_add_f32_e32 v56, v56, v74
	s_waitcnt vmcnt(0)
	v_add_f32_e32 v60, v60, v72
	global_store_dword v[66:67], v48, off
	global_store_dword v[66:67], v52, off offset:64
	global_store_dword v[66:67], v56, off offset:128
	global_store_dword v[66:67], v60, off offset:192
	global_load_dword v48, v[68:69], off
	s_nop 0
	global_load_dword v52, v[68:69], off offset:64
	global_load_dword v56, v[68:69], off offset:128
	global_load_dword v60, v[68:69], off offset:192
	v_or_b32_e32 v66, 0x42, v114
	v_ashrrev_i32_e32 v67, 31, v66
	v_lshlrev_b64 v[66:67], 10, v[66:67]
	v_lshl_add_u64 v[66:67], v[66:67], 0, v[112:113]
	v_lshlrev_b64 v[66:67], 2, v[66:67]
	v_lshl_add_u64 v[68:69], s[8:9], 0, v[66:67]
	s_waitcnt vmcnt(3)
; template <int EPI>
; DI void gemm_phase(const u16* __restrict__ A, int lda, const u16* __restrict__ Bt, int K, int N, u16* outb, int ldo,
;                    const float* r0, const float* r1, float* outf, char* lds, int bid, int nb) {
;     ...
;       for (int i = 0; i < 8; ++i)
; #pragma unroll
;         for (int r = 0; r < 4; ++r) {
;           const size_t i0 = (size_t)(mrow + i * 16 + r) * DM + col;
;           const float x0 = rb_[i0], x1 = rb_[i0 + 16], x2 = rb_[i0 + 32], x3 = rb_[i0 + 48];
;           outf[i0] = x0 + acc[i][0][r]; outf[i0 + 16] = x1 + acc[i][1][r]; outf[i0 + 32] = x2 + acc[i][2][r]; outf[i0 + 48] = x3 + acc[i][3][r];
;         }
	v_add_f32_e32 v48, v49, v48
	s_waitcnt vmcnt(2)
	v_add_f32_e32 v49, v53, v52
	s_waitcnt vmcnt(1)
	v_add_f32_e32 v52, v57, v56
	s_waitcnt vmcnt(0)
	v_add_f32_e32 v53, v61, v60
	global_store_dword v[64:65], v48, off
	global_store_dword v[64:65], v49, off offset:64
	global_store_dword v[64:65], v52, off offset:128
	global_store_dword v[64:65], v53, off offset:192
	global_load_dword v60, v[68:69], off
	global_load_dword v61, v[68:69], off offset:64
	s_nop 0
	global_load_dword v64, v[68:69], off offset:128
	global_load_dword v65, v[68:69], off offset:192
	v_or_b32_e32 v48, 0x43, v114
	v_ashrrev_i32_e32 v49, 31, v48
	v_lshlrev_b64 v[48:49], 10, v[48:49]
	v_lshl_add_u64 v[48:49], v[48:49], 0, v[112:113]
	v_lshlrev_b64 v[48:49], 2, v[48:49]
	v_lshl_add_u64 v[52:53], s[22:23], 0, v[66:67]
	v_lshl_add_u64 v[56:57], s[8:9], 0, v[48:49]
	v_lshl_add_u64 v[48:49], s[22:23], 0, v[48:49]
	s_waitcnt vmcnt(3)
	v_add_f32_e32 v50, v50, v60
	s_waitcnt vmcnt(2)
	v_add_f32_e32 v54, v54, v61
	s_waitcnt vmcnt(1)
	v_add_f32_e32 v58, v58, v64
	s_waitcnt vmcnt(0)
	v_add_f32_e32 v60, v62, v65
	global_store_dword v[52:53], v50, off
	global_store_dword v[52:53], v54, off offset:64
	global_store_dword v[52:53], v58, off offset:128
	global_store_dword v[52:53], v60, off offset:192
	global_load_dword v50, v[56:57], off
	s_nop 0
	global_load_dword v54, v[56:57], off offset:64
	global_load_dword v58, v[56:57], off offset:128
	global_load_dword v60, v[56:57], off offset:192
	v_or_b32_e32 v52, 0x50, v114
	v_ashrrev_i32_e32 v53, 31, v52
	v_lshlrev_b64 v[52:53], 10, v[52:53]
	v_lshl_add_u64 v[52:53], v[52:53], 0, v[112:113]
	v_lshlrev_b64 v[52:53], 2, v[52:53]
	v_lshl_add_u64 v[56:57], s[8:9], 0, v[52:53]
	s_waitcnt vmcnt(3)
	v_add_f32_e32 v50, v51, v50
	s_waitcnt vmcnt(2)
	v_add_f32_e32 v51, v55, v54
	s_waitcnt vmcnt(1)
	v_add_f32_e32 v54, v59, v58
	s_waitcnt vmcnt(0)
	v_add_f32_e32 v55, v63, v60
	global_store_dword v[48:49], v50, off
	global_store_dword v[48:49], v51, off offset:64
	global_store_dword v[48:49], v54, off offset:128
	global_store_dword v[48:49], v55, off offset:192
	global_load_dword v54, v[56:57], off
	s_nop 0
	global_load_dword v55, v[56:57], off offset:64
	global_load_dword v58, v[56:57], off offset:128
	s_nop 0
	global_load_dword v56, v[56:57], off offset:192
	v_or_b32_e32 v48, 0x51, v114
	v_ashrrev_i32_e32 v49, 31, v48
	v_lshlrev_b64 v[48:49], 10, v[48:49]
	v_lshl_add_u64 v[48:49], v[48:49], 0, v[112:113]
	v_lshlrev_b64 v[48:49], 2, v[48:49]
	v_lshl_add_u64 v[50:51], s[22:23], 0, v[52:53]
	v_lshl_add_u64 v[52:53], s[8:9], 0, v[48:49]
	v_lshl_add_u64 v[48:49], s[22:23], 0, v[48:49]
	s_waitcnt vmcnt(3)
	v_add_f32_e32 v32, v32, v54
	s_waitcnt vmcnt(2)
	v_add_f32_e32 v36, v36, v55
	s_waitcnt vmcnt(1)
	v_add_f32_e32 v40, v40, v58
	s_waitcnt vmcnt(0)
	v_add_f32_e32 v44, v44, v56
	global_store_dword v[50:51], v32, off
	global_store_dword v[50:51], v36, off offset:64
	global_store_dword v[50:51], v40, off offset:128
	global_store_dword v[50:51], v44, off offset:192
	global_load_dword v32, v[52:53], off
	s_nop 0
	global_load_dword v36, v[52:53], off offset:64
	global_load_dword v40, v[52:53], off offset:128
	global_load_dword v44, v[52:53], off offset:192
	v_or_b32_e32 v50, 0x52, v114
	v_ashrrev_i32_e32 v51, 31, v50
	v_lshlrev_b64 v[50:51], 10, v[50:51]
	v_lshl_add_u64 v[50:51], v[50:51], 0, v[112:113]
	v_lshlrev_b64 v[50:51], 2, v[50:51]
	v_lshl_add_u64 v[52:53], s[8:9], 0, v[50:51]
	s_waitcnt vmcnt(3)
	v_add_f32_e32 v32, v33, v32
	s_waitcnt vmcnt(2)
	v_add_f32_e32 v33, v37, v36
	s_waitcnt vmcnt(1)
	v_add_f32_e32 v36, v41, v40
	s_waitcnt vmcnt(0)
	v_add_f32_e32 v37, v45, v44
	global_store_dword v[48:49], v32, off
	global_store_dword v[48:49], v33, off offset:64
	global_store_dword v[48:49], v36, off offset:128
	global_store_dword v[48:49], v37, off offset:192
	global_load_dword v44, v[52:53], off
	global_load_dword v45, v[52:53], off offset:64
	s_nop 0
	global_load_dword v48, v[52:53], off offset:128
	global_load_dword v49, v[52:53], off offset:192
	v_or_b32_e32 v32, 0x53, v114
	v_ashrrev_i32_e32 v33, 31, v32
	v_lshlrev_b64 v[32:33], 10, v[32:33]
	v_lshl_add_u64 v[32:33], v[32:33], 0, v[112:113]
	v_lshlrev_b64 v[32:33], 2, v[32:33]
	v_lshl_add_u64 v[36:37], s[22:23], 0, v[50:51]
	v_lshl_add_u64 v[40:41], s[8:9], 0, v[32:33]
	v_lshl_add_u64 v[32:33], s[22:23], 0, v[32:33]
	s_waitcnt vmcnt(3)
	v_add_f32_e32 v34, v34, v44
	s_waitcnt vmcnt(2)
	v_add_f32_e32 v38, v38, v45
	s_waitcnt vmcnt(1)
	v_add_f32_e32 v42, v42, v48
	s_waitcnt vmcnt(0)
	v_add_f32_e32 v44, v46, v49
	global_store_dword v[36:37], v34, off
	global_store_dword v[36:37], v38, off offset:64
	global_store_dword v[36:37], v42, off offset:128
	global_store_dword v[36:37], v44, off offset:192
	global_load_dword v34, v[40:41], off
	s_nop 0
	global_load_dword v38, v[40:41], off offset:64
	global_load_dword v42, v[40:41], off offset:128
	global_load_dword v44, v[40:41], off offset:192
	v_or_b32_e32 v36, 0x60, v114
	v_ashrrev_i32_e32 v37, 31, v36
	v_lshlrev_b64 v[36:37], 10, v[36:37]
	v_lshl_add_u64 v[36:37], v[36:37], 0, v[112:113]
	v_lshlrev_b64 v[36:37], 2, v[36:37]
	v_lshl_add_u64 v[40:41], s[8:9], 0, v[36:37]
	s_waitcnt vmcnt(3)
	v_add_f32_e32 v34, v35, v34
	s_waitcnt vmcnt(2)
	v_add_f32_e32 v35, v39, v38
	s_waitcnt vmcnt(1)
	v_add_f32_e32 v38, v43, v42
	s_waitcnt vmcnt(0)
; template <int EPI>
; DI void gemm_phase(const u16* __restrict__ A, int lda, const u16* __restrict__ Bt, int K, int N, u16* outb, int ldo,
;                    const float* r0, const float* r1, float* outf, char* lds, int bid, int nb) {
;     ...
;       for (int i = 0; i < 8; ++i)
; #pragma unroll
;         for (int r = 0; r < 4; ++r) {
;           const size_t i0 = (size_t)(mrow + i * 16 + r) * DM + col;
;           const float x0 = rb_[i0], x1 = rb_[i0 + 16], x2 = rb_[i0 + 32], x3 = rb_[i0 + 48];
;           outf[i0] = x0 + acc[i][0][r]; outf[i0 + 16] = x1 + acc[i][1][r]; outf[i0 + 32] = x2 + acc[i][2][r]; outf[i0 + 48] = x3 + acc[i][3][r];
;         }
	v_add_f32_e32 v39, v47, v44
	global_store_dword v[32:33], v34, off
	global_store_dword v[32:33], v35, off offset:64
	global_store_dword v[32:33], v38, off offset:128
	global_store_dword v[32:33], v39, off offset:192
	global_load_dword v38, v[40:41], off
	s_nop 0
	global_load_dword v39, v[40:41], off offset:64
	global_load_dword v42, v[40:41], off offset:128
	s_nop 0
	global_load_dword v40, v[40:41], off offset:192
	v_or_b32_e32 v32, 0x61, v114
	v_ashrrev_i32_e32 v33, 31, v32
	v_lshlrev_b64 v[32:33], 10, v[32:33]
	v_lshl_add_u64 v[32:33], v[32:33], 0, v[112:113]
	v_lshlrev_b64 v[32:33], 2, v[32:33]
	v_lshl_add_u64 v[34:35], s[22:23], 0, v[36:37]
	v_lshl_add_u64 v[36:37], s[8:9], 0, v[32:33]
	v_lshl_add_u64 v[32:33], s[22:23], 0, v[32:33]
	s_waitcnt vmcnt(3)
	v_add_f32_e32 v16, v16, v38
	s_waitcnt vmcnt(2)
	v_add_f32_e32 v20, v20, v39
	s_waitcnt vmcnt(1)
	v_add_f32_e32 v24, v24, v42
	s_waitcnt vmcnt(0)
	v_add_f32_e32 v28, v28, v40
	global_store_dword v[34:35], v16, off
	global_store_dword v[34:35], v20, off offset:64
	global_store_dword v[34:35], v24, off offset:128
	global_store_dword v[34:35], v28, off offset:192
	global_load_dword v16, v[36:37], off
	s_nop 0
	global_load_dword v20, v[36:37], off offset:64
	global_load_dword v24, v[36:37], off offset:128
	global_load_dword v28, v[36:37], off offset:192
	v_or_b32_e32 v34, 0x62, v114
	v_ashrrev_i32_e32 v35, 31, v34
	v_lshlrev_b64 v[34:35], 10, v[34:35]
	v_lshl_add_u64 v[34:35], v[34:35], 0, v[112:113]
	v_lshlrev_b64 v[34:35], 2, v[34:35]
	v_lshl_add_u64 v[36:37], s[8:9], 0, v[34:35]
	s_waitcnt vmcnt(3)
	v_add_f32_e32 v16, v17, v16
	s_waitcnt vmcnt(2)
	v_add_f32_e32 v17, v21, v20
	s_waitcnt vmcnt(1)
	v_add_f32_e32 v20, v25, v24
	s_waitcnt vmcnt(0)
	v_add_f32_e32 v21, v29, v28
	global_store_dword v[32:33], v16, off
	global_store_dword v[32:33], v17, off offset:64
	global_store_dword v[32:33], v20, off offset:128
	global_store_dword v[32:33], v21, off offset:192
	global_load_dword v28, v[36:37], off
	global_load_dword v29, v[36:37], off offset:64
	s_nop 0
	global_load_dword v32, v[36:37], off offset:128
	global_load_dword v33, v[36:37], off offset:192
	v_or_b32_e32 v16, 0x63, v114
	v_ashrrev_i32_e32 v17, 31, v16
	v_lshlrev_b64 v[16:17], 10, v[16:17]
	v_lshl_add_u64 v[16:17], v[16:17], 0, v[112:113]
	v_lshlrev_b64 v[16:17], 2, v[16:17]
	v_lshl_add_u64 v[20:21], s[22:23], 0, v[34:35]
	v_lshl_add_u64 v[24:25], s[8:9], 0, v[16:17]
	v_lshl_add_u64 v[16:17], s[22:23], 0, v[16:17]
	s_waitcnt vmcnt(3)
	v_add_f32_e32 v18, v18, v28
	s_waitcnt vmcnt(2)
	v_add_f32_e32 v22, v22, v29
	s_waitcnt vmcnt(1)
	v_add_f32_e32 v26, v26, v32
	s_waitcnt vmcnt(0)
	v_add_f32_e32 v28, v30, v33
	global_store_dword v[20:21], v18, off
	global_store_dword v[20:21], v22, off offset:64
	global_store_dword v[20:21], v26, off offset:128
	global_store_dword v[20:21], v28, off offset:192
	global_load_dword v18, v[24:25], off
	s_nop 0
	global_load_dword v22, v[24:25], off offset:64
	global_load_dword v26, v[24:25], off offset:128
	global_load_dword v28, v[24:25], off offset:192
	v_or_b32_e32 v20, 0x70, v114
	v_ashrrev_i32_e32 v21, 31, v20
	v_lshlrev_b64 v[20:21], 10, v[20:21]
	v_lshl_add_u64 v[20:21], v[20:21], 0, v[112:113]
	v_lshlrev_b64 v[20:21], 2, v[20:21]
	v_lshl_add_u64 v[24:25], s[8:9], 0, v[20:21]
	s_waitcnt vmcnt(3)
	v_add_f32_e32 v18, v19, v18
	s_waitcnt vmcnt(2)
	v_add_f32_e32 v19, v23, v22
	s_waitcnt vmcnt(1)
	v_add_f32_e32 v22, v27, v26
	s_waitcnt vmcnt(0)
	v_add_f32_e32 v23, v31, v28
	global_store_dword v[16:17], v18, off
	global_store_dword v[16:17], v19, off offset:64
	global_store_dword v[16:17], v22, off offset:128
	global_store_dword v[16:17], v23, off offset:192
	global_load_dword v22, v[24:25], off
	s_nop 0
	global_load_dword v23, v[24:25], off offset:64
	global_load_dword v26, v[24:25], off offset:128
	s_nop 0
	global_load_dword v24, v[24:25], off offset:192
	v_or_b32_e32 v16, 0x71, v114
	v_ashrrev_i32_e32 v17, 31, v16
	v_lshlrev_b64 v[16:17], 10, v[16:17]
	v_lshl_add_u64 v[16:17], v[16:17], 0, v[112:113]
	v_lshlrev_b64 v[16:17], 2, v[16:17]
	v_lshl_add_u64 v[18:19], s[22:23], 0, v[20:21]
	v_lshl_add_u64 v[20:21], s[8:9], 0, v[16:17]
	v_lshl_add_u64 v[16:17], s[22:23], 0, v[16:17]
	s_waitcnt vmcnt(3)
	v_add_f32_e32 v0, v0, v22
	s_waitcnt vmcnt(2)
	v_add_f32_e32 v4, v4, v23
	s_waitcnt vmcnt(1)
	v_add_f32_e32 v8, v8, v26
	s_waitcnt vmcnt(0)
	v_add_f32_e32 v12, v12, v24
	global_store_dword v[18:19], v0, off
	global_store_dword v[18:19], v4, off offset:64
	global_store_dword v[18:19], v8, off offset:128
	global_store_dword v[18:19], v12, off offset:192
	global_load_dword v0, v[20:21], off
	s_nop 0
	global_load_dword v4, v[20:21], off offset:64
	global_load_dword v8, v[20:21], off offset:128
	global_load_dword v12, v[20:21], off offset:192
	v_or_b32_e32 v18, 0x72, v114
	v_ashrrev_i32_e32 v19, 31, v18
	v_lshlrev_b64 v[18:19], 10, v[18:19]
	v_lshl_add_u64 v[18:19], v[18:19], 0, v[112:113]
	v_lshlrev_b64 v[18:19], 2, v[18:19]
	v_lshl_add_u64 v[20:21], s[8:9], 0, v[18:19]
	s_waitcnt vmcnt(3)
	v_add_f32_e32 v0, v1, v0
	s_waitcnt vmcnt(2)
	v_add_f32_e32 v1, v5, v4
	s_waitcnt vmcnt(1)
	v_add_f32_e32 v4, v9, v8
	s_waitcnt vmcnt(0)
	v_add_f32_e32 v5, v13, v12
	global_store_dword v[16:17], v0, off
	global_store_dword v[16:17], v1, off offset:64
	global_store_dword v[16:17], v4, off offset:128
	global_store_dword v[16:17], v5, off offset:192
	global_load_dword v12, v[20:21], off
	global_load_dword v13, v[20:21], off offset:64
	s_nop 0
	global_load_dword v16, v[20:21], off offset:128
	global_load_dword v17, v[20:21], off offset:192
	v_or_b32_e32 v0, 0x73, v114
	v_ashrrev_i32_e32 v1, 31, v0
	v_lshlrev_b64 v[0:1], 10, v[0:1]
	v_lshl_add_u64 v[0:1], v[0:1], 0, v[112:113]
	v_lshlrev_b64 v[0:1], 2, v[0:1]
	v_lshl_add_u64 v[4:5], s[22:23], 0, v[18:19]
	v_lshl_add_u64 v[8:9], s[8:9], 0, v[0:1]
	v_lshl_add_u64 v[0:1], s[22:23], 0, v[0:1]
	s_waitcnt vmcnt(3)
	v_add_f32_e32 v2, v2, v12
	s_waitcnt vmcnt(2)
	v_add_f32_e32 v6, v6, v13
	s_waitcnt vmcnt(1)
	v_add_f32_e32 v10, v10, v16
	s_waitcnt vmcnt(0)
	v_add_f32_e32 v12, v14, v17
	global_store_dword v[4:5], v2, off
	global_store_dword v[4:5], v6, off offset:64
	global_store_dword v[4:5], v10, off offset:128
	global_store_dword v[4:5], v12, off offset:192
	global_load_dword v2, v[8:9], off
	s_nop 0
	global_load_dword v4, v[8:9], off offset:64
	global_load_dword v5, v[8:9], off offset:128
	global_load_dword v6, v[8:9], off offset:192
	s_waitcnt vmcnt(3)
	v_add_f32_e32 v2, v3, v2
	s_waitcnt vmcnt(2)
	v_add_f32_e32 v3, v7, v4
	s_waitcnt vmcnt(1)
	v_add_f32_e32 v4, v11, v5
	s_waitcnt vmcnt(0)
	v_add_f32_e32 v5, v15, v6
	global_store_dword v[0:1], v2, off
	global_store_dword v[0:1], v3, off offset:64
	global_store_dword v[0:1], v4, off offset:128
	global_store_dword v[0:1], v5, off offset:192
	s_cbranch_scc0 .LBB0_577

; #define G_LOAD(KT) do { _Pragma("unroll") for (int i = 0; i < 4; ++i) { ra[i] = *(const u32x4*)(Ag + (size_t)i * 64 * lda + (KT) * 64); rb[i] = *(const u32x4*)(Bg + (size_t)i * 64 * K + (KT) * 64); } } while (0)
; #define G_STORE(BUF) do { u16* ad = As + (BUF) * 256 * 64 + sto; u16* bd = Bs + (BUF) * 256 * 64 + sto; _Pragma("unroll") for (int i = 0; i < 4; ++i) { *(u32x4*)(ad + i * 64 * 64) = ra[i]; *(u32x4*)(bd + i * 64 * 64) = rb[i]; } } while (0)
; template <int EPI>
; DI void gemm_phase(const u16* __restrict__ A, int lda, const u16* __restrict__ Bt, int K, int N, u16* outb, int ldo,
;                    const float* r0, const float* r1, float* outf, char* lds, int bid, int nb) {
;     ...
;     const u16* Ag = A + (size_t)(tm * 256 + lrow) * lda + lch * 8;
;     const u16* Bg = Bt + (size_t)(tn * 256 + lrow) * K + lch * 8;
;     f32x4 acc[8][4];
; #pragma unroll
;     for (int i = 0; i < 8; ++i)
; #pragma unroll
;       for (int j = 0; j < 4; ++j) acc[i][j] = (f32x4){0.f, 0.f, 0.f, 0.f};
;     u32x4 ra[4], rb[4];
;     ...
;     G_LOAD(0);
;     G_STORE(0);
;     __syncthreads();
.LBB0_701:
	s_lshl_b32 s49, s49, 8
	v_or_b32_e32 v0, s49, v138
	v_ashrrev_i32_e32 v1, 31, v0
	v_lshlrev_b64 v[64:65], 11, v[0:1]
	v_lshl_or_b32 v0, s48, 8, v138
	v_ashrrev_i32_e32 v1, 31, v0
	v_lshlrev_b64 v[66:67], 11, v[0:1]
	v_lshl_add_u64 v[0:1], v[128:129], 0, v[64:65]
	v_add_co_u32_e32 v4, vcc, 0x20000, v0
	v_lshl_add_u64 v[2:3], v[130:131], 0, v[66:67]
	s_nop 0
	v_addc_co_u32_e32 v5, vcc, 0, v1, vcc
	v_add_co_u32_e32 v6, vcc, 0x20000, v2
	s_nop 1
	v_readfirstlane_b32 s98, v0
	v_readfirstlane_b32 s99, v1
	s_nop 1
	v_readfirstlane_b32 s100, v2
	v_readfirstlane_b32 s101, v3
	v_addc_co_u32_e32 v7, vcc, 0, v3, vcc
	v_add_co_u32_e32 v4, vcc, 0x40000, v0
	s_mov_b32 s50, 0
	s_nop 0
	v_addc_co_u32_e32 v5, vcc, 0, v1, vcc
	v_add_co_u32_e32 v6, vcc, 0x40000, v2
	s_mov_b64 s[14:15], 0
	s_nop 0
	v_addc_co_u32_e32 v7, vcc, 0, v3, vcc
	v_add_co_u32_e32 v0, vcc, 0x60000, v0
	v_addc_co_u32_e32 v1, vcc, 0, v1, vcc
	v_add_co_u32_e32 v2, vcc, 0x60000, v2
	v_lshl_add_u64 v[134:135], v[132:133], 0, v[66:67]
	s_nop 0
	v_addc_co_u32_e32 v3, vcc, 0, v3, vcc
	v_mov_b32_e32 v0, 0
	v_mov_b32_e32 v1, v0
	v_mov_b32_e32 v2, v0
	v_mov_b32_e32 v3, v0
	v_mov_b32_e32 v4, v0
	v_mov_b32_e32 v5, v0
	v_mov_b32_e32 v6, v0
	v_mov_b32_e32 v7, v0
	v_mov_b32_e32 v8, v0
	v_mov_b32_e32 v9, v0
	v_mov_b32_e32 v10, v0
	v_mov_b32_e32 v11, v0
	v_mov_b32_e32 v12, v0
	v_mov_b32_e32 v13, v0
	v_mov_b32_e32 v14, v0
	v_mov_b32_e32 v15, v0
	v_mov_b32_e32 v16, v0
	v_mov_b32_e32 v17, v0
	v_mov_b32_e32 v18, v0
	v_mov_b32_e32 v19, v0
	v_mov_b32_e32 v20, v0
	v_mov_b32_e32 v21, v0
	v_mov_b32_e32 v22, v0
	v_mov_b32_e32 v23, v0
	v_mov_b32_e32 v24, v0
	v_mov_b32_e32 v25, v0
	v_mov_b32_e32 v26, v0
	v_mov_b32_e32 v27, v0
	v_mov_b32_e32 v28, v0
	v_mov_b32_e32 v29, v0
	v_mov_b32_e32 v30, v0
	v_lshl_add_u64 v[136:137], v[132:133], 0, v[64:65]
	v_mov_b32_e32 v31, v0
	v_mov_b32_e32 v64, v0
	v_mov_b32_e32 v65, v0
	v_mov_b32_e32 v66, v0
	v_mov_b32_e32 v67, v0
	v_mov_b32_e32 v68, v0
	v_mov_b32_e32 v69, v0
	v_mov_b32_e32 v70, v0
	v_mov_b32_e32 v71, v0
	v_mov_b32_e32 v72, v0
	v_mov_b32_e32 v73, v0
	v_mov_b32_e32 v74, v0
	v_mov_b32_e32 v75, v0
	v_mov_b32_e32 v76, v0
	v_mov_b32_e32 v77, v0
	v_mov_b32_e32 v78, v0
	v_mov_b32_e32 v79, v0
	v_mov_b32_e32 v80, v0
	v_mov_b32_e32 v81, v0
	v_mov_b32_e32 v82, v0
	v_mov_b32_e32 v83, v0
	v_mov_b32_e32 v84, v0
	v_mov_b32_e32 v85, v0
	v_mov_b32_e32 v86, v0
	v_mov_b32_e32 v87, v0
	v_mov_b32_e32 v32, v0
	v_mov_b32_e32 v33, v0
	v_mov_b32_e32 v34, v0
	v_mov_b32_e32 v35, v0
	v_mov_b32_e32 v36, v0
	v_mov_b32_e32 v37, v0
	v_mov_b32_e32 v38, v0
	v_mov_b32_e32 v39, v0
	v_mov_b32_e32 v40, v0
	v_mov_b32_e32 v41, v0
	v_mov_b32_e32 v42, v0
	v_mov_b32_e32 v43, v0
	v_mov_b32_e32 v44, v0
	v_mov_b32_e32 v45, v0
	v_mov_b32_e32 v46, v0
	v_mov_b32_e32 v47, v0
	v_mov_b32_e32 v48, v0
	v_mov_b32_e32 v49, v0
	v_mov_b32_e32 v50, v0
	v_mov_b32_e32 v51, v0
	v_mov_b32_e32 v52, v0
	v_mov_b32_e32 v53, v0
	v_mov_b32_e32 v54, v0
	v_mov_b32_e32 v55, v0
	v_mov_b32_e32 v56, v0
	v_mov_b32_e32 v57, v0
	v_mov_b32_e32 v58, v0
	v_mov_b32_e32 v59, v0
	v_mov_b32_e32 v60, v0
	v_mov_b32_e32 v61, v0
	v_mov_b32_e32 v62, v0
	v_mov_b32_e32 v63, v0
	v_mov_b32_e32 v88, v0
	v_mov_b32_e32 v89, v0
	v_mov_b32_e32 v90, v0
	v_mov_b32_e32 v91, v0
	v_mov_b32_e32 v92, v0
	v_mov_b32_e32 v93, v0
	v_mov_b32_e32 v94, v0
	v_mov_b32_e32 v95, v0
	v_mov_b32_e32 v96, v0
	v_mov_b32_e32 v97, v0
	v_mov_b32_e32 v98, v0
	v_mov_b32_e32 v99, v0
	v_mov_b32_e32 v100, v0
	v_mov_b32_e32 v101, v0
	v_mov_b32_e32 v102, v0
	v_mov_b32_e32 v103, v0
	v_mov_b32_e32 v104, v0
	v_mov_b32_e32 v105, v0
	v_mov_b32_e32 v106, v0
	v_mov_b32_e32 v107, v0
	v_mov_b32_e32 v108, v0
	v_mov_b32_e32 v109, v0
	v_mov_b32_e32 v110, v0
	v_mov_b32_e32 v111, v0
	v_mov_b32_e32 v112, v0
	v_mov_b32_e32 v113, v0
	v_mov_b32_e32 v114, v0
	v_mov_b32_e32 v115, v0
	v_mov_b32_e32 v116, v0
	v_mov_b32_e32 v117, v0
	v_mov_b32_e32 v118, v0
	v_mov_b32_e32 v119, v0
	v_mov_b32_e32 v120, v0
	v_mov_b32_e32 v121, v0
	v_mov_b32_e32 v122, v0
	v_mov_b32_e32 v123, v0
	v_mov_b32_e32 v124, v0
	v_mov_b32_e32 v125, v0
	v_mov_b32_e32 v126, v0
	v_mov_b32_e32 v127, v0
	v_and_b32_e32 v229, 63, v174
	v_lshrrev_b32_e32 v230, 3, v229
	v_mov_b32_e32 v233, 0x800
	v_mul_u32_u24_e32 v224, v230, v233
	v_bfe_u32 v231, v174, 4, 2
	v_bfe_u32 v232, v174, 6, 1
	v_lshl_or_b32 v232, v232, 2, v231
	v_and_b32_e32 v233, 7, v174
	v_xor_b32_e32 v232, v232, v233
	v_lshl_add_u32 v224, v232, 4, v224
	v_and_b32_e32 v229, 15, v174
	v_bfe_u32 v230, v174, 1, 3
	v_xor_b32_e32 v230, v230, v231
	v_lshlrev_b32_e32 v230, 4, v230
	v_lshl_or_b32 v230, v229, 7, v230
	v_lshrrev_b32_e32 v229, 8, v174
	v_lshl_or_b32 v225, v229, 14, v230
	v_bfe_u32 v229, v174, 6, 2
	v_lshl_or_b32 v227, v229, 13, v230
	v_or_b32_e32 v227, 0x10000, v227
	v_xor_b32_e32 v226, 64, v225
	v_xor_b32_e32 v228, 64, v227
	v_readfirstlane_b32 s97, v174
	s_lshl_b32 s97, s97, 4
	s_mov_b32 s28, 14
	s_add_u32 s14, s98, 0x0
	s_addc_u32 s15, s99, 0
	s_add_u32 m0, s97, 0x0
	s_nop 0
	global_load_lds_dwordx4 v224, s[14:15]
	s_add_u32 s14, s100, 0x0
	s_addc_u32 s15, s101, 0
	s_add_u32 m0, s97, 0x10000
	s_nop 0
	global_load_lds_dwordx4 v224, s[14:15]
	s_add_u32 s14, s98, 0x20000
	s_addc_u32 s15, s99, 0
	s_add_u32 m0, s97, 0x2000
	s_nop 0
	global_load_lds_dwordx4 v224, s[14:15]
	s_add_u32 s14, s100, 0x20000
	s_addc_u32 s15, s101, 0
	s_add_u32 m0, s97, 0x12000
	s_nop 0
	global_load_lds_dwordx4 v224, s[14:15]
	s_add_u32 s14, s98, 0x40000
	s_addc_u32 s15, s99, 0
	s_add_u32 m0, s97, 0x4000
	s_nop 0
	global_load_lds_dwordx4 v224, s[14:15]
	s_add_u32 s14, s100, 0x40000
	s_addc_u32 s15, s101, 0
	s_add_u32 m0, s97, 0x14000
	s_nop 0
	global_load_lds_dwordx4 v224, s[14:15]
	s_add_u32 s14, s98, 0x60000
	s_addc_u32 s15, s99, 0
	s_add_u32 m0, s97, 0x6000
	s_nop 0
	global_load_lds_dwordx4 v224, s[14:15]
	s_add_u32 s14, s100, 0x60000
	s_addc_u32 s15, s101, 0
	s_add_u32 m0, s97, 0x16000
	s_nop 0
	global_load_lds_dwordx4 v224, s[14:15]
	s_add_u32 s14, s98, 0x80
	s_addc_u32 s15, s99, 0
	s_add_u32 m0, s97, 0x8000
	s_nop 0
	global_load_lds_dwordx4 v224, s[14:15]
	s_add_u32 s14, s100, 0x80
	s_addc_u32 s15, s101, 0
	s_add_u32 m0, s97, 0x18000
	s_nop 0
	global_load_lds_dwordx4 v224, s[14:15]
	s_add_u32 s14, s98, 0x20080
	s_addc_u32 s15, s99, 0
	s_add_u32 m0, s97, 0xa000
	s_nop 0
	global_load_lds_dwordx4 v224, s[14:15]
	s_add_u32 s14, s100, 0x20080
	s_addc_u32 s15, s101, 0
	s_add_u32 m0, s97, 0x1a000
	s_nop 0
	global_load_lds_dwordx4 v224, s[14:15]
	s_add_u32 s14, s98, 0x40080
	s_addc_u32 s15, s99, 0
	s_add_u32 m0, s97, 0xc000
	s_nop 0
	global_load_lds_dwordx4 v224, s[14:15]
	s_add_u32 s14, s100, 0x40080
	s_addc_u32 s15, s101, 0
	s_add_u32 m0, s97, 0x1c000
	s_nop 0
	global_load_lds_dwordx4 v224, s[14:15]
	s_add_u32 s14, s98, 0x60080
	s_addc_u32 s15, s99, 0
	s_add_u32 m0, s97, 0xe000
	s_nop 0
	global_load_lds_dwordx4 v224, s[14:15]
	s_add_u32 s14, s100, 0x60080
	s_addc_u32 s15, s101, 0
	s_add_u32 m0, s97, 0x1e000
	s_nop 0
	global_load_lds_dwordx4 v224, s[14:15]
	s_add_u32 s98, s98, 0x100
	s_addc_u32 s99, s99, 0
	s_add_u32 s100, s100, 0x100
	s_addc_u32 s101, s101, 0
	s_waitcnt vmcnt(8)
	s_barrier
; #define G_LOAD(KT) do { _Pragma("unroll") for (int i = 0; i < 4; ++i) { ra[i] = *(const u32x4*)(Ag + (size_t)i * 64 * lda + (KT) * 64); rb[i] = *(const u32x4*)(Bg + (size_t)i * 64 * K + (KT) * 64); } } while (0)
; #define G_STORE(BUF) do { u16* ad = As + (BUF) * 256 * 64 + sto; u16* bd = Bs + (BUF) * 256 * 64 + sto; _Pragma("unroll") for (int i = 0; i < 4; ++i) { *(u32x4*)(ad + i * 64 * 64) = ra[i]; *(u32x4*)(bd + i * 64 * 64) = rb[i]; } } while (0)
; template <int EPI>
; DI void gemm_phase(const u16* __restrict__ A, int lda, const u16* __restrict__ Bt, int K, int N, u16* outb, int ldo,
;                    const float* r0, const float* r1, float* outf, char* lds, int bid, int nb) {
;     ...
;     G_LOAD(0);
;     G_STORE(0);
;     __syncthreads();
;     for (int kt = 0; kt < nk; ++kt) {
;       const int cur = kt & 1;
;       if (kt + 1 < nk) G_LOAD(kt + 1);
;       G_MMA(cur, fo0);
;       G_MMA(cur, fo1);
;       if (kt + 1 < nk) G_STORE(cur ^ 1);
;       __syncthreads();
;     }
	ds_read_b128 v[152:155], v227 offset:0
	ds_read_b128 v[156:159], v227 offset:2048
	ds_read_b128 v[160:163], v227 offset:4096
	ds_read_b128 v[164:167], v227 offset:6144
	ds_read_b128 v[188:191], v225 offset:0
	ds_read_b128 v[192:195], v225 offset:2048
	ds_read_b128 v[196:199], v225 offset:4096
	ds_read_b128 v[200:203], v225 offset:6144
	ds_read_b128 v[204:207], v225 offset:8192
	ds_read_b128 v[208:211], v225 offset:10240
	ds_read_b128 v[212:215], v225 offset:12288
	ds_read_b128 v[216:219], v225 offset:14336
	v_xor_b32_e32 v225, 0x8000, v225
	v_xor_b32_e32 v227, 0x8000, v227
	s_waitcnt lgkmcnt(0)
.Lgm2_loop:
	s_waitcnt lgkmcnt(4)
	v_mfma_f32_16x16x32_bf16 v[124:127], v[188:191], v[152:155], v[124:127]
	v_mfma_f32_16x16x32_bf16 v[120:123], v[188:191], v[156:159], v[120:123]
	v_mfma_f32_16x16x32_bf16 v[116:119], v[188:191], v[160:163], v[116:119]
	v_mfma_f32_16x16x32_bf16 v[112:115], v[188:191], v[164:167], v[112:115]
	ds_read_b128 v[188:191], v226 offset:0
	ds_read_b128 v[168:171], v228 offset:0
	v_mfma_f32_16x16x32_bf16 v[108:111], v[192:195], v[152:155], v[108:111]
	v_mfma_f32_16x16x32_bf16 v[104:107], v[192:195], v[156:159], v[104:107]
	v_mfma_f32_16x16x32_bf16 v[100:103], v[192:195], v[160:163], v[100:103]
	v_mfma_f32_16x16x32_bf16 v[96:99], v[192:195], v[164:167], v[96:99]
	ds_read_b128 v[192:195], v226 offset:2048
	ds_read_b128 v[176:179], v228 offset:2048
	v_mfma_f32_16x16x32_bf16 v[92:95], v[196:199], v[152:155], v[92:95]
	v_mfma_f32_16x16x32_bf16 v[88:91], v[196:199], v[156:159], v[88:91]
	v_mfma_f32_16x16x32_bf16 v[84:87], v[196:199], v[160:163], v[84:87]
	v_mfma_f32_16x16x32_bf16 v[80:83], v[196:199], v[164:167], v[80:83]
	ds_read_b128 v[196:199], v226 offset:4096
	ds_read_b128 v[180:183], v228 offset:4096
	v_mfma_f32_16x16x32_bf16 v[76:79], v[200:203], v[152:155], v[76:79]
	v_mfma_f32_16x16x32_bf16 v[72:75], v[200:203], v[156:159], v[72:75]
	v_mfma_f32_16x16x32_bf16 v[68:71], v[200:203], v[160:163], v[68:71]
	v_mfma_f32_16x16x32_bf16 v[64:67], v[200:203], v[164:167], v[64:67]
	ds_read_b128 v[200:203], v226 offset:6144
	ds_read_b128 v[184:187], v228 offset:6144
	s_waitcnt lgkmcnt(11)
	v_mfma_f32_16x16x32_bf16 v[60:63], v[204:207], v[152:155], v[60:63]
	v_mfma_f32_16x16x32_bf16 v[56:59], v[204:207], v[156:159], v[56:59]
	v_mfma_f32_16x16x32_bf16 v[52:55], v[204:207], v[160:163], v[52:55]
	v_mfma_f32_16x16x32_bf16 v[48:51], v[204:207], v[164:167], v[48:51]
	ds_read_b128 v[204:207], v226 offset:8192
	ds_read_b128 v[220:223], v226 offset:14336
	s_waitcnt lgkmcnt(11)
	v_mfma_f32_16x16x32_bf16 v[44:47], v[208:211], v[152:155], v[44:47]
	v_mfma_f32_16x16x32_bf16 v[40:43], v[208:211], v[156:159], v[40:43]
	v_mfma_f32_16x16x32_bf16 v[36:39], v[208:211], v[160:163], v[36:39]
	v_mfma_f32_16x16x32_bf16 v[32:35], v[208:211], v[164:167], v[32:35]
	ds_read_b128 v[208:211], v226 offset:10240
	s_waitcnt lgkmcnt(11)
	v_mfma_f32_16x16x32_bf16 v[28:31], v[212:215], v[152:155], v[28:31]
	v_mfma_f32_16x16x32_bf16 v[24:27], v[212:215], v[156:159], v[24:27]
	v_mfma_f32_16x16x32_bf16 v[20:23], v[212:215], v[160:163], v[20:23]
	v_mfma_f32_16x16x32_bf16 v[16:19], v[212:215], v[164:167], v[16:19]
	ds_read_b128 v[212:215], v226 offset:12288
	v_mfma_f32_16x16x32_bf16 v[12:15], v[216:219], v[152:155], v[12:15]
	v_mfma_f32_16x16x32_bf16 v[8:11], v[216:219], v[156:159], v[8:11]
	v_mfma_f32_16x16x32_bf16 v[4:7], v[216:219], v[160:163], v[4:7]
	v_mfma_f32_16x16x32_bf16 v[0:3], v[216:219], v[164:167], v[0:3]
	s_waitcnt vmcnt(0) lgkmcnt(0)
	s_barrier
	v_mfma_f32_16x16x32_bf16 v[124:127], v[188:191], v[168:171], v[124:127]
	v_mfma_f32_16x16x32_bf16 v[120:123], v[188:191], v[176:179], v[120:123]
	v_mfma_f32_16x16x32_bf16 v[116:119], v[188:191], v[180:183], v[116:119]
	v_mfma_f32_16x16x32_bf16 v[112:115], v[188:191], v[184:187], v[112:115]
	ds_read_b128 v[188:191], v225 offset:0
	ds_read_b128 v[152:155], v227 offset:0
	s_add_u32 s14, s98, 0x0
	s_addc_u32 s15, s99, 0
	s_add_u32 m0, s97, 0x0
	s_nop 0
	global_load_lds_dwordx4 v224, s[14:15]
	v_mfma_f32_16x16x32_bf16 v[108:111], v[192:195], v[168:171], v[108:111]
	v_mfma_f32_16x16x32_bf16 v[104:107], v[192:195], v[176:179], v[104:107]
	v_mfma_f32_16x16x32_bf16 v[100:103], v[192:195], v[180:183], v[100:103]
	v_mfma_f32_16x16x32_bf16 v[96:99], v[192:195], v[184:187], v[96:99]
	ds_read_b128 v[192:195], v225 offset:2048
	ds_read_b128 v[156:159], v227 offset:2048
	s_add_u32 s14, s100, 0x0
	s_addc_u32 s15, s101, 0
	s_add_u32 m0, s97, 0x10000
	s_nop 0
	global_load_lds_dwordx4 v224, s[14:15]
	v_mfma_f32_16x16x32_bf16 v[92:95], v[196:199], v[168:171], v[92:95]
	v_mfma_f32_16x16x32_bf16 v[88:91], v[196:199], v[176:179], v[88:91]
	v_mfma_f32_16x16x32_bf16 v[84:87], v[196:199], v[180:183], v[84:87]
	v_mfma_f32_16x16x32_bf16 v[80:83], v[196:199], v[184:187], v[80:83]
	ds_read_b128 v[196:199], v225 offset:4096
	ds_read_b128 v[160:163], v227 offset:4096
	s_add_u32 s14, s98, 0x20000
	s_addc_u32 s15, s99, 0
	s_add_u32 m0, s97, 0x2000
	s_nop 0
	global_load_lds_dwordx4 v224, s[14:15]
	v_mfma_f32_16x16x32_bf16 v[76:79], v[200:203], v[168:171], v[76:79]
	v_mfma_f32_16x16x32_bf16 v[72:75], v[200:203], v[176:179], v[72:75]
	v_mfma_f32_16x16x32_bf16 v[68:71], v[200:203], v[180:183], v[68:71]
	v_mfma_f32_16x16x32_bf16 v[64:67], v[200:203], v[184:187], v[64:67]
	ds_read_b128 v[200:203], v225 offset:6144
	ds_read_b128 v[164:167], v227 offset:6144
	s_add_u32 s14, s100, 0x20000
	s_addc_u32 s15, s101, 0
	s_add_u32 m0, s97, 0x12000
	s_nop 0
	global_load_lds_dwordx4 v224, s[14:15]
	v_mfma_f32_16x16x32_bf16 v[60:63], v[204:207], v[168:171], v[60:63]
	v_mfma_f32_16x16x32_bf16 v[56:59], v[204:207], v[176:179], v[56:59]
; #define G_LOAD(KT) do { _Pragma("unroll") for (int i = 0; i < 4; ++i) { ra[i] = *(const u32x4*)(Ag + (size_t)i * 64 * lda + (KT) * 64); rb[i] = *(const u32x4*)(Bg + (size_t)i * 64 * K + (KT) * 64); } } while (0)
; #define G_STORE(BUF) do { u16* ad = As + (BUF) * 256 * 64 + sto; u16* bd = Bs + (BUF) * 256 * 64 + sto; _Pragma("unroll") for (int i = 0; i < 4; ++i) { *(u32x4*)(ad + i * 64 * 64) = ra[i]; *(u32x4*)(bd + i * 64 * 64) = rb[i]; } } while (0)
; template <int EPI>
; DI void gemm_phase(const u16* __restrict__ A, int lda, const u16* __restrict__ Bt, int K, int N, u16* outb, int ldo,
;                    const float* r0, const float* r1, float* outf, char* lds, int bid, int nb) {
;     ...
;     G_LOAD(0);
;     G_STORE(0);
;     __syncthreads();
;     for (int kt = 0; kt < nk; ++kt) {
;       const int cur = kt & 1;
;       if (kt + 1 < nk) G_LOAD(kt + 1);
;       G_MMA(cur, fo0);
;       G_MMA(cur, fo1);
;       if (kt + 1 < nk) G_STORE(cur ^ 1);
;       __syncthreads();
;     }
	v_mfma_f32_16x16x32_bf16 v[52:55], v[204:207], v[180:183], v[52:55]
	v_mfma_f32_16x16x32_bf16 v[48:51], v[204:207], v[184:187], v[48:51]
	ds_read_b128 v[204:207], v225 offset:8192
	ds_read_b128 v[216:219], v225 offset:14336
	s_add_u32 s14, s98, 0x40000
	s_addc_u32 s15, s99, 0
	s_add_u32 m0, s97, 0x4000
	s_nop 0
	global_load_lds_dwordx4 v224, s[14:15]
	v_mfma_f32_16x16x32_bf16 v[44:47], v[208:211], v[168:171], v[44:47]
	v_mfma_f32_16x16x32_bf16 v[40:43], v[208:211], v[176:179], v[40:43]
	v_mfma_f32_16x16x32_bf16 v[36:39], v[208:211], v[180:183], v[36:39]
	v_mfma_f32_16x16x32_bf16 v[32:35], v[208:211], v[184:187], v[32:35]
	ds_read_b128 v[208:211], v225 offset:10240
	s_add_u32 s14, s100, 0x40000
	s_addc_u32 s15, s101, 0
	s_add_u32 m0, s97, 0x14000
	s_nop 0
	global_load_lds_dwordx4 v224, s[14:15]
	v_mfma_f32_16x16x32_bf16 v[28:31], v[212:215], v[168:171], v[28:31]
	v_mfma_f32_16x16x32_bf16 v[24:27], v[212:215], v[176:179], v[24:27]
	v_mfma_f32_16x16x32_bf16 v[20:23], v[212:215], v[180:183], v[20:23]
	v_mfma_f32_16x16x32_bf16 v[16:19], v[212:215], v[184:187], v[16:19]
	ds_read_b128 v[212:215], v225 offset:12288
	s_add_u32 s14, s98, 0x60000
	s_addc_u32 s15, s99, 0
	s_add_u32 m0, s97, 0x6000
	s_nop 0
	global_load_lds_dwordx4 v224, s[14:15]
	v_mfma_f32_16x16x32_bf16 v[12:15], v[220:223], v[168:171], v[12:15]
	v_mfma_f32_16x16x32_bf16 v[8:11], v[220:223], v[176:179], v[8:11]
	v_mfma_f32_16x16x32_bf16 v[4:7], v[220:223], v[180:183], v[4:7]
	v_mfma_f32_16x16x32_bf16 v[0:3], v[220:223], v[184:187], v[0:3]
	s_add_u32 s14, s100, 0x60000
	s_addc_u32 s15, s101, 0
	s_add_u32 m0, s97, 0x16000
	s_nop 0
	global_load_lds_dwordx4 v224, s[14:15]
	v_xor_b32_e32 v225, 0x8000, v225
	v_xor_b32_e32 v227, 0x8000, v227
	v_xor_b32_e32 v226, 0x8000, v226
	v_xor_b32_e32 v228, 0x8000, v228
	s_xor_b32 s97, s97, 0x8000
	s_add_u32 s98, s98, 0x80
	s_addc_u32 s99, s99, 0
	s_add_u32 s100, s100, 0x80
	s_addc_u32 s101, s101, 0
	s_sub_u32 s28, s28, 1
	s_cmp_lg_u32 s28, 0
	s_cbranch_scc1 .Lgm2_loop
	s_waitcnt lgkmcnt(4)
	v_mfma_f32_16x16x32_bf16 v[124:127], v[188:191], v[152:155], v[124:127]
	v_mfma_f32_16x16x32_bf16 v[120:123], v[188:191], v[156:159], v[120:123]
	v_mfma_f32_16x16x32_bf16 v[116:119], v[188:191], v[160:163], v[116:119]
	v_mfma_f32_16x16x32_bf16 v[112:115], v[188:191], v[164:167], v[112:115]
	ds_read_b128 v[188:191], v226 offset:0
	ds_read_b128 v[168:171], v228 offset:0
	v_mfma_f32_16x16x32_bf16 v[108:111], v[192:195], v[152:155], v[108:111]
	v_mfma_f32_16x16x32_bf16 v[104:107], v[192:195], v[156:159], v[104:107]
	v_mfma_f32_16x16x32_bf16 v[100:103], v[192:195], v[160:163], v[100:103]
	v_mfma_f32_16x16x32_bf16 v[96:99], v[192:195], v[164:167], v[96:99]
	ds_read_b128 v[192:195], v226 offset:2048
	ds_read_b128 v[176:179], v228 offset:2048
	v_mfma_f32_16x16x32_bf16 v[92:95], v[196:199], v[152:155], v[92:95]
	v_mfma_f32_16x16x32_bf16 v[88:91], v[196:199], v[156:159], v[88:91]
	v_mfma_f32_16x16x32_bf16 v[84:87], v[196:199], v[160:163], v[84:87]
	v_mfma_f32_16x16x32_bf16 v[80:83], v[196:199], v[164:167], v[80:83]
	ds_read_b128 v[196:199], v226 offset:4096
	ds_read_b128 v[180:183], v228 offset:4096
	v_mfma_f32_16x16x32_bf16 v[76:79], v[200:203], v[152:155], v[76:79]
	v_mfma_f32_16x16x32_bf16 v[72:75], v[200:203], v[156:159], v[72:75]
	v_mfma_f32_16x16x32_bf16 v[68:71], v[200:203], v[160:163], v[68:71]
	v_mfma_f32_16x16x32_bf16 v[64:67], v[200:203], v[164:167], v[64:67]
	ds_read_b128 v[200:203], v226 offset:6144
	ds_read_b128 v[184:187], v228 offset:6144
	s_waitcnt lgkmcnt(11)
	v_mfma_f32_16x16x32_bf16 v[60:63], v[204:207], v[152:155], v[60:63]
	v_mfma_f32_16x16x32_bf16 v[56:59], v[204:207], v[156:159], v[56:59]
	v_mfma_f32_16x16x32_bf16 v[52:55], v[204:207], v[160:163], v[52:55]
	v_mfma_f32_16x16x32_bf16 v[48:51], v[204:207], v[164:167], v[48:51]
	ds_read_b128 v[204:207], v226 offset:8192
	ds_read_b128 v[220:223], v226 offset:14336
	s_waitcnt lgkmcnt(11)
	v_mfma_f32_16x16x32_bf16 v[44:47], v[208:211], v[152:155], v[44:47]
	v_mfma_f32_16x16x32_bf16 v[40:43], v[208:211], v[156:159], v[40:43]
	v_mfma_f32_16x16x32_bf16 v[36:39], v[208:211], v[160:163], v[36:39]
	v_mfma_f32_16x16x32_bf16 v[32:35], v[208:211], v[164:167], v[32:35]
	ds_read_b128 v[208:211], v226 offset:10240
	s_waitcnt lgkmcnt(11)
	v_mfma_f32_16x16x32_bf16 v[28:31], v[212:215], v[152:155], v[28:31]
	v_mfma_f32_16x16x32_bf16 v[24:27], v[212:215], v[156:159], v[24:27]
	v_mfma_f32_16x16x32_bf16 v[20:23], v[212:215], v[160:163], v[20:23]
	v_mfma_f32_16x16x32_bf16 v[16:19], v[212:215], v[164:167], v[16:19]
	ds_read_b128 v[212:215], v226 offset:12288
	v_mfma_f32_16x16x32_bf16 v[12:15], v[216:219], v[152:155], v[12:15]
	v_mfma_f32_16x16x32_bf16 v[8:11], v[216:219], v[156:159], v[8:11]
	v_mfma_f32_16x16x32_bf16 v[4:7], v[216:219], v[160:163], v[4:7]
	v_mfma_f32_16x16x32_bf16 v[0:3], v[216:219], v[164:167], v[0:3]
	s_waitcnt vmcnt(0) lgkmcnt(0)
	s_barrier
; #define G_LOAD(KT) do { _Pragma("unroll") for (int i = 0; i < 4; ++i) { ra[i] = *(const u32x4*)(Ag + (size_t)i * 64 * lda + (KT) * 64); rb[i] = *(const u32x4*)(Bg + (size_t)i * 64 * K + (KT) * 64); } } while (0)
; #define G_STORE(BUF) do { u16* ad = As + (BUF) * 256 * 64 + sto; u16* bd = Bs + (BUF) * 256 * 64 + sto; _Pragma("unroll") for (int i = 0; i < 4; ++i) { *(u32x4*)(ad + i * 64 * 64) = ra[i]; *(u32x4*)(bd + i * 64 * 64) = rb[i]; } } while (0)
; template <int EPI>
; DI void gemm_phase(const u16* __restrict__ A, int lda, const u16* __restrict__ Bt, int K, int N, u16* outb, int ldo,
;                    const float* r0, const float* r1, float* outf, char* lds, int bid, int nb) {
;     ...
;     G_LOAD(0);
;     G_STORE(0);
;     __syncthreads();
;     for (int kt = 0; kt < nk; ++kt) {
;       const int cur = kt & 1;
;       if (kt + 1 < nk) G_LOAD(kt + 1);
;       G_MMA(cur, fo0);
;       G_MMA(cur, fo1);
;       if (kt + 1 < nk) G_STORE(cur ^ 1);
;       __syncthreads();
;     }
	v_mfma_f32_16x16x32_bf16 v[124:127], v[188:191], v[168:171], v[124:127]
	v_mfma_f32_16x16x32_bf16 v[120:123], v[188:191], v[176:179], v[120:123]
	v_mfma_f32_16x16x32_bf16 v[116:119], v[188:191], v[180:183], v[116:119]
	v_mfma_f32_16x16x32_bf16 v[112:115], v[188:191], v[184:187], v[112:115]
	ds_read_b128 v[188:191], v225 offset:0
	ds_read_b128 v[152:155], v227 offset:0
	v_mfma_f32_16x16x32_bf16 v[108:111], v[192:195], v[168:171], v[108:111]
	v_mfma_f32_16x16x32_bf16 v[104:107], v[192:195], v[176:179], v[104:107]
	v_mfma_f32_16x16x32_bf16 v[100:103], v[192:195], v[180:183], v[100:103]
	v_mfma_f32_16x16x32_bf16 v[96:99], v[192:195], v[184:187], v[96:99]
	ds_read_b128 v[192:195], v225 offset:2048
	ds_read_b128 v[156:159], v227 offset:2048
	v_mfma_f32_16x16x32_bf16 v[92:95], v[196:199], v[168:171], v[92:95]
	v_mfma_f32_16x16x32_bf16 v[88:91], v[196:199], v[176:179], v[88:91]
	v_mfma_f32_16x16x32_bf16 v[84:87], v[196:199], v[180:183], v[84:87]
	v_mfma_f32_16x16x32_bf16 v[80:83], v[196:199], v[184:187], v[80:83]
	ds_read_b128 v[196:199], v225 offset:4096
	ds_read_b128 v[160:163], v227 offset:4096
	v_mfma_f32_16x16x32_bf16 v[76:79], v[200:203], v[168:171], v[76:79]
	v_mfma_f32_16x16x32_bf16 v[72:75], v[200:203], v[176:179], v[72:75]
	v_mfma_f32_16x16x32_bf16 v[68:71], v[200:203], v[180:183], v[68:71]
	v_mfma_f32_16x16x32_bf16 v[64:67], v[200:203], v[184:187], v[64:67]
	ds_read_b128 v[200:203], v225 offset:6144
	ds_read_b128 v[164:167], v227 offset:6144
	v_mfma_f32_16x16x32_bf16 v[60:63], v[204:207], v[168:171], v[60:63]
	v_mfma_f32_16x16x32_bf16 v[56:59], v[204:207], v[176:179], v[56:59]
	v_mfma_f32_16x16x32_bf16 v[52:55], v[204:207], v[180:183], v[52:55]
	v_mfma_f32_16x16x32_bf16 v[48:51], v[204:207], v[184:187], v[48:51]
	ds_read_b128 v[204:207], v225 offset:8192
	ds_read_b128 v[216:219], v225 offset:14336
	v_mfma_f32_16x16x32_bf16 v[44:47], v[208:211], v[168:171], v[44:47]
	v_mfma_f32_16x16x32_bf16 v[40:43], v[208:211], v[176:179], v[40:43]
	v_mfma_f32_16x16x32_bf16 v[36:39], v[208:211], v[180:183], v[36:39]
	v_mfma_f32_16x16x32_bf16 v[32:35], v[208:211], v[184:187], v[32:35]
	ds_read_b128 v[208:211], v225 offset:10240
	v_mfma_f32_16x16x32_bf16 v[28:31], v[212:215], v[168:171], v[28:31]
	v_mfma_f32_16x16x32_bf16 v[24:27], v[212:215], v[176:179], v[24:27]
	v_mfma_f32_16x16x32_bf16 v[20:23], v[212:215], v[180:183], v[20:23]
	v_mfma_f32_16x16x32_bf16 v[16:19], v[212:215], v[184:187], v[16:19]
	ds_read_b128 v[212:215], v225 offset:12288
	v_mfma_f32_16x16x32_bf16 v[12:15], v[220:223], v[168:171], v[12:15]
	v_mfma_f32_16x16x32_bf16 v[8:11], v[220:223], v[176:179], v[8:11]
	v_mfma_f32_16x16x32_bf16 v[4:7], v[220:223], v[180:183], v[4:7]
	v_mfma_f32_16x16x32_bf16 v[0:3], v[220:223], v[184:187], v[0:3]
	v_xor_b32_e32 v226, 0x8000, v226
	v_xor_b32_e32 v228, 0x8000, v228
	s_waitcnt lgkmcnt(4)
	v_mfma_f32_16x16x32_bf16 v[124:127], v[188:191], v[152:155], v[124:127]
	v_mfma_f32_16x16x32_bf16 v[120:123], v[188:191], v[156:159], v[120:123]
	v_mfma_f32_16x16x32_bf16 v[116:119], v[188:191], v[160:163], v[116:119]
	v_mfma_f32_16x16x32_bf16 v[112:115], v[188:191], v[164:167], v[112:115]
	ds_read_b128 v[188:191], v226 offset:0
	ds_read_b128 v[168:171], v228 offset:0
	v_mfma_f32_16x16x32_bf16 v[108:111], v[192:195], v[152:155], v[108:111]
	v_mfma_f32_16x16x32_bf16 v[104:107], v[192:195], v[156:159], v[104:107]
	v_mfma_f32_16x16x32_bf16 v[100:103], v[192:195], v[160:163], v[100:103]
	v_mfma_f32_16x16x32_bf16 v[96:99], v[192:195], v[164:167], v[96:99]
	ds_read_b128 v[192:195], v226 offset:2048
	ds_read_b128 v[176:179], v228 offset:2048
	v_mfma_f32_16x16x32_bf16 v[92:95], v[196:199], v[152:155], v[92:95]
	v_mfma_f32_16x16x32_bf16 v[88:91], v[196:199], v[156:159], v[88:91]
	v_mfma_f32_16x16x32_bf16 v[84:87], v[196:199], v[160:163], v[84:87]
	v_mfma_f32_16x16x32_bf16 v[80:83], v[196:199], v[164:167], v[80:83]
	ds_read_b128 v[196:199], v226 offset:4096
	ds_read_b128 v[180:183], v228 offset:4096
	v_mfma_f32_16x16x32_bf16 v[76:79], v[200:203], v[152:155], v[76:79]
	v_mfma_f32_16x16x32_bf16 v[72:75], v[200:203], v[156:159], v[72:75]
	v_mfma_f32_16x16x32_bf16 v[68:71], v[200:203], v[160:163], v[68:71]
	v_mfma_f32_16x16x32_bf16 v[64:67], v[200:203], v[164:167], v[64:67]
	ds_read_b128 v[200:203], v226 offset:6144
	ds_read_b128 v[184:187], v228 offset:6144
	s_waitcnt lgkmcnt(11)
	v_mfma_f32_16x16x32_bf16 v[60:63], v[204:207], v[152:155], v[60:63]
	v_mfma_f32_16x16x32_bf16 v[56:59], v[204:207], v[156:159], v[56:59]
	v_mfma_f32_16x16x32_bf16 v[52:55], v[204:207], v[160:163], v[52:55]
	v_mfma_f32_16x16x32_bf16 v[48:51], v[204:207], v[164:167], v[48:51]
	ds_read_b128 v[204:207], v226 offset:8192
	ds_read_b128 v[220:223], v226 offset:14336
	s_waitcnt lgkmcnt(11)
	v_mfma_f32_16x16x32_bf16 v[44:47], v[208:211], v[152:155], v[44:47]
	v_mfma_f32_16x16x32_bf16 v[40:43], v[208:211], v[156:159], v[40:43]
	v_mfma_f32_16x16x32_bf16 v[36:39], v[208:211], v[160:163], v[36:39]
	v_mfma_f32_16x16x32_bf16 v[32:35], v[208:211], v[164:167], v[32:35]
	ds_read_b128 v[208:211], v226 offset:10240
	s_waitcnt lgkmcnt(11)
	v_mfma_f32_16x16x32_bf16 v[28:31], v[212:215], v[152:155], v[28:31]
	v_mfma_f32_16x16x32_bf16 v[24:27], v[212:215], v[156:159], v[24:27]
	v_mfma_f32_16x16x32_bf16 v[20:23], v[212:215], v[160:163], v[20:23]
	v_mfma_f32_16x16x32_bf16 v[16:19], v[212:215], v[164:167], v[16:19]
	ds_read_b128 v[212:215], v226 offset:12288
	v_mfma_f32_16x16x32_bf16 v[12:15], v[216:219], v[152:155], v[12:15]
	v_mfma_f32_16x16x32_bf16 v[8:11], v[216:219], v[156:159], v[8:11]
	v_mfma_f32_16x16x32_bf16 v[4:7], v[216:219], v[160:163], v[4:7]
	v_mfma_f32_16x16x32_bf16 v[0:3], v[216:219], v[164:167], v[0:3]
	s_waitcnt vmcnt(0) lgkmcnt(0)
	s_barrier
; DI u16 f2bf(float a) { return (u16)(pk2(a, 0.f) & 0xffffu); }
; DI float sigmoidf_(float x) { return __builtin_amdgcn_rcpf(1.f + __builtin_amdgcn_exp2f(-1.4426950408889634f * x)); }
; template <int EPI>
; DI void gemm_phase(const u16* __restrict__ A, int lda, const u16* __restrict__ Bt, int K, int N, u16* outb, int ldo,
;                    const float* r0, const float* r1, float* outf, char* lds, int bid, int nb) {
;     ...
;     } else {
;       const int col = (tn * 4 + wc) * 32 + l15;
; #pragma unroll
;       for (int i = 0; i < 8; ++i)
; #pragma unroll
;         for (int r = 0; r < 4; ++r) {
;           const float g0 = acc[i][0][r], u0 = acc[i][2][r], g1 = acc[i][1][r], u1 = acc[i][3][r];
;           u16* o0 = outb + (size_t)(mrow + i * 16 + r) * ldo + col;
;           o0[0] = f2bf(g0 * sigmoidf_(g0) * u0); o0[16] = f2bf(g1 * sigmoidf_(g1) * u1);
;         }
	v_mfma_f32_16x16x32_bf16 v[124:127], v[188:191], v[168:171], v[124:127]
	v_mfma_f32_16x16x32_bf16 v[120:123], v[188:191], v[176:179], v[120:123]
	v_mfma_f32_16x16x32_bf16 v[116:119], v[188:191], v[180:183], v[116:119]
	v_mfma_f32_16x16x32_bf16 v[112:115], v[188:191], v[184:187], v[112:115]
	v_mfma_f32_16x16x32_bf16 v[108:111], v[192:195], v[168:171], v[108:111]
	v_mfma_f32_16x16x32_bf16 v[104:107], v[192:195], v[176:179], v[104:107]
	v_mfma_f32_16x16x32_bf16 v[100:103], v[192:195], v[180:183], v[100:103]
	v_mfma_f32_16x16x32_bf16 v[96:99], v[192:195], v[184:187], v[96:99]
	v_mfma_f32_16x16x32_bf16 v[92:95], v[196:199], v[168:171], v[92:95]
	v_mfma_f32_16x16x32_bf16 v[88:91], v[196:199], v[176:179], v[88:91]
	v_mfma_f32_16x16x32_bf16 v[84:87], v[196:199], v[180:183], v[84:87]
	v_mfma_f32_16x16x32_bf16 v[80:83], v[196:199], v[184:187], v[80:83]
	v_mfma_f32_16x16x32_bf16 v[76:79], v[200:203], v[168:171], v[76:79]
	v_mfma_f32_16x16x32_bf16 v[72:75], v[200:203], v[176:179], v[72:75]
	v_mfma_f32_16x16x32_bf16 v[68:71], v[200:203], v[180:183], v[68:71]
	v_mfma_f32_16x16x32_bf16 v[64:67], v[200:203], v[184:187], v[64:67]
	v_mfma_f32_16x16x32_bf16 v[60:63], v[204:207], v[168:171], v[60:63]
	v_mfma_f32_16x16x32_bf16 v[56:59], v[204:207], v[176:179], v[56:59]
	v_mfma_f32_16x16x32_bf16 v[52:55], v[204:207], v[180:183], v[52:55]
	v_mfma_f32_16x16x32_bf16 v[48:51], v[204:207], v[184:187], v[48:51]
	v_mfma_f32_16x16x32_bf16 v[44:47], v[208:211], v[168:171], v[44:47]
	v_mfma_f32_16x16x32_bf16 v[40:43], v[208:211], v[176:179], v[40:43]
	v_mfma_f32_16x16x32_bf16 v[36:39], v[208:211], v[180:183], v[36:39]
	v_mfma_f32_16x16x32_bf16 v[32:35], v[208:211], v[184:187], v[32:35]
	v_mfma_f32_16x16x32_bf16 v[28:31], v[212:215], v[168:171], v[28:31]
	v_mfma_f32_16x16x32_bf16 v[24:27], v[212:215], v[176:179], v[24:27]
	v_mfma_f32_16x16x32_bf16 v[20:23], v[212:215], v[180:183], v[20:23]
	v_mfma_f32_16x16x32_bf16 v[16:19], v[212:215], v[184:187], v[16:19]
	v_mfma_f32_16x16x32_bf16 v[12:15], v[220:223], v[168:171], v[12:15]
	v_mfma_f32_16x16x32_bf16 v[8:11], v[220:223], v[176:179], v[8:11]
	v_mfma_f32_16x16x32_bf16 v[4:7], v[220:223], v[180:183], v[4:7]
	v_mfma_f32_16x16x32_bf16 v[0:3], v[220:223], v[184:187], v[0:3]
	s_nop 7
	s_nop 3
	v_mov_b32_e32 v208, v96
	v_mov_b32_e32 v209, v97
	v_mov_b32_e32 v210, v98
	v_mov_b32_e32 v211, v99
	v_mov_b32_e32 v172, v80
	v_mov_b32_e32 v80, v88
	v_mov_b32_e32 v88, v84
	v_mov_b32_e32 v84, v172
	v_mov_b32_e32 v172, v81
	v_mov_b32_e32 v81, v89
	v_mov_b32_e32 v89, v85
	v_mov_b32_e32 v85, v172
	v_mov_b32_e32 v172, v82
	v_mov_b32_e32 v82, v90
	v_mov_b32_e32 v90, v86
	v_mov_b32_e32 v86, v172
	v_mov_b32_e32 v172, v83
	v_mov_b32_e32 v83, v91
	v_mov_b32_e32 v91, v87
	v_mov_b32_e32 v87, v172
	v_mov_b32_e32 v172, v64
	v_mov_b32_e32 v64, v72
	v_mov_b32_e32 v72, v68
	v_mov_b32_e32 v68, v172
	v_mov_b32_e32 v172, v65
	v_mov_b32_e32 v65, v73
	v_mov_b32_e32 v73, v69
	v_mov_b32_e32 v69, v172
	v_mov_b32_e32 v172, v66
	v_mov_b32_e32 v66, v74
	v_mov_b32_e32 v74, v70
	v_mov_b32_e32 v70, v172
	v_mov_b32_e32 v172, v67
	v_mov_b32_e32 v67, v75
	v_mov_b32_e32 v75, v71
	v_mov_b32_e32 v71, v172
	v_mov_b32_e32 v172, v48
	v_mov_b32_e32 v48, v56
	v_mov_b32_e32 v56, v52
	v_mov_b32_e32 v52, v172
	v_mov_b32_e32 v172, v49
	v_mov_b32_e32 v49, v57
	v_mov_b32_e32 v57, v53
	v_mov_b32_e32 v53, v172
	v_mov_b32_e32 v172, v50
	v_mov_b32_e32 v50, v58
	v_mov_b32_e32 v58, v54
	v_mov_b32_e32 v54, v172
	v_mov_b32_e32 v172, v51
	v_mov_b32_e32 v51, v59
	v_mov_b32_e32 v59, v55
	v_mov_b32_e32 v55, v172
	v_mov_b32_e32 v172, v32
	v_mov_b32_e32 v32, v40
	v_mov_b32_e32 v40, v36
	v_mov_b32_e32 v36, v172
	v_mov_b32_e32 v172, v33
	v_mov_b32_e32 v33, v41
	v_mov_b32_e32 v41, v37
	v_mov_b32_e32 v37, v172
	v_mov_b32_e32 v172, v34
	v_mov_b32_e32 v34, v42
	v_mov_b32_e32 v42, v38
	v_mov_b32_e32 v38, v172
	v_mov_b32_e32 v172, v35
	v_mov_b32_e32 v35, v43
	v_mov_b32_e32 v43, v39
	v_mov_b32_e32 v39, v172
	v_mov_b32_e32 v172, v16
	v_mov_b32_e32 v16, v24
	v_mov_b32_e32 v24, v20
	v_mov_b32_e32 v20, v172
	v_mov_b32_e32 v172, v17
	v_mov_b32_e32 v17, v25
	v_mov_b32_e32 v25, v21
	v_mov_b32_e32 v21, v172
	v_mov_b32_e32 v172, v18
	v_mov_b32_e32 v18, v26
	v_mov_b32_e32 v26, v22
	v_mov_b32_e32 v22, v172
	v_mov_b32_e32 v172, v19
	v_mov_b32_e32 v19, v27
	v_mov_b32_e32 v27, v23
	v_mov_b32_e32 v23, v172
	v_mov_b32_e32 v172, v0
	v_mov_b32_e32 v0, v8
	v_mov_b32_e32 v8, v4
	v_mov_b32_e32 v4, v172
	v_mov_b32_e32 v172, v1
	v_mov_b32_e32 v1, v9
	v_mov_b32_e32 v9, v5
	v_mov_b32_e32 v5, v172
	v_mov_b32_e32 v172, v2
	v_mov_b32_e32 v2, v10
	v_mov_b32_e32 v10, v6
	v_mov_b32_e32 v6, v172
	v_mov_b32_e32 v172, v3
	v_mov_b32_e32 v3, v11
	v_mov_b32_e32 v11, v7
	v_mov_b32_e32 v7, v172
	v_mul_f32_e32 v96, 0xbfb8aa3b, v124
	v_exp_f32_e32 v99, v96
	v_mul_f32_e32 v134, 0xbfb8aa3b, v120
	v_exp_f32_e32 v136, v134
	v_lshl_or_b32 v96, s48, 7, v148
	v_add_f32_e32 v99, 1.0, v99
	v_rcp_f32_e32 v99, v99
	v_ashrrev_i32_e32 v97, 31, v96
	v_add_u32_e32 v98, s49, v143
	v_lshl_add_u64 v[96:97], v[96:97], 1, s[8:9]
	v_mul_f32_e32 v99, v124, v99
	v_add_f32_e32 v124, 1.0, v136
	v_rcp_f32_e32 v124, v124
	v_mul_f32_e32 v99, v116, v99
	v_mad_i64_i32 v[134:135], s[14:15], v98, s47, v[96:97]
	v_cvt_pk_bf16_f32 v99, v99, s0
	global_store_short v[134:135], v99, off
	v_mul_f32_e32 v99, v120, v124
	v_mul_f32_e32 v99, v112, v99
	v_mul_f32_e32 v112, 0xbfb8aa3b, v125
	v_exp_f32_e32 v112, v112
	v_mul_f32_e32 v116, 0xbfb8aa3b, v121
	v_exp_f32_e32 v116, v116
	v_cvt_pk_bf16_f32 v99, v99, s0
	v_add_f32_e32 v112, 1.0, v112
	v_rcp_f32_e32 v112, v112
	global_store_short v[134:135], v99, off offset:32
	v_or_b32_e32 v99, 1, v98
	v_mad_i64_i32 v[134:135], s[14:15], v99, s47, v[96:97]
; DI u16 f2bf(float a) { return (u16)(pk2(a, 0.f) & 0xffffu); }
; DI float sigmoidf_(float x) { return __builtin_amdgcn_rcpf(1.f + __builtin_amdgcn_exp2f(-1.4426950408889634f * x)); }
; template <int EPI>
; DI void gemm_phase(const u16* __restrict__ A, int lda, const u16* __restrict__ Bt, int K, int N, u16* outb, int ldo,
;                    const float* r0, const float* r1, float* outf, char* lds, int bid, int nb) {
;     ...
;       const int col = (tn * 4 + wc) * 32 + l15;
; #pragma unroll
;       for (int i = 0; i < 8; ++i)
; #pragma unroll
;         for (int r = 0; r < 4; ++r) {
;           const float g0 = acc[i][0][r], u0 = acc[i][2][r], g1 = acc[i][1][r], u1 = acc[i][3][r];
;           u16* o0 = outb + (size_t)(mrow + i * 16 + r) * ldo + col;
;           o0[0] = f2bf(g0 * sigmoidf_(g0) * u0); o0[16] = f2bf(g1 * sigmoidf_(g1) * u1);
;         }
	v_mul_f32_e32 v99, v125, v112
	v_add_f32_e32 v112, 1.0, v116
	v_rcp_f32_e32 v112, v112
	v_mul_f32_e32 v99, v117, v99
	v_cvt_pk_bf16_f32 v99, v99, s0
	global_store_short v[134:135], v99, off
	v_mul_f32_e32 v99, v121, v112
	v_mul_f32_e32 v112, 0xbfb8aa3b, v126
	v_exp_f32_e32 v112, v112
	v_mul_f32_e32 v99, v113, v99
	v_cvt_pk_bf16_f32 v99, v99, s0
	global_store_short v[134:135], v99, off offset:32
	v_add_f32_e32 v112, 1.0, v112
	v_rcp_f32_e32 v116, v112
	v_mul_f32_e32 v112, 0xbfb8aa3b, v122
	v_exp_f32_e32 v117, v112
	v_or_b32_e32 v99, 2, v98
	v_mad_i64_i32 v[112:113], s[14:15], v99, s47, v[96:97]
	v_mul_f32_e32 v99, v126, v116
	v_add_f32_e32 v116, 1.0, v117
	v_rcp_f32_e32 v116, v116
	v_mul_f32_e32 v99, v118, v99
	v_cvt_pk_bf16_f32 v99, v99, s0
	global_store_short v[112:113], v99, off
	v_mul_f32_e32 v99, v122, v116
	v_mul_f32_e32 v99, v114, v99
	v_mul_f32_e32 v114, 0xbfb8aa3b, v127
	v_exp_f32_e32 v114, v114
	v_cvt_pk_bf16_f32 v99, v99, s0
	global_store_short v[112:113], v99, off offset:32
	v_or_b32_e32 v99, 3, v98
	v_add_f32_e32 v112, 1.0, v114
	v_rcp_f32_e32 v114, v112
	v_mul_f32_e32 v112, 0xbfb8aa3b, v123
	v_exp_f32_e32 v116, v112
	v_mad_i64_i32 v[112:113], s[14:15], v99, s47, v[96:97]
	v_mul_f32_e32 v99, v127, v114
	v_add_f32_e32 v114, 1.0, v116
	v_rcp_f32_e32 v114, v114
	v_mul_f32_e32 v99, v119, v99
	v_cvt_pk_bf16_f32 v99, v99, s0
	global_store_short v[112:113], v99, off
	v_mul_f32_e32 v99, v123, v114
	v_mul_f32_e32 v114, 0xbfb8aa3b, v108
	v_exp_f32_e32 v114, v114
	v_mul_f32_e32 v99, v115, v99
	v_cvt_pk_bf16_f32 v99, v99, s0
	global_store_short v[112:113], v99, off offset:32
	v_add_f32_e32 v112, 1.0, v114
	v_rcp_f32_e32 v114, v112
	v_mul_f32_e32 v112, 0xbfb8aa3b, v104
	v_exp_f32_e32 v115, v112
	v_or_b32_e32 v99, 16, v98
	v_mad_i64_i32 v[112:113], s[14:15], v99, s47, v[96:97]
	v_mul_f32_e32 v99, v108, v114
	v_add_f32_e32 v108, 1.0, v115
	v_mul_f32_e32 v99, v100, v99
	v_mul_f32_e32 v100, 0xbfb8aa3b, v109
	v_rcp_f32_e32 v108, v108
	v_exp_f32_e32 v100, v100
	v_cvt_pk_bf16_f32 v99, v99, s0
	global_store_short v[112:113], v99, off
	v_mul_f32_e32 v99, v104, v108
	v_add_f32_e32 v100, 1.0, v100
	v_mul_f32_e32 v104, 0xbfb8aa3b, v105
	v_rcp_f32_e32 v100, v100
	v_exp_f32_e32 v104, v104
	v_mul_f32_e32 v99, v208, v99
	v_cvt_pk_bf16_f32 v99, v99, s0
	global_store_short v[112:113], v99, off offset:32
	v_or_b32_e32 v99, 17, v98
	v_mad_i64_i32 v[112:113], s[14:15], v99, s47, v[96:97]
	v_mul_f32_e32 v99, v109, v100
	v_add_f32_e32 v100, 1.0, v104
	v_rcp_f32_e32 v100, v100
	v_mul_f32_e32 v99, v101, v99
	v_cvt_pk_bf16_f32 v99, v99, s0
	global_store_short v[112:113], v99, off
	v_mul_f32_e32 v99, v105, v100
	v_mul_f32_e32 v100, 0xbfb8aa3b, v110
	v_exp_f32_e32 v100, v100
	v_mul_f32_e32 v99, v209, v99
	v_cvt_pk_bf16_f32 v99, v99, s0
	global_store_short v[112:113], v99, off offset:32
	v_add_f32_e32 v100, 1.0, v100
	v_rcp_f32_e32 v104, v100
	v_mul_f32_e32 v100, 0xbfb8aa3b, v106
	v_exp_f32_e32 v105, v100
	v_or_b32_e32 v99, 18, v98
	v_mad_i64_i32 v[100:101], s[14:15], v99, s47, v[96:97]
	v_mul_f32_e32 v99, v110, v104
	v_add_f32_e32 v104, 1.0, v105
	v_rcp_f32_e32 v104, v104
	v_mul_f32_e32 v99, v102, v99
	v_mul_f32_e32 v102, 0xbfb8aa3b, v111
	v_cvt_pk_bf16_f32 v99, v99, s0
	v_exp_f32_e32 v102, v102
	global_store_short v[100:101], v99, off
	v_mul_f32_e32 v99, v106, v104
	v_mul_f32_e32 v99, v210, v99
	v_cvt_pk_bf16_f32 v99, v99, s0
	global_store_short v[100:101], v99, off offset:32
	v_add_f32_e32 v100, 1.0, v102
	v_rcp_f32_e32 v102, v100
	v_mul_f32_e32 v100, 0xbfb8aa3b, v107
	v_exp_f32_e32 v104, v100
	v_or_b32_e32 v99, 19, v98
	v_mad_i64_i32 v[100:101], s[14:15], v99, s47, v[96:97]
	v_mul_f32_e32 v99, v111, v102
	v_add_f32_e32 v102, 1.0, v104
	v_rcp_f32_e32 v102, v102
	v_mul_f32_e32 v99, v103, v99
	v_cvt_pk_bf16_f32 v99, v99, s0
	global_store_short v[100:101], v99, off
	v_mul_f32_e32 v99, v107, v102
	v_mul_f32_e32 v102, 0xbfb8aa3b, v92
	v_exp_f32_e32 v102, v102
	v_mul_f32_e32 v99, v211, v99
	v_cvt_pk_bf16_f32 v99, v99, s0
	global_store_short v[100:101], v99, off offset:32
	v_add_f32_e32 v100, 1.0, v102
	v_rcp_f32_e32 v102, v100
	v_mul_f32_e32 v100, 0xbfb8aa3b, v80
	v_exp_f32_e32 v103, v100
	v_or_b32_e32 v99, 32, v98
	v_mad_i64_i32 v[100:101], s[14:15], v99, s47, v[96:97]
	v_add_f32_e32 v99, 1.0, v103
	v_rcp_f32_e32 v99, v99
	v_mul_f32_e32 v92, v92, v102
	v_mul_f32_e32 v88, v88, v92
	v_cvt_pk_bf16_f32 v88, v88, s0
	v_mul_f32_e32 v80, v80, v99
	v_mul_f32_e32 v80, v84, v80
	v_mul_f32_e32 v84, 0xbfb8aa3b, v93
	v_exp_f32_e32 v84, v84
	global_store_short v[100:101], v88, off
	v_mul_f32_e32 v88, 0xbfb8aa3b, v81
	v_exp_f32_e32 v88, v88
	v_add_f32_e32 v84, 1.0, v84
	v_rcp_f32_e32 v84, v84
	v_cvt_pk_bf16_f32 v80, v80, s0
	global_store_short v[100:101], v80, off offset:32
	v_or_b32_e32 v80, 33, v98
	v_mad_i64_i32 v[100:101], s[14:15], v80, s47, v[96:97]
	v_mul_f32_e32 v80, v93, v84
	v_add_f32_e32 v84, 1.0, v88
	v_rcp_f32_e32 v84, v84
	v_mul_f32_e32 v80, v89, v80
	v_cvt_pk_bf16_f32 v80, v80, s0
	global_store_short v[100:101], v80, off
	v_mul_f32_e32 v80, v81, v84
	v_mul_f32_e32 v81, 0xbfb8aa3b, v94
	v_exp_f32_e32 v81, v81
	v_mul_f32_e32 v80, v85, v80
	v_cvt_pk_bf16_f32 v80, v80, s0
	global_store_short v[100:101], v80, off offset:32
	v_add_f32_e32 v81, 1.0, v81
	v_rcp_f32_e32 v84, v81
	v_mul_f32_e32 v81, 0xbfb8aa3b, v82
	v_exp_f32_e32 v85, v81
	v_or_b32_e32 v80, 34, v98
	v_mul_f32_e32 v84, v94, v84
	v_mul_f32_e32 v84, v90, v84
	v_add_f32_e32 v85, 1.0, v85
	v_rcp_f32_e32 v85, v85
	v_mad_i64_i32 v[80:81], s[14:15], v80, s47, v[96:97]
	v_cvt_pk_bf16_f32 v84, v84, s0
	global_store_short v[80:81], v84, off
	v_mul_f32_e32 v84, 0xbfb8aa3b, v95
	v_exp_f32_e32 v84, v84
	v_mul_f32_e32 v82, v82, v85
; DI u16 f2bf(float a) { return (u16)(pk2(a, 0.f) & 0xffffu); }
; DI float sigmoidf_(float x) { return __builtin_amdgcn_rcpf(1.f + __builtin_amdgcn_exp2f(-1.4426950408889634f * x)); }
; template <int EPI>
; DI void gemm_phase(const u16* __restrict__ A, int lda, const u16* __restrict__ Bt, int K, int N, u16* outb, int ldo,
;                    const float* r0, const float* r1, float* outf, char* lds, int bid, int nb) {
;     ...
;       const int col = (tn * 4 + wc) * 32 + l15;
; #pragma unroll
;       for (int i = 0; i < 8; ++i)
; #pragma unroll
;         for (int r = 0; r < 4; ++r) {
;           const float g0 = acc[i][0][r], u0 = acc[i][2][r], g1 = acc[i][1][r], u1 = acc[i][3][r];
;           u16* o0 = outb + (size_t)(mrow + i * 16 + r) * ldo + col;
;           o0[0] = f2bf(g0 * sigmoidf_(g0) * u0); o0[16] = f2bf(g1 * sigmoidf_(g1) * u1);
;         }
	v_mul_f32_e32 v82, v86, v82
	v_cvt_pk_bf16_f32 v82, v82, s0
	global_store_short v[80:81], v82, off offset:32
	v_add_f32_e32 v81, 1.0, v84
	v_rcp_f32_e32 v82, v81
	v_mul_f32_e32 v81, 0xbfb8aa3b, v83
	v_exp_f32_e32 v84, v81
	v_or_b32_e32 v80, 35, v98
	v_mul_f32_e32 v82, v95, v82
	v_mul_f32_e32 v82, v91, v82
	v_add_f32_e32 v84, 1.0, v84
	v_rcp_f32_e32 v84, v84
	v_mad_i64_i32 v[80:81], s[14:15], v80, s47, v[96:97]
	v_cvt_pk_bf16_f32 v82, v82, s0
	global_store_short v[80:81], v82, off
	v_mul_f32_e32 v82, v83, v84
	v_mul_f32_e32 v83, 0xbfb8aa3b, v76
	v_exp_f32_e32 v83, v83
	v_mul_f32_e32 v82, v87, v82
	v_cvt_pk_bf16_f32 v82, v82, s0
	global_store_short v[80:81], v82, off offset:32
	v_add_f32_e32 v81, 1.0, v83
	v_rcp_f32_e32 v82, v81
	v_mul_f32_e32 v81, 0xbfb8aa3b, v64
	v_exp_f32_e32 v83, v81
	v_or_b32_e32 v80, 48, v98
	v_mul_f32_e32 v76, v76, v82
	v_mul_f32_e32 v72, v72, v76
	v_add_f32_e32 v82, 1.0, v83
	v_rcp_f32_e32 v82, v82
	v_mad_i64_i32 v[80:81], s[14:15], v80, s47, v[96:97]
	v_cvt_pk_bf16_f32 v72, v72, s0
	v_mul_f32_e32 v64, v64, v82
	v_mul_f32_e32 v64, v68, v64
	v_mul_f32_e32 v68, 0xbfb8aa3b, v77
	v_exp_f32_e32 v68, v68
	global_store_short v[80:81], v72, off
	v_mul_f32_e32 v72, 0xbfb8aa3b, v65
	v_exp_f32_e32 v72, v72
	v_add_f32_e32 v68, 1.0, v68
	v_rcp_f32_e32 v68, v68
	v_cvt_pk_bf16_f32 v64, v64, s0
	global_store_short v[80:81], v64, off offset:32
	v_or_b32_e32 v64, 49, v98
	v_mad_i64_i32 v[80:81], s[14:15], v64, s47, v[96:97]
	v_mul_f32_e32 v64, v77, v68
	v_add_f32_e32 v68, 1.0, v72
	v_rcp_f32_e32 v68, v68
	v_mul_f32_e32 v64, v73, v64
	v_cvt_pk_bf16_f32 v64, v64, s0
	global_store_short v[80:81], v64, off
	v_mul_f32_e32 v64, v65, v68
	v_mul_f32_e32 v65, 0xbfb8aa3b, v78
	v_exp_f32_e32 v65, v65
	v_mul_f32_e32 v64, v69, v64
	v_cvt_pk_bf16_f32 v64, v64, s0
	global_store_short v[80:81], v64, off offset:32
	v_add_f32_e32 v65, 1.0, v65
	v_rcp_f32_e32 v68, v65
	v_mul_f32_e32 v65, 0xbfb8aa3b, v66
	v_exp_f32_e32 v69, v65
	v_or_b32_e32 v64, 50, v98
	v_mul_f32_e32 v68, v78, v68
	v_mul_f32_e32 v68, v74, v68
	v_add_f32_e32 v69, 1.0, v69
	v_rcp_f32_e32 v69, v69
	v_mad_i64_i32 v[64:65], s[14:15], v64, s47, v[96:97]
	v_cvt_pk_bf16_f32 v68, v68, s0
	global_store_short v[64:65], v68, off
	v_mul_f32_e32 v68, 0xbfb8aa3b, v79
	v_exp_f32_e32 v68, v68
	v_mul_f32_e32 v66, v66, v69
	v_mul_f32_e32 v66, v70, v66
	v_cvt_pk_bf16_f32 v66, v66, s0
	global_store_short v[64:65], v66, off offset:32
	v_add_f32_e32 v65, 1.0, v68
	v_rcp_f32_e32 v66, v65
	v_mul_f32_e32 v65, 0xbfb8aa3b, v67
	v_exp_f32_e32 v68, v65
	v_or_b32_e32 v64, 51, v98
	v_mul_f32_e32 v66, v79, v66
	v_mul_f32_e32 v66, v75, v66
	v_add_f32_e32 v68, 1.0, v68
	v_rcp_f32_e32 v68, v68
	v_mad_i64_i32 v[64:65], s[14:15], v64, s47, v[96:97]
	v_cvt_pk_bf16_f32 v66, v66, s0
	global_store_short v[64:65], v66, off
	v_mul_f32_e32 v66, v67, v68
	v_mul_f32_e32 v67, 0xbfb8aa3b, v60
	v_exp_f32_e32 v67, v67
	v_mul_f32_e32 v66, v71, v66
	v_cvt_pk_bf16_f32 v66, v66, s0
	global_store_short v[64:65], v66, off offset:32
	v_add_f32_e32 v65, 1.0, v67
	v_rcp_f32_e32 v66, v65
	v_mul_f32_e32 v65, 0xbfb8aa3b, v48
	v_exp_f32_e32 v67, v65
	v_or_b32_e32 v64, 64, v98
	v_mul_f32_e32 v60, v60, v66
	v_mul_f32_e32 v56, v56, v60
	v_add_f32_e32 v66, 1.0, v67
	v_rcp_f32_e32 v66, v66
	v_mad_i64_i32 v[64:65], s[14:15], v64, s47, v[96:97]
	v_cvt_pk_bf16_f32 v56, v56, s0
	v_mul_f32_e32 v48, v48, v66
	v_mul_f32_e32 v48, v52, v48
	v_mul_f32_e32 v52, 0xbfb8aa3b, v61
	v_exp_f32_e32 v52, v52
	global_store_short v[64:65], v56, off
	v_mul_f32_e32 v56, 0xbfb8aa3b, v49
	v_exp_f32_e32 v56, v56
	v_add_f32_e32 v52, 1.0, v52
	v_rcp_f32_e32 v52, v52
	v_cvt_pk_bf16_f32 v48, v48, s0
	global_store_short v[64:65], v48, off offset:32
	v_or_b32_e32 v48, 0x41, v98
	v_mad_i64_i32 v[64:65], s[14:15], v48, s47, v[96:97]
	v_mul_f32_e32 v48, v61, v52
	v_add_f32_e32 v52, 1.0, v56
	v_rcp_f32_e32 v52, v52
	v_mul_f32_e32 v48, v57, v48
	v_cvt_pk_bf16_f32 v48, v48, s0
	global_store_short v[64:65], v48, off
	v_mul_f32_e32 v48, v49, v52
	v_mul_f32_e32 v49, 0xbfb8aa3b, v62
	v_exp_f32_e32 v49, v49
	v_mul_f32_e32 v48, v53, v48
	v_cvt_pk_bf16_f32 v48, v48, s0
	global_store_short v[64:65], v48, off offset:32
	v_add_f32_e32 v49, 1.0, v49
	v_rcp_f32_e32 v52, v49
	v_mul_f32_e32 v49, 0xbfb8aa3b, v50
	v_exp_f32_e32 v53, v49
	v_or_b32_e32 v48, 0x42, v98
	v_mul_f32_e32 v52, v62, v52
	v_mul_f32_e32 v52, v58, v52
	v_add_f32_e32 v53, 1.0, v53
	v_rcp_f32_e32 v53, v53
	v_mad_i64_i32 v[48:49], s[14:15], v48, s47, v[96:97]
	v_cvt_pk_bf16_f32 v52, v52, s0
	global_store_short v[48:49], v52, off
	v_mul_f32_e32 v52, 0xbfb8aa3b, v63
	v_exp_f32_e32 v52, v52
	v_mul_f32_e32 v50, v50, v53
	v_mul_f32_e32 v50, v54, v50
	v_cvt_pk_bf16_f32 v50, v50, s0
	global_store_short v[48:49], v50, off offset:32
	v_add_f32_e32 v49, 1.0, v52
	v_rcp_f32_e32 v50, v49
	v_mul_f32_e32 v49, 0xbfb8aa3b, v51
	v_exp_f32_e32 v52, v49
	v_or_b32_e32 v48, 0x43, v98
	v_mul_f32_e32 v50, v63, v50
	v_mul_f32_e32 v50, v59, v50
	v_add_f32_e32 v52, 1.0, v52
	v_rcp_f32_e32 v52, v52
	v_mad_i64_i32 v[48:49], s[14:15], v48, s47, v[96:97]
	v_cvt_pk_bf16_f32 v50, v50, s0
	global_store_short v[48:49], v50, off
	v_mul_f32_e32 v50, v51, v52
	v_mul_f32_e32 v51, 0xbfb8aa3b, v44
	v_exp_f32_e32 v51, v51
	v_mul_f32_e32 v50, v55, v50
	v_cvt_pk_bf16_f32 v50, v50, s0
	global_store_short v[48:49], v50, off offset:32
	v_add_f32_e32 v49, 1.0, v51
	v_rcp_f32_e32 v50, v49
	v_mul_f32_e32 v49, 0xbfb8aa3b, v32
	v_exp_f32_e32 v51, v49
	v_or_b32_e32 v48, 0x50, v98
	v_mul_f32_e32 v44, v44, v50
	v_mul_f32_e32 v40, v40, v44
	v_add_f32_e32 v50, 1.0, v51
	v_rcp_f32_e32 v50, v50
	v_mad_i64_i32 v[48:49], s[14:15], v48, s47, v[96:97]
	v_cvt_pk_bf16_f32 v40, v40, s0
; DI u16 f2bf(float a) { return (u16)(pk2(a, 0.f) & 0xffffu); }
; DI float sigmoidf_(float x) { return __builtin_amdgcn_rcpf(1.f + __builtin_amdgcn_exp2f(-1.4426950408889634f * x)); }
; template <int EPI>
; DI void gemm_phase(const u16* __restrict__ A, int lda, const u16* __restrict__ Bt, int K, int N, u16* outb, int ldo,
;                    const float* r0, const float* r1, float* outf, char* lds, int bid, int nb) {
;     ...
;   for (int it = 0; it < nIter; ++it) {
;     ...
;       const int col = (tn * 4 + wc) * 32 + l15;
; #pragma unroll
;       for (int i = 0; i < 8; ++i)
; #pragma unroll
;         for (int r = 0; r < 4; ++r) {
;           const float g0 = acc[i][0][r], u0 = acc[i][2][r], g1 = acc[i][1][r], u1 = acc[i][3][r];
;           u16* o0 = outb + (size_t)(mrow + i * 16 + r) * ldo + col;
;           o0[0] = f2bf(g0 * sigmoidf_(g0) * u0); o0[16] = f2bf(g1 * sigmoidf_(g1) * u1);
;         }
	v_mul_f32_e32 v32, v32, v50
	v_mul_f32_e32 v32, v36, v32
	v_mul_f32_e32 v36, 0xbfb8aa3b, v45
	v_exp_f32_e32 v36, v36
	global_store_short v[48:49], v40, off
	v_mul_f32_e32 v40, 0xbfb8aa3b, v33
	v_exp_f32_e32 v40, v40
	v_add_f32_e32 v36, 1.0, v36
	v_rcp_f32_e32 v36, v36
	v_cvt_pk_bf16_f32 v32, v32, s0
	global_store_short v[48:49], v32, off offset:32
	v_or_b32_e32 v32, 0x51, v98
	v_mad_i64_i32 v[48:49], s[14:15], v32, s47, v[96:97]
	v_mul_f32_e32 v32, v45, v36
	v_add_f32_e32 v36, 1.0, v40
	v_rcp_f32_e32 v36, v36
	v_mul_f32_e32 v32, v41, v32
	v_cvt_pk_bf16_f32 v32, v32, s0
	global_store_short v[48:49], v32, off
	v_mul_f32_e32 v32, v33, v36
	v_mul_f32_e32 v33, 0xbfb8aa3b, v46
	v_exp_f32_e32 v33, v33
	v_mul_f32_e32 v32, v37, v32
	v_cvt_pk_bf16_f32 v32, v32, s0
	global_store_short v[48:49], v32, off offset:32
	v_add_f32_e32 v33, 1.0, v33
	v_rcp_f32_e32 v36, v33
	v_mul_f32_e32 v33, 0xbfb8aa3b, v34
	v_exp_f32_e32 v37, v33
	v_or_b32_e32 v32, 0x52, v98
	v_mul_f32_e32 v36, v46, v36
	v_mul_f32_e32 v36, v42, v36
	v_add_f32_e32 v37, 1.0, v37
	v_rcp_f32_e32 v37, v37
	v_mad_i64_i32 v[32:33], s[14:15], v32, s47, v[96:97]
	v_cvt_pk_bf16_f32 v36, v36, s0
	global_store_short v[32:33], v36, off
	v_mul_f32_e32 v36, 0xbfb8aa3b, v47
	v_exp_f32_e32 v36, v36
	v_mul_f32_e32 v34, v34, v37
	v_mul_f32_e32 v34, v38, v34
	v_cvt_pk_bf16_f32 v34, v34, s0
	global_store_short v[32:33], v34, off offset:32
	v_add_f32_e32 v33, 1.0, v36
	v_rcp_f32_e32 v34, v33
	v_mul_f32_e32 v33, 0xbfb8aa3b, v35
	v_exp_f32_e32 v36, v33
	v_or_b32_e32 v32, 0x53, v98
	v_mul_f32_e32 v34, v47, v34
	v_mul_f32_e32 v34, v43, v34
	v_add_f32_e32 v36, 1.0, v36
	v_rcp_f32_e32 v36, v36
	v_mad_i64_i32 v[32:33], s[14:15], v32, s47, v[96:97]
	v_cvt_pk_bf16_f32 v34, v34, s0
	global_store_short v[32:33], v34, off
	v_mul_f32_e32 v34, v35, v36
	v_mul_f32_e32 v35, 0xbfb8aa3b, v28
	v_exp_f32_e32 v35, v35
	v_mul_f32_e32 v34, v39, v34
	v_cvt_pk_bf16_f32 v34, v34, s0
	global_store_short v[32:33], v34, off offset:32
	v_add_f32_e32 v33, 1.0, v35
	v_rcp_f32_e32 v34, v33
	v_mul_f32_e32 v33, 0xbfb8aa3b, v16
	v_exp_f32_e32 v35, v33
	v_or_b32_e32 v32, 0x60, v98
	v_mul_f32_e32 v28, v28, v34
	v_mul_f32_e32 v24, v24, v28
	v_add_f32_e32 v34, 1.0, v35
	v_rcp_f32_e32 v34, v34
	v_mad_i64_i32 v[32:33], s[14:15], v32, s47, v[96:97]
	v_cvt_pk_bf16_f32 v24, v24, s0
	v_mul_f32_e32 v16, v16, v34
	v_mul_f32_e32 v16, v20, v16
	v_mul_f32_e32 v20, 0xbfb8aa3b, v29
	v_exp_f32_e32 v20, v20
	global_store_short v[32:33], v24, off
	v_mul_f32_e32 v24, 0xbfb8aa3b, v17
	v_exp_f32_e32 v24, v24
	v_add_f32_e32 v20, 1.0, v20
	v_rcp_f32_e32 v20, v20
	v_cvt_pk_bf16_f32 v16, v16, s0
	global_store_short v[32:33], v16, off offset:32
	v_or_b32_e32 v16, 0x61, v98
	v_mad_i64_i32 v[32:33], s[14:15], v16, s47, v[96:97]
	v_mul_f32_e32 v16, v29, v20
	v_add_f32_e32 v20, 1.0, v24
	v_rcp_f32_e32 v20, v20
	v_mul_f32_e32 v16, v25, v16
	v_cvt_pk_bf16_f32 v16, v16, s0
	global_store_short v[32:33], v16, off
	v_mul_f32_e32 v16, v17, v20
	v_mul_f32_e32 v17, 0xbfb8aa3b, v30
	v_exp_f32_e32 v17, v17
	v_mul_f32_e32 v16, v21, v16
	v_cvt_pk_bf16_f32 v16, v16, s0
	global_store_short v[32:33], v16, off offset:32
	v_add_f32_e32 v17, 1.0, v17
	v_rcp_f32_e32 v20, v17
	v_mul_f32_e32 v17, 0xbfb8aa3b, v18
	v_exp_f32_e32 v21, v17
	v_or_b32_e32 v16, 0x62, v98
	v_mul_f32_e32 v20, v30, v20
	v_mul_f32_e32 v20, v26, v20
	v_add_f32_e32 v21, 1.0, v21
	v_rcp_f32_e32 v21, v21
	v_mad_i64_i32 v[16:17], s[14:15], v16, s47, v[96:97]
	v_cvt_pk_bf16_f32 v20, v20, s0
	global_store_short v[16:17], v20, off
	v_mul_f32_e32 v20, 0xbfb8aa3b, v31
	v_exp_f32_e32 v20, v20
	v_mul_f32_e32 v18, v18, v21
	v_mul_f32_e32 v18, v22, v18
	v_cvt_pk_bf16_f32 v18, v18, s0
	global_store_short v[16:17], v18, off offset:32
	v_add_f32_e32 v17, 1.0, v20
	v_rcp_f32_e32 v18, v17
	v_mul_f32_e32 v17, 0xbfb8aa3b, v19
	v_exp_f32_e32 v20, v17
	v_or_b32_e32 v16, 0x63, v98
	v_mul_f32_e32 v18, v31, v18
	v_mul_f32_e32 v18, v27, v18
	v_add_f32_e32 v20, 1.0, v20
	v_rcp_f32_e32 v20, v20
	v_mad_i64_i32 v[16:17], s[14:15], v16, s47, v[96:97]
	v_cvt_pk_bf16_f32 v18, v18, s0
	global_store_short v[16:17], v18, off
	v_mul_f32_e32 v18, v19, v20
	v_mul_f32_e32 v19, 0xbfb8aa3b, v12
	v_exp_f32_e32 v19, v19
	v_mul_f32_e32 v18, v23, v18
	v_cvt_pk_bf16_f32 v18, v18, s0
	global_store_short v[16:17], v18, off offset:32
	v_add_f32_e32 v17, 1.0, v19
	v_rcp_f32_e32 v18, v17
	v_mul_f32_e32 v17, 0xbfb8aa3b, v0
	v_exp_f32_e32 v19, v17
	v_or_b32_e32 v16, 0x70, v98
	v_mul_f32_e32 v12, v12, v18
	v_mul_f32_e32 v8, v8, v12
	v_add_f32_e32 v18, 1.0, v19
	v_rcp_f32_e32 v18, v18
	v_mad_i64_i32 v[16:17], s[14:15], v16, s47, v[96:97]
	v_cvt_pk_bf16_f32 v8, v8, s0
	v_mul_f32_e32 v0, v0, v18
	v_mul_f32_e32 v0, v4, v0
	v_mul_f32_e32 v4, 0xbfb8aa3b, v13
	v_exp_f32_e32 v4, v4
	global_store_short v[16:17], v8, off
	v_mul_f32_e32 v8, 0xbfb8aa3b, v1
	v_exp_f32_e32 v8, v8
	v_add_f32_e32 v4, 1.0, v4
	v_rcp_f32_e32 v4, v4
	v_cvt_pk_bf16_f32 v0, v0, s0
	global_store_short v[16:17], v0, off offset:32
	v_or_b32_e32 v0, 0x71, v98
	v_mad_i64_i32 v[16:17], s[14:15], v0, s47, v[96:97]
	v_mul_f32_e32 v0, v13, v4
	v_add_f32_e32 v4, 1.0, v8
	v_rcp_f32_e32 v4, v4
	v_mul_f32_e32 v0, v9, v0
	v_cvt_pk_bf16_f32 v0, v0, s0
	global_store_short v[16:17], v0, off
	v_mul_f32_e32 v0, v1, v4
	v_mul_f32_e32 v1, 0xbfb8aa3b, v14
	v_exp_f32_e32 v1, v1
	v_mul_f32_e32 v0, v5, v0
	v_cvt_pk_bf16_f32 v0, v0, s0
	global_store_short v[16:17], v0, off offset:32
	v_add_f32_e32 v1, 1.0, v1
	v_rcp_f32_e32 v4, v1
	v_mul_f32_e32 v1, 0xbfb8aa3b, v2
	v_exp_f32_e32 v5, v1
	v_or_b32_e32 v0, 0x72, v98
	v_mul_f32_e32 v4, v14, v4
	v_mul_f32_e32 v4, v10, v4
	v_add_f32_e32 v5, 1.0, v5
	v_rcp_f32_e32 v5, v5
	v_mad_i64_i32 v[0:1], s[14:15], v0, s47, v[96:97]
	v_cvt_pk_bf16_f32 v4, v4, s0
	global_store_short v[0:1], v4, off
	v_mul_f32_e32 v4, 0xbfb8aa3b, v15
	v_exp_f32_e32 v4, v4
	v_mul_f32_e32 v2, v2, v5
	v_mul_f32_e32 v2, v6, v2
	v_cvt_pk_bf16_f32 v2, v2, s0
	global_store_short v[0:1], v2, off offset:32
	v_add_f32_e32 v1, 1.0, v4
	v_rcp_f32_e32 v2, v1
	v_mul_f32_e32 v1, 0xbfb8aa3b, v3
	v_exp_f32_e32 v4, v1
	v_or_b32_e32 v0, 0x73, v98
	v_mul_f32_e32 v2, v15, v2
	v_mul_f32_e32 v2, v11, v2
	v_add_f32_e32 v4, 1.0, v4
	v_rcp_f32_e32 v4, v4
	v_mad_i64_i32 v[0:1], s[14:15], v0, s47, v[96:97]
	v_cvt_pk_bf16_f32 v2, v2, s0
	global_store_short v[0:1], v2, off
	v_mul_f32_e32 v2, v3, v4
	v_mul_f32_e32 v2, v7, v2
	s_add_i32 s19, s19, 1
	v_cvt_pk_bf16_f32 v2, v2, s0
	s_cmp_eq_u32 s19, s3
	global_store_short v[0:1], v2, off offset:32
	s_cbranch_scc0 .LBB0_697

; #define G_LOAD(KT) do { _Pragma("unroll") for (int i = 0; i < 4; ++i) { ra[i] = *(const u32x4*)(Ag + (size_t)i * 64 * lda + (KT) * 64); rb[i] = *(const u32x4*)(Bg + (size_t)i * 64 * K + (KT) * 64); } } while (0)
; #define G_STORE(BUF) do { u16* ad = As + (BUF) * 256 * 64 + sto; u16* bd = Bs + (BUF) * 256 * 64 + sto; _Pragma("unroll") for (int i = 0; i < 4; ++i) { *(u32x4*)(ad + i * 64 * 64) = ra[i]; *(u32x4*)(bd + i * 64 * 64) = rb[i]; } } while (0)
; template <int EPI>
; DI void gemm_phase(const u16* __restrict__ A, int lda, const u16* __restrict__ Bt, int K, int N, u16* outb, int ldo,
;                    const float* r0, const float* r1, float* outf, char* lds, int bid, int nb) {
;     ...
;     const u16* Ag = A + (size_t)(tm * 256 + lrow) * lda + lch * 8;
;     const u16* Bg = Bt + (size_t)(tn * 256 + lrow) * K + lch * 8;
;     f32x4 acc[8][4];
; #pragma unroll
;     for (int i = 0; i < 8; ++i)
; #pragma unroll
;       for (int j = 0; j < 4; ++j) acc[i][j] = (f32x4){0.f, 0.f, 0.f, 0.f};
;     u32x4 ra[4], rb[4];
;     ...
;     G_LOAD(0);
;     G_STORE(0);
;     __syncthreads();
;     for (int kt = 0; kt < nk; ++kt) {
;       const int cur = kt & 1;
;       if (kt + 1 < nk) G_LOAD(kt + 1);
.LBB0_763:
	s_lshl_b32 s39, s39, 8
	v_or_b32_e32 v60, s39, v138
	s_lshl_b32 s46, s46, 8
	v_mad_i64_i32 v[0:1], s[8:9], v60, s17, v[128:129]
	v_or_b32_e32 v61, s46, v138
	v_add_co_u32_e32 v4, vcc, 0x58000, v0
	v_mad_i64_i32 v[2:3], s[8:9], v61, s17, v[130:131]
	s_nop 0
	v_addc_co_u32_e32 v5, vcc, 0, v1, vcc
	v_add_co_u32_e32 v6, vcc, 0x58000, v2
	s_nop 1
	v_readfirstlane_b32 s98, v0
	v_readfirstlane_b32 s99, v1
	s_nop 1
	v_readfirstlane_b32 s100, v2
	v_readfirstlane_b32 s101, v3
	v_addc_co_u32_e32 v7, vcc, 0, v3, vcc
	v_add_co_u32_e32 v4, vcc, 0xb0000, v0
	s_mov_b32 s47, 0
	s_nop 0
	v_addc_co_u32_e32 v5, vcc, 0, v1, vcc
	v_add_co_u32_e32 v6, vcc, 0xb0000, v2
	s_mov_b64 s[8:9], 0
	s_nop 0
	v_addc_co_u32_e32 v7, vcc, 0, v3, vcc
	v_add_co_u32_e32 v0, vcc, 0x108000, v0
	v_addc_co_u32_e32 v1, vcc, 0, v1, vcc
	v_add_co_u32_e32 v2, vcc, 0x108000, v2
	v_mad_i64_i32 v[134:135], s[28:29], v60, s17, v[132:133]
	s_nop 0
	v_addc_co_u32_e32 v3, vcc, 0, v3, vcc
	v_mov_b32_e32 v0, 0
	v_mov_b32_e32 v1, v0
	v_mov_b32_e32 v2, v0
	v_mov_b32_e32 v3, v0
	v_mov_b32_e32 v4, v0
	v_mov_b32_e32 v5, v0
	v_mov_b32_e32 v6, v0
	v_mov_b32_e32 v7, v0
	v_mov_b32_e32 v8, v0
	v_mov_b32_e32 v9, v0
	v_mov_b32_e32 v10, v0
	v_mov_b32_e32 v11, v0
	v_mov_b32_e32 v12, v0
	v_mov_b32_e32 v13, v0
	v_mov_b32_e32 v14, v0
	v_mov_b32_e32 v15, v0
	v_mov_b32_e32 v16, v0
	v_mov_b32_e32 v17, v0
	v_mov_b32_e32 v18, v0
	v_mov_b32_e32 v19, v0
	v_mov_b32_e32 v20, v0
	v_mov_b32_e32 v21, v0
	v_mov_b32_e32 v22, v0
	v_mov_b32_e32 v23, v0
	v_mov_b32_e32 v24, v0
	v_mov_b32_e32 v25, v0
	v_mov_b32_e32 v26, v0
	v_mov_b32_e32 v27, v0
	v_mad_i64_i32 v[136:137], s[28:29], v61, s17, v[132:133]
	v_mov_b32_e32 v60, v0
	v_mov_b32_e32 v61, v0
	v_mov_b32_e32 v62, v0
	v_mov_b32_e32 v63, v0
	v_mov_b32_e32 v64, v0
	v_mov_b32_e32 v65, v0
	v_mov_b32_e32 v66, v0
	v_mov_b32_e32 v67, v0
	v_mov_b32_e32 v68, v0
	v_mov_b32_e32 v69, v0
	v_mov_b32_e32 v70, v0
	v_mov_b32_e32 v71, v0
	v_mov_b32_e32 v72, v0
	v_mov_b32_e32 v73, v0
	v_mov_b32_e32 v74, v0
	v_mov_b32_e32 v75, v0
	v_mov_b32_e32 v76, v0
	v_mov_b32_e32 v77, v0
	v_mov_b32_e32 v78, v0
	v_mov_b32_e32 v79, v0
	v_mov_b32_e32 v80, v0
	v_mov_b32_e32 v81, v0
	v_mov_b32_e32 v82, v0
	v_mov_b32_e32 v83, v0
	v_mov_b32_e32 v28, v0
	v_mov_b32_e32 v29, v0
	v_mov_b32_e32 v30, v0
	v_mov_b32_e32 v31, v0
	v_mov_b32_e32 v32, v0
	v_mov_b32_e32 v33, v0
	v_mov_b32_e32 v34, v0
	v_mov_b32_e32 v35, v0
	v_mov_b32_e32 v36, v0
	v_mov_b32_e32 v37, v0
	v_mov_b32_e32 v38, v0
	v_mov_b32_e32 v39, v0
	v_mov_b32_e32 v40, v0
	v_mov_b32_e32 v41, v0
	v_mov_b32_e32 v42, v0
	v_mov_b32_e32 v43, v0
	v_mov_b32_e32 v44, v0
	v_mov_b32_e32 v45, v0
	v_mov_b32_e32 v46, v0
	v_mov_b32_e32 v47, v0
	v_mov_b32_e32 v48, v0
	v_mov_b32_e32 v49, v0
	v_mov_b32_e32 v50, v0
	v_mov_b32_e32 v51, v0
	v_mov_b32_e32 v52, v0
	v_mov_b32_e32 v53, v0
	v_mov_b32_e32 v54, v0
	v_mov_b32_e32 v55, v0
	v_mov_b32_e32 v56, v0
	v_mov_b32_e32 v57, v0
	v_mov_b32_e32 v58, v0
	v_mov_b32_e32 v59, v0
	v_mov_b32_e32 v84, v0
	v_mov_b32_e32 v85, v0
	v_mov_b32_e32 v86, v0
	v_mov_b32_e32 v87, v0
	v_mov_b32_e32 v88, v0
	v_mov_b32_e32 v89, v0
	v_mov_b32_e32 v90, v0
	v_mov_b32_e32 v91, v0
	v_mov_b32_e32 v92, v0
	v_mov_b32_e32 v93, v0
	v_mov_b32_e32 v94, v0
	v_mov_b32_e32 v95, v0
	v_mov_b32_e32 v96, v0
	v_mov_b32_e32 v97, v0
	v_mov_b32_e32 v98, v0
	v_mov_b32_e32 v99, v0
	v_mov_b32_e32 v100, v0
	v_mov_b32_e32 v101, v0
	v_mov_b32_e32 v102, v0
	v_mov_b32_e32 v103, v0
	v_mov_b32_e32 v104, v0
	v_mov_b32_e32 v105, v0
	v_mov_b32_e32 v106, v0
	v_mov_b32_e32 v107, v0
	v_mov_b32_e32 v108, v0
	v_mov_b32_e32 v109, v0
	v_mov_b32_e32 v110, v0
	v_mov_b32_e32 v111, v0
	v_mov_b32_e32 v112, v0
	v_mov_b32_e32 v113, v0
	v_mov_b32_e32 v114, v0
	v_mov_b32_e32 v115, v0
	v_mov_b32_e32 v116, v0
	v_mov_b32_e32 v117, v0
	v_mov_b32_e32 v118, v0
	v_mov_b32_e32 v119, v0
	v_mov_b32_e32 v120, v0
	v_mov_b32_e32 v121, v0
	v_mov_b32_e32 v122, v0
	v_mov_b32_e32 v123, v0
	v_mov_b32_e32 v124, v0
	v_mov_b32_e32 v125, v0
	v_mov_b32_e32 v126, v0
	v_mov_b32_e32 v127, v0
	v_and_b32_e32 v229, 63, v174
	v_lshrrev_b32_e32 v230, 3, v229
	v_mov_b32_e32 v233, 0x1600
	v_mul_u32_u24_e32 v224, v230, v233
	v_bfe_u32 v231, v174, 4, 2
	v_bfe_u32 v232, v174, 6, 1
	v_lshl_or_b32 v232, v232, 2, v231
	v_and_b32_e32 v233, 7, v174
	v_xor_b32_e32 v232, v232, v233
	v_lshl_add_u32 v224, v232, 4, v224
	v_and_b32_e32 v229, 15, v174
	v_bfe_u32 v230, v174, 1, 3
	v_xor_b32_e32 v230, v230, v231
	v_lshlrev_b32_e32 v230, 4, v230
	v_lshl_or_b32 v230, v229, 7, v230
	v_lshrrev_b32_e32 v229, 8, v174
	v_lshl_or_b32 v225, v229, 14, v230
	v_bfe_u32 v229, v174, 6, 2
	v_lshl_or_b32 v227, v229, 13, v230
	v_or_b32_e32 v227, 0x10000, v227
	v_xor_b32_e32 v226, 64, v225
	v_xor_b32_e32 v228, 64, v227
	v_readfirstlane_b32 s97, v174
	s_lshl_b32 s97, s97, 4
	s_mov_b32 s28, 42
	s_add_u32 s8, s98, 0x0
	s_addc_u32 s9, s99, 0
	s_add_u32 m0, s97, 0x0
	s_nop 0
	global_load_lds_dwordx4 v224, s[8:9]
	s_add_u32 s8, s100, 0x0
	s_addc_u32 s9, s101, 0
	s_add_u32 m0, s97, 0x10000
	s_nop 0
	global_load_lds_dwordx4 v224, s[8:9]
	s_add_u32 s8, s98, 0x58000
	s_addc_u32 s9, s99, 0
	s_add_u32 m0, s97, 0x2000
	s_nop 0
	global_load_lds_dwordx4 v224, s[8:9]
	s_add_u32 s8, s100, 0x58000
	s_addc_u32 s9, s101, 0
	s_add_u32 m0, s97, 0x12000
	s_nop 0
	global_load_lds_dwordx4 v224, s[8:9]
	s_add_u32 s8, s98, 0xb0000
	s_addc_u32 s9, s99, 0
	s_add_u32 m0, s97, 0x4000
	s_nop 0
	global_load_lds_dwordx4 v224, s[8:9]
	s_add_u32 s8, s100, 0xb0000
	s_addc_u32 s9, s101, 0
	s_add_u32 m0, s97, 0x14000
	s_nop 0
	global_load_lds_dwordx4 v224, s[8:9]
	s_add_u32 s8, s98, 0x108000
	s_addc_u32 s9, s99, 0
	s_add_u32 m0, s97, 0x6000
	s_nop 0
	global_load_lds_dwordx4 v224, s[8:9]
	s_add_u32 s8, s100, 0x108000
	s_addc_u32 s9, s101, 0
	s_add_u32 m0, s97, 0x16000
	s_nop 0
	global_load_lds_dwordx4 v224, s[8:9]
	s_add_u32 s8, s98, 0x80
	s_addc_u32 s9, s99, 0
	s_add_u32 m0, s97, 0x8000
	s_nop 0
	global_load_lds_dwordx4 v224, s[8:9]
	s_add_u32 s8, s100, 0x80
	s_addc_u32 s9, s101, 0
	s_add_u32 m0, s97, 0x18000
	s_nop 0
	global_load_lds_dwordx4 v224, s[8:9]
	s_add_u32 s8, s98, 0x58080
	s_addc_u32 s9, s99, 0
	s_add_u32 m0, s97, 0xa000
	s_nop 0
	global_load_lds_dwordx4 v224, s[8:9]
	s_add_u32 s8, s100, 0x58080
	s_addc_u32 s9, s101, 0
	s_add_u32 m0, s97, 0x1a000
	s_nop 0
	global_load_lds_dwordx4 v224, s[8:9]
	s_add_u32 s8, s98, 0xb0080
	s_addc_u32 s9, s99, 0
	s_add_u32 m0, s97, 0xc000
	s_nop 0
	global_load_lds_dwordx4 v224, s[8:9]
	s_add_u32 s8, s100, 0xb0080
	s_addc_u32 s9, s101, 0
	s_add_u32 m0, s97, 0x1c000
	s_nop 0
	global_load_lds_dwordx4 v224, s[8:9]
	s_add_u32 s8, s98, 0x108080
	s_addc_u32 s9, s99, 0
	s_add_u32 m0, s97, 0xe000
	s_nop 0
	global_load_lds_dwordx4 v224, s[8:9]
	s_add_u32 s8, s100, 0x108080
	s_addc_u32 s9, s101, 0
	s_add_u32 m0, s97, 0x1e000
	s_nop 0
	global_load_lds_dwordx4 v224, s[8:9]
	s_add_u32 s98, s98, 0x100
	s_addc_u32 s99, s99, 0
	s_add_u32 s100, s100, 0x100
	s_addc_u32 s101, s101, 0
	s_waitcnt vmcnt(8)
	s_barrier
; #define G_LOAD(KT) do { _Pragma("unroll") for (int i = 0; i < 4; ++i) { ra[i] = *(const u32x4*)(Ag + (size_t)i * 64 * lda + (KT) * 64); rb[i] = *(const u32x4*)(Bg + (size_t)i * 64 * K + (KT) * 64); } } while (0)
; #define G_STORE(BUF) do { u16* ad = As + (BUF) * 256 * 64 + sto; u16* bd = Bs + (BUF) * 256 * 64 + sto; _Pragma("unroll") for (int i = 0; i < 4; ++i) { *(u32x4*)(ad + i * 64 * 64) = ra[i]; *(u32x4*)(bd + i * 64 * 64) = rb[i]; } } while (0)
; template <int EPI>
; DI void gemm_phase(const u16* __restrict__ A, int lda, const u16* __restrict__ Bt, int K, int N, u16* outb, int ldo,
;                    const float* r0, const float* r1, float* outf, char* lds, int bid, int nb) {
;     ...
;     G_LOAD(0);
;     G_STORE(0);
;     __syncthreads();
;     for (int kt = 0; kt < nk; ++kt) {
;       const int cur = kt & 1;
;       if (kt + 1 < nk) G_LOAD(kt + 1);
;       G_MMA(cur, fo0);
;       G_MMA(cur, fo1);
;       if (kt + 1 < nk) G_STORE(cur ^ 1);
;       __syncthreads();
;     }
	ds_read_b128 v[152:155], v227 offset:0
	ds_read_b128 v[156:159], v227 offset:2048
	ds_read_b128 v[160:163], v227 offset:4096
	ds_read_b128 v[164:167], v227 offset:6144
	ds_read_b128 v[188:191], v225 offset:0
	ds_read_b128 v[192:195], v225 offset:2048
	ds_read_b128 v[196:199], v225 offset:4096
	ds_read_b128 v[200:203], v225 offset:6144
	ds_read_b128 v[204:207], v225 offset:8192
	ds_read_b128 v[208:211], v225 offset:10240
	ds_read_b128 v[212:215], v225 offset:12288
	ds_read_b128 v[216:219], v225 offset:14336
	v_xor_b32_e32 v225, 0x8000, v225
	v_xor_b32_e32 v227, 0x8000, v227
	s_waitcnt lgkmcnt(0)
.Lgm3_loop:
	s_waitcnt lgkmcnt(4)
	v_mfma_f32_16x16x32_bf16 v[124:127], v[188:191], v[152:155], v[124:127]
	v_mfma_f32_16x16x32_bf16 v[120:123], v[188:191], v[156:159], v[120:123]
	v_mfma_f32_16x16x32_bf16 v[116:119], v[188:191], v[160:163], v[116:119]
	v_mfma_f32_16x16x32_bf16 v[112:115], v[188:191], v[164:167], v[112:115]
	ds_read_b128 v[188:191], v226 offset:0
	ds_read_b128 v[168:171], v228 offset:0
	v_mfma_f32_16x16x32_bf16 v[108:111], v[192:195], v[152:155], v[108:111]
	v_mfma_f32_16x16x32_bf16 v[104:107], v[192:195], v[156:159], v[104:107]
	v_mfma_f32_16x16x32_bf16 v[100:103], v[192:195], v[160:163], v[100:103]
	v_mfma_f32_16x16x32_bf16 v[96:99], v[192:195], v[164:167], v[96:99]
	ds_read_b128 v[192:195], v226 offset:2048
	ds_read_b128 v[176:179], v228 offset:2048
	v_mfma_f32_16x16x32_bf16 v[92:95], v[196:199], v[152:155], v[92:95]
	v_mfma_f32_16x16x32_bf16 v[88:91], v[196:199], v[156:159], v[88:91]
	v_mfma_f32_16x16x32_bf16 v[84:87], v[196:199], v[160:163], v[84:87]
	v_mfma_f32_16x16x32_bf16 v[80:83], v[196:199], v[164:167], v[80:83]
	ds_read_b128 v[196:199], v226 offset:4096
	ds_read_b128 v[180:183], v228 offset:4096
	v_mfma_f32_16x16x32_bf16 v[76:79], v[200:203], v[152:155], v[76:79]
	v_mfma_f32_16x16x32_bf16 v[72:75], v[200:203], v[156:159], v[72:75]
	v_mfma_f32_16x16x32_bf16 v[68:71], v[200:203], v[160:163], v[68:71]
	v_mfma_f32_16x16x32_bf16 v[64:67], v[200:203], v[164:167], v[64:67]
	ds_read_b128 v[200:203], v226 offset:6144
	ds_read_b128 v[184:187], v228 offset:6144
	s_waitcnt lgkmcnt(11)
	v_mfma_f32_16x16x32_bf16 v[60:63], v[204:207], v[152:155], v[60:63]
	v_mfma_f32_16x16x32_bf16 v[56:59], v[204:207], v[156:159], v[56:59]
	v_mfma_f32_16x16x32_bf16 v[52:55], v[204:207], v[160:163], v[52:55]
	v_mfma_f32_16x16x32_bf16 v[48:51], v[204:207], v[164:167], v[48:51]
	ds_read_b128 v[204:207], v226 offset:8192
	ds_read_b128 v[220:223], v226 offset:14336
	s_waitcnt lgkmcnt(11)
	v_mfma_f32_16x16x32_bf16 v[44:47], v[208:211], v[152:155], v[44:47]
	v_mfma_f32_16x16x32_bf16 v[40:43], v[208:211], v[156:159], v[40:43]
	v_mfma_f32_16x16x32_bf16 v[36:39], v[208:211], v[160:163], v[36:39]
	v_mfma_f32_16x16x32_bf16 v[32:35], v[208:211], v[164:167], v[32:35]
	ds_read_b128 v[208:211], v226 offset:10240
	s_waitcnt lgkmcnt(11)
	v_mfma_f32_16x16x32_bf16 v[28:31], v[212:215], v[152:155], v[28:31]
	v_mfma_f32_16x16x32_bf16 v[24:27], v[212:215], v[156:159], v[24:27]
	v_mfma_f32_16x16x32_bf16 v[20:23], v[212:215], v[160:163], v[20:23]
	v_mfma_f32_16x16x32_bf16 v[16:19], v[212:215], v[164:167], v[16:19]
	ds_read_b128 v[212:215], v226 offset:12288
	v_mfma_f32_16x16x32_bf16 v[12:15], v[216:219], v[152:155], v[12:15]
	v_mfma_f32_16x16x32_bf16 v[8:11], v[216:219], v[156:159], v[8:11]
	v_mfma_f32_16x16x32_bf16 v[4:7], v[216:219], v[160:163], v[4:7]
	v_mfma_f32_16x16x32_bf16 v[0:3], v[216:219], v[164:167], v[0:3]
	s_waitcnt vmcnt(0) lgkmcnt(0)
	s_barrier
	v_mfma_f32_16x16x32_bf16 v[124:127], v[188:191], v[168:171], v[124:127]
	v_mfma_f32_16x16x32_bf16 v[120:123], v[188:191], v[176:179], v[120:123]
	v_mfma_f32_16x16x32_bf16 v[116:119], v[188:191], v[180:183], v[116:119]
	v_mfma_f32_16x16x32_bf16 v[112:115], v[188:191], v[184:187], v[112:115]
	ds_read_b128 v[188:191], v225 offset:0
	ds_read_b128 v[152:155], v227 offset:0
	s_add_u32 s8, s98, 0x0
	s_addc_u32 s9, s99, 0
	s_add_u32 m0, s97, 0x0
	s_nop 0
	global_load_lds_dwordx4 v224, s[8:9]
	v_mfma_f32_16x16x32_bf16 v[108:111], v[192:195], v[168:171], v[108:111]
	v_mfma_f32_16x16x32_bf16 v[104:107], v[192:195], v[176:179], v[104:107]
	v_mfma_f32_16x16x32_bf16 v[100:103], v[192:195], v[180:183], v[100:103]
	v_mfma_f32_16x16x32_bf16 v[96:99], v[192:195], v[184:187], v[96:99]
	ds_read_b128 v[192:195], v225 offset:2048
	ds_read_b128 v[156:159], v227 offset:2048
	s_add_u32 s8, s100, 0x0
	s_addc_u32 s9, s101, 0
	s_add_u32 m0, s97, 0x10000
	s_nop 0
	global_load_lds_dwordx4 v224, s[8:9]
	v_mfma_f32_16x16x32_bf16 v[92:95], v[196:199], v[168:171], v[92:95]
	v_mfma_f32_16x16x32_bf16 v[88:91], v[196:199], v[176:179], v[88:91]
	v_mfma_f32_16x16x32_bf16 v[84:87], v[196:199], v[180:183], v[84:87]
	v_mfma_f32_16x16x32_bf16 v[80:83], v[196:199], v[184:187], v[80:83]
	ds_read_b128 v[196:199], v225 offset:4096
	ds_read_b128 v[160:163], v227 offset:4096
	s_add_u32 s8, s98, 0x58000
	s_addc_u32 s9, s99, 0
	s_add_u32 m0, s97, 0x2000
	s_nop 0
	global_load_lds_dwordx4 v224, s[8:9]
	v_mfma_f32_16x16x32_bf16 v[76:79], v[200:203], v[168:171], v[76:79]
	v_mfma_f32_16x16x32_bf16 v[72:75], v[200:203], v[176:179], v[72:75]
	v_mfma_f32_16x16x32_bf16 v[68:71], v[200:203], v[180:183], v[68:71]
	v_mfma_f32_16x16x32_bf16 v[64:67], v[200:203], v[184:187], v[64:67]
	ds_read_b128 v[200:203], v225 offset:6144
	ds_read_b128 v[164:167], v227 offset:6144
	s_add_u32 s8, s100, 0x58000
	s_addc_u32 s9, s101, 0
	s_add_u32 m0, s97, 0x12000
	s_nop 0
	global_load_lds_dwordx4 v224, s[8:9]
	v_mfma_f32_16x16x32_bf16 v[60:63], v[204:207], v[168:171], v[60:63]
	v_mfma_f32_16x16x32_bf16 v[56:59], v[204:207], v[176:179], v[56:59]
	v_mfma_f32_16x16x32_bf16 v[52:55], v[204:207], v[180:183], v[52:55]
; #define G_LOAD(KT) do { _Pragma("unroll") for (int i = 0; i < 4; ++i) { ra[i] = *(const u32x4*)(Ag + (size_t)i * 64 * lda + (KT) * 64); rb[i] = *(const u32x4*)(Bg + (size_t)i * 64 * K + (KT) * 64); } } while (0)
; #define G_STORE(BUF) do { u16* ad = As + (BUF) * 256 * 64 + sto; u16* bd = Bs + (BUF) * 256 * 64 + sto; _Pragma("unroll") for (int i = 0; i < 4; ++i) { *(u32x4*)(ad + i * 64 * 64) = ra[i]; *(u32x4*)(bd + i * 64 * 64) = rb[i]; } } while (0)
; template <int EPI>
; DI void gemm_phase(const u16* __restrict__ A, int lda, const u16* __restrict__ Bt, int K, int N, u16* outb, int ldo,
;                    const float* r0, const float* r1, float* outf, char* lds, int bid, int nb) {
;     ...
;     G_LOAD(0);
;     G_STORE(0);
;     __syncthreads();
;     for (int kt = 0; kt < nk; ++kt) {
;       const int cur = kt & 1;
;       if (kt + 1 < nk) G_LOAD(kt + 1);
;       G_MMA(cur, fo0);
;       G_MMA(cur, fo1);
;       if (kt + 1 < nk) G_STORE(cur ^ 1);
;       __syncthreads();
;     }
	v_mfma_f32_16x16x32_bf16 v[48:51], v[204:207], v[184:187], v[48:51]
	ds_read_b128 v[204:207], v225 offset:8192
	ds_read_b128 v[216:219], v225 offset:14336
	s_add_u32 s8, s98, 0xb0000
	s_addc_u32 s9, s99, 0
	s_add_u32 m0, s97, 0x4000
	s_nop 0
	global_load_lds_dwordx4 v224, s[8:9]
	v_mfma_f32_16x16x32_bf16 v[44:47], v[208:211], v[168:171], v[44:47]
	v_mfma_f32_16x16x32_bf16 v[40:43], v[208:211], v[176:179], v[40:43]
	v_mfma_f32_16x16x32_bf16 v[36:39], v[208:211], v[180:183], v[36:39]
	v_mfma_f32_16x16x32_bf16 v[32:35], v[208:211], v[184:187], v[32:35]
	ds_read_b128 v[208:211], v225 offset:10240
	s_add_u32 s8, s100, 0xb0000
	s_addc_u32 s9, s101, 0
	s_add_u32 m0, s97, 0x14000
	s_nop 0
	global_load_lds_dwordx4 v224, s[8:9]
	v_mfma_f32_16x16x32_bf16 v[28:31], v[212:215], v[168:171], v[28:31]
	v_mfma_f32_16x16x32_bf16 v[24:27], v[212:215], v[176:179], v[24:27]
	v_mfma_f32_16x16x32_bf16 v[20:23], v[212:215], v[180:183], v[20:23]
	v_mfma_f32_16x16x32_bf16 v[16:19], v[212:215], v[184:187], v[16:19]
	ds_read_b128 v[212:215], v225 offset:12288
	s_add_u32 s8, s98, 0x108000
	s_addc_u32 s9, s99, 0
	s_add_u32 m0, s97, 0x6000
	s_nop 0
	global_load_lds_dwordx4 v224, s[8:9]
	v_mfma_f32_16x16x32_bf16 v[12:15], v[220:223], v[168:171], v[12:15]
	v_mfma_f32_16x16x32_bf16 v[8:11], v[220:223], v[176:179], v[8:11]
	v_mfma_f32_16x16x32_bf16 v[4:7], v[220:223], v[180:183], v[4:7]
	v_mfma_f32_16x16x32_bf16 v[0:3], v[220:223], v[184:187], v[0:3]
	s_add_u32 s8, s100, 0x108000
	s_addc_u32 s9, s101, 0
	s_add_u32 m0, s97, 0x16000
	s_nop 0
	global_load_lds_dwordx4 v224, s[8:9]
	v_xor_b32_e32 v225, 0x8000, v225
	v_xor_b32_e32 v227, 0x8000, v227
	v_xor_b32_e32 v226, 0x8000, v226
	v_xor_b32_e32 v228, 0x8000, v228
	s_xor_b32 s97, s97, 0x8000
	s_add_u32 s98, s98, 0x80
	s_addc_u32 s99, s99, 0
	s_add_u32 s100, s100, 0x80
	s_addc_u32 s101, s101, 0
	s_sub_u32 s28, s28, 1
	s_cmp_lg_u32 s28, 0
	s_cbranch_scc1 .Lgm3_loop
	s_waitcnt lgkmcnt(4)
	v_mfma_f32_16x16x32_bf16 v[124:127], v[188:191], v[152:155], v[124:127]
	v_mfma_f32_16x16x32_bf16 v[120:123], v[188:191], v[156:159], v[120:123]
	v_mfma_f32_16x16x32_bf16 v[116:119], v[188:191], v[160:163], v[116:119]
	v_mfma_f32_16x16x32_bf16 v[112:115], v[188:191], v[164:167], v[112:115]
	ds_read_b128 v[188:191], v226 offset:0
	ds_read_b128 v[168:171], v228 offset:0
	v_mfma_f32_16x16x32_bf16 v[108:111], v[192:195], v[152:155], v[108:111]
	v_mfma_f32_16x16x32_bf16 v[104:107], v[192:195], v[156:159], v[104:107]
	v_mfma_f32_16x16x32_bf16 v[100:103], v[192:195], v[160:163], v[100:103]
	v_mfma_f32_16x16x32_bf16 v[96:99], v[192:195], v[164:167], v[96:99]
	ds_read_b128 v[192:195], v226 offset:2048
	ds_read_b128 v[176:179], v228 offset:2048
	v_mfma_f32_16x16x32_bf16 v[92:95], v[196:199], v[152:155], v[92:95]
	v_mfma_f32_16x16x32_bf16 v[88:91], v[196:199], v[156:159], v[88:91]
	v_mfma_f32_16x16x32_bf16 v[84:87], v[196:199], v[160:163], v[84:87]
	v_mfma_f32_16x16x32_bf16 v[80:83], v[196:199], v[164:167], v[80:83]
	ds_read_b128 v[196:199], v226 offset:4096
	ds_read_b128 v[180:183], v228 offset:4096
	v_mfma_f32_16x16x32_bf16 v[76:79], v[200:203], v[152:155], v[76:79]
	v_mfma_f32_16x16x32_bf16 v[72:75], v[200:203], v[156:159], v[72:75]
	v_mfma_f32_16x16x32_bf16 v[68:71], v[200:203], v[160:163], v[68:71]
	v_mfma_f32_16x16x32_bf16 v[64:67], v[200:203], v[164:167], v[64:67]
	ds_read_b128 v[200:203], v226 offset:6144
	ds_read_b128 v[184:187], v228 offset:6144
	s_waitcnt lgkmcnt(11)
	v_mfma_f32_16x16x32_bf16 v[60:63], v[204:207], v[152:155], v[60:63]
	v_mfma_f32_16x16x32_bf16 v[56:59], v[204:207], v[156:159], v[56:59]
	v_mfma_f32_16x16x32_bf16 v[52:55], v[204:207], v[160:163], v[52:55]
	v_mfma_f32_16x16x32_bf16 v[48:51], v[204:207], v[164:167], v[48:51]
	ds_read_b128 v[204:207], v226 offset:8192
	ds_read_b128 v[220:223], v226 offset:14336
	s_waitcnt lgkmcnt(11)
	v_mfma_f32_16x16x32_bf16 v[44:47], v[208:211], v[152:155], v[44:47]
	v_mfma_f32_16x16x32_bf16 v[40:43], v[208:211], v[156:159], v[40:43]
	v_mfma_f32_16x16x32_bf16 v[36:39], v[208:211], v[160:163], v[36:39]
	v_mfma_f32_16x16x32_bf16 v[32:35], v[208:211], v[164:167], v[32:35]
	ds_read_b128 v[208:211], v226 offset:10240
	s_waitcnt lgkmcnt(11)
	v_mfma_f32_16x16x32_bf16 v[28:31], v[212:215], v[152:155], v[28:31]
	v_mfma_f32_16x16x32_bf16 v[24:27], v[212:215], v[156:159], v[24:27]
	v_mfma_f32_16x16x32_bf16 v[20:23], v[212:215], v[160:163], v[20:23]
	v_mfma_f32_16x16x32_bf16 v[16:19], v[212:215], v[164:167], v[16:19]
	ds_read_b128 v[212:215], v226 offset:12288
	v_mfma_f32_16x16x32_bf16 v[12:15], v[216:219], v[152:155], v[12:15]
	v_mfma_f32_16x16x32_bf16 v[8:11], v[216:219], v[156:159], v[8:11]
	v_mfma_f32_16x16x32_bf16 v[4:7], v[216:219], v[160:163], v[4:7]
	v_mfma_f32_16x16x32_bf16 v[0:3], v[216:219], v[164:167], v[0:3]
	s_waitcnt vmcnt(0) lgkmcnt(0)
	s_barrier
; #define G_LOAD(KT) do { _Pragma("unroll") for (int i = 0; i < 4; ++i) { ra[i] = *(const u32x4*)(Ag + (size_t)i * 64 * lda + (KT) * 64); rb[i] = *(const u32x4*)(Bg + (size_t)i * 64 * K + (KT) * 64); } } while (0)
; #define G_STORE(BUF) do { u16* ad = As + (BUF) * 256 * 64 + sto; u16* bd = Bs + (BUF) * 256 * 64 + sto; _Pragma("unroll") for (int i = 0; i < 4; ++i) { *(u32x4*)(ad + i * 64 * 64) = ra[i]; *(u32x4*)(bd + i * 64 * 64) = rb[i]; } } while (0)
; template <int EPI>
; DI void gemm_phase(const u16* __restrict__ A, int lda, const u16* __restrict__ Bt, int K, int N, u16* outb, int ldo,
;                    const float* r0, const float* r1, float* outf, char* lds, int bid, int nb) {
;     ...
;     G_LOAD(0);
;     G_STORE(0);
;     __syncthreads();
;     for (int kt = 0; kt < nk; ++kt) {
;       const int cur = kt & 1;
;       if (kt + 1 < nk) G_LOAD(kt + 1);
;       G_MMA(cur, fo0);
;       G_MMA(cur, fo1);
;       if (kt + 1 < nk) G_STORE(cur ^ 1);
;       __syncthreads();
;     }
	v_mfma_f32_16x16x32_bf16 v[124:127], v[188:191], v[168:171], v[124:127]
	v_mfma_f32_16x16x32_bf16 v[120:123], v[188:191], v[176:179], v[120:123]
	v_mfma_f32_16x16x32_bf16 v[116:119], v[188:191], v[180:183], v[116:119]
	v_mfma_f32_16x16x32_bf16 v[112:115], v[188:191], v[184:187], v[112:115]
	ds_read_b128 v[188:191], v225 offset:0
	ds_read_b128 v[152:155], v227 offset:0
	v_mfma_f32_16x16x32_bf16 v[108:111], v[192:195], v[168:171], v[108:111]
	v_mfma_f32_16x16x32_bf16 v[104:107], v[192:195], v[176:179], v[104:107]
	v_mfma_f32_16x16x32_bf16 v[100:103], v[192:195], v[180:183], v[100:103]
	v_mfma_f32_16x16x32_bf16 v[96:99], v[192:195], v[184:187], v[96:99]
	ds_read_b128 v[192:195], v225 offset:2048
	ds_read_b128 v[156:159], v227 offset:2048
	v_mfma_f32_16x16x32_bf16 v[92:95], v[196:199], v[168:171], v[92:95]
	v_mfma_f32_16x16x32_bf16 v[88:91], v[196:199], v[176:179], v[88:91]
	v_mfma_f32_16x16x32_bf16 v[84:87], v[196:199], v[180:183], v[84:87]
	v_mfma_f32_16x16x32_bf16 v[80:83], v[196:199], v[184:187], v[80:83]
	ds_read_b128 v[196:199], v225 offset:4096
	ds_read_b128 v[160:163], v227 offset:4096
	v_mfma_f32_16x16x32_bf16 v[76:79], v[200:203], v[168:171], v[76:79]
	v_mfma_f32_16x16x32_bf16 v[72:75], v[200:203], v[176:179], v[72:75]
	v_mfma_f32_16x16x32_bf16 v[68:71], v[200:203], v[180:183], v[68:71]
	v_mfma_f32_16x16x32_bf16 v[64:67], v[200:203], v[184:187], v[64:67]
	ds_read_b128 v[200:203], v225 offset:6144
	ds_read_b128 v[164:167], v227 offset:6144
	v_mfma_f32_16x16x32_bf16 v[60:63], v[204:207], v[168:171], v[60:63]
	v_mfma_f32_16x16x32_bf16 v[56:59], v[204:207], v[176:179], v[56:59]
	v_mfma_f32_16x16x32_bf16 v[52:55], v[204:207], v[180:183], v[52:55]
	v_mfma_f32_16x16x32_bf16 v[48:51], v[204:207], v[184:187], v[48:51]
	ds_read_b128 v[204:207], v225 offset:8192
	ds_read_b128 v[216:219], v225 offset:14336
	v_mfma_f32_16x16x32_bf16 v[44:47], v[208:211], v[168:171], v[44:47]
	v_mfma_f32_16x16x32_bf16 v[40:43], v[208:211], v[176:179], v[40:43]
	v_mfma_f32_16x16x32_bf16 v[36:39], v[208:211], v[180:183], v[36:39]
	v_mfma_f32_16x16x32_bf16 v[32:35], v[208:211], v[184:187], v[32:35]
	ds_read_b128 v[208:211], v225 offset:10240
	v_mfma_f32_16x16x32_bf16 v[28:31], v[212:215], v[168:171], v[28:31]
	v_mfma_f32_16x16x32_bf16 v[24:27], v[212:215], v[176:179], v[24:27]
	v_mfma_f32_16x16x32_bf16 v[20:23], v[212:215], v[180:183], v[20:23]
	v_mfma_f32_16x16x32_bf16 v[16:19], v[212:215], v[184:187], v[16:19]
	ds_read_b128 v[212:215], v225 offset:12288
	v_mfma_f32_16x16x32_bf16 v[12:15], v[220:223], v[168:171], v[12:15]
	v_mfma_f32_16x16x32_bf16 v[8:11], v[220:223], v[176:179], v[8:11]
	v_mfma_f32_16x16x32_bf16 v[4:7], v[220:223], v[180:183], v[4:7]
	v_mfma_f32_16x16x32_bf16 v[0:3], v[220:223], v[184:187], v[0:3]
	v_xor_b32_e32 v226, 0x8000, v226
	v_xor_b32_e32 v228, 0x8000, v228
	s_waitcnt lgkmcnt(4)
	v_mfma_f32_16x16x32_bf16 v[124:127], v[188:191], v[152:155], v[124:127]
	v_mfma_f32_16x16x32_bf16 v[120:123], v[188:191], v[156:159], v[120:123]
	v_mfma_f32_16x16x32_bf16 v[116:119], v[188:191], v[160:163], v[116:119]
	v_mfma_f32_16x16x32_bf16 v[112:115], v[188:191], v[164:167], v[112:115]
	ds_read_b128 v[188:191], v226 offset:0
	ds_read_b128 v[168:171], v228 offset:0
	v_mfma_f32_16x16x32_bf16 v[108:111], v[192:195], v[152:155], v[108:111]
	v_mfma_f32_16x16x32_bf16 v[104:107], v[192:195], v[156:159], v[104:107]
	v_mfma_f32_16x16x32_bf16 v[100:103], v[192:195], v[160:163], v[100:103]
	v_mfma_f32_16x16x32_bf16 v[96:99], v[192:195], v[164:167], v[96:99]
	ds_read_b128 v[192:195], v226 offset:2048
	ds_read_b128 v[176:179], v228 offset:2048
	v_mfma_f32_16x16x32_bf16 v[92:95], v[196:199], v[152:155], v[92:95]
	v_mfma_f32_16x16x32_bf16 v[88:91], v[196:199], v[156:159], v[88:91]
	v_mfma_f32_16x16x32_bf16 v[84:87], v[196:199], v[160:163], v[84:87]
	v_mfma_f32_16x16x32_bf16 v[80:83], v[196:199], v[164:167], v[80:83]
	ds_read_b128 v[196:199], v226 offset:4096
	ds_read_b128 v[180:183], v228 offset:4096
	v_mfma_f32_16x16x32_bf16 v[76:79], v[200:203], v[152:155], v[76:79]
	v_mfma_f32_16x16x32_bf16 v[72:75], v[200:203], v[156:159], v[72:75]
	v_mfma_f32_16x16x32_bf16 v[68:71], v[200:203], v[160:163], v[68:71]
	v_mfma_f32_16x16x32_bf16 v[64:67], v[200:203], v[164:167], v[64:67]
	ds_read_b128 v[200:203], v226 offset:6144
	ds_read_b128 v[184:187], v228 offset:6144
	s_waitcnt lgkmcnt(11)
	v_mfma_f32_16x16x32_bf16 v[60:63], v[204:207], v[152:155], v[60:63]
	v_mfma_f32_16x16x32_bf16 v[56:59], v[204:207], v[156:159], v[56:59]
	v_mfma_f32_16x16x32_bf16 v[52:55], v[204:207], v[160:163], v[52:55]
	v_mfma_f32_16x16x32_bf16 v[48:51], v[204:207], v[164:167], v[48:51]
	ds_read_b128 v[204:207], v226 offset:8192
	ds_read_b128 v[220:223], v226 offset:14336
	s_waitcnt lgkmcnt(11)
	v_mfma_f32_16x16x32_bf16 v[44:47], v[208:211], v[152:155], v[44:47]
	v_mfma_f32_16x16x32_bf16 v[40:43], v[208:211], v[156:159], v[40:43]
	v_mfma_f32_16x16x32_bf16 v[36:39], v[208:211], v[160:163], v[36:39]
	v_mfma_f32_16x16x32_bf16 v[32:35], v[208:211], v[164:167], v[32:35]
	ds_read_b128 v[208:211], v226 offset:10240
	s_waitcnt lgkmcnt(11)
	v_mfma_f32_16x16x32_bf16 v[28:31], v[212:215], v[152:155], v[28:31]
	v_mfma_f32_16x16x32_bf16 v[24:27], v[212:215], v[156:159], v[24:27]
	v_mfma_f32_16x16x32_bf16 v[20:23], v[212:215], v[160:163], v[20:23]
	v_mfma_f32_16x16x32_bf16 v[16:19], v[212:215], v[164:167], v[16:19]
	ds_read_b128 v[212:215], v226 offset:12288
	v_mfma_f32_16x16x32_bf16 v[12:15], v[216:219], v[152:155], v[12:15]
	v_mfma_f32_16x16x32_bf16 v[8:11], v[216:219], v[156:159], v[8:11]
	v_mfma_f32_16x16x32_bf16 v[4:7], v[216:219], v[160:163], v[4:7]
	v_mfma_f32_16x16x32_bf16 v[0:3], v[216:219], v[164:167], v[0:3]
	s_waitcnt vmcnt(0) lgkmcnt(0)
	s_barrier
; template <int EPI>
; DI void gemm_phase(const u16* __restrict__ A, int lda, const u16* __restrict__ Bt, int K, int N, u16* outb, int ldo,
;                    const float* r0, const float* r1, float* outf, char* lds, int bid, int nb) {
;     ...
;     } else if constexpr (EPI == EPI_RESID) {
;       const int col = tn * 256 + wc * 64 + l15;
;       const float* rb_ = (tm * 256 < M_P) ? r0 : (r1 - (size_t)M_P * DM);
; #pragma unroll
;       for (int i = 0; i < 8; ++i)
; #pragma unroll
;         for (int r = 0; r < 4; ++r) {
;           const size_t i0 = (size_t)(mrow + i * 16 + r) * DM + col;
;           const float x0 = rb_[i0], x1 = rb_[i0 + 16], x2 = rb_[i0 + 32], x3 = rb_[i0 + 48];
;           outf[i0] = x0 + acc[i][0][r]; outf[i0 + 16] = x1 + acc[i][1][r]; outf[i0 + 32] = x2 + acc[i][2][r]; outf[i0 + 48] = x3 + acc[i][3][r];
;         }
	v_mfma_f32_16x16x32_bf16 v[124:127], v[188:191], v[168:171], v[124:127]
	v_mfma_f32_16x16x32_bf16 v[120:123], v[188:191], v[176:179], v[120:123]
	v_mfma_f32_16x16x32_bf16 v[116:119], v[188:191], v[180:183], v[116:119]
	v_mfma_f32_16x16x32_bf16 v[112:115], v[188:191], v[184:187], v[112:115]
	v_mfma_f32_16x16x32_bf16 v[108:111], v[192:195], v[168:171], v[108:111]
	v_mfma_f32_16x16x32_bf16 v[104:107], v[192:195], v[176:179], v[104:107]
	v_mfma_f32_16x16x32_bf16 v[100:103], v[192:195], v[180:183], v[100:103]
	v_mfma_f32_16x16x32_bf16 v[96:99], v[192:195], v[184:187], v[96:99]
	v_mfma_f32_16x16x32_bf16 v[92:95], v[196:199], v[168:171], v[92:95]
	v_mfma_f32_16x16x32_bf16 v[88:91], v[196:199], v[176:179], v[88:91]
	v_mfma_f32_16x16x32_bf16 v[84:87], v[196:199], v[180:183], v[84:87]
	v_mfma_f32_16x16x32_bf16 v[80:83], v[196:199], v[184:187], v[80:83]
	v_mfma_f32_16x16x32_bf16 v[76:79], v[200:203], v[168:171], v[76:79]
	v_mfma_f32_16x16x32_bf16 v[72:75], v[200:203], v[176:179], v[72:75]
	v_mfma_f32_16x16x32_bf16 v[68:71], v[200:203], v[180:183], v[68:71]
	v_mfma_f32_16x16x32_bf16 v[64:67], v[200:203], v[184:187], v[64:67]
	v_mfma_f32_16x16x32_bf16 v[60:63], v[204:207], v[168:171], v[60:63]
	v_mfma_f32_16x16x32_bf16 v[56:59], v[204:207], v[176:179], v[56:59]
	v_mfma_f32_16x16x32_bf16 v[52:55], v[204:207], v[180:183], v[52:55]
	v_mfma_f32_16x16x32_bf16 v[48:51], v[204:207], v[184:187], v[48:51]
	v_mfma_f32_16x16x32_bf16 v[44:47], v[208:211], v[168:171], v[44:47]
	v_mfma_f32_16x16x32_bf16 v[40:43], v[208:211], v[176:179], v[40:43]
	v_mfma_f32_16x16x32_bf16 v[36:39], v[208:211], v[180:183], v[36:39]
	v_mfma_f32_16x16x32_bf16 v[32:35], v[208:211], v[184:187], v[32:35]
	v_mfma_f32_16x16x32_bf16 v[28:31], v[212:215], v[168:171], v[28:31]
	v_mfma_f32_16x16x32_bf16 v[24:27], v[212:215], v[176:179], v[24:27]
	v_mfma_f32_16x16x32_bf16 v[20:23], v[212:215], v[180:183], v[20:23]
	v_mfma_f32_16x16x32_bf16 v[16:19], v[212:215], v[184:187], v[16:19]
	v_mfma_f32_16x16x32_bf16 v[12:15], v[220:223], v[168:171], v[12:15]
	v_mfma_f32_16x16x32_bf16 v[8:11], v[220:223], v[176:179], v[8:11]
	v_mfma_f32_16x16x32_bf16 v[4:7], v[220:223], v[180:183], v[4:7]
	v_mfma_f32_16x16x32_bf16 v[0:3], v[220:223], v[184:187], v[0:3]
	s_nop 7
	s_nop 3
	v_mov_b32_e32 v224, v96
	v_mov_b32_e32 v225, v97
	v_mov_b32_e32 v226, v98
	v_mov_b32_e32 v227, v99
	v_mov_b32_e32 v172, v80
	v_mov_b32_e32 v80, v92
	v_mov_b32_e32 v92, v172
	v_mov_b32_e32 v172, v81
	v_mov_b32_e32 v81, v93
	v_mov_b32_e32 v93, v172
	v_mov_b32_e32 v172, v82
	v_mov_b32_e32 v82, v94
	v_mov_b32_e32 v94, v172
	v_mov_b32_e32 v172, v83
	v_mov_b32_e32 v83, v95
	v_mov_b32_e32 v95, v172
	v_mov_b32_e32 v172, v84
	v_mov_b32_e32 v84, v88
	v_mov_b32_e32 v88, v172
	v_mov_b32_e32 v172, v85
	v_mov_b32_e32 v85, v89
	v_mov_b32_e32 v89, v172
	v_mov_b32_e32 v172, v86
	v_mov_b32_e32 v86, v90
	v_mov_b32_e32 v90, v172
	v_mov_b32_e32 v172, v87
	v_mov_b32_e32 v87, v91
	v_mov_b32_e32 v91, v172
	v_mov_b32_e32 v172, v64
	v_mov_b32_e32 v64, v76
	v_mov_b32_e32 v76, v172
	v_mov_b32_e32 v172, v65
	v_mov_b32_e32 v65, v77
	v_mov_b32_e32 v77, v172
	v_mov_b32_e32 v172, v66
	v_mov_b32_e32 v66, v78
	v_mov_b32_e32 v78, v172
	v_mov_b32_e32 v172, v67
	v_mov_b32_e32 v67, v79
	v_mov_b32_e32 v79, v172
	v_mov_b32_e32 v172, v68
	v_mov_b32_e32 v68, v72
	v_mov_b32_e32 v72, v172
	v_mov_b32_e32 v172, v69
	v_mov_b32_e32 v69, v73
	v_mov_b32_e32 v73, v172
	v_mov_b32_e32 v172, v70
	v_mov_b32_e32 v70, v74
	v_mov_b32_e32 v74, v172
	v_mov_b32_e32 v172, v71
	v_mov_b32_e32 v71, v75
	v_mov_b32_e32 v75, v172
	v_mov_b32_e32 v172, v48
	v_mov_b32_e32 v48, v60
	v_mov_b32_e32 v60, v172
	v_mov_b32_e32 v172, v49
	v_mov_b32_e32 v49, v61
	v_mov_b32_e32 v61, v172
	v_mov_b32_e32 v172, v50
	v_mov_b32_e32 v50, v62
	v_mov_b32_e32 v62, v172
	v_mov_b32_e32 v172, v51
	v_mov_b32_e32 v51, v63
	v_mov_b32_e32 v63, v172
	v_mov_b32_e32 v172, v52
	v_mov_b32_e32 v52, v56
	v_mov_b32_e32 v56, v172
	v_mov_b32_e32 v172, v53
	v_mov_b32_e32 v53, v57
	v_mov_b32_e32 v57, v172
	v_mov_b32_e32 v172, v54
	v_mov_b32_e32 v54, v58
	v_mov_b32_e32 v58, v172
	v_mov_b32_e32 v172, v55
	v_mov_b32_e32 v55, v59
	v_mov_b32_e32 v59, v172
	v_mov_b32_e32 v172, v32
	v_mov_b32_e32 v32, v44
	v_mov_b32_e32 v44, v172
	v_mov_b32_e32 v172, v33
	v_mov_b32_e32 v33, v45
	v_mov_b32_e32 v45, v172
	v_mov_b32_e32 v172, v34
	v_mov_b32_e32 v34, v46
	v_mov_b32_e32 v46, v172
	v_mov_b32_e32 v172, v35
	v_mov_b32_e32 v35, v47
	v_mov_b32_e32 v47, v172
	v_mov_b32_e32 v172, v36
	v_mov_b32_e32 v36, v40
	v_mov_b32_e32 v40, v172
	v_mov_b32_e32 v172, v37
	v_mov_b32_e32 v37, v41
	v_mov_b32_e32 v41, v172
	v_mov_b32_e32 v172, v38
	v_mov_b32_e32 v38, v42
	v_mov_b32_e32 v42, v172
	v_mov_b32_e32 v172, v39
	v_mov_b32_e32 v39, v43
	v_mov_b32_e32 v43, v172
	v_mov_b32_e32 v172, v16
	v_mov_b32_e32 v16, v28
	v_mov_b32_e32 v28, v172
	v_mov_b32_e32 v172, v17
	v_mov_b32_e32 v17, v29
	v_mov_b32_e32 v29, v172
	v_mov_b32_e32 v172, v18
	v_mov_b32_e32 v18, v30
	v_mov_b32_e32 v30, v172
	v_mov_b32_e32 v172, v19
	v_mov_b32_e32 v19, v31
	v_mov_b32_e32 v31, v172
	v_mov_b32_e32 v172, v20
	v_mov_b32_e32 v20, v24
	v_mov_b32_e32 v24, v172
	v_mov_b32_e32 v172, v21
	v_mov_b32_e32 v21, v25
	v_mov_b32_e32 v25, v172
	v_mov_b32_e32 v172, v22
	v_mov_b32_e32 v22, v26
	v_mov_b32_e32 v26, v172
	v_mov_b32_e32 v172, v23
	v_mov_b32_e32 v23, v27
	v_mov_b32_e32 v27, v172
	v_mov_b32_e32 v172, v0
	v_mov_b32_e32 v0, v12
	v_mov_b32_e32 v12, v172
	v_mov_b32_e32 v172, v1
	v_mov_b32_e32 v1, v13
	v_mov_b32_e32 v13, v172
	v_mov_b32_e32 v172, v2
	v_mov_b32_e32 v2, v14
	v_mov_b32_e32 v14, v172
	v_mov_b32_e32 v172, v3
	v_mov_b32_e32 v3, v15
	v_mov_b32_e32 v15, v172
	v_mov_b32_e32 v172, v4
	v_mov_b32_e32 v4, v8
	v_mov_b32_e32 v8, v172
	v_mov_b32_e32 v172, v5
	v_mov_b32_e32 v5, v9
	v_mov_b32_e32 v9, v172
	v_mov_b32_e32 v172, v6
	v_mov_b32_e32 v6, v10
	v_mov_b32_e32 v10, v172
	v_mov_b32_e32 v172, v7
	v_mov_b32_e32 v7, v11
	v_mov_b32_e32 v11, v172
	v_add_u32_e32 v98, s39, v143
	v_or_b32_e32 v96, s46, v144
	v_ashrrev_i32_e32 v99, 31, v98
	v_ashrrev_i32_e32 v97, 31, v96
	v_lshlrev_b64 v[134:135], 10, v[98:99]
	v_lshl_add_u64 v[134:135], v[134:135], 0, v[96:97]
	v_lshl_add_u64 v[134:135], v[134:135], 2, s[22:23]
	global_load_dword v99, v[134:135], off
	global_load_dword v151, v[134:135], off offset:64
	global_load_dword v152, v[134:135], off offset:128
	global_load_dword v153, v[134:135], off offset:192
	v_or_b32_e32 v136, 1, v98
	v_ashrrev_i32_e32 v137, 31, v136
	v_lshlrev_b64 v[136:137], 10, v[136:137]
	v_lshl_add_u64 v[136:137], v[136:137], 0, v[96:97]
	v_lshl_add_u64 v[136:137], v[136:137], 2, s[22:23]
	s_add_i32 s16, s16, 1
	s_cmp_eq_u32 s16, s3
	s_waitcnt vmcnt(3)
; template <int EPI>
; DI void gemm_phase(const u16* __restrict__ A, int lda, const u16* __restrict__ Bt, int K, int N, u16* outb, int ldo,
;                    const float* r0, const float* r1, float* outf, char* lds, int bid, int nb) {
;     ...
;       const int col = tn * 256 + wc * 64 + l15;
;       const float* rb_ = (tm * 256 < M_P) ? r0 : (r1 - (size_t)M_P * DM);
; #pragma unroll
;       for (int i = 0; i < 8; ++i)
; #pragma unroll
;         for (int r = 0; r < 4; ++r) {
;           const size_t i0 = (size_t)(mrow + i * 16 + r) * DM + col;
;           const float x0 = rb_[i0], x1 = rb_[i0 + 16], x2 = rb_[i0 + 32], x3 = rb_[i0 + 48];
;           outf[i0] = x0 + acc[i][0][r]; outf[i0 + 16] = x1 + acc[i][1][r]; outf[i0 + 32] = x2 + acc[i][2][r]; outf[i0 + 48] = x3 + acc[i][3][r];
;         }
	v_add_f32_e32 v99, v124, v99
	s_waitcnt vmcnt(2)
	v_add_f32_e32 v120, v120, v151
	s_waitcnt vmcnt(1)
	v_add_f32_e32 v116, v116, v152
	s_waitcnt vmcnt(0)
	v_add_f32_e32 v112, v112, v153
	global_store_dword v[134:135], v99, off
	global_store_dword v[134:135], v120, off offset:64
	global_store_dword v[134:135], v116, off offset:128
	global_store_dword v[134:135], v112, off offset:192
	global_load_dword v99, v[136:137], off
	s_nop 0
	global_load_dword v112, v[136:137], off offset:64
	global_load_dword v116, v[136:137], off offset:128
	global_load_dword v120, v[136:137], off offset:192
	v_or_b32_e32 v134, 2, v98
	v_ashrrev_i32_e32 v135, 31, v134
	v_lshlrev_b64 v[134:135], 10, v[134:135]
	v_lshl_add_u64 v[134:135], v[134:135], 0, v[96:97]
	v_lshl_add_u64 v[134:135], v[134:135], 2, s[22:23]
	s_waitcnt vmcnt(3)
	v_add_f32_e32 v99, v125, v99
	s_waitcnt vmcnt(2)
	v_add_f32_e32 v112, v121, v112
	s_waitcnt vmcnt(1)
	v_add_f32_e32 v116, v117, v116
	s_waitcnt vmcnt(0)
	v_add_f32_e32 v113, v113, v120
	global_store_dword v[136:137], v99, off
	global_store_dword v[136:137], v112, off offset:64
	global_store_dword v[136:137], v116, off offset:128
	global_store_dword v[136:137], v113, off offset:192
	global_load_dword v99, v[134:135], off
	s_nop 0
	global_load_dword v116, v[134:135], off offset:64
	global_load_dword v117, v[134:135], off offset:128
	global_load_dword v120, v[134:135], off offset:192
	v_or_b32_e32 v112, 3, v98
	v_ashrrev_i32_e32 v113, 31, v112
	v_lshlrev_b64 v[112:113], 10, v[112:113]
	v_lshl_add_u64 v[112:113], v[112:113], 0, v[96:97]
	v_lshl_add_u64 v[112:113], v[112:113], 2, s[22:23]
	s_waitcnt vmcnt(3)
	v_add_f32_e32 v99, v126, v99
	s_waitcnt vmcnt(2)
	v_add_f32_e32 v116, v122, v116
	s_waitcnt vmcnt(1)
	v_add_f32_e32 v117, v118, v117
	s_waitcnt vmcnt(0)
	v_add_f32_e32 v114, v114, v120
	global_store_dword v[134:135], v99, off
	global_store_dword v[134:135], v116, off offset:64
	global_store_dword v[134:135], v117, off offset:128
	global_store_dword v[134:135], v114, off offset:192
	global_load_dword v99, v[112:113], off
	s_nop 0
	global_load_dword v114, v[112:113], off offset:64
	global_load_dword v118, v[112:113], off offset:128
	global_load_dword v120, v[112:113], off offset:192
	v_or_b32_e32 v116, 16, v98
	v_ashrrev_i32_e32 v117, 31, v116
	v_lshlrev_b64 v[116:117], 10, v[116:117]
	v_lshl_add_u64 v[116:117], v[116:117], 0, v[96:97]
	v_lshl_add_u64 v[116:117], v[116:117], 2, s[22:23]
	s_waitcnt vmcnt(3)
	v_add_f32_e32 v99, v127, v99
	s_waitcnt vmcnt(2)
	v_add_f32_e32 v114, v123, v114
	s_waitcnt vmcnt(1)
	v_add_f32_e32 v118, v119, v118
	s_waitcnt vmcnt(0)
	v_add_f32_e32 v115, v115, v120
	global_store_dword v[112:113], v99, off
	global_store_dword v[112:113], v114, off offset:64
	global_store_dword v[112:113], v118, off offset:128
	global_store_dword v[112:113], v115, off offset:192
	global_load_dword v99, v[116:117], off
	s_nop 0
	global_load_dword v114, v[116:117], off offset:64
	global_load_dword v115, v[116:117], off offset:128
	global_load_dword v118, v[116:117], off offset:192
	v_or_b32_e32 v112, 17, v98
	v_ashrrev_i32_e32 v113, 31, v112
	v_lshlrev_b64 v[112:113], 10, v[112:113]
	v_lshl_add_u64 v[112:113], v[112:113], 0, v[96:97]
	v_lshl_add_u64 v[112:113], v[112:113], 2, s[22:23]
	s_waitcnt vmcnt(3)
	v_add_f32_e32 v99, v108, v99
	s_waitcnt vmcnt(2)
	v_add_f32_e32 v104, v104, v114
	s_waitcnt vmcnt(1)
	v_add_f32_e32 v100, v100, v115
	s_waitcnt vmcnt(0)
	v_add_f32_e32 v108, v224, v118
	global_store_dword v[116:117], v99, off
	global_store_dword v[116:117], v104, off offset:64
	global_store_dword v[116:117], v100, off offset:128
	global_store_dword v[116:117], v108, off offset:192
	global_load_dword v99, v[112:113], off
	s_nop 0
	global_load_dword v100, v[112:113], off offset:64
	global_load_dword v104, v[112:113], off offset:128
	global_load_dword v108, v[112:113], off offset:192
	v_or_b32_e32 v114, 18, v98
	v_ashrrev_i32_e32 v115, 31, v114
	v_lshlrev_b64 v[114:115], 10, v[114:115]
	v_lshl_add_u64 v[114:115], v[114:115], 0, v[96:97]
	v_lshl_add_u64 v[114:115], v[114:115], 2, s[22:23]
	s_waitcnt vmcnt(3)
	v_add_f32_e32 v99, v109, v99
	s_waitcnt vmcnt(2)
	v_add_f32_e32 v100, v105, v100
	s_waitcnt vmcnt(1)
	v_add_f32_e32 v101, v101, v104
	s_waitcnt vmcnt(0)
	v_add_f32_e32 v104, v225, v108
	global_store_dword v[112:113], v99, off
	global_store_dword v[112:113], v100, off offset:64
	global_store_dword v[112:113], v101, off offset:128
	global_store_dword v[112:113], v104, off offset:192
	global_load_dword v99, v[114:115], off
	s_nop 0
	global_load_dword v104, v[114:115], off offset:64
	global_load_dword v105, v[114:115], off offset:128
	global_load_dword v108, v[114:115], off offset:192
	v_or_b32_e32 v100, 19, v98
	v_ashrrev_i32_e32 v101, 31, v100
	v_lshlrev_b64 v[100:101], 10, v[100:101]
	v_lshl_add_u64 v[100:101], v[100:101], 0, v[96:97]
	v_lshl_add_u64 v[100:101], v[100:101], 2, s[22:23]
	s_waitcnt vmcnt(3)
	v_add_f32_e32 v99, v110, v99
	s_waitcnt vmcnt(2)
	v_add_f32_e32 v104, v106, v104
	s_waitcnt vmcnt(1)
	v_add_f32_e32 v102, v102, v105
	s_waitcnt vmcnt(0)
	v_add_f32_e32 v105, v226, v108
	global_store_dword v[114:115], v99, off
	global_store_dword v[114:115], v104, off offset:64
	global_store_dword v[114:115], v102, off offset:128
	global_store_dword v[114:115], v105, off offset:192
	global_load_dword v99, v[100:101], off
	s_nop 0
	global_load_dword v102, v[100:101], off offset:64
	global_load_dword v106, v[100:101], off offset:128
	global_load_dword v108, v[100:101], off offset:192
	v_or_b32_e32 v104, 32, v98
	v_ashrrev_i32_e32 v105, 31, v104
	v_lshlrev_b64 v[104:105], 10, v[104:105]
	v_lshl_add_u64 v[104:105], v[104:105], 0, v[96:97]
	v_lshl_add_u64 v[104:105], v[104:105], 2, s[22:23]
	s_waitcnt vmcnt(3)
; template <int EPI>
; DI void gemm_phase(const u16* __restrict__ A, int lda, const u16* __restrict__ Bt, int K, int N, u16* outb, int ldo,
;                    const float* r0, const float* r1, float* outf, char* lds, int bid, int nb) {
;     ...
;       const int col = tn * 256 + wc * 64 + l15;
;       const float* rb_ = (tm * 256 < M_P) ? r0 : (r1 - (size_t)M_P * DM);
; #pragma unroll
;       for (int i = 0; i < 8; ++i)
; #pragma unroll
;         for (int r = 0; r < 4; ++r) {
;           const size_t i0 = (size_t)(mrow + i * 16 + r) * DM + col;
;           const float x0 = rb_[i0], x1 = rb_[i0 + 16], x2 = rb_[i0 + 32], x3 = rb_[i0 + 48];
;           outf[i0] = x0 + acc[i][0][r]; outf[i0 + 16] = x1 + acc[i][1][r]; outf[i0 + 32] = x2 + acc[i][2][r]; outf[i0 + 48] = x3 + acc[i][3][r];
;         }
	v_add_f32_e32 v99, v111, v99
	s_waitcnt vmcnt(2)
	v_add_f32_e32 v102, v107, v102
	s_waitcnt vmcnt(1)
	v_add_f32_e32 v103, v103, v106
	s_waitcnt vmcnt(0)
	v_add_f32_e32 v106, v227, v108
	global_store_dword v[100:101], v99, off
	global_store_dword v[100:101], v102, off offset:64
	global_store_dword v[100:101], v103, off offset:128
	global_store_dword v[100:101], v106, off offset:192
	global_load_dword v99, v[104:105], off
	s_nop 0
	global_load_dword v102, v[104:105], off offset:64
	global_load_dword v103, v[104:105], off offset:128
	global_load_dword v106, v[104:105], off offset:192
	v_or_b32_e32 v100, 33, v98
	v_ashrrev_i32_e32 v101, 31, v100
	v_lshlrev_b64 v[100:101], 10, v[100:101]
	v_lshl_add_u64 v[100:101], v[100:101], 0, v[96:97]
	v_lshl_add_u64 v[100:101], v[100:101], 2, s[22:23]
	s_waitcnt vmcnt(3)
	v_add_f32_e32 v80, v80, v99
	s_waitcnt vmcnt(2)
	v_add_f32_e32 v84, v84, v102
	s_waitcnt vmcnt(1)
	v_add_f32_e32 v88, v88, v103
	s_waitcnt vmcnt(0)
	v_add_f32_e32 v92, v92, v106
	global_store_dword v[104:105], v80, off
	global_store_dword v[104:105], v84, off offset:64
	global_store_dword v[104:105], v88, off offset:128
	global_store_dword v[104:105], v92, off offset:192
	global_load_dword v80, v[100:101], off
	s_nop 0
	global_load_dword v84, v[100:101], off offset:64
	global_load_dword v88, v[100:101], off offset:128
	global_load_dword v92, v[100:101], off offset:192
	v_or_b32_e32 v102, 34, v98
	v_ashrrev_i32_e32 v103, 31, v102
	v_lshlrev_b64 v[102:103], 10, v[102:103]
	v_lshl_add_u64 v[102:103], v[102:103], 0, v[96:97]
	v_lshl_add_u64 v[102:103], v[102:103], 2, s[22:23]
	s_waitcnt vmcnt(3)
	v_add_f32_e32 v80, v81, v80
	s_waitcnt vmcnt(2)
	v_add_f32_e32 v81, v85, v84
	s_waitcnt vmcnt(1)
	v_add_f32_e32 v84, v89, v88
	s_waitcnt vmcnt(0)
	v_add_f32_e32 v85, v93, v92
	global_store_dword v[100:101], v80, off
	global_store_dword v[100:101], v81, off offset:64
	global_store_dword v[100:101], v84, off offset:128
	global_store_dword v[100:101], v85, off offset:192
	global_load_dword v84, v[102:103], off
	s_nop 0
	global_load_dword v85, v[102:103], off offset:64
	global_load_dword v88, v[102:103], off offset:128
	global_load_dword v89, v[102:103], off offset:192
	v_or_b32_e32 v80, 35, v98
	v_ashrrev_i32_e32 v81, 31, v80
	v_lshlrev_b64 v[80:81], 10, v[80:81]
	v_lshl_add_u64 v[80:81], v[80:81], 0, v[96:97]
	v_lshl_add_u64 v[80:81], v[80:81], 2, s[22:23]
	s_waitcnt vmcnt(3)
	v_add_f32_e32 v82, v82, v84
	s_waitcnt vmcnt(2)
	v_add_f32_e32 v84, v86, v85
	s_waitcnt vmcnt(1)
	v_add_f32_e32 v85, v90, v88
	s_waitcnt vmcnt(0)
	v_add_f32_e32 v86, v94, v89
	global_store_dword v[102:103], v82, off
	global_store_dword v[102:103], v84, off offset:64
	global_store_dword v[102:103], v85, off offset:128
	global_store_dword v[102:103], v86, off offset:192
	global_load_dword v82, v[80:81], off
	s_nop 0
	global_load_dword v86, v[80:81], off offset:64
	global_load_dword v88, v[80:81], off offset:128
	global_load_dword v89, v[80:81], off offset:192
	v_or_b32_e32 v84, 48, v98
	v_ashrrev_i32_e32 v85, 31, v84
	v_lshlrev_b64 v[84:85], 10, v[84:85]
	v_lshl_add_u64 v[84:85], v[84:85], 0, v[96:97]
	v_lshl_add_u64 v[84:85], v[84:85], 2, s[22:23]
	s_waitcnt vmcnt(3)
	v_add_f32_e32 v82, v83, v82
	s_waitcnt vmcnt(2)
	v_add_f32_e32 v83, v87, v86
	s_waitcnt vmcnt(1)
	v_add_f32_e32 v86, v91, v88
	s_waitcnt vmcnt(0)
	v_add_f32_e32 v87, v95, v89
	global_store_dword v[80:81], v82, off
	global_store_dword v[80:81], v83, off offset:64
	global_store_dword v[80:81], v86, off offset:128
	global_store_dword v[80:81], v87, off offset:192
	global_load_dword v82, v[84:85], off
	s_nop 0
	global_load_dword v83, v[84:85], off offset:64
	global_load_dword v86, v[84:85], off offset:128
	global_load_dword v87, v[84:85], off offset:192
	v_or_b32_e32 v80, 49, v98
	v_ashrrev_i32_e32 v81, 31, v80
	v_lshlrev_b64 v[80:81], 10, v[80:81]
	v_lshl_add_u64 v[80:81], v[80:81], 0, v[96:97]
	v_lshl_add_u64 v[80:81], v[80:81], 2, s[22:23]
	s_waitcnt vmcnt(3)
	v_add_f32_e32 v64, v64, v82
	s_waitcnt vmcnt(2)
	v_add_f32_e32 v68, v68, v83
	s_waitcnt vmcnt(1)
	v_add_f32_e32 v72, v72, v86
	s_waitcnt vmcnt(0)
	v_add_f32_e32 v76, v76, v87
	global_store_dword v[84:85], v64, off
	global_store_dword v[84:85], v68, off offset:64
	global_store_dword v[84:85], v72, off offset:128
	global_store_dword v[84:85], v76, off offset:192
	global_load_dword v64, v[80:81], off
	s_nop 0
	global_load_dword v68, v[80:81], off offset:64
	global_load_dword v72, v[80:81], off offset:128
	global_load_dword v76, v[80:81], off offset:192
	v_or_b32_e32 v82, 50, v98
	v_ashrrev_i32_e32 v83, 31, v82
	v_lshlrev_b64 v[82:83], 10, v[82:83]
	v_lshl_add_u64 v[82:83], v[82:83], 0, v[96:97]
	v_lshl_add_u64 v[82:83], v[82:83], 2, s[22:23]
	s_waitcnt vmcnt(3)
	v_add_f32_e32 v64, v65, v64
	s_waitcnt vmcnt(2)
	v_add_f32_e32 v65, v69, v68
	s_waitcnt vmcnt(1)
	v_add_f32_e32 v68, v73, v72
	s_waitcnt vmcnt(0)
	v_add_f32_e32 v69, v77, v76
	global_store_dword v[80:81], v64, off
	global_store_dword v[80:81], v65, off offset:64
	global_store_dword v[80:81], v68, off offset:128
	global_store_dword v[80:81], v69, off offset:192
	global_load_dword v68, v[82:83], off
	s_nop 0
	global_load_dword v69, v[82:83], off offset:64
	global_load_dword v72, v[82:83], off offset:128
	global_load_dword v73, v[82:83], off offset:192
	v_or_b32_e32 v64, 51, v98
	v_ashrrev_i32_e32 v65, 31, v64
	v_lshlrev_b64 v[64:65], 10, v[64:65]
	v_lshl_add_u64 v[64:65], v[64:65], 0, v[96:97]
	v_lshl_add_u64 v[64:65], v[64:65], 2, s[22:23]
	s_waitcnt vmcnt(3)
	v_add_f32_e32 v66, v66, v68
	s_waitcnt vmcnt(2)
	v_add_f32_e32 v68, v70, v69
	s_waitcnt vmcnt(1)
	v_add_f32_e32 v69, v74, v72
	s_waitcnt vmcnt(0)
; template <int EPI>
; DI void gemm_phase(const u16* __restrict__ A, int lda, const u16* __restrict__ Bt, int K, int N, u16* outb, int ldo,
;                    const float* r0, const float* r1, float* outf, char* lds, int bid, int nb) {
;     ...
;       const int col = tn * 256 + wc * 64 + l15;
;       const float* rb_ = (tm * 256 < M_P) ? r0 : (r1 - (size_t)M_P * DM);
; #pragma unroll
;       for (int i = 0; i < 8; ++i)
; #pragma unroll
;         for (int r = 0; r < 4; ++r) {
;           const size_t i0 = (size_t)(mrow + i * 16 + r) * DM + col;
;           const float x0 = rb_[i0], x1 = rb_[i0 + 16], x2 = rb_[i0 + 32], x3 = rb_[i0 + 48];
;           outf[i0] = x0 + acc[i][0][r]; outf[i0 + 16] = x1 + acc[i][1][r]; outf[i0 + 32] = x2 + acc[i][2][r]; outf[i0 + 48] = x3 + acc[i][3][r];
;         }
	v_add_f32_e32 v70, v78, v73
	global_store_dword v[82:83], v66, off
	global_store_dword v[82:83], v68, off offset:64
	global_store_dword v[82:83], v69, off offset:128
	global_store_dword v[82:83], v70, off offset:192
	global_load_dword v66, v[64:65], off
	s_nop 0
	global_load_dword v70, v[64:65], off offset:64
	global_load_dword v72, v[64:65], off offset:128
	global_load_dword v73, v[64:65], off offset:192
	v_or_b32_e32 v68, 64, v98
	v_ashrrev_i32_e32 v69, 31, v68
	v_lshlrev_b64 v[68:69], 10, v[68:69]
	v_lshl_add_u64 v[68:69], v[68:69], 0, v[96:97]
	v_lshl_add_u64 v[68:69], v[68:69], 2, s[22:23]
	s_waitcnt vmcnt(3)
	v_add_f32_e32 v66, v67, v66
	s_waitcnt vmcnt(2)
	v_add_f32_e32 v67, v71, v70
	s_waitcnt vmcnt(1)
	v_add_f32_e32 v70, v75, v72
	s_waitcnt vmcnt(0)
	v_add_f32_e32 v71, v79, v73
	global_store_dword v[64:65], v66, off
	global_store_dword v[64:65], v67, off offset:64
	global_store_dword v[64:65], v70, off offset:128
	global_store_dword v[64:65], v71, off offset:192
	global_load_dword v66, v[68:69], off
	s_nop 0
	global_load_dword v67, v[68:69], off offset:64
	global_load_dword v70, v[68:69], off offset:128
	global_load_dword v71, v[68:69], off offset:192
	v_or_b32_e32 v64, 0x41, v98
	v_ashrrev_i32_e32 v65, 31, v64
	v_lshlrev_b64 v[64:65], 10, v[64:65]
	v_lshl_add_u64 v[64:65], v[64:65], 0, v[96:97]
	v_lshl_add_u64 v[64:65], v[64:65], 2, s[22:23]
	s_waitcnt vmcnt(3)
	v_add_f32_e32 v48, v48, v66
	s_waitcnt vmcnt(2)
	v_add_f32_e32 v52, v52, v67
	s_waitcnt vmcnt(1)
	v_add_f32_e32 v56, v56, v70
	s_waitcnt vmcnt(0)
	v_add_f32_e32 v60, v60, v71
	global_store_dword v[68:69], v48, off
	global_store_dword v[68:69], v52, off offset:64
	global_store_dword v[68:69], v56, off offset:128
	global_store_dword v[68:69], v60, off offset:192
	global_load_dword v48, v[64:65], off
	s_nop 0
	global_load_dword v52, v[64:65], off offset:64
	global_load_dword v56, v[64:65], off offset:128
	global_load_dword v60, v[64:65], off offset:192
	v_or_b32_e32 v66, 0x42, v98
	v_ashrrev_i32_e32 v67, 31, v66
	v_lshlrev_b64 v[66:67], 10, v[66:67]
	v_lshl_add_u64 v[66:67], v[66:67], 0, v[96:97]
	v_lshl_add_u64 v[66:67], v[66:67], 2, s[22:23]
	s_waitcnt vmcnt(3)
	v_add_f32_e32 v48, v49, v48
	s_waitcnt vmcnt(2)
	v_add_f32_e32 v49, v53, v52
	s_waitcnt vmcnt(1)
	v_add_f32_e32 v52, v57, v56
	s_waitcnt vmcnt(0)
	v_add_f32_e32 v53, v61, v60
	global_store_dword v[64:65], v48, off
	global_store_dword v[64:65], v49, off offset:64
	global_store_dword v[64:65], v52, off offset:128
	global_store_dword v[64:65], v53, off offset:192
	global_load_dword v52, v[66:67], off
	s_nop 0
	global_load_dword v53, v[66:67], off offset:64
	global_load_dword v56, v[66:67], off offset:128
	global_load_dword v57, v[66:67], off offset:192
	v_or_b32_e32 v48, 0x43, v98
	v_ashrrev_i32_e32 v49, 31, v48
	v_lshlrev_b64 v[48:49], 10, v[48:49]
	v_lshl_add_u64 v[48:49], v[48:49], 0, v[96:97]
	v_lshl_add_u64 v[48:49], v[48:49], 2, s[22:23]
	s_waitcnt vmcnt(3)
	v_add_f32_e32 v50, v50, v52
	s_waitcnt vmcnt(2)
	v_add_f32_e32 v52, v54, v53
	s_waitcnt vmcnt(1)
	v_add_f32_e32 v53, v58, v56
	s_waitcnt vmcnt(0)
	v_add_f32_e32 v54, v62, v57
	global_store_dword v[66:67], v50, off
	global_store_dword v[66:67], v52, off offset:64
	global_store_dword v[66:67], v53, off offset:128
	global_store_dword v[66:67], v54, off offset:192
	global_load_dword v50, v[48:49], off
	s_nop 0
	global_load_dword v54, v[48:49], off offset:64
	global_load_dword v56, v[48:49], off offset:128
	global_load_dword v57, v[48:49], off offset:192
	v_or_b32_e32 v52, 0x50, v98
	v_ashrrev_i32_e32 v53, 31, v52
	v_lshlrev_b64 v[52:53], 10, v[52:53]
	v_lshl_add_u64 v[52:53], v[52:53], 0, v[96:97]
	v_lshl_add_u64 v[52:53], v[52:53], 2, s[22:23]
	s_waitcnt vmcnt(3)
	v_add_f32_e32 v50, v51, v50
	s_waitcnt vmcnt(2)
	v_add_f32_e32 v51, v55, v54
	s_waitcnt vmcnt(1)
	v_add_f32_e32 v54, v59, v56
	s_waitcnt vmcnt(0)
	v_add_f32_e32 v55, v63, v57
	global_store_dword v[48:49], v50, off
	global_store_dword v[48:49], v51, off offset:64
	global_store_dword v[48:49], v54, off offset:128
	global_store_dword v[48:49], v55, off offset:192
	global_load_dword v50, v[52:53], off
	s_nop 0
	global_load_dword v51, v[52:53], off offset:64
	global_load_dword v54, v[52:53], off offset:128
	global_load_dword v55, v[52:53], off offset:192
	v_or_b32_e32 v48, 0x51, v98
	v_ashrrev_i32_e32 v49, 31, v48
	v_lshlrev_b64 v[48:49], 10, v[48:49]
	v_lshl_add_u64 v[48:49], v[48:49], 0, v[96:97]
	v_lshl_add_u64 v[48:49], v[48:49], 2, s[22:23]
	s_waitcnt vmcnt(3)
	v_add_f32_e32 v32, v32, v50
	s_waitcnt vmcnt(2)
	v_add_f32_e32 v36, v36, v51
	s_waitcnt vmcnt(1)
	v_add_f32_e32 v40, v40, v54
	s_waitcnt vmcnt(0)
	v_add_f32_e32 v44, v44, v55
	global_store_dword v[52:53], v32, off
	global_store_dword v[52:53], v36, off offset:64
	global_store_dword v[52:53], v40, off offset:128
	global_store_dword v[52:53], v44, off offset:192
	global_load_dword v32, v[48:49], off
	s_nop 0
	global_load_dword v36, v[48:49], off offset:64
	global_load_dword v40, v[48:49], off offset:128
	global_load_dword v44, v[48:49], off offset:192
	v_or_b32_e32 v50, 0x52, v98
	v_ashrrev_i32_e32 v51, 31, v50
	v_lshlrev_b64 v[50:51], 10, v[50:51]
	v_lshl_add_u64 v[50:51], v[50:51], 0, v[96:97]
	v_lshl_add_u64 v[50:51], v[50:51], 2, s[22:23]
	s_waitcnt vmcnt(3)
	v_add_f32_e32 v32, v33, v32
	s_waitcnt vmcnt(2)
	v_add_f32_e32 v33, v37, v36
	s_waitcnt vmcnt(1)
	v_add_f32_e32 v36, v41, v40
	s_waitcnt vmcnt(0)
; template <int EPI>
; DI void gemm_phase(const u16* __restrict__ A, int lda, const u16* __restrict__ Bt, int K, int N, u16* outb, int ldo,
;                    const float* r0, const float* r1, float* outf, char* lds, int bid, int nb) {
;     ...
;       const int col = tn * 256 + wc * 64 + l15;
;       const float* rb_ = (tm * 256 < M_P) ? r0 : (r1 - (size_t)M_P * DM);
; #pragma unroll
;       for (int i = 0; i < 8; ++i)
; #pragma unroll
;         for (int r = 0; r < 4; ++r) {
;           const size_t i0 = (size_t)(mrow + i * 16 + r) * DM + col;
;           const float x0 = rb_[i0], x1 = rb_[i0 + 16], x2 = rb_[i0 + 32], x3 = rb_[i0 + 48];
;           outf[i0] = x0 + acc[i][0][r]; outf[i0 + 16] = x1 + acc[i][1][r]; outf[i0 + 32] = x2 + acc[i][2][r]; outf[i0 + 48] = x3 + acc[i][3][r];
;         }
	v_add_f32_e32 v37, v45, v44
	global_store_dword v[48:49], v32, off
	global_store_dword v[48:49], v33, off offset:64
	global_store_dword v[48:49], v36, off offset:128
	global_store_dword v[48:49], v37, off offset:192
	global_load_dword v36, v[50:51], off
	s_nop 0
	global_load_dword v37, v[50:51], off offset:64
	global_load_dword v40, v[50:51], off offset:128
	global_load_dword v41, v[50:51], off offset:192
	v_or_b32_e32 v32, 0x53, v98
	v_ashrrev_i32_e32 v33, 31, v32
	v_lshlrev_b64 v[32:33], 10, v[32:33]
	v_lshl_add_u64 v[32:33], v[32:33], 0, v[96:97]
	v_lshl_add_u64 v[32:33], v[32:33], 2, s[22:23]
	s_waitcnt vmcnt(3)
	v_add_f32_e32 v34, v34, v36
	s_waitcnt vmcnt(2)
	v_add_f32_e32 v36, v38, v37
	s_waitcnt vmcnt(1)
	v_add_f32_e32 v37, v42, v40
	s_waitcnt vmcnt(0)
	v_add_f32_e32 v38, v46, v41
	global_store_dword v[50:51], v34, off
	global_store_dword v[50:51], v36, off offset:64
	global_store_dword v[50:51], v37, off offset:128
	global_store_dword v[50:51], v38, off offset:192
	global_load_dword v34, v[32:33], off
	s_nop 0
	global_load_dword v38, v[32:33], off offset:64
	global_load_dword v40, v[32:33], off offset:128
	global_load_dword v41, v[32:33], off offset:192
	v_or_b32_e32 v36, 0x60, v98
	v_ashrrev_i32_e32 v37, 31, v36
	v_lshlrev_b64 v[36:37], 10, v[36:37]
	v_lshl_add_u64 v[36:37], v[36:37], 0, v[96:97]
	v_lshl_add_u64 v[36:37], v[36:37], 2, s[22:23]
	s_waitcnt vmcnt(3)
	v_add_f32_e32 v34, v35, v34
	s_waitcnt vmcnt(2)
	v_add_f32_e32 v35, v39, v38
	s_waitcnt vmcnt(1)
	v_add_f32_e32 v38, v43, v40
	s_waitcnt vmcnt(0)
	v_add_f32_e32 v39, v47, v41
	global_store_dword v[32:33], v34, off
	global_store_dword v[32:33], v35, off offset:64
	global_store_dword v[32:33], v38, off offset:128
	global_store_dword v[32:33], v39, off offset:192
	global_load_dword v34, v[36:37], off
	s_nop 0
	global_load_dword v35, v[36:37], off offset:64
	global_load_dword v38, v[36:37], off offset:128
	global_load_dword v39, v[36:37], off offset:192
	v_or_b32_e32 v32, 0x61, v98
	v_ashrrev_i32_e32 v33, 31, v32
	v_lshlrev_b64 v[32:33], 10, v[32:33]
	v_lshl_add_u64 v[32:33], v[32:33], 0, v[96:97]
	v_lshl_add_u64 v[32:33], v[32:33], 2, s[22:23]
	s_waitcnt vmcnt(3)
	v_add_f32_e32 v16, v16, v34
	s_waitcnt vmcnt(2)
	v_add_f32_e32 v20, v20, v35
	s_waitcnt vmcnt(1)
	v_add_f32_e32 v24, v24, v38
	s_waitcnt vmcnt(0)
	v_add_f32_e32 v28, v28, v39
	global_store_dword v[36:37], v16, off
	global_store_dword v[36:37], v20, off offset:64
	global_store_dword v[36:37], v24, off offset:128
	global_store_dword v[36:37], v28, off offset:192
	global_load_dword v16, v[32:33], off
	s_nop 0
	global_load_dword v20, v[32:33], off offset:64
	global_load_dword v24, v[32:33], off offset:128
	global_load_dword v28, v[32:33], off offset:192
	v_or_b32_e32 v34, 0x62, v98
	v_ashrrev_i32_e32 v35, 31, v34
	v_lshlrev_b64 v[34:35], 10, v[34:35]
	v_lshl_add_u64 v[34:35], v[34:35], 0, v[96:97]
	v_lshl_add_u64 v[34:35], v[34:35], 2, s[22:23]
	s_waitcnt vmcnt(3)
	v_add_f32_e32 v16, v17, v16
	s_waitcnt vmcnt(2)
	v_add_f32_e32 v17, v21, v20
	s_waitcnt vmcnt(1)
	v_add_f32_e32 v20, v25, v24
	s_waitcnt vmcnt(0)
	v_add_f32_e32 v21, v29, v28
	global_store_dword v[32:33], v16, off
	global_store_dword v[32:33], v17, off offset:64
	global_store_dword v[32:33], v20, off offset:128
	global_store_dword v[32:33], v21, off offset:192
	global_load_dword v20, v[34:35], off
	s_nop 0
	global_load_dword v21, v[34:35], off offset:64
	global_load_dword v24, v[34:35], off offset:128
	global_load_dword v25, v[34:35], off offset:192
	v_or_b32_e32 v16, 0x63, v98
	v_ashrrev_i32_e32 v17, 31, v16
	v_lshlrev_b64 v[16:17], 10, v[16:17]
	v_lshl_add_u64 v[16:17], v[16:17], 0, v[96:97]
	v_lshl_add_u64 v[16:17], v[16:17], 2, s[22:23]
	s_waitcnt vmcnt(3)
	v_add_f32_e32 v18, v18, v20
	s_waitcnt vmcnt(2)
	v_add_f32_e32 v20, v22, v21
	s_waitcnt vmcnt(1)
	v_add_f32_e32 v21, v26, v24
	s_waitcnt vmcnt(0)
; template <int EPI>
; DI void gemm_phase(const u16* __restrict__ A, int lda, const u16* __restrict__ Bt, int K, int N, u16* outb, int ldo,
;                    const float* r0, const float* r1, float* outf, char* lds, int bid, int nb) {
;     ...
;   for (int it = 0; it < nIter; ++it) {
;     ...
;       const int col = tn * 256 + wc * 64 + l15;
;       const float* rb_ = (tm * 256 < M_P) ? r0 : (r1 - (size_t)M_P * DM);
; #pragma unroll
;       for (int i = 0; i < 8; ++i)
; #pragma unroll
;         for (int r = 0; r < 4; ++r) {
;           const size_t i0 = (size_t)(mrow + i * 16 + r) * DM + col;
;           const float x0 = rb_[i0], x1 = rb_[i0 + 16], x2 = rb_[i0 + 32], x3 = rb_[i0 + 48];
;           outf[i0] = x0 + acc[i][0][r]; outf[i0 + 16] = x1 + acc[i][1][r]; outf[i0 + 32] = x2 + acc[i][2][r]; outf[i0 + 48] = x3 + acc[i][3][r];
;         }
	v_add_f32_e32 v22, v30, v25
	global_store_dword v[34:35], v18, off
	global_store_dword v[34:35], v20, off offset:64
	global_store_dword v[34:35], v21, off offset:128
	global_store_dword v[34:35], v22, off offset:192
	global_load_dword v18, v[16:17], off
	s_nop 0
	global_load_dword v22, v[16:17], off offset:64
	global_load_dword v24, v[16:17], off offset:128
	global_load_dword v25, v[16:17], off offset:192
	v_or_b32_e32 v20, 0x70, v98
	v_ashrrev_i32_e32 v21, 31, v20
	v_lshlrev_b64 v[20:21], 10, v[20:21]
	v_lshl_add_u64 v[20:21], v[20:21], 0, v[96:97]
	v_lshl_add_u64 v[20:21], v[20:21], 2, s[22:23]
	s_waitcnt vmcnt(3)
	v_add_f32_e32 v18, v19, v18
	s_waitcnt vmcnt(2)
	v_add_f32_e32 v19, v23, v22
	s_waitcnt vmcnt(1)
	v_add_f32_e32 v22, v27, v24
	s_waitcnt vmcnt(0)
	v_add_f32_e32 v23, v31, v25
	global_store_dword v[16:17], v18, off
	global_store_dword v[16:17], v19, off offset:64
	global_store_dword v[16:17], v22, off offset:128
	global_store_dword v[16:17], v23, off offset:192
	global_load_dword v18, v[20:21], off
	s_nop 0
	global_load_dword v19, v[20:21], off offset:64
	global_load_dword v22, v[20:21], off offset:128
	global_load_dword v23, v[20:21], off offset:192
	v_or_b32_e32 v16, 0x71, v98
	v_ashrrev_i32_e32 v17, 31, v16
	v_lshlrev_b64 v[16:17], 10, v[16:17]
	v_lshl_add_u64 v[16:17], v[16:17], 0, v[96:97]
	v_lshl_add_u64 v[16:17], v[16:17], 2, s[22:23]
	s_waitcnt vmcnt(3)
	v_add_f32_e32 v0, v0, v18
	s_waitcnt vmcnt(2)
	v_add_f32_e32 v4, v4, v19
	s_waitcnt vmcnt(1)
	v_add_f32_e32 v8, v8, v22
	s_waitcnt vmcnt(0)
	v_add_f32_e32 v12, v12, v23
	global_store_dword v[20:21], v0, off
	global_store_dword v[20:21], v4, off offset:64
	global_store_dword v[20:21], v8, off offset:128
	global_store_dword v[20:21], v12, off offset:192
	global_load_dword v0, v[16:17], off
	s_nop 0
	global_load_dword v4, v[16:17], off offset:64
	global_load_dword v8, v[16:17], off offset:128
	global_load_dword v12, v[16:17], off offset:192
	v_or_b32_e32 v18, 0x72, v98
	v_ashrrev_i32_e32 v19, 31, v18
	v_lshlrev_b64 v[18:19], 10, v[18:19]
	v_lshl_add_u64 v[18:19], v[18:19], 0, v[96:97]
	v_lshl_add_u64 v[18:19], v[18:19], 2, s[22:23]
	s_waitcnt vmcnt(3)
	v_add_f32_e32 v0, v1, v0
	s_waitcnt vmcnt(2)
	v_add_f32_e32 v1, v5, v4
	s_waitcnt vmcnt(1)
	v_add_f32_e32 v4, v9, v8
	s_waitcnt vmcnt(0)
	v_add_f32_e32 v5, v13, v12
	global_store_dword v[16:17], v0, off
	global_store_dword v[16:17], v1, off offset:64
	global_store_dword v[16:17], v4, off offset:128
	global_store_dword v[16:17], v5, off offset:192
	global_load_dword v4, v[18:19], off
	s_nop 0
	global_load_dword v5, v[18:19], off offset:64
	global_load_dword v8, v[18:19], off offset:128
	global_load_dword v9, v[18:19], off offset:192
	v_or_b32_e32 v0, 0x73, v98
	v_ashrrev_i32_e32 v1, 31, v0
	v_lshlrev_b64 v[0:1], 10, v[0:1]
	v_lshl_add_u64 v[0:1], v[0:1], 0, v[96:97]
	v_lshl_add_u64 v[0:1], v[0:1], 2, s[22:23]
	s_waitcnt vmcnt(3)
	v_add_f32_e32 v2, v2, v4
	s_waitcnt vmcnt(2)
	v_add_f32_e32 v4, v6, v5
	s_waitcnt vmcnt(1)
	v_add_f32_e32 v5, v10, v8
	s_waitcnt vmcnt(0)
	v_add_f32_e32 v6, v14, v9
	global_store_dword v[18:19], v2, off
	global_store_dword v[18:19], v4, off offset:64
	global_store_dword v[18:19], v5, off offset:128
	global_store_dword v[18:19], v6, off offset:192
	global_load_dword v2, v[0:1], off
	s_nop 0
	global_load_dword v4, v[0:1], off offset:64
	global_load_dword v5, v[0:1], off offset:128
	global_load_dword v6, v[0:1], off offset:192
	s_waitcnt vmcnt(3)
	v_add_f32_e32 v2, v3, v2
	s_waitcnt vmcnt(2)
	v_add_f32_e32 v3, v7, v4
	s_waitcnt vmcnt(1)
	v_add_f32_e32 v4, v11, v5
	s_waitcnt vmcnt(0)
	v_add_f32_e32 v5, v15, v6
	global_store_dword v[0:1], v2, off
	global_store_dword v[0:1], v3, off offset:64
	global_store_dword v[0:1], v4, off offset:128
	global_store_dword v[0:1], v5, off offset:192
	s_cbranch_scc0 .LBB0_759

; #define G_LOAD(KT) do { _Pragma("unroll") for (int i = 0; i < 4; ++i) { ra[i] = *(const u32x4*)(Ag + (size_t)i * 64 * lda + (KT) * 64); rb[i] = *(const u32x4*)(Bg + (size_t)i * 64 * K + (KT) * 64); } } while (0)
; #define G_STORE(BUF) do { u16* ad = As + (BUF) * 256 * 64 + sto; u16* bd = Bs + (BUF) * 256 * 64 + sto; _Pragma("unroll") for (int i = 0; i < 4; ++i) { *(u32x4*)(ad + i * 64 * 64) = ra[i]; *(u32x4*)(bd + i * 64 * 64) = rb[i]; } } while (0)
; template <int EPI>
; DI void gemm_phase(const u16* __restrict__ A, int lda, const u16* __restrict__ Bt, int K, int N, u16* outb, int ldo,
;                    const float* r0, const float* r1, float* outf, char* lds, int bid, int nb) {
;     ...
;     const u16* Ag = A + (size_t)(tm * 256 + lrow) * lda + lch * 8;
;     const u16* Bg = Bt + (size_t)(tn * 256 + lrow) * K + lch * 8;
;     f32x4 acc[8][4];
; #pragma unroll
;     for (int i = 0; i < 8; ++i)
; #pragma unroll
;       for (int j = 0; j < 4; ++j) acc[i][j] = (f32x4){0.f, 0.f, 0.f, 0.f};
;     u32x4 ra[4], rb[4];
;     ...
;     G_LOAD(0);
;     G_STORE(0);
;     __syncthreads();
;     for (int kt = 0; kt < nk; ++kt) {
;       const int cur = kt & 1;
;       if (kt + 1 < nk) G_LOAD(kt + 1);
.LBB0_883:
	s_lshl_b32 s48, s48, 8
	v_or_b32_e32 v0, s48, v138
	v_ashrrev_i32_e32 v1, 31, v0
	s_lshl_b32 s49, s49, 8
	v_or_b32_e32 v2, s49, v138
	v_lshlrev_b64 v[62:63], 11, v[0:1]
	v_ashrrev_i32_e32 v3, 31, v2
	v_lshl_add_u64 v[0:1], v[128:129], 0, v[62:63]
	v_lshlrev_b64 v[64:65], 11, v[2:3]
	v_add_co_u32_e32 v4, vcc, s19, v0
	v_lshl_add_u64 v[2:3], v[130:131], 0, v[64:65]
	s_nop 0
	v_addc_co_u32_e32 v5, vcc, 0, v1, vcc
	v_add_co_u32_e32 v6, vcc, s19, v2
	s_nop 1
	v_readfirstlane_b32 s98, v0
	v_readfirstlane_b32 s99, v1
	s_nop 1
	v_readfirstlane_b32 s100, v2
	v_readfirstlane_b32 s101, v3
	v_addc_co_u32_e32 v7, vcc, 0, v3, vcc
	v_add_co_u32_e32 v4, vcc, s20, v0
	s_mov_b32 s50, 0
	s_nop 0
	v_addc_co_u32_e32 v5, vcc, 0, v1, vcc
	v_add_co_u32_e32 v6, vcc, s20, v2
	s_mov_b64 s[14:15], 0
	s_nop 0
	v_addc_co_u32_e32 v7, vcc, 0, v3, vcc
	v_add_co_u32_e32 v0, vcc, s21, v0
	v_addc_co_u32_e32 v1, vcc, 0, v1, vcc
	v_add_co_u32_e32 v2, vcc, s21, v2
	v_lshl_add_u64 v[134:135], v[132:133], 0, v[62:63]
	s_nop 0
	v_addc_co_u32_e32 v3, vcc, 0, v3, vcc
	v_mov_b32_e32 v0, 0
	v_mov_b32_e32 v1, v0
	v_mov_b32_e32 v2, v0
	v_mov_b32_e32 v3, v0
	v_mov_b32_e32 v4, v0
	v_mov_b32_e32 v5, v0
	v_mov_b32_e32 v6, v0
	v_mov_b32_e32 v7, v0
	v_mov_b32_e32 v8, v0
	v_mov_b32_e32 v9, v0
	v_mov_b32_e32 v10, v0
	v_mov_b32_e32 v11, v0
	v_mov_b32_e32 v12, v0
	v_mov_b32_e32 v13, v0
	v_mov_b32_e32 v14, v0
	v_mov_b32_e32 v15, v0
	v_mov_b32_e32 v16, v0
	v_mov_b32_e32 v17, v0
	v_mov_b32_e32 v18, v0
	v_mov_b32_e32 v19, v0
	v_mov_b32_e32 v20, v0
	v_mov_b32_e32 v21, v0
	v_mov_b32_e32 v22, v0
	v_mov_b32_e32 v23, v0
	v_mov_b32_e32 v24, v0
	v_mov_b32_e32 v25, v0
	v_mov_b32_e32 v26, v0
	v_mov_b32_e32 v27, v0
	v_mov_b32_e32 v28, v0
	v_mov_b32_e32 v29, v0
	v_lshl_add_u64 v[136:137], v[132:133], 0, v[64:65]
	v_mov_b32_e32 v62, v0
	v_mov_b32_e32 v63, v0
	v_mov_b32_e32 v64, v0
	v_mov_b32_e32 v65, v0
	v_mov_b32_e32 v66, v0
	v_mov_b32_e32 v67, v0
	v_mov_b32_e32 v68, v0
	v_mov_b32_e32 v69, v0
	v_mov_b32_e32 v70, v0
	v_mov_b32_e32 v71, v0
	v_mov_b32_e32 v72, v0
	v_mov_b32_e32 v73, v0
	v_mov_b32_e32 v74, v0
	v_mov_b32_e32 v75, v0
	v_mov_b32_e32 v76, v0
	v_mov_b32_e32 v77, v0
	v_mov_b32_e32 v78, v0
	v_mov_b32_e32 v79, v0
	v_mov_b32_e32 v80, v0
	v_mov_b32_e32 v81, v0
	v_mov_b32_e32 v82, v0
	v_mov_b32_e32 v83, v0
	v_mov_b32_e32 v84, v0
	v_mov_b32_e32 v85, v0
	v_mov_b32_e32 v30, v0
	v_mov_b32_e32 v31, v0
	v_mov_b32_e32 v32, v0
	v_mov_b32_e32 v33, v0
	v_mov_b32_e32 v34, v0
	v_mov_b32_e32 v35, v0
	v_mov_b32_e32 v36, v0
	v_mov_b32_e32 v37, v0
	v_mov_b32_e32 v38, v0
	v_mov_b32_e32 v39, v0
	v_mov_b32_e32 v40, v0
	v_mov_b32_e32 v41, v0
	v_mov_b32_e32 v42, v0
	v_mov_b32_e32 v43, v0
	v_mov_b32_e32 v44, v0
	v_mov_b32_e32 v45, v0
	v_mov_b32_e32 v46, v0
	v_mov_b32_e32 v47, v0
	v_mov_b32_e32 v48, v0
	v_mov_b32_e32 v49, v0
	v_mov_b32_e32 v50, v0
	v_mov_b32_e32 v51, v0
	v_mov_b32_e32 v52, v0
	v_mov_b32_e32 v53, v0
	v_mov_b32_e32 v54, v0
	v_mov_b32_e32 v55, v0
	v_mov_b32_e32 v56, v0
	v_mov_b32_e32 v57, v0
	v_mov_b32_e32 v58, v0
	v_mov_b32_e32 v59, v0
	v_mov_b32_e32 v60, v0
	v_mov_b32_e32 v61, v0
	v_mov_b32_e32 v86, v0
	v_mov_b32_e32 v87, v0
	v_mov_b32_e32 v88, v0
	v_mov_b32_e32 v89, v0
	v_mov_b32_e32 v90, v0
	v_mov_b32_e32 v91, v0
	v_mov_b32_e32 v92, v0
	v_mov_b32_e32 v93, v0
	v_mov_b32_e32 v94, v0
	v_mov_b32_e32 v95, v0
	v_mov_b32_e32 v96, v0
	v_mov_b32_e32 v97, v0
	v_mov_b32_e32 v98, v0
	v_mov_b32_e32 v99, v0
	v_mov_b32_e32 v100, v0
	v_mov_b32_e32 v101, v0
	v_mov_b32_e32 v102, v0
	v_mov_b32_e32 v103, v0
	v_mov_b32_e32 v104, v0
	v_mov_b32_e32 v105, v0
	v_mov_b32_e32 v106, v0
	v_mov_b32_e32 v107, v0
	v_mov_b32_e32 v108, v0
	v_mov_b32_e32 v109, v0
	v_mov_b32_e32 v110, v0
	v_mov_b32_e32 v111, v0
	v_mov_b32_e32 v112, v0
	v_mov_b32_e32 v113, v0
	v_mov_b32_e32 v114, v0
	v_mov_b32_e32 v115, v0
	v_mov_b32_e32 v116, v0
	v_mov_b32_e32 v117, v0
	v_mov_b32_e32 v118, v0
	v_mov_b32_e32 v119, v0
	v_mov_b32_e32 v120, v0
	v_mov_b32_e32 v121, v0
	v_mov_b32_e32 v122, v0
	v_mov_b32_e32 v123, v0
	v_mov_b32_e32 v124, v0
	v_mov_b32_e32 v125, v0
	v_mov_b32_e32 v126, v0
	v_mov_b32_e32 v127, v0
	v_and_b32_e32 v229, 63, v174
	v_lshrrev_b32_e32 v230, 3, v229
	v_mov_b32_e32 v233, 0x800
	v_mul_u32_u24_e32 v224, v230, v233
	v_bfe_u32 v231, v174, 4, 2
	v_bfe_u32 v232, v174, 6, 1
	v_lshl_or_b32 v232, v232, 2, v231
	v_and_b32_e32 v233, 7, v174
	v_xor_b32_e32 v232, v232, v233
	v_lshl_add_u32 v224, v232, 4, v224
	v_and_b32_e32 v229, 15, v174
	v_bfe_u32 v230, v174, 1, 3
	v_xor_b32_e32 v230, v230, v231
	v_lshlrev_b32_e32 v230, 4, v230
	v_lshl_or_b32 v230, v229, 7, v230
	v_lshrrev_b32_e32 v229, 8, v174
	v_lshl_or_b32 v225, v229, 14, v230
	v_bfe_u32 v229, v174, 6, 2
	v_lshl_or_b32 v227, v229, 13, v230
	v_or_b32_e32 v227, 0x10000, v227
	v_xor_b32_e32 v226, 64, v225
	v_xor_b32_e32 v228, 64, v227
	v_readfirstlane_b32 s97, v174
	s_lshl_b32 s97, s97, 4
	s_mov_b32 s28, 14
	s_add_u32 s14, s98, 0x0
	s_addc_u32 s15, s99, 0
	s_add_u32 m0, s97, 0x0
	s_nop 0
	global_load_lds_dwordx4 v224, s[14:15]
	s_add_u32 s14, s100, 0x0
	s_addc_u32 s15, s101, 0
	s_add_u32 m0, s97, 0x10000
	s_nop 0
	global_load_lds_dwordx4 v224, s[14:15]
	s_add_u32 s14, s98, 0x20000
	s_addc_u32 s15, s99, 0
	s_add_u32 m0, s97, 0x2000
	s_nop 0
	global_load_lds_dwordx4 v224, s[14:15]
	s_add_u32 s14, s100, 0x20000
	s_addc_u32 s15, s101, 0
	s_add_u32 m0, s97, 0x12000
	s_nop 0
	global_load_lds_dwordx4 v224, s[14:15]
	s_add_u32 s14, s98, 0x40000
	s_addc_u32 s15, s99, 0
	s_add_u32 m0, s97, 0x4000
	s_nop 0
	global_load_lds_dwordx4 v224, s[14:15]
	s_add_u32 s14, s100, 0x40000
	s_addc_u32 s15, s101, 0
	s_add_u32 m0, s97, 0x14000
	s_nop 0
	global_load_lds_dwordx4 v224, s[14:15]
	s_add_u32 s14, s98, 0x60000
	s_addc_u32 s15, s99, 0
	s_add_u32 m0, s97, 0x6000
	s_nop 0
	global_load_lds_dwordx4 v224, s[14:15]
	s_add_u32 s14, s100, 0x60000
	s_addc_u32 s15, s101, 0
	s_add_u32 m0, s97, 0x16000
	s_nop 0
	global_load_lds_dwordx4 v224, s[14:15]
	s_add_u32 s14, s98, 0x80
	s_addc_u32 s15, s99, 0
	s_add_u32 m0, s97, 0x8000
	s_nop 0
	global_load_lds_dwordx4 v224, s[14:15]
	s_add_u32 s14, s100, 0x80
	s_addc_u32 s15, s101, 0
	s_add_u32 m0, s97, 0x18000
	s_nop 0
	global_load_lds_dwordx4 v224, s[14:15]
	s_add_u32 s14, s98, 0x20080
	s_addc_u32 s15, s99, 0
	s_add_u32 m0, s97, 0xa000
	s_nop 0
	global_load_lds_dwordx4 v224, s[14:15]
	s_add_u32 s14, s100, 0x20080
	s_addc_u32 s15, s101, 0
	s_add_u32 m0, s97, 0x1a000
	s_nop 0
	global_load_lds_dwordx4 v224, s[14:15]
	s_add_u32 s14, s98, 0x40080
	s_addc_u32 s15, s99, 0
	s_add_u32 m0, s97, 0xc000
	s_nop 0
	global_load_lds_dwordx4 v224, s[14:15]
	s_add_u32 s14, s100, 0x40080
	s_addc_u32 s15, s101, 0
	s_add_u32 m0, s97, 0x1c000
	s_nop 0
	global_load_lds_dwordx4 v224, s[14:15]
	s_add_u32 s14, s98, 0x60080
	s_addc_u32 s15, s99, 0
	s_add_u32 m0, s97, 0xe000
	s_nop 0
	global_load_lds_dwordx4 v224, s[14:15]
	s_add_u32 s14, s100, 0x60080
	s_addc_u32 s15, s101, 0
	s_add_u32 m0, s97, 0x1e000
	s_nop 0
	global_load_lds_dwordx4 v224, s[14:15]
	s_add_u32 s98, s98, 0x100
	s_addc_u32 s99, s99, 0
	s_add_u32 s100, s100, 0x100
	s_addc_u32 s101, s101, 0
	s_waitcnt vmcnt(8)
	s_barrier
; #define G_LOAD(KT) do { _Pragma("unroll") for (int i = 0; i < 4; ++i) { ra[i] = *(const u32x4*)(Ag + (size_t)i * 64 * lda + (KT) * 64); rb[i] = *(const u32x4*)(Bg + (size_t)i * 64 * K + (KT) * 64); } } while (0)
; #define G_STORE(BUF) do { u16* ad = As + (BUF) * 256 * 64 + sto; u16* bd = Bs + (BUF) * 256 * 64 + sto; _Pragma("unroll") for (int i = 0; i < 4; ++i) { *(u32x4*)(ad + i * 64 * 64) = ra[i]; *(u32x4*)(bd + i * 64 * 64) = rb[i]; } } while (0)
; template <int EPI>
; DI void gemm_phase(const u16* __restrict__ A, int lda, const u16* __restrict__ Bt, int K, int N, u16* outb, int ldo,
;                    const float* r0, const float* r1, float* outf, char* lds, int bid, int nb) {
;     ...
;     G_LOAD(0);
;     G_STORE(0);
;     __syncthreads();
;     for (int kt = 0; kt < nk; ++kt) {
;       const int cur = kt & 1;
;       if (kt + 1 < nk) G_LOAD(kt + 1);
;       G_MMA(cur, fo0);
;       G_MMA(cur, fo1);
;       if (kt + 1 < nk) G_STORE(cur ^ 1);
;       __syncthreads();
	ds_read_b128 v[152:155], v227 offset:0
	ds_read_b128 v[156:159], v227 offset:2048
	ds_read_b128 v[160:163], v227 offset:4096
	ds_read_b128 v[164:167], v227 offset:6144
	ds_read_b128 v[188:191], v225 offset:0
	ds_read_b128 v[192:195], v225 offset:2048
	ds_read_b128 v[196:199], v225 offset:4096
	ds_read_b128 v[200:203], v225 offset:6144
	ds_read_b128 v[204:207], v225 offset:8192
	ds_read_b128 v[208:211], v225 offset:10240
	ds_read_b128 v[212:215], v225 offset:12288
	ds_read_b128 v[216:219], v225 offset:14336
	v_xor_b32_e32 v225, 0x8000, v225
	v_xor_b32_e32 v227, 0x8000, v227
	s_waitcnt lgkmcnt(0)
.Lgm4_loop:
	s_waitcnt lgkmcnt(4)
	v_mfma_f32_16x16x32_bf16 v[124:127], v[188:191], v[152:155], v[124:127]
	v_mfma_f32_16x16x32_bf16 v[120:123], v[188:191], v[156:159], v[120:123]
	v_mfma_f32_16x16x32_bf16 v[116:119], v[188:191], v[160:163], v[116:119]
	v_mfma_f32_16x16x32_bf16 v[112:115], v[188:191], v[164:167], v[112:115]
	ds_read_b128 v[188:191], v226 offset:0
	ds_read_b128 v[168:171], v228 offset:0
	v_mfma_f32_16x16x32_bf16 v[108:111], v[192:195], v[152:155], v[108:111]
	v_mfma_f32_16x16x32_bf16 v[104:107], v[192:195], v[156:159], v[104:107]
	v_mfma_f32_16x16x32_bf16 v[100:103], v[192:195], v[160:163], v[100:103]
	v_mfma_f32_16x16x32_bf16 v[96:99], v[192:195], v[164:167], v[96:99]
	ds_read_b128 v[192:195], v226 offset:2048
	ds_read_b128 v[176:179], v228 offset:2048
	v_mfma_f32_16x16x32_bf16 v[92:95], v[196:199], v[152:155], v[92:95]
	v_mfma_f32_16x16x32_bf16 v[88:91], v[196:199], v[156:159], v[88:91]
	v_mfma_f32_16x16x32_bf16 v[84:87], v[196:199], v[160:163], v[84:87]
	v_mfma_f32_16x16x32_bf16 v[80:83], v[196:199], v[164:167], v[80:83]
	ds_read_b128 v[196:199], v226 offset:4096
	ds_read_b128 v[180:183], v228 offset:4096
	v_mfma_f32_16x16x32_bf16 v[76:79], v[200:203], v[152:155], v[76:79]
	v_mfma_f32_16x16x32_bf16 v[72:75], v[200:203], v[156:159], v[72:75]
	v_mfma_f32_16x16x32_bf16 v[68:71], v[200:203], v[160:163], v[68:71]
	v_mfma_f32_16x16x32_bf16 v[64:67], v[200:203], v[164:167], v[64:67]
	ds_read_b128 v[200:203], v226 offset:6144
	ds_read_b128 v[184:187], v228 offset:6144
	s_waitcnt lgkmcnt(11)
	v_mfma_f32_16x16x32_bf16 v[60:63], v[204:207], v[152:155], v[60:63]
	v_mfma_f32_16x16x32_bf16 v[56:59], v[204:207], v[156:159], v[56:59]
	v_mfma_f32_16x16x32_bf16 v[52:55], v[204:207], v[160:163], v[52:55]
	v_mfma_f32_16x16x32_bf16 v[48:51], v[204:207], v[164:167], v[48:51]
	ds_read_b128 v[204:207], v226 offset:8192
	ds_read_b128 v[220:223], v226 offset:14336
	s_waitcnt lgkmcnt(11)
	v_mfma_f32_16x16x32_bf16 v[44:47], v[208:211], v[152:155], v[44:47]
	v_mfma_f32_16x16x32_bf16 v[40:43], v[208:211], v[156:159], v[40:43]
	v_mfma_f32_16x16x32_bf16 v[36:39], v[208:211], v[160:163], v[36:39]
	v_mfma_f32_16x16x32_bf16 v[32:35], v[208:211], v[164:167], v[32:35]
	ds_read_b128 v[208:211], v226 offset:10240
	s_waitcnt lgkmcnt(11)
	v_mfma_f32_16x16x32_bf16 v[28:31], v[212:215], v[152:155], v[28:31]
	v_mfma_f32_16x16x32_bf16 v[24:27], v[212:215], v[156:159], v[24:27]
	v_mfma_f32_16x16x32_bf16 v[20:23], v[212:215], v[160:163], v[20:23]
	v_mfma_f32_16x16x32_bf16 v[16:19], v[212:215], v[164:167], v[16:19]
	ds_read_b128 v[212:215], v226 offset:12288
	v_mfma_f32_16x16x32_bf16 v[12:15], v[216:219], v[152:155], v[12:15]
	v_mfma_f32_16x16x32_bf16 v[8:11], v[216:219], v[156:159], v[8:11]
	v_mfma_f32_16x16x32_bf16 v[4:7], v[216:219], v[160:163], v[4:7]
	v_mfma_f32_16x16x32_bf16 v[0:3], v[216:219], v[164:167], v[0:3]
	s_waitcnt vmcnt(0) lgkmcnt(0)
	s_barrier
	v_mfma_f32_16x16x32_bf16 v[124:127], v[188:191], v[168:171], v[124:127]
	v_mfma_f32_16x16x32_bf16 v[120:123], v[188:191], v[176:179], v[120:123]
	v_mfma_f32_16x16x32_bf16 v[116:119], v[188:191], v[180:183], v[116:119]
	v_mfma_f32_16x16x32_bf16 v[112:115], v[188:191], v[184:187], v[112:115]
	ds_read_b128 v[188:191], v225 offset:0
	ds_read_b128 v[152:155], v227 offset:0
	s_add_u32 s14, s98, 0x0
	s_addc_u32 s15, s99, 0
	s_add_u32 m0, s97, 0x0
	s_nop 0
	global_load_lds_dwordx4 v224, s[14:15]
	v_mfma_f32_16x16x32_bf16 v[108:111], v[192:195], v[168:171], v[108:111]
	v_mfma_f32_16x16x32_bf16 v[104:107], v[192:195], v[176:179], v[104:107]
	v_mfma_f32_16x16x32_bf16 v[100:103], v[192:195], v[180:183], v[100:103]
	v_mfma_f32_16x16x32_bf16 v[96:99], v[192:195], v[184:187], v[96:99]
	ds_read_b128 v[192:195], v225 offset:2048
	ds_read_b128 v[156:159], v227 offset:2048
	s_add_u32 s14, s100, 0x0
	s_addc_u32 s15, s101, 0
	s_add_u32 m0, s97, 0x10000
	s_nop 0
	global_load_lds_dwordx4 v224, s[14:15]
	v_mfma_f32_16x16x32_bf16 v[92:95], v[196:199], v[168:171], v[92:95]
	v_mfma_f32_16x16x32_bf16 v[88:91], v[196:199], v[176:179], v[88:91]
	v_mfma_f32_16x16x32_bf16 v[84:87], v[196:199], v[180:183], v[84:87]
	v_mfma_f32_16x16x32_bf16 v[80:83], v[196:199], v[184:187], v[80:83]
	ds_read_b128 v[196:199], v225 offset:4096
	ds_read_b128 v[160:163], v227 offset:4096
	s_add_u32 s14, s98, 0x20000
	s_addc_u32 s15, s99, 0
	s_add_u32 m0, s97, 0x2000
	s_nop 0
	global_load_lds_dwordx4 v224, s[14:15]
	v_mfma_f32_16x16x32_bf16 v[76:79], v[200:203], v[168:171], v[76:79]
	v_mfma_f32_16x16x32_bf16 v[72:75], v[200:203], v[176:179], v[72:75]
	v_mfma_f32_16x16x32_bf16 v[68:71], v[200:203], v[180:183], v[68:71]
	v_mfma_f32_16x16x32_bf16 v[64:67], v[200:203], v[184:187], v[64:67]
	ds_read_b128 v[200:203], v225 offset:6144
	ds_read_b128 v[164:167], v227 offset:6144
	s_add_u32 s14, s100, 0x20000
	s_addc_u32 s15, s101, 0
	s_add_u32 m0, s97, 0x12000
	s_nop 0
	global_load_lds_dwordx4 v224, s[14:15]
	v_mfma_f32_16x16x32_bf16 v[60:63], v[204:207], v[168:171], v[60:63]
	v_mfma_f32_16x16x32_bf16 v[56:59], v[204:207], v[176:179], v[56:59]
; #define G_LOAD(KT) do { _Pragma("unroll") for (int i = 0; i < 4; ++i) { ra[i] = *(const u32x4*)(Ag + (size_t)i * 64 * lda + (KT) * 64); rb[i] = *(const u32x4*)(Bg + (size_t)i * 64 * K + (KT) * 64); } } while (0)
; #define G_STORE(BUF) do { u16* ad = As + (BUF) * 256 * 64 + sto; u16* bd = Bs + (BUF) * 256 * 64 + sto; _Pragma("unroll") for (int i = 0; i < 4; ++i) { *(u32x4*)(ad + i * 64 * 64) = ra[i]; *(u32x4*)(bd + i * 64 * 64) = rb[i]; } } while (0)
; template <int EPI>
; DI void gemm_phase(const u16* __restrict__ A, int lda, const u16* __restrict__ Bt, int K, int N, u16* outb, int ldo,
;                    const float* r0, const float* r1, float* outf, char* lds, int bid, int nb) {
;     ...
;     for (int kt = 0; kt < nk; ++kt) {
;       const int cur = kt & 1;
;       if (kt + 1 < nk) G_LOAD(kt + 1);
;       G_MMA(cur, fo0);
;       G_MMA(cur, fo1);
;       if (kt + 1 < nk) G_STORE(cur ^ 1);
;       __syncthreads();
	v_mfma_f32_16x16x32_bf16 v[52:55], v[204:207], v[180:183], v[52:55]
	v_mfma_f32_16x16x32_bf16 v[48:51], v[204:207], v[184:187], v[48:51]
	ds_read_b128 v[204:207], v225 offset:8192
	ds_read_b128 v[216:219], v225 offset:14336
	s_add_u32 s14, s98, 0x40000
	s_addc_u32 s15, s99, 0
	s_add_u32 m0, s97, 0x4000
	s_nop 0
	global_load_lds_dwordx4 v224, s[14:15]
	v_mfma_f32_16x16x32_bf16 v[44:47], v[208:211], v[168:171], v[44:47]
	v_mfma_f32_16x16x32_bf16 v[40:43], v[208:211], v[176:179], v[40:43]
	v_mfma_f32_16x16x32_bf16 v[36:39], v[208:211], v[180:183], v[36:39]
	v_mfma_f32_16x16x32_bf16 v[32:35], v[208:211], v[184:187], v[32:35]
	ds_read_b128 v[208:211], v225 offset:10240
	s_add_u32 s14, s100, 0x40000
	s_addc_u32 s15, s101, 0
	s_add_u32 m0, s97, 0x14000
	s_nop 0
	global_load_lds_dwordx4 v224, s[14:15]
	v_mfma_f32_16x16x32_bf16 v[28:31], v[212:215], v[168:171], v[28:31]
	v_mfma_f32_16x16x32_bf16 v[24:27], v[212:215], v[176:179], v[24:27]
	v_mfma_f32_16x16x32_bf16 v[20:23], v[212:215], v[180:183], v[20:23]
	v_mfma_f32_16x16x32_bf16 v[16:19], v[212:215], v[184:187], v[16:19]
	ds_read_b128 v[212:215], v225 offset:12288
	s_add_u32 s14, s98, 0x60000
	s_addc_u32 s15, s99, 0
	s_add_u32 m0, s97, 0x6000
	s_nop 0
	global_load_lds_dwordx4 v224, s[14:15]
	v_mfma_f32_16x16x32_bf16 v[12:15], v[220:223], v[168:171], v[12:15]
	v_mfma_f32_16x16x32_bf16 v[8:11], v[220:223], v[176:179], v[8:11]
	v_mfma_f32_16x16x32_bf16 v[4:7], v[220:223], v[180:183], v[4:7]
	v_mfma_f32_16x16x32_bf16 v[0:3], v[220:223], v[184:187], v[0:3]
	s_add_u32 s14, s100, 0x60000
	s_addc_u32 s15, s101, 0
	s_add_u32 m0, s97, 0x16000
	s_nop 0
	global_load_lds_dwordx4 v224, s[14:15]
	v_xor_b32_e32 v225, 0x8000, v225
	v_xor_b32_e32 v227, 0x8000, v227
	v_xor_b32_e32 v226, 0x8000, v226
	v_xor_b32_e32 v228, 0x8000, v228
	s_xor_b32 s97, s97, 0x8000
	s_add_u32 s98, s98, 0x80
	s_addc_u32 s99, s99, 0
	s_add_u32 s100, s100, 0x80
	s_addc_u32 s101, s101, 0
	s_sub_u32 s28, s28, 1
	s_cmp_lg_u32 s28, 0
	s_cbranch_scc1 .Lgm4_loop
	s_waitcnt lgkmcnt(4)
	v_mfma_f32_16x16x32_bf16 v[124:127], v[188:191], v[152:155], v[124:127]
	v_mfma_f32_16x16x32_bf16 v[120:123], v[188:191], v[156:159], v[120:123]
	v_mfma_f32_16x16x32_bf16 v[116:119], v[188:191], v[160:163], v[116:119]
	v_mfma_f32_16x16x32_bf16 v[112:115], v[188:191], v[164:167], v[112:115]
	ds_read_b128 v[188:191], v226 offset:0
	ds_read_b128 v[168:171], v228 offset:0
	v_mfma_f32_16x16x32_bf16 v[108:111], v[192:195], v[152:155], v[108:111]
	v_mfma_f32_16x16x32_bf16 v[104:107], v[192:195], v[156:159], v[104:107]
	v_mfma_f32_16x16x32_bf16 v[100:103], v[192:195], v[160:163], v[100:103]
	v_mfma_f32_16x16x32_bf16 v[96:99], v[192:195], v[164:167], v[96:99]
	ds_read_b128 v[192:195], v226 offset:2048
	ds_read_b128 v[176:179], v228 offset:2048
	v_mfma_f32_16x16x32_bf16 v[92:95], v[196:199], v[152:155], v[92:95]
	v_mfma_f32_16x16x32_bf16 v[88:91], v[196:199], v[156:159], v[88:91]
	v_mfma_f32_16x16x32_bf16 v[84:87], v[196:199], v[160:163], v[84:87]
	v_mfma_f32_16x16x32_bf16 v[80:83], v[196:199], v[164:167], v[80:83]
	ds_read_b128 v[196:199], v226 offset:4096
	ds_read_b128 v[180:183], v228 offset:4096
	v_mfma_f32_16x16x32_bf16 v[76:79], v[200:203], v[152:155], v[76:79]
	v_mfma_f32_16x16x32_bf16 v[72:75], v[200:203], v[156:159], v[72:75]
	v_mfma_f32_16x16x32_bf16 v[68:71], v[200:203], v[160:163], v[68:71]
	v_mfma_f32_16x16x32_bf16 v[64:67], v[200:203], v[164:167], v[64:67]
	ds_read_b128 v[200:203], v226 offset:6144
	ds_read_b128 v[184:187], v228 offset:6144
	s_waitcnt lgkmcnt(11)
	v_mfma_f32_16x16x32_bf16 v[60:63], v[204:207], v[152:155], v[60:63]
	v_mfma_f32_16x16x32_bf16 v[56:59], v[204:207], v[156:159], v[56:59]
	v_mfma_f32_16x16x32_bf16 v[52:55], v[204:207], v[160:163], v[52:55]
	v_mfma_f32_16x16x32_bf16 v[48:51], v[204:207], v[164:167], v[48:51]
	ds_read_b128 v[204:207], v226 offset:8192
	ds_read_b128 v[220:223], v226 offset:14336
	s_waitcnt lgkmcnt(11)
	v_mfma_f32_16x16x32_bf16 v[44:47], v[208:211], v[152:155], v[44:47]
	v_mfma_f32_16x16x32_bf16 v[40:43], v[208:211], v[156:159], v[40:43]
	v_mfma_f32_16x16x32_bf16 v[36:39], v[208:211], v[160:163], v[36:39]
	v_mfma_f32_16x16x32_bf16 v[32:35], v[208:211], v[164:167], v[32:35]
	ds_read_b128 v[208:211], v226 offset:10240
	s_waitcnt lgkmcnt(11)
	v_mfma_f32_16x16x32_bf16 v[28:31], v[212:215], v[152:155], v[28:31]
	v_mfma_f32_16x16x32_bf16 v[24:27], v[212:215], v[156:159], v[24:27]
	v_mfma_f32_16x16x32_bf16 v[20:23], v[212:215], v[160:163], v[20:23]
	v_mfma_f32_16x16x32_bf16 v[16:19], v[212:215], v[164:167], v[16:19]
	ds_read_b128 v[212:215], v226 offset:12288
	v_mfma_f32_16x16x32_bf16 v[12:15], v[216:219], v[152:155], v[12:15]
	v_mfma_f32_16x16x32_bf16 v[8:11], v[216:219], v[156:159], v[8:11]
	v_mfma_f32_16x16x32_bf16 v[4:7], v[216:219], v[160:163], v[4:7]
	v_mfma_f32_16x16x32_bf16 v[0:3], v[216:219], v[164:167], v[0:3]
	s_waitcnt vmcnt(0) lgkmcnt(0)
	s_barrier
; #define G_LOAD(KT) do { _Pragma("unroll") for (int i = 0; i < 4; ++i) { ra[i] = *(const u32x4*)(Ag + (size_t)i * 64 * lda + (KT) * 64); rb[i] = *(const u32x4*)(Bg + (size_t)i * 64 * K + (KT) * 64); } } while (0)
; #define G_STORE(BUF) do { u16* ad = As + (BUF) * 256 * 64 + sto; u16* bd = Bs + (BUF) * 256 * 64 + sto; _Pragma("unroll") for (int i = 0; i < 4; ++i) { *(u32x4*)(ad + i * 64 * 64) = ra[i]; *(u32x4*)(bd + i * 64 * 64) = rb[i]; } } while (0)
; template <int EPI>
; DI void gemm_phase(const u16* __restrict__ A, int lda, const u16* __restrict__ Bt, int K, int N, u16* outb, int ldo,
;                    const float* r0, const float* r1, float* outf, char* lds, int bid, int nb) {
;     ...
;     for (int kt = 0; kt < nk; ++kt) {
;       const int cur = kt & 1;
;       if (kt + 1 < nk) G_LOAD(kt + 1);
;       G_MMA(cur, fo0);
;       G_MMA(cur, fo1);
;       if (kt + 1 < nk) G_STORE(cur ^ 1);
;       __syncthreads();
	v_mfma_f32_16x16x32_bf16 v[124:127], v[188:191], v[168:171], v[124:127]
	v_mfma_f32_16x16x32_bf16 v[120:123], v[188:191], v[176:179], v[120:123]
	v_mfma_f32_16x16x32_bf16 v[116:119], v[188:191], v[180:183], v[116:119]
	v_mfma_f32_16x16x32_bf16 v[112:115], v[188:191], v[184:187], v[112:115]
	ds_read_b128 v[188:191], v225 offset:0
	ds_read_b128 v[152:155], v227 offset:0
	v_mfma_f32_16x16x32_bf16 v[108:111], v[192:195], v[168:171], v[108:111]
	v_mfma_f32_16x16x32_bf16 v[104:107], v[192:195], v[176:179], v[104:107]
	v_mfma_f32_16x16x32_bf16 v[100:103], v[192:195], v[180:183], v[100:103]
	v_mfma_f32_16x16x32_bf16 v[96:99], v[192:195], v[184:187], v[96:99]
	ds_read_b128 v[192:195], v225 offset:2048
	ds_read_b128 v[156:159], v227 offset:2048
	v_mfma_f32_16x16x32_bf16 v[92:95], v[196:199], v[168:171], v[92:95]
	v_mfma_f32_16x16x32_bf16 v[88:91], v[196:199], v[176:179], v[88:91]
	v_mfma_f32_16x16x32_bf16 v[84:87], v[196:199], v[180:183], v[84:87]
	v_mfma_f32_16x16x32_bf16 v[80:83], v[196:199], v[184:187], v[80:83]
	ds_read_b128 v[196:199], v225 offset:4096
	ds_read_b128 v[160:163], v227 offset:4096
	v_mfma_f32_16x16x32_bf16 v[76:79], v[200:203], v[168:171], v[76:79]
	v_mfma_f32_16x16x32_bf16 v[72:75], v[200:203], v[176:179], v[72:75]
	v_mfma_f32_16x16x32_bf16 v[68:71], v[200:203], v[180:183], v[68:71]
	v_mfma_f32_16x16x32_bf16 v[64:67], v[200:203], v[184:187], v[64:67]
	ds_read_b128 v[200:203], v225 offset:6144
	ds_read_b128 v[164:167], v227 offset:6144
	v_mfma_f32_16x16x32_bf16 v[60:63], v[204:207], v[168:171], v[60:63]
	v_mfma_f32_16x16x32_bf16 v[56:59], v[204:207], v[176:179], v[56:59]
	v_mfma_f32_16x16x32_bf16 v[52:55], v[204:207], v[180:183], v[52:55]
	v_mfma_f32_16x16x32_bf16 v[48:51], v[204:207], v[184:187], v[48:51]
	ds_read_b128 v[204:207], v225 offset:8192
	ds_read_b128 v[216:219], v225 offset:14336
	v_mfma_f32_16x16x32_bf16 v[44:47], v[208:211], v[168:171], v[44:47]
	v_mfma_f32_16x16x32_bf16 v[40:43], v[208:211], v[176:179], v[40:43]
	v_mfma_f32_16x16x32_bf16 v[36:39], v[208:211], v[180:183], v[36:39]
	v_mfma_f32_16x16x32_bf16 v[32:35], v[208:211], v[184:187], v[32:35]
	ds_read_b128 v[208:211], v225 offset:10240
	v_mfma_f32_16x16x32_bf16 v[28:31], v[212:215], v[168:171], v[28:31]
	v_mfma_f32_16x16x32_bf16 v[24:27], v[212:215], v[176:179], v[24:27]
	v_mfma_f32_16x16x32_bf16 v[20:23], v[212:215], v[180:183], v[20:23]
	v_mfma_f32_16x16x32_bf16 v[16:19], v[212:215], v[184:187], v[16:19]
	ds_read_b128 v[212:215], v225 offset:12288
	v_mfma_f32_16x16x32_bf16 v[12:15], v[220:223], v[168:171], v[12:15]
	v_mfma_f32_16x16x32_bf16 v[8:11], v[220:223], v[176:179], v[8:11]
	v_mfma_f32_16x16x32_bf16 v[4:7], v[220:223], v[180:183], v[4:7]
	v_mfma_f32_16x16x32_bf16 v[0:3], v[220:223], v[184:187], v[0:3]
	v_xor_b32_e32 v226, 0x8000, v226
	v_xor_b32_e32 v228, 0x8000, v228
	s_waitcnt lgkmcnt(4)
	v_mfma_f32_16x16x32_bf16 v[124:127], v[188:191], v[152:155], v[124:127]
	v_mfma_f32_16x16x32_bf16 v[120:123], v[188:191], v[156:159], v[120:123]
	v_mfma_f32_16x16x32_bf16 v[116:119], v[188:191], v[160:163], v[116:119]
	v_mfma_f32_16x16x32_bf16 v[112:115], v[188:191], v[164:167], v[112:115]
	ds_read_b128 v[188:191], v226 offset:0
	ds_read_b128 v[168:171], v228 offset:0
	v_mfma_f32_16x16x32_bf16 v[108:111], v[192:195], v[152:155], v[108:111]
	v_mfma_f32_16x16x32_bf16 v[104:107], v[192:195], v[156:159], v[104:107]
	v_mfma_f32_16x16x32_bf16 v[100:103], v[192:195], v[160:163], v[100:103]
	v_mfma_f32_16x16x32_bf16 v[96:99], v[192:195], v[164:167], v[96:99]
	ds_read_b128 v[192:195], v226 offset:2048
	ds_read_b128 v[176:179], v228 offset:2048
	v_mfma_f32_16x16x32_bf16 v[92:95], v[196:199], v[152:155], v[92:95]
	v_mfma_f32_16x16x32_bf16 v[88:91], v[196:199], v[156:159], v[88:91]
	v_mfma_f32_16x16x32_bf16 v[84:87], v[196:199], v[160:163], v[84:87]
	v_mfma_f32_16x16x32_bf16 v[80:83], v[196:199], v[164:167], v[80:83]
	ds_read_b128 v[196:199], v226 offset:4096
	ds_read_b128 v[180:183], v228 offset:4096
	v_mfma_f32_16x16x32_bf16 v[76:79], v[200:203], v[152:155], v[76:79]
	v_mfma_f32_16x16x32_bf16 v[72:75], v[200:203], v[156:159], v[72:75]
	v_mfma_f32_16x16x32_bf16 v[68:71], v[200:203], v[160:163], v[68:71]
	v_mfma_f32_16x16x32_bf16 v[64:67], v[200:203], v[164:167], v[64:67]
	ds_read_b128 v[200:203], v226 offset:6144
	ds_read_b128 v[184:187], v228 offset:6144
	s_waitcnt lgkmcnt(11)
	v_mfma_f32_16x16x32_bf16 v[60:63], v[204:207], v[152:155], v[60:63]
	v_mfma_f32_16x16x32_bf16 v[56:59], v[204:207], v[156:159], v[56:59]
	v_mfma_f32_16x16x32_bf16 v[52:55], v[204:207], v[160:163], v[52:55]
	v_mfma_f32_16x16x32_bf16 v[48:51], v[204:207], v[164:167], v[48:51]
	ds_read_b128 v[204:207], v226 offset:8192
	ds_read_b128 v[220:223], v226 offset:14336
	s_waitcnt lgkmcnt(11)
	v_mfma_f32_16x16x32_bf16 v[44:47], v[208:211], v[152:155], v[44:47]
	v_mfma_f32_16x16x32_bf16 v[40:43], v[208:211], v[156:159], v[40:43]
	v_mfma_f32_16x16x32_bf16 v[36:39], v[208:211], v[160:163], v[36:39]
	v_mfma_f32_16x16x32_bf16 v[32:35], v[208:211], v[164:167], v[32:35]
	ds_read_b128 v[208:211], v226 offset:10240
	s_waitcnt lgkmcnt(11)
	v_mfma_f32_16x16x32_bf16 v[28:31], v[212:215], v[152:155], v[28:31]
	v_mfma_f32_16x16x32_bf16 v[24:27], v[212:215], v[156:159], v[24:27]
	v_mfma_f32_16x16x32_bf16 v[20:23], v[212:215], v[160:163], v[20:23]
	v_mfma_f32_16x16x32_bf16 v[16:19], v[212:215], v[164:167], v[16:19]
	ds_read_b128 v[212:215], v226 offset:12288
	v_mfma_f32_16x16x32_bf16 v[12:15], v[216:219], v[152:155], v[12:15]
	v_mfma_f32_16x16x32_bf16 v[8:11], v[216:219], v[156:159], v[8:11]
	v_mfma_f32_16x16x32_bf16 v[4:7], v[216:219], v[160:163], v[4:7]
	v_mfma_f32_16x16x32_bf16 v[0:3], v[216:219], v[164:167], v[0:3]
	s_waitcnt vmcnt(0) lgkmcnt(0)
	s_barrier
; DI u16 f2bf(float a) { return (u16)(pk2(a, 0.f) & 0xffffu); }
; template <int EPI>
; DI void gemm_phase(const u16* __restrict__ A, int lda, const u16* __restrict__ Bt, int K, int N, u16* outb, int ldo,
;                    const float* r0, const float* r1, float* outf, char* lds, int bid, int nb) {
;     ...
;     const int mrow = tm * 256 + wr * 128 + quad * 4;
;     if constexpr (EPI == EPI_BF16) {
;       const int col = tn * 256 + wc * 64 + l15;
; #pragma unroll
;       for (int i = 0; i < 8; ++i)
; #pragma unroll
;         for (int r = 0; r < 4; ++r) {
;           u16* o0 = outb + (size_t)(mrow + i * 16 + r) * ldo + col;
;           o0[0] = f2bf(acc[i][0][r]); o0[16] = f2bf(acc[i][1][r]); o0[32] = f2bf(acc[i][2][r]); o0[48] = f2bf(acc[i][3][r]);
;         }
	v_mfma_f32_16x16x32_bf16 v[124:127], v[188:191], v[168:171], v[124:127]
	v_mfma_f32_16x16x32_bf16 v[120:123], v[188:191], v[176:179], v[120:123]
	v_mfma_f32_16x16x32_bf16 v[116:119], v[188:191], v[180:183], v[116:119]
	v_mfma_f32_16x16x32_bf16 v[112:115], v[188:191], v[184:187], v[112:115]
	v_mfma_f32_16x16x32_bf16 v[108:111], v[192:195], v[168:171], v[108:111]
	v_mfma_f32_16x16x32_bf16 v[104:107], v[192:195], v[176:179], v[104:107]
	v_mfma_f32_16x16x32_bf16 v[100:103], v[192:195], v[180:183], v[100:103]
	v_mfma_f32_16x16x32_bf16 v[96:99], v[192:195], v[184:187], v[96:99]
	v_mfma_f32_16x16x32_bf16 v[92:95], v[196:199], v[168:171], v[92:95]
	v_mfma_f32_16x16x32_bf16 v[88:91], v[196:199], v[176:179], v[88:91]
	v_mfma_f32_16x16x32_bf16 v[84:87], v[196:199], v[180:183], v[84:87]
	v_mfma_f32_16x16x32_bf16 v[80:83], v[196:199], v[184:187], v[80:83]
	v_mfma_f32_16x16x32_bf16 v[76:79], v[200:203], v[168:171], v[76:79]
	v_mfma_f32_16x16x32_bf16 v[72:75], v[200:203], v[176:179], v[72:75]
	v_mfma_f32_16x16x32_bf16 v[68:71], v[200:203], v[180:183], v[68:71]
	v_mfma_f32_16x16x32_bf16 v[64:67], v[200:203], v[184:187], v[64:67]
	v_mfma_f32_16x16x32_bf16 v[60:63], v[204:207], v[168:171], v[60:63]
	v_mfma_f32_16x16x32_bf16 v[56:59], v[204:207], v[176:179], v[56:59]
	v_mfma_f32_16x16x32_bf16 v[52:55], v[204:207], v[180:183], v[52:55]
	v_mfma_f32_16x16x32_bf16 v[48:51], v[204:207], v[184:187], v[48:51]
	v_mfma_f32_16x16x32_bf16 v[44:47], v[208:211], v[168:171], v[44:47]
	v_mfma_f32_16x16x32_bf16 v[40:43], v[208:211], v[176:179], v[40:43]
	v_mfma_f32_16x16x32_bf16 v[36:39], v[208:211], v[180:183], v[36:39]
	v_mfma_f32_16x16x32_bf16 v[32:35], v[208:211], v[184:187], v[32:35]
	v_mfma_f32_16x16x32_bf16 v[28:31], v[212:215], v[168:171], v[28:31]
	v_mfma_f32_16x16x32_bf16 v[24:27], v[212:215], v[176:179], v[24:27]
	v_mfma_f32_16x16x32_bf16 v[20:23], v[212:215], v[180:183], v[20:23]
	v_mfma_f32_16x16x32_bf16 v[16:19], v[212:215], v[184:187], v[16:19]
	v_mfma_f32_16x16x32_bf16 v[12:15], v[220:223], v[168:171], v[12:15]
	v_mfma_f32_16x16x32_bf16 v[8:11], v[220:223], v[176:179], v[8:11]
	v_mfma_f32_16x16x32_bf16 v[4:7], v[220:223], v[180:183], v[4:7]
	v_mfma_f32_16x16x32_bf16 v[0:3], v[220:223], v[184:187], v[0:3]
	s_nop 7
	s_nop 3
	v_mov_b32_e32 v164, v48
	v_mov_b32_e32 v165, v49
	v_mov_b32_e32 v166, v50
	v_mov_b32_e32 v167, v51
	v_or_b32_e32 v48, s49, v144
	v_ashrrev_i32_e32 v49, 31, v48
	v_add_u32_e32 v134, s48, v143
	v_lshl_add_u64 v[48:49], v[48:49], 1, s[8:9]
	v_mad_i64_i32 v[50:51], s[14:15], v134, s47, v[48:49]
	v_cvt_pk_bf16_f32 v124, v124, s0
	v_cvt_pk_bf16_f32 v120, v120, s0
	v_cvt_pk_bf16_f32 v116, v116, s0
	v_cvt_pk_bf16_f32 v112, v112, s0
	global_store_short v[50:51], v124, off
	global_store_short v[50:51], v120, off offset:32
	global_store_short v[50:51], v116, off offset:64
	global_store_short v[50:51], v112, off offset:96
	v_or_b32_e32 v50, 1, v134
	v_mad_i64_i32 v[50:51], s[14:15], v50, s47, v[48:49]
	v_cvt_pk_bf16_f32 v112, v125, s0
	global_store_short v[50:51], v112, off
	v_cvt_pk_bf16_f32 v112, v121, s0
	global_store_short v[50:51], v112, off offset:32
	v_cvt_pk_bf16_f32 v112, v117, s0
	global_store_short v[50:51], v112, off offset:64
	v_cvt_pk_bf16_f32 v112, v113, s0
	global_store_short v[50:51], v112, off offset:96
	v_or_b32_e32 v50, 2, v134
	v_mad_i64_i32 v[50:51], s[14:15], v50, s47, v[48:49]
	v_cvt_pk_bf16_f32 v112, v126, s0
	global_store_short v[50:51], v112, off
	v_cvt_pk_bf16_f32 v112, v122, s0
	global_store_short v[50:51], v112, off offset:32
	v_cvt_pk_bf16_f32 v112, v118, s0
	global_store_short v[50:51], v112, off offset:64
	v_cvt_pk_bf16_f32 v112, v114, s0
	global_store_short v[50:51], v112, off offset:96
	v_or_b32_e32 v50, 3, v134
	v_mad_i64_i32 v[50:51], s[14:15], v50, s47, v[48:49]
	v_cvt_pk_bf16_f32 v112, v127, s0
	global_store_short v[50:51], v112, off
	v_cvt_pk_bf16_f32 v112, v123, s0
	global_store_short v[50:51], v112, off offset:32
	v_cvt_pk_bf16_f32 v112, v119, s0
	global_store_short v[50:51], v112, off offset:64
	v_cvt_pk_bf16_f32 v112, v115, s0
	global_store_short v[50:51], v112, off offset:96
	v_or_b32_e32 v50, 16, v134
	v_mad_i64_i32 v[50:51], s[14:15], v50, s47, v[48:49]
	v_cvt_pk_bf16_f32 v108, v108, s0
	v_cvt_pk_bf16_f32 v104, v104, s0
	v_cvt_pk_bf16_f32 v100, v100, s0
	v_cvt_pk_bf16_f32 v96, v96, s0
	global_store_short v[50:51], v108, off
	global_store_short v[50:51], v104, off offset:32
	global_store_short v[50:51], v100, off offset:64
	global_store_short v[50:51], v96, off offset:96
	v_or_b32_e32 v50, 17, v134
	v_mad_i64_i32 v[50:51], s[14:15], v50, s47, v[48:49]
	v_cvt_pk_bf16_f32 v96, v109, s0
	global_store_short v[50:51], v96, off
	v_cvt_pk_bf16_f32 v96, v105, s0
	global_store_short v[50:51], v96, off offset:32
	v_cvt_pk_bf16_f32 v96, v101, s0
	global_store_short v[50:51], v96, off offset:64
	v_cvt_pk_bf16_f32 v96, v97, s0
	global_store_short v[50:51], v96, off offset:96
	v_or_b32_e32 v50, 18, v134
	v_mad_i64_i32 v[50:51], s[14:15], v50, s47, v[48:49]
	v_cvt_pk_bf16_f32 v96, v110, s0
	global_store_short v[50:51], v96, off
	v_cvt_pk_bf16_f32 v96, v106, s0
	global_store_short v[50:51], v96, off offset:32
	v_cvt_pk_bf16_f32 v96, v102, s0
	global_store_short v[50:51], v96, off offset:64
	v_cvt_pk_bf16_f32 v96, v98, s0
	global_store_short v[50:51], v96, off offset:96
	v_or_b32_e32 v50, 19, v134
	v_mad_i64_i32 v[50:51], s[14:15], v50, s47, v[48:49]
	v_cvt_pk_bf16_f32 v96, v111, s0
	global_store_short v[50:51], v96, off
	v_cvt_pk_bf16_f32 v96, v107, s0
	global_store_short v[50:51], v96, off offset:32
	v_cvt_pk_bf16_f32 v96, v103, s0
	global_store_short v[50:51], v96, off offset:64
	v_cvt_pk_bf16_f32 v96, v99, s0
; DI u16 f2bf(float a) { return (u16)(pk2(a, 0.f) & 0xffffu); }
; template <int EPI>
; DI void gemm_phase(const u16* __restrict__ A, int lda, const u16* __restrict__ Bt, int K, int N, u16* outb, int ldo,
;                    const float* r0, const float* r1, float* outf, char* lds, int bid, int nb) {
;     ...
;       for (int i = 0; i < 8; ++i)
; #pragma unroll
;         for (int r = 0; r < 4; ++r) {
;           u16* o0 = outb + (size_t)(mrow + i * 16 + r) * ldo + col;
;           o0[0] = f2bf(acc[i][0][r]); o0[16] = f2bf(acc[i][1][r]); o0[32] = f2bf(acc[i][2][r]); o0[48] = f2bf(acc[i][3][r]);
;         }
	global_store_short v[50:51], v96, off offset:96
	v_or_b32_e32 v50, 32, v134
	v_mad_i64_i32 v[50:51], s[14:15], v50, s47, v[48:49]
	v_cvt_pk_bf16_f32 v92, v92, s0
	v_cvt_pk_bf16_f32 v88, v88, s0
	v_cvt_pk_bf16_f32 v84, v84, s0
	v_cvt_pk_bf16_f32 v80, v80, s0
	global_store_short v[50:51], v92, off
	global_store_short v[50:51], v88, off offset:32
	global_store_short v[50:51], v84, off offset:64
	global_store_short v[50:51], v80, off offset:96
	v_or_b32_e32 v50, 33, v134
	v_mad_i64_i32 v[50:51], s[14:15], v50, s47, v[48:49]
	v_cvt_pk_bf16_f32 v80, v93, s0
	global_store_short v[50:51], v80, off
	v_cvt_pk_bf16_f32 v80, v89, s0
	global_store_short v[50:51], v80, off offset:32
	v_cvt_pk_bf16_f32 v80, v85, s0
	global_store_short v[50:51], v80, off offset:64
	v_cvt_pk_bf16_f32 v80, v81, s0
	global_store_short v[50:51], v80, off offset:96
	v_or_b32_e32 v50, 34, v134
	v_mad_i64_i32 v[50:51], s[14:15], v50, s47, v[48:49]
	v_cvt_pk_bf16_f32 v80, v94, s0
	global_store_short v[50:51], v80, off
	v_cvt_pk_bf16_f32 v80, v90, s0
	global_store_short v[50:51], v80, off offset:32
	v_cvt_pk_bf16_f32 v80, v86, s0
	global_store_short v[50:51], v80, off offset:64
	v_cvt_pk_bf16_f32 v80, v82, s0
	global_store_short v[50:51], v80, off offset:96
	v_or_b32_e32 v50, 35, v134
	v_mad_i64_i32 v[50:51], s[14:15], v50, s47, v[48:49]
	v_cvt_pk_bf16_f32 v80, v95, s0
	global_store_short v[50:51], v80, off
	v_cvt_pk_bf16_f32 v80, v91, s0
	global_store_short v[50:51], v80, off offset:32
	v_cvt_pk_bf16_f32 v80, v87, s0
	global_store_short v[50:51], v80, off offset:64
	v_cvt_pk_bf16_f32 v80, v83, s0
	global_store_short v[50:51], v80, off offset:96
	v_or_b32_e32 v50, 48, v134
	v_mad_i64_i32 v[50:51], s[14:15], v50, s47, v[48:49]
	v_cvt_pk_bf16_f32 v76, v76, s0
	v_cvt_pk_bf16_f32 v72, v72, s0
	v_cvt_pk_bf16_f32 v68, v68, s0
	v_cvt_pk_bf16_f32 v64, v64, s0
	global_store_short v[50:51], v76, off
	global_store_short v[50:51], v72, off offset:32
	global_store_short v[50:51], v68, off offset:64
	global_store_short v[50:51], v64, off offset:96
	v_or_b32_e32 v50, 49, v134
	v_mad_i64_i32 v[50:51], s[14:15], v50, s47, v[48:49]
	v_cvt_pk_bf16_f32 v64, v77, s0
	global_store_short v[50:51], v64, off
	v_cvt_pk_bf16_f32 v64, v73, s0
	global_store_short v[50:51], v64, off offset:32
	v_cvt_pk_bf16_f32 v64, v69, s0
	global_store_short v[50:51], v64, off offset:64
	v_cvt_pk_bf16_f32 v64, v65, s0
	global_store_short v[50:51], v64, off offset:96
	v_or_b32_e32 v50, 50, v134
	v_mad_i64_i32 v[50:51], s[14:15], v50, s47, v[48:49]
	v_cvt_pk_bf16_f32 v64, v78, s0
	global_store_short v[50:51], v64, off
	v_cvt_pk_bf16_f32 v64, v74, s0
	global_store_short v[50:51], v64, off offset:32
	v_cvt_pk_bf16_f32 v64, v70, s0
	global_store_short v[50:51], v64, off offset:64
	v_cvt_pk_bf16_f32 v64, v66, s0
	global_store_short v[50:51], v64, off offset:96
	v_or_b32_e32 v50, 51, v134
	v_mad_i64_i32 v[50:51], s[14:15], v50, s47, v[48:49]
	v_cvt_pk_bf16_f32 v64, v79, s0
	global_store_short v[50:51], v64, off
	v_cvt_pk_bf16_f32 v64, v75, s0
	global_store_short v[50:51], v64, off offset:32
	v_cvt_pk_bf16_f32 v64, v71, s0
	global_store_short v[50:51], v64, off offset:64
	v_cvt_pk_bf16_f32 v64, v67, s0
	global_store_short v[50:51], v64, off offset:96
	v_or_b32_e32 v50, 64, v134
	v_mad_i64_i32 v[50:51], s[14:15], v50, s47, v[48:49]
	v_cvt_pk_bf16_f32 v52, v52, s0
	v_cvt_pk_bf16_f32 v60, v60, s0
	v_cvt_pk_bf16_f32 v56, v56, s0
	global_store_short v[50:51], v52, off offset:64
	v_cvt_pk_bf16_f32 v52, v164, s0
	global_store_short v[50:51], v60, off
	global_store_short v[50:51], v56, off offset:32
	global_store_short v[50:51], v52, off offset:96
	v_or_b32_e32 v50, 0x41, v134
	v_mad_i64_i32 v[50:51], s[14:15], v50, s47, v[48:49]
	v_cvt_pk_bf16_f32 v52, v61, s0
	global_store_short v[50:51], v52, off
	v_cvt_pk_bf16_f32 v52, v57, s0
	global_store_short v[50:51], v52, off offset:32
	v_cvt_pk_bf16_f32 v52, v53, s0
	global_store_short v[50:51], v52, off offset:64
	v_cvt_pk_bf16_f32 v52, v165, s0
	global_store_short v[50:51], v52, off offset:96
	v_or_b32_e32 v50, 0x42, v134
	v_mad_i64_i32 v[50:51], s[14:15], v50, s47, v[48:49]
	v_cvt_pk_bf16_f32 v52, v62, s0
	global_store_short v[50:51], v52, off
	v_cvt_pk_bf16_f32 v52, v58, s0
	global_store_short v[50:51], v52, off offset:32
	v_cvt_pk_bf16_f32 v52, v54, s0
	global_store_short v[50:51], v52, off offset:64
	v_cvt_pk_bf16_f32 v52, v166, s0
	global_store_short v[50:51], v52, off offset:96
	v_or_b32_e32 v50, 0x43, v134
	v_mad_i64_i32 v[50:51], s[14:15], v50, s47, v[48:49]
	v_cvt_pk_bf16_f32 v52, v63, s0
	global_store_short v[50:51], v52, off
	v_cvt_pk_bf16_f32 v52, v59, s0
	global_store_short v[50:51], v52, off offset:32
	v_cvt_pk_bf16_f32 v52, v55, s0
	global_store_short v[50:51], v52, off offset:64
	v_cvt_pk_bf16_f32 v52, v167, s0
	global_store_short v[50:51], v52, off offset:96
; DI u16 f2bf(float a) { return (u16)(pk2(a, 0.f) & 0xffffu); }
; template <int EPI>
; DI void gemm_phase(const u16* __restrict__ A, int lda, const u16* __restrict__ Bt, int K, int N, u16* outb, int ldo,
;                    const float* r0, const float* r1, float* outf, char* lds, int bid, int nb) {
;     ...
;       for (int i = 0; i < 8; ++i)
; #pragma unroll
;         for (int r = 0; r < 4; ++r) {
;           u16* o0 = outb + (size_t)(mrow + i * 16 + r) * ldo + col;
;           o0[0] = f2bf(acc[i][0][r]); o0[16] = f2bf(acc[i][1][r]); o0[32] = f2bf(acc[i][2][r]); o0[48] = f2bf(acc[i][3][r]);
;         }
	v_or_b32_e32 v50, 0x50, v134
	v_mad_i64_i32 v[50:51], s[14:15], v50, s47, v[48:49]
	v_cvt_pk_bf16_f32 v32, v32, s0
	v_cvt_pk_bf16_f32 v44, v44, s0
	v_cvt_pk_bf16_f32 v40, v40, s0
	v_cvt_pk_bf16_f32 v36, v36, s0
	global_store_short v[50:51], v32, off offset:96
	v_or_b32_e32 v32, 0x51, v134
	global_store_short v[50:51], v44, off
	global_store_short v[50:51], v40, off offset:32
	global_store_short v[50:51], v36, off offset:64
	v_mad_i64_i32 v[50:51], s[14:15], v32, s47, v[48:49]
	v_cvt_pk_bf16_f32 v32, v45, s0
	global_store_short v[50:51], v32, off
	v_cvt_pk_bf16_f32 v32, v41, s0
	global_store_short v[50:51], v32, off offset:32
	v_cvt_pk_bf16_f32 v32, v37, s0
	global_store_short v[50:51], v32, off offset:64
	v_cvt_pk_bf16_f32 v32, v33, s0
	global_store_short v[50:51], v32, off offset:96
	v_or_b32_e32 v32, 0x52, v134
	v_mad_i64_i32 v[32:33], s[14:15], v32, s47, v[48:49]
	v_cvt_pk_bf16_f32 v36, v46, s0
	global_store_short v[32:33], v36, off
	v_cvt_pk_bf16_f32 v36, v42, s0
	global_store_short v[32:33], v36, off offset:32
	v_cvt_pk_bf16_f32 v36, v38, s0
	v_cvt_pk_bf16_f32 v34, v34, s0
	global_store_short v[32:33], v36, off offset:64
	global_store_short v[32:33], v34, off offset:96
	v_or_b32_e32 v32, 0x53, v134
	v_mad_i64_i32 v[32:33], s[14:15], v32, s47, v[48:49]
	v_cvt_pk_bf16_f32 v34, v47, s0
	global_store_short v[32:33], v34, off
	v_cvt_pk_bf16_f32 v34, v43, s0
	global_store_short v[32:33], v34, off offset:32
	v_cvt_pk_bf16_f32 v34, v39, s0
	global_store_short v[32:33], v34, off offset:64
	v_cvt_pk_bf16_f32 v34, v35, s0
	global_store_short v[32:33], v34, off offset:96
	v_or_b32_e32 v32, 0x60, v134
	v_mad_i64_i32 v[32:33], s[14:15], v32, s47, v[48:49]
	v_cvt_pk_bf16_f32 v16, v16, s0
	v_cvt_pk_bf16_f32 v28, v28, s0
	v_cvt_pk_bf16_f32 v24, v24, s0
	v_cvt_pk_bf16_f32 v20, v20, s0
	global_store_short v[32:33], v16, off offset:96
	v_or_b32_e32 v16, 0x61, v134
	global_store_short v[32:33], v28, off
	global_store_short v[32:33], v24, off offset:32
	global_store_short v[32:33], v20, off offset:64
	v_mad_i64_i32 v[32:33], s[14:15], v16, s47, v[48:49]
	v_cvt_pk_bf16_f32 v16, v29, s0
	global_store_short v[32:33], v16, off
	v_cvt_pk_bf16_f32 v16, v25, s0
	global_store_short v[32:33], v16, off offset:32
	v_cvt_pk_bf16_f32 v16, v21, s0
	global_store_short v[32:33], v16, off offset:64
	v_cvt_pk_bf16_f32 v16, v17, s0
	global_store_short v[32:33], v16, off offset:96
	v_or_b32_e32 v16, 0x62, v134
	v_mad_i64_i32 v[16:17], s[14:15], v16, s47, v[48:49]
	v_cvt_pk_bf16_f32 v20, v30, s0
	global_store_short v[16:17], v20, off
	v_cvt_pk_bf16_f32 v20, v26, s0
	global_store_short v[16:17], v20, off offset:32
	v_cvt_pk_bf16_f32 v20, v22, s0
	v_cvt_pk_bf16_f32 v18, v18, s0
	global_store_short v[16:17], v20, off offset:64
	global_store_short v[16:17], v18, off offset:96
	v_or_b32_e32 v16, 0x63, v134
	v_mad_i64_i32 v[16:17], s[14:15], v16, s47, v[48:49]
	v_cvt_pk_bf16_f32 v18, v31, s0
	global_store_short v[16:17], v18, off
	v_cvt_pk_bf16_f32 v18, v27, s0
	global_store_short v[16:17], v18, off offset:32
	v_cvt_pk_bf16_f32 v18, v23, s0
	global_store_short v[16:17], v18, off offset:64
	v_cvt_pk_bf16_f32 v18, v19, s0
	global_store_short v[16:17], v18, off offset:96
	v_or_b32_e32 v16, 0x70, v134
	v_mad_i64_i32 v[16:17], s[14:15], v16, s47, v[48:49]
	v_cvt_pk_bf16_f32 v0, v0, s0
	v_cvt_pk_bf16_f32 v12, v12, s0
	v_cvt_pk_bf16_f32 v8, v8, s0
	v_cvt_pk_bf16_f32 v4, v4, s0
	global_store_short v[16:17], v0, off offset:96
	v_or_b32_e32 v0, 0x71, v134
	global_store_short v[16:17], v12, off
	global_store_short v[16:17], v8, off offset:32
	global_store_short v[16:17], v4, off offset:64
	v_mad_i64_i32 v[16:17], s[14:15], v0, s47, v[48:49]
	v_cvt_pk_bf16_f32 v0, v13, s0
	global_store_short v[16:17], v0, off
	v_cvt_pk_bf16_f32 v0, v9, s0
	global_store_short v[16:17], v0, off offset:32
	v_cvt_pk_bf16_f32 v0, v5, s0
	global_store_short v[16:17], v0, off offset:64
	v_cvt_pk_bf16_f32 v0, v1, s0
	global_store_short v[16:17], v0, off offset:96
	v_or_b32_e32 v0, 0x72, v134
	v_mad_i64_i32 v[0:1], s[14:15], v0, s47, v[48:49]
	v_cvt_pk_bf16_f32 v4, v14, s0
	global_store_short v[0:1], v4, off
	v_cvt_pk_bf16_f32 v4, v10, s0
	global_store_short v[0:1], v4, off offset:32
	v_cvt_pk_bf16_f32 v4, v6, s0
	v_cvt_pk_bf16_f32 v2, v2, s0
	global_store_short v[0:1], v4, off offset:64
	global_store_short v[0:1], v2, off offset:96
	v_or_b32_e32 v0, 0x73, v134
	v_mad_i64_i32 v[0:1], s[14:15], v0, s47, v[48:49]
	v_cvt_pk_bf16_f32 v2, v15, s0
	global_store_short v[0:1], v2, off
	v_cvt_pk_bf16_f32 v2, v11, s0
	global_store_short v[0:1], v2, off offset:32
	v_cvt_pk_bf16_f32 v2, v7, s0
	s_add_i32 s18, s18, 1
	global_store_short v[0:1], v2, off offset:64
	v_cvt_pk_bf16_f32 v2, v3, s0
	s_cmp_eq_u32 s18, s3
	global_store_short v[0:1], v2, off offset:96
	s_cbranch_scc0 .LBB0_879

; #define G_LOAD(KT) do { _Pragma("unroll") for (int i = 0; i < 4; ++i) { ra[i] = *(const u32x4*)(Ag + (size_t)i * 64 * lda + (KT) * 64); rb[i] = *(const u32x4*)(Bg + (size_t)i * 64 * K + (KT) * 64); } } while (0)
; #define G_STORE(BUF) do { u16* ad = As + (BUF) * 256 * 64 + sto; u16* bd = Bs + (BUF) * 256 * 64 + sto; _Pragma("unroll") for (int i = 0; i < 4; ++i) { *(u32x4*)(ad + i * 64 * 64) = ra[i]; *(u32x4*)(bd + i * 64 * 64) = rb[i]; } } while (0)
; template <int EPI>
; DI void gemm_phase(const u16* __restrict__ A, int lda, const u16* __restrict__ Bt, int K, int N, u16* outb, int ldo,
;                    const float* r0, const float* r1, float* outf, char* lds, int bid, int nb) {
;     ...
;   for (int it = 0; it < nIter; ++it) {
;     int tm, tn;
;     if (swz) { const int st = xcd + 8 * it, sm = st / nSN, sn = st - sm * nSN; tm = sm * GM + jb / GN; tn = sn * GN + (jb % GN); }
;     else { const int t = bid + it * nb; tm = t / nN; tn = t - tm * nN; }
;     const u16* Ag = A + (size_t)(tm * 256 + lrow) * lda + lch * 8;
;     const u16* Bg = Bt + (size_t)(tn * 256 + lrow) * K + lch * 8;
;     f32x4 acc[8][4];
; #pragma unroll
;     for (int i = 0; i < 8; ++i)
; #pragma unroll
;       for (int j = 0; j < 4; ++j) acc[i][j] = (f32x4){0.f, 0.f, 0.f, 0.f};
;     u32x4 ra[4], rb[4];
;     ...
;     G_LOAD(0);
;     G_STORE(0);
;     __syncthreads();
.LBB0_1181:
	s_lshl_b32 s39, s39, 8
	v_or_b32_e32 v0, s39, v138
	v_ashrrev_i32_e32 v1, 31, v0
	s_lshl_b32 s40, s40, 8
	v_or_b32_e32 v2, s40, v138
	v_lshlrev_b64 v[62:63], 11, v[0:1]
	v_ashrrev_i32_e32 v3, 31, v2
	v_lshl_add_u64 v[0:1], v[128:129], 0, v[62:63]
	v_lshlrev_b64 v[64:65], 11, v[2:3]
	v_add_co_u32_e32 v4, vcc, s15, v0
	v_lshl_add_u64 v[2:3], v[130:131], 0, v[64:65]
	s_nop 0
	v_addc_co_u32_e32 v5, vcc, 0, v1, vcc
	v_add_co_u32_e32 v6, vcc, s15, v2
	s_nop 1
	v_readfirstlane_b32 s98, v0
	v_readfirstlane_b32 s99, v1
	s_nop 1
	v_readfirstlane_b32 s100, v2
	v_readfirstlane_b32 s101, v3
	v_addc_co_u32_e32 v7, vcc, 0, v3, vcc
	v_add_co_u32_e32 v4, vcc, s16, v0
	s_mov_b32 s41, 0
	s_nop 0
	v_addc_co_u32_e32 v5, vcc, 0, v1, vcc
	v_add_co_u32_e32 v6, vcc, s16, v2
	s_mov_b64 s[8:9], 0
	s_nop 0
	v_addc_co_u32_e32 v7, vcc, 0, v3, vcc
	v_add_co_u32_e32 v0, vcc, s17, v0
	v_addc_co_u32_e32 v1, vcc, 0, v1, vcc
	v_add_co_u32_e32 v2, vcc, s17, v2
	v_lshl_add_u64 v[134:135], v[132:133], 0, v[62:63]
	s_nop 0
	v_addc_co_u32_e32 v3, vcc, 0, v3, vcc
	v_mov_b32_e32 v0, 0
	v_mov_b32_e32 v1, v0
	v_mov_b32_e32 v2, v0
	v_mov_b32_e32 v3, v0
	v_mov_b32_e32 v4, v0
	v_mov_b32_e32 v5, v0
	v_mov_b32_e32 v6, v0
	v_mov_b32_e32 v7, v0
	v_mov_b32_e32 v8, v0
	v_mov_b32_e32 v9, v0
	v_mov_b32_e32 v10, v0
	v_mov_b32_e32 v11, v0
	v_mov_b32_e32 v12, v0
	v_mov_b32_e32 v13, v0
	v_mov_b32_e32 v14, v0
	v_mov_b32_e32 v15, v0
	v_mov_b32_e32 v16, v0
	v_mov_b32_e32 v17, v0
	v_mov_b32_e32 v18, v0
	v_mov_b32_e32 v19, v0
	v_mov_b32_e32 v20, v0
	v_mov_b32_e32 v21, v0
	v_mov_b32_e32 v22, v0
	v_mov_b32_e32 v23, v0
	v_mov_b32_e32 v24, v0
	v_mov_b32_e32 v25, v0
	v_mov_b32_e32 v26, v0
	v_mov_b32_e32 v27, v0
	v_mov_b32_e32 v28, v0
	v_mov_b32_e32 v29, v0
	v_lshl_add_u64 v[136:137], v[132:133], 0, v[64:65]
	v_mov_b32_e32 v62, v0
	v_mov_b32_e32 v63, v0
	v_mov_b32_e32 v64, v0
	v_mov_b32_e32 v65, v0
	v_mov_b32_e32 v66, v0
	v_mov_b32_e32 v67, v0
	v_mov_b32_e32 v68, v0
	v_mov_b32_e32 v69, v0
	v_mov_b32_e32 v70, v0
	v_mov_b32_e32 v71, v0
	v_mov_b32_e32 v72, v0
	v_mov_b32_e32 v73, v0
	v_mov_b32_e32 v74, v0
	v_mov_b32_e32 v75, v0
	v_mov_b32_e32 v76, v0
	v_mov_b32_e32 v77, v0
	v_mov_b32_e32 v78, v0
	v_mov_b32_e32 v79, v0
	v_mov_b32_e32 v80, v0
	v_mov_b32_e32 v81, v0
	v_mov_b32_e32 v82, v0
	v_mov_b32_e32 v83, v0
	v_mov_b32_e32 v84, v0
	v_mov_b32_e32 v85, v0
	v_mov_b32_e32 v30, v0
	v_mov_b32_e32 v31, v0
	v_mov_b32_e32 v32, v0
	v_mov_b32_e32 v33, v0
	v_mov_b32_e32 v34, v0
	v_mov_b32_e32 v35, v0
	v_mov_b32_e32 v36, v0
	v_mov_b32_e32 v37, v0
	v_mov_b32_e32 v38, v0
	v_mov_b32_e32 v39, v0
	v_mov_b32_e32 v40, v0
	v_mov_b32_e32 v41, v0
	v_mov_b32_e32 v42, v0
	v_mov_b32_e32 v43, v0
	v_mov_b32_e32 v44, v0
	v_mov_b32_e32 v45, v0
	v_mov_b32_e32 v46, v0
	v_mov_b32_e32 v47, v0
	v_mov_b32_e32 v48, v0
	v_mov_b32_e32 v49, v0
	v_mov_b32_e32 v50, v0
	v_mov_b32_e32 v51, v0
	v_mov_b32_e32 v52, v0
	v_mov_b32_e32 v53, v0
	v_mov_b32_e32 v54, v0
	v_mov_b32_e32 v55, v0
	v_mov_b32_e32 v56, v0
	v_mov_b32_e32 v57, v0
	v_mov_b32_e32 v58, v0
	v_mov_b32_e32 v59, v0
	v_mov_b32_e32 v60, v0
	v_mov_b32_e32 v61, v0
	v_mov_b32_e32 v86, v0
	v_mov_b32_e32 v87, v0
	v_mov_b32_e32 v88, v0
	v_mov_b32_e32 v89, v0
	v_mov_b32_e32 v90, v0
	v_mov_b32_e32 v91, v0
	v_mov_b32_e32 v92, v0
	v_mov_b32_e32 v93, v0
	v_mov_b32_e32 v94, v0
	v_mov_b32_e32 v95, v0
	v_mov_b32_e32 v96, v0
	v_mov_b32_e32 v97, v0
	v_mov_b32_e32 v98, v0
	v_mov_b32_e32 v99, v0
	v_mov_b32_e32 v100, v0
	v_mov_b32_e32 v101, v0
	v_mov_b32_e32 v102, v0
	v_mov_b32_e32 v103, v0
	v_mov_b32_e32 v104, v0
	v_mov_b32_e32 v105, v0
	v_mov_b32_e32 v106, v0
	v_mov_b32_e32 v107, v0
	v_mov_b32_e32 v108, v0
	v_mov_b32_e32 v109, v0
	v_mov_b32_e32 v110, v0
	v_mov_b32_e32 v111, v0
	v_mov_b32_e32 v112, v0
	v_mov_b32_e32 v113, v0
	v_mov_b32_e32 v114, v0
	v_mov_b32_e32 v115, v0
	v_mov_b32_e32 v116, v0
	v_mov_b32_e32 v117, v0
	v_mov_b32_e32 v118, v0
	v_mov_b32_e32 v119, v0
	v_mov_b32_e32 v120, v0
	v_mov_b32_e32 v121, v0
	v_mov_b32_e32 v122, v0
	v_mov_b32_e32 v123, v0
	v_mov_b32_e32 v124, v0
	v_mov_b32_e32 v125, v0
	v_mov_b32_e32 v126, v0
	v_mov_b32_e32 v127, v0
	v_and_b32_e32 v229, 63, v174
	v_lshrrev_b32_e32 v230, 3, v229
	v_mov_b32_e32 v233, 0x800
	v_mul_u32_u24_e32 v224, v230, v233
	v_bfe_u32 v231, v174, 4, 2
	v_bfe_u32 v232, v174, 6, 1
	v_lshl_or_b32 v232, v232, 2, v231
	v_and_b32_e32 v233, 7, v174
	v_xor_b32_e32 v232, v232, v233
	v_lshl_add_u32 v224, v232, 4, v224
	v_and_b32_e32 v229, 15, v174
	v_bfe_u32 v230, v174, 1, 3
	v_xor_b32_e32 v230, v230, v231
	v_lshlrev_b32_e32 v230, 4, v230
	v_lshl_or_b32 v230, v229, 7, v230
	v_lshrrev_b32_e32 v229, 8, v174
	v_lshl_or_b32 v225, v229, 14, v230
	v_bfe_u32 v229, v174, 6, 2
	v_lshl_or_b32 v227, v229, 13, v230
	v_or_b32_e32 v227, 0x10000, v227
	v_xor_b32_e32 v226, 64, v225
	v_xor_b32_e32 v228, 64, v227
	v_readfirstlane_b32 s97, v174
	s_lshl_b32 s97, s97, 4
	s_mov_b32 s28, 14
	s_add_u32 s8, s98, 0x0
	s_addc_u32 s9, s99, 0
	s_add_u32 m0, s97, 0x0
	s_nop 0
	global_load_lds_dwordx4 v224, s[8:9]
	s_add_u32 s8, s100, 0x0
	s_addc_u32 s9, s101, 0
	s_add_u32 m0, s97, 0x10000
	s_nop 0
	global_load_lds_dwordx4 v224, s[8:9]
	s_add_u32 s8, s98, 0x20000
	s_addc_u32 s9, s99, 0
	s_add_u32 m0, s97, 0x2000
	s_nop 0
	global_load_lds_dwordx4 v224, s[8:9]
	s_add_u32 s8, s100, 0x20000
	s_addc_u32 s9, s101, 0
	s_add_u32 m0, s97, 0x12000
	s_nop 0
	global_load_lds_dwordx4 v224, s[8:9]
	s_add_u32 s8, s98, 0x40000
	s_addc_u32 s9, s99, 0
	s_add_u32 m0, s97, 0x4000
	s_nop 0
	global_load_lds_dwordx4 v224, s[8:9]
	s_add_u32 s8, s100, 0x40000
	s_addc_u32 s9, s101, 0
	s_add_u32 m0, s97, 0x14000
	s_nop 0
	global_load_lds_dwordx4 v224, s[8:9]
	s_add_u32 s8, s98, 0x60000
	s_addc_u32 s9, s99, 0
	s_add_u32 m0, s97, 0x6000
	s_nop 0
	global_load_lds_dwordx4 v224, s[8:9]
	s_add_u32 s8, s100, 0x60000
	s_addc_u32 s9, s101, 0
	s_add_u32 m0, s97, 0x16000
	s_nop 0
	global_load_lds_dwordx4 v224, s[8:9]
	s_add_u32 s8, s98, 0x80
	s_addc_u32 s9, s99, 0
	s_add_u32 m0, s97, 0x8000
	s_nop 0
	global_load_lds_dwordx4 v224, s[8:9]
	s_add_u32 s8, s100, 0x80
	s_addc_u32 s9, s101, 0
	s_add_u32 m0, s97, 0x18000
	s_nop 0
	global_load_lds_dwordx4 v224, s[8:9]
	s_add_u32 s8, s98, 0x20080
	s_addc_u32 s9, s99, 0
	s_add_u32 m0, s97, 0xa000
	s_nop 0
	global_load_lds_dwordx4 v224, s[8:9]
	s_add_u32 s8, s100, 0x20080
	s_addc_u32 s9, s101, 0
	s_add_u32 m0, s97, 0x1a000
	s_nop 0
	global_load_lds_dwordx4 v224, s[8:9]
	s_add_u32 s8, s98, 0x40080
	s_addc_u32 s9, s99, 0
	s_add_u32 m0, s97, 0xc000
	s_nop 0
	global_load_lds_dwordx4 v224, s[8:9]
	s_add_u32 s8, s100, 0x40080
	s_addc_u32 s9, s101, 0
	s_add_u32 m0, s97, 0x1c000
	s_nop 0
	global_load_lds_dwordx4 v224, s[8:9]
	s_add_u32 s8, s98, 0x60080
	s_addc_u32 s9, s99, 0
	s_add_u32 m0, s97, 0xe000
	s_nop 0
	global_load_lds_dwordx4 v224, s[8:9]
	s_add_u32 s8, s100, 0x60080
	s_addc_u32 s9, s101, 0
	s_add_u32 m0, s97, 0x1e000
	s_nop 0
	global_load_lds_dwordx4 v224, s[8:9]
	s_add_u32 s98, s98, 0x100
	s_addc_u32 s99, s99, 0
	s_add_u32 s100, s100, 0x100
	s_addc_u32 s101, s101, 0
	s_waitcnt vmcnt(8)
	s_barrier
; #define G_LOAD(KT) do { _Pragma("unroll") for (int i = 0; i < 4; ++i) { ra[i] = *(const u32x4*)(Ag + (size_t)i * 64 * lda + (KT) * 64); rb[i] = *(const u32x4*)(Bg + (size_t)i * 64 * K + (KT) * 64); } } while (0)
; #define G_STORE(BUF) do { u16* ad = As + (BUF) * 256 * 64 + sto; u16* bd = Bs + (BUF) * 256 * 64 + sto; _Pragma("unroll") for (int i = 0; i < 4; ++i) { *(u32x4*)(ad + i * 64 * 64) = ra[i]; *(u32x4*)(bd + i * 64 * 64) = rb[i]; } } while (0)
; template <int EPI>
; DI void gemm_phase(const u16* __restrict__ A, int lda, const u16* __restrict__ Bt, int K, int N, u16* outb, int ldo,
;                    const float* r0, const float* r1, float* outf, char* lds, int bid, int nb) {
;     ...
;     G_LOAD(0);
;     G_STORE(0);
;     __syncthreads();
;     for (int kt = 0; kt < nk; ++kt) {
;       const int cur = kt & 1;
;       if (kt + 1 < nk) G_LOAD(kt + 1);
;       G_MMA(cur, fo0);
;       G_MMA(cur, fo1);
;       if (kt + 1 < nk) G_STORE(cur ^ 1);
;       __syncthreads();
	ds_read_b128 v[152:155], v227 offset:0
	ds_read_b128 v[156:159], v227 offset:2048
	ds_read_b128 v[160:163], v227 offset:4096
	ds_read_b128 v[164:167], v227 offset:6144
	ds_read_b128 v[188:191], v225 offset:0
	ds_read_b128 v[192:195], v225 offset:2048
	ds_read_b128 v[196:199], v225 offset:4096
	ds_read_b128 v[200:203], v225 offset:6144
	ds_read_b128 v[204:207], v225 offset:8192
	ds_read_b128 v[208:211], v225 offset:10240
	ds_read_b128 v[212:215], v225 offset:12288
	ds_read_b128 v[216:219], v225 offset:14336
	v_xor_b32_e32 v225, 0x8000, v225
	v_xor_b32_e32 v227, 0x8000, v227
	s_waitcnt lgkmcnt(0)
.Lgm5_loop:
	s_waitcnt lgkmcnt(4)
	v_mfma_f32_16x16x32_bf16 v[124:127], v[188:191], v[152:155], v[124:127]
	v_mfma_f32_16x16x32_bf16 v[120:123], v[188:191], v[156:159], v[120:123]
	v_mfma_f32_16x16x32_bf16 v[116:119], v[188:191], v[160:163], v[116:119]
	v_mfma_f32_16x16x32_bf16 v[112:115], v[188:191], v[164:167], v[112:115]
	ds_read_b128 v[188:191], v226 offset:0
	ds_read_b128 v[168:171], v228 offset:0
	v_mfma_f32_16x16x32_bf16 v[108:111], v[192:195], v[152:155], v[108:111]
	v_mfma_f32_16x16x32_bf16 v[104:107], v[192:195], v[156:159], v[104:107]
	v_mfma_f32_16x16x32_bf16 v[100:103], v[192:195], v[160:163], v[100:103]
	v_mfma_f32_16x16x32_bf16 v[96:99], v[192:195], v[164:167], v[96:99]
	ds_read_b128 v[192:195], v226 offset:2048
	ds_read_b128 v[176:179], v228 offset:2048
	v_mfma_f32_16x16x32_bf16 v[92:95], v[196:199], v[152:155], v[92:95]
	v_mfma_f32_16x16x32_bf16 v[88:91], v[196:199], v[156:159], v[88:91]
	v_mfma_f32_16x16x32_bf16 v[84:87], v[196:199], v[160:163], v[84:87]
	v_mfma_f32_16x16x32_bf16 v[80:83], v[196:199], v[164:167], v[80:83]
	ds_read_b128 v[196:199], v226 offset:4096
	ds_read_b128 v[180:183], v228 offset:4096
	v_mfma_f32_16x16x32_bf16 v[76:79], v[200:203], v[152:155], v[76:79]
	v_mfma_f32_16x16x32_bf16 v[72:75], v[200:203], v[156:159], v[72:75]
	v_mfma_f32_16x16x32_bf16 v[68:71], v[200:203], v[160:163], v[68:71]
	v_mfma_f32_16x16x32_bf16 v[64:67], v[200:203], v[164:167], v[64:67]
	ds_read_b128 v[200:203], v226 offset:6144
	ds_read_b128 v[184:187], v228 offset:6144
	s_waitcnt lgkmcnt(11)
	v_mfma_f32_16x16x32_bf16 v[60:63], v[204:207], v[152:155], v[60:63]
	v_mfma_f32_16x16x32_bf16 v[56:59], v[204:207], v[156:159], v[56:59]
	v_mfma_f32_16x16x32_bf16 v[52:55], v[204:207], v[160:163], v[52:55]
	v_mfma_f32_16x16x32_bf16 v[48:51], v[204:207], v[164:167], v[48:51]
	ds_read_b128 v[204:207], v226 offset:8192
	ds_read_b128 v[220:223], v226 offset:14336
	s_waitcnt lgkmcnt(11)
	v_mfma_f32_16x16x32_bf16 v[44:47], v[208:211], v[152:155], v[44:47]
	v_mfma_f32_16x16x32_bf16 v[40:43], v[208:211], v[156:159], v[40:43]
	v_mfma_f32_16x16x32_bf16 v[36:39], v[208:211], v[160:163], v[36:39]
	v_mfma_f32_16x16x32_bf16 v[32:35], v[208:211], v[164:167], v[32:35]
	ds_read_b128 v[208:211], v226 offset:10240
	s_waitcnt lgkmcnt(11)
	v_mfma_f32_16x16x32_bf16 v[28:31], v[212:215], v[152:155], v[28:31]
	v_mfma_f32_16x16x32_bf16 v[24:27], v[212:215], v[156:159], v[24:27]
	v_mfma_f32_16x16x32_bf16 v[20:23], v[212:215], v[160:163], v[20:23]
	v_mfma_f32_16x16x32_bf16 v[16:19], v[212:215], v[164:167], v[16:19]
	ds_read_b128 v[212:215], v226 offset:12288
	v_mfma_f32_16x16x32_bf16 v[12:15], v[216:219], v[152:155], v[12:15]
	v_mfma_f32_16x16x32_bf16 v[8:11], v[216:219], v[156:159], v[8:11]
	v_mfma_f32_16x16x32_bf16 v[4:7], v[216:219], v[160:163], v[4:7]
	v_mfma_f32_16x16x32_bf16 v[0:3], v[216:219], v[164:167], v[0:3]
	s_waitcnt vmcnt(0) lgkmcnt(0)
	s_barrier
	v_mfma_f32_16x16x32_bf16 v[124:127], v[188:191], v[168:171], v[124:127]
	v_mfma_f32_16x16x32_bf16 v[120:123], v[188:191], v[176:179], v[120:123]
	v_mfma_f32_16x16x32_bf16 v[116:119], v[188:191], v[180:183], v[116:119]
	v_mfma_f32_16x16x32_bf16 v[112:115], v[188:191], v[184:187], v[112:115]
	ds_read_b128 v[188:191], v225 offset:0
	ds_read_b128 v[152:155], v227 offset:0
	s_add_u32 s8, s98, 0x0
	s_addc_u32 s9, s99, 0
	s_add_u32 m0, s97, 0x0
	s_nop 0
	global_load_lds_dwordx4 v224, s[8:9]
	v_mfma_f32_16x16x32_bf16 v[108:111], v[192:195], v[168:171], v[108:111]
	v_mfma_f32_16x16x32_bf16 v[104:107], v[192:195], v[176:179], v[104:107]
	v_mfma_f32_16x16x32_bf16 v[100:103], v[192:195], v[180:183], v[100:103]
	v_mfma_f32_16x16x32_bf16 v[96:99], v[192:195], v[184:187], v[96:99]
	ds_read_b128 v[192:195], v225 offset:2048
	ds_read_b128 v[156:159], v227 offset:2048
	s_add_u32 s8, s100, 0x0
	s_addc_u32 s9, s101, 0
	s_add_u32 m0, s97, 0x10000
	s_nop 0
	global_load_lds_dwordx4 v224, s[8:9]
	v_mfma_f32_16x16x32_bf16 v[92:95], v[196:199], v[168:171], v[92:95]
	v_mfma_f32_16x16x32_bf16 v[88:91], v[196:199], v[176:179], v[88:91]
	v_mfma_f32_16x16x32_bf16 v[84:87], v[196:199], v[180:183], v[84:87]
	v_mfma_f32_16x16x32_bf16 v[80:83], v[196:199], v[184:187], v[80:83]
	ds_read_b128 v[196:199], v225 offset:4096
	ds_read_b128 v[160:163], v227 offset:4096
	s_add_u32 s8, s98, 0x20000
	s_addc_u32 s9, s99, 0
	s_add_u32 m0, s97, 0x2000
	s_nop 0
	global_load_lds_dwordx4 v224, s[8:9]
	v_mfma_f32_16x16x32_bf16 v[76:79], v[200:203], v[168:171], v[76:79]
	v_mfma_f32_16x16x32_bf16 v[72:75], v[200:203], v[176:179], v[72:75]
	v_mfma_f32_16x16x32_bf16 v[68:71], v[200:203], v[180:183], v[68:71]
	v_mfma_f32_16x16x32_bf16 v[64:67], v[200:203], v[184:187], v[64:67]
	ds_read_b128 v[200:203], v225 offset:6144
	ds_read_b128 v[164:167], v227 offset:6144
	s_add_u32 s8, s100, 0x20000
	s_addc_u32 s9, s101, 0
	s_add_u32 m0, s97, 0x12000
	s_nop 0
	global_load_lds_dwordx4 v224, s[8:9]
	v_mfma_f32_16x16x32_bf16 v[60:63], v[204:207], v[168:171], v[60:63]
	v_mfma_f32_16x16x32_bf16 v[56:59], v[204:207], v[176:179], v[56:59]
	v_mfma_f32_16x16x32_bf16 v[52:55], v[204:207], v[180:183], v[52:55]
; #define G_LOAD(KT) do { _Pragma("unroll") for (int i = 0; i < 4; ++i) { ra[i] = *(const u32x4*)(Ag + (size_t)i * 64 * lda + (KT) * 64); rb[i] = *(const u32x4*)(Bg + (size_t)i * 64 * K + (KT) * 64); } } while (0)
; #define G_STORE(BUF) do { u16* ad = As + (BUF) * 256 * 64 + sto; u16* bd = Bs + (BUF) * 256 * 64 + sto; _Pragma("unroll") for (int i = 0; i < 4; ++i) { *(u32x4*)(ad + i * 64 * 64) = ra[i]; *(u32x4*)(bd + i * 64 * 64) = rb[i]; } } while (0)
; template <int EPI>
; DI void gemm_phase(const u16* __restrict__ A, int lda, const u16* __restrict__ Bt, int K, int N, u16* outb, int ldo,
;                    const float* r0, const float* r1, float* outf, char* lds, int bid, int nb) {
;     ...
;     for (int kt = 0; kt < nk; ++kt) {
;       const int cur = kt & 1;
;       if (kt + 1 < nk) G_LOAD(kt + 1);
;       G_MMA(cur, fo0);
;       G_MMA(cur, fo1);
;       if (kt + 1 < nk) G_STORE(cur ^ 1);
;       __syncthreads();
	v_mfma_f32_16x16x32_bf16 v[48:51], v[204:207], v[184:187], v[48:51]
	ds_read_b128 v[204:207], v225 offset:8192
	ds_read_b128 v[216:219], v225 offset:14336
	s_add_u32 s8, s98, 0x40000
	s_addc_u32 s9, s99, 0
	s_add_u32 m0, s97, 0x4000
	s_nop 0
	global_load_lds_dwordx4 v224, s[8:9]
	v_mfma_f32_16x16x32_bf16 v[44:47], v[208:211], v[168:171], v[44:47]
	v_mfma_f32_16x16x32_bf16 v[40:43], v[208:211], v[176:179], v[40:43]
	v_mfma_f32_16x16x32_bf16 v[36:39], v[208:211], v[180:183], v[36:39]
	v_mfma_f32_16x16x32_bf16 v[32:35], v[208:211], v[184:187], v[32:35]
	ds_read_b128 v[208:211], v225 offset:10240
	s_add_u32 s8, s100, 0x40000
	s_addc_u32 s9, s101, 0
	s_add_u32 m0, s97, 0x14000
	s_nop 0
	global_load_lds_dwordx4 v224, s[8:9]
	v_mfma_f32_16x16x32_bf16 v[28:31], v[212:215], v[168:171], v[28:31]
	v_mfma_f32_16x16x32_bf16 v[24:27], v[212:215], v[176:179], v[24:27]
	v_mfma_f32_16x16x32_bf16 v[20:23], v[212:215], v[180:183], v[20:23]
	v_mfma_f32_16x16x32_bf16 v[16:19], v[212:215], v[184:187], v[16:19]
	ds_read_b128 v[212:215], v225 offset:12288
	s_add_u32 s8, s98, 0x60000
	s_addc_u32 s9, s99, 0
	s_add_u32 m0, s97, 0x6000
	s_nop 0
	global_load_lds_dwordx4 v224, s[8:9]
	v_mfma_f32_16x16x32_bf16 v[12:15], v[220:223], v[168:171], v[12:15]
	v_mfma_f32_16x16x32_bf16 v[8:11], v[220:223], v[176:179], v[8:11]
	v_mfma_f32_16x16x32_bf16 v[4:7], v[220:223], v[180:183], v[4:7]
	v_mfma_f32_16x16x32_bf16 v[0:3], v[220:223], v[184:187], v[0:3]
	s_add_u32 s8, s100, 0x60000
	s_addc_u32 s9, s101, 0
	s_add_u32 m0, s97, 0x16000
	s_nop 0
	global_load_lds_dwordx4 v224, s[8:9]
	v_xor_b32_e32 v225, 0x8000, v225
	v_xor_b32_e32 v227, 0x8000, v227
	v_xor_b32_e32 v226, 0x8000, v226
	v_xor_b32_e32 v228, 0x8000, v228
	s_xor_b32 s97, s97, 0x8000
	s_add_u32 s98, s98, 0x80
	s_addc_u32 s99, s99, 0
	s_add_u32 s100, s100, 0x80
	s_addc_u32 s101, s101, 0
	s_sub_u32 s28, s28, 1
	s_cmp_lg_u32 s28, 0
	s_cbranch_scc1 .Lgm5_loop
	s_waitcnt lgkmcnt(4)
	v_mfma_f32_16x16x32_bf16 v[124:127], v[188:191], v[152:155], v[124:127]
	v_mfma_f32_16x16x32_bf16 v[120:123], v[188:191], v[156:159], v[120:123]
	v_mfma_f32_16x16x32_bf16 v[116:119], v[188:191], v[160:163], v[116:119]
	v_mfma_f32_16x16x32_bf16 v[112:115], v[188:191], v[164:167], v[112:115]
	ds_read_b128 v[188:191], v226 offset:0
	ds_read_b128 v[168:171], v228 offset:0
	v_mfma_f32_16x16x32_bf16 v[108:111], v[192:195], v[152:155], v[108:111]
	v_mfma_f32_16x16x32_bf16 v[104:107], v[192:195], v[156:159], v[104:107]
	v_mfma_f32_16x16x32_bf16 v[100:103], v[192:195], v[160:163], v[100:103]
	v_mfma_f32_16x16x32_bf16 v[96:99], v[192:195], v[164:167], v[96:99]
	ds_read_b128 v[192:195], v226 offset:2048
	ds_read_b128 v[176:179], v228 offset:2048
	v_mfma_f32_16x16x32_bf16 v[92:95], v[196:199], v[152:155], v[92:95]
	v_mfma_f32_16x16x32_bf16 v[88:91], v[196:199], v[156:159], v[88:91]
	v_mfma_f32_16x16x32_bf16 v[84:87], v[196:199], v[160:163], v[84:87]
	v_mfma_f32_16x16x32_bf16 v[80:83], v[196:199], v[164:167], v[80:83]
	ds_read_b128 v[196:199], v226 offset:4096
	ds_read_b128 v[180:183], v228 offset:4096
	v_mfma_f32_16x16x32_bf16 v[76:79], v[200:203], v[152:155], v[76:79]
	v_mfma_f32_16x16x32_bf16 v[72:75], v[200:203], v[156:159], v[72:75]
	v_mfma_f32_16x16x32_bf16 v[68:71], v[200:203], v[160:163], v[68:71]
	v_mfma_f32_16x16x32_bf16 v[64:67], v[200:203], v[164:167], v[64:67]
	ds_read_b128 v[200:203], v226 offset:6144
	ds_read_b128 v[184:187], v228 offset:6144
	s_waitcnt lgkmcnt(11)
	v_mfma_f32_16x16x32_bf16 v[60:63], v[204:207], v[152:155], v[60:63]
	v_mfma_f32_16x16x32_bf16 v[56:59], v[204:207], v[156:159], v[56:59]
	v_mfma_f32_16x16x32_bf16 v[52:55], v[204:207], v[160:163], v[52:55]
	v_mfma_f32_16x16x32_bf16 v[48:51], v[204:207], v[164:167], v[48:51]
	ds_read_b128 v[204:207], v226 offset:8192
	ds_read_b128 v[220:223], v226 offset:14336
	s_waitcnt lgkmcnt(11)
	v_mfma_f32_16x16x32_bf16 v[44:47], v[208:211], v[152:155], v[44:47]
	v_mfma_f32_16x16x32_bf16 v[40:43], v[208:211], v[156:159], v[40:43]
	v_mfma_f32_16x16x32_bf16 v[36:39], v[208:211], v[160:163], v[36:39]
	v_mfma_f32_16x16x32_bf16 v[32:35], v[208:211], v[164:167], v[32:35]
	ds_read_b128 v[208:211], v226 offset:10240
	s_waitcnt lgkmcnt(11)
	v_mfma_f32_16x16x32_bf16 v[28:31], v[212:215], v[152:155], v[28:31]
	v_mfma_f32_16x16x32_bf16 v[24:27], v[212:215], v[156:159], v[24:27]
	v_mfma_f32_16x16x32_bf16 v[20:23], v[212:215], v[160:163], v[20:23]
	v_mfma_f32_16x16x32_bf16 v[16:19], v[212:215], v[164:167], v[16:19]
	ds_read_b128 v[212:215], v226 offset:12288
	v_mfma_f32_16x16x32_bf16 v[12:15], v[216:219], v[152:155], v[12:15]
	v_mfma_f32_16x16x32_bf16 v[8:11], v[216:219], v[156:159], v[8:11]
	v_mfma_f32_16x16x32_bf16 v[4:7], v[216:219], v[160:163], v[4:7]
	v_mfma_f32_16x16x32_bf16 v[0:3], v[216:219], v[164:167], v[0:3]
	s_waitcnt vmcnt(0) lgkmcnt(0)
	s_barrier
; #define G_LOAD(KT) do { _Pragma("unroll") for (int i = 0; i < 4; ++i) { ra[i] = *(const u32x4*)(Ag + (size_t)i * 64 * lda + (KT) * 64); rb[i] = *(const u32x4*)(Bg + (size_t)i * 64 * K + (KT) * 64); } } while (0)
; #define G_STORE(BUF) do { u16* ad = As + (BUF) * 256 * 64 + sto; u16* bd = Bs + (BUF) * 256 * 64 + sto; _Pragma("unroll") for (int i = 0; i < 4; ++i) { *(u32x4*)(ad + i * 64 * 64) = ra[i]; *(u32x4*)(bd + i * 64 * 64) = rb[i]; } } while (0)
; template <int EPI>
; DI void gemm_phase(const u16* __restrict__ A, int lda, const u16* __restrict__ Bt, int K, int N, u16* outb, int ldo,
;                    const float* r0, const float* r1, float* outf, char* lds, int bid, int nb) {
;     ...
;     for (int kt = 0; kt < nk; ++kt) {
;       const int cur = kt & 1;
;       if (kt + 1 < nk) G_LOAD(kt + 1);
;       G_MMA(cur, fo0);
;       G_MMA(cur, fo1);
;       if (kt + 1 < nk) G_STORE(cur ^ 1);
;       __syncthreads();
	v_mfma_f32_16x16x32_bf16 v[124:127], v[188:191], v[168:171], v[124:127]
	v_mfma_f32_16x16x32_bf16 v[120:123], v[188:191], v[176:179], v[120:123]
	v_mfma_f32_16x16x32_bf16 v[116:119], v[188:191], v[180:183], v[116:119]
	v_mfma_f32_16x16x32_bf16 v[112:115], v[188:191], v[184:187], v[112:115]
	ds_read_b128 v[188:191], v225 offset:0
	ds_read_b128 v[152:155], v227 offset:0
	v_mfma_f32_16x16x32_bf16 v[108:111], v[192:195], v[168:171], v[108:111]
	v_mfma_f32_16x16x32_bf16 v[104:107], v[192:195], v[176:179], v[104:107]
	v_mfma_f32_16x16x32_bf16 v[100:103], v[192:195], v[180:183], v[100:103]
	v_mfma_f32_16x16x32_bf16 v[96:99], v[192:195], v[184:187], v[96:99]
	ds_read_b128 v[192:195], v225 offset:2048
	ds_read_b128 v[156:159], v227 offset:2048
	v_mfma_f32_16x16x32_bf16 v[92:95], v[196:199], v[168:171], v[92:95]
	v_mfma_f32_16x16x32_bf16 v[88:91], v[196:199], v[176:179], v[88:91]
	v_mfma_f32_16x16x32_bf16 v[84:87], v[196:199], v[180:183], v[84:87]
	v_mfma_f32_16x16x32_bf16 v[80:83], v[196:199], v[184:187], v[80:83]
	ds_read_b128 v[196:199], v225 offset:4096
	ds_read_b128 v[160:163], v227 offset:4096
	v_mfma_f32_16x16x32_bf16 v[76:79], v[200:203], v[168:171], v[76:79]
	v_mfma_f32_16x16x32_bf16 v[72:75], v[200:203], v[176:179], v[72:75]
	v_mfma_f32_16x16x32_bf16 v[68:71], v[200:203], v[180:183], v[68:71]
	v_mfma_f32_16x16x32_bf16 v[64:67], v[200:203], v[184:187], v[64:67]
	ds_read_b128 v[200:203], v225 offset:6144
	ds_read_b128 v[164:167], v227 offset:6144
	v_mfma_f32_16x16x32_bf16 v[60:63], v[204:207], v[168:171], v[60:63]
	v_mfma_f32_16x16x32_bf16 v[56:59], v[204:207], v[176:179], v[56:59]
	v_mfma_f32_16x16x32_bf16 v[52:55], v[204:207], v[180:183], v[52:55]
	v_mfma_f32_16x16x32_bf16 v[48:51], v[204:207], v[184:187], v[48:51]
	ds_read_b128 v[204:207], v225 offset:8192
	ds_read_b128 v[216:219], v225 offset:14336
	v_mfma_f32_16x16x32_bf16 v[44:47], v[208:211], v[168:171], v[44:47]
	v_mfma_f32_16x16x32_bf16 v[40:43], v[208:211], v[176:179], v[40:43]
	v_mfma_f32_16x16x32_bf16 v[36:39], v[208:211], v[180:183], v[36:39]
	v_mfma_f32_16x16x32_bf16 v[32:35], v[208:211], v[184:187], v[32:35]
	ds_read_b128 v[208:211], v225 offset:10240
	v_mfma_f32_16x16x32_bf16 v[28:31], v[212:215], v[168:171], v[28:31]
	v_mfma_f32_16x16x32_bf16 v[24:27], v[212:215], v[176:179], v[24:27]
	v_mfma_f32_16x16x32_bf16 v[20:23], v[212:215], v[180:183], v[20:23]
	v_mfma_f32_16x16x32_bf16 v[16:19], v[212:215], v[184:187], v[16:19]
	ds_read_b128 v[212:215], v225 offset:12288
	v_mfma_f32_16x16x32_bf16 v[12:15], v[220:223], v[168:171], v[12:15]
	v_mfma_f32_16x16x32_bf16 v[8:11], v[220:223], v[176:179], v[8:11]
	v_mfma_f32_16x16x32_bf16 v[4:7], v[220:223], v[180:183], v[4:7]
	v_mfma_f32_16x16x32_bf16 v[0:3], v[220:223], v[184:187], v[0:3]
	v_xor_b32_e32 v226, 0x8000, v226
	v_xor_b32_e32 v228, 0x8000, v228
	s_waitcnt lgkmcnt(4)
	v_mfma_f32_16x16x32_bf16 v[124:127], v[188:191], v[152:155], v[124:127]
	v_mfma_f32_16x16x32_bf16 v[120:123], v[188:191], v[156:159], v[120:123]
	v_mfma_f32_16x16x32_bf16 v[116:119], v[188:191], v[160:163], v[116:119]
	v_mfma_f32_16x16x32_bf16 v[112:115], v[188:191], v[164:167], v[112:115]
	ds_read_b128 v[188:191], v226 offset:0
	ds_read_b128 v[168:171], v228 offset:0
	v_mfma_f32_16x16x32_bf16 v[108:111], v[192:195], v[152:155], v[108:111]
	v_mfma_f32_16x16x32_bf16 v[104:107], v[192:195], v[156:159], v[104:107]
	v_mfma_f32_16x16x32_bf16 v[100:103], v[192:195], v[160:163], v[100:103]
	v_mfma_f32_16x16x32_bf16 v[96:99], v[192:195], v[164:167], v[96:99]
	ds_read_b128 v[192:195], v226 offset:2048
	ds_read_b128 v[176:179], v228 offset:2048
	v_mfma_f32_16x16x32_bf16 v[92:95], v[196:199], v[152:155], v[92:95]
	v_mfma_f32_16x16x32_bf16 v[88:91], v[196:199], v[156:159], v[88:91]
	v_mfma_f32_16x16x32_bf16 v[84:87], v[196:199], v[160:163], v[84:87]
	v_mfma_f32_16x16x32_bf16 v[80:83], v[196:199], v[164:167], v[80:83]
	ds_read_b128 v[196:199], v226 offset:4096
	ds_read_b128 v[180:183], v228 offset:4096
	v_mfma_f32_16x16x32_bf16 v[76:79], v[200:203], v[152:155], v[76:79]
	v_mfma_f32_16x16x32_bf16 v[72:75], v[200:203], v[156:159], v[72:75]
	v_mfma_f32_16x16x32_bf16 v[68:71], v[200:203], v[160:163], v[68:71]
	v_mfma_f32_16x16x32_bf16 v[64:67], v[200:203], v[164:167], v[64:67]
	ds_read_b128 v[200:203], v226 offset:6144
	ds_read_b128 v[184:187], v228 offset:6144
	s_waitcnt lgkmcnt(11)
	v_mfma_f32_16x16x32_bf16 v[60:63], v[204:207], v[152:155], v[60:63]
	v_mfma_f32_16x16x32_bf16 v[56:59], v[204:207], v[156:159], v[56:59]
	v_mfma_f32_16x16x32_bf16 v[52:55], v[204:207], v[160:163], v[52:55]
	v_mfma_f32_16x16x32_bf16 v[48:51], v[204:207], v[164:167], v[48:51]
	ds_read_b128 v[204:207], v226 offset:8192
	ds_read_b128 v[220:223], v226 offset:14336
	s_waitcnt lgkmcnt(11)
	v_mfma_f32_16x16x32_bf16 v[44:47], v[208:211], v[152:155], v[44:47]
	v_mfma_f32_16x16x32_bf16 v[40:43], v[208:211], v[156:159], v[40:43]
	v_mfma_f32_16x16x32_bf16 v[36:39], v[208:211], v[160:163], v[36:39]
	v_mfma_f32_16x16x32_bf16 v[32:35], v[208:211], v[164:167], v[32:35]
	ds_read_b128 v[208:211], v226 offset:10240
	s_waitcnt lgkmcnt(11)
	v_mfma_f32_16x16x32_bf16 v[28:31], v[212:215], v[152:155], v[28:31]
	v_mfma_f32_16x16x32_bf16 v[24:27], v[212:215], v[156:159], v[24:27]
	v_mfma_f32_16x16x32_bf16 v[20:23], v[212:215], v[160:163], v[20:23]
	v_mfma_f32_16x16x32_bf16 v[16:19], v[212:215], v[164:167], v[16:19]
	ds_read_b128 v[212:215], v226 offset:12288
	v_mfma_f32_16x16x32_bf16 v[12:15], v[216:219], v[152:155], v[12:15]
	v_mfma_f32_16x16x32_bf16 v[8:11], v[216:219], v[156:159], v[8:11]
	v_mfma_f32_16x16x32_bf16 v[4:7], v[216:219], v[160:163], v[4:7]
	v_mfma_f32_16x16x32_bf16 v[0:3], v[216:219], v[164:167], v[0:3]
	s_waitcnt vmcnt(0) lgkmcnt(0)
	s_barrier
; template <int EPI>
; DI void gemm_phase(const u16* __restrict__ A, int lda, const u16* __restrict__ Bt, int K, int N, u16* outb, int ldo,
;                    const float* r0, const float* r1, float* outf, char* lds, int bid, int nb) {
;     ...
;     } else if constexpr (EPI == EPI_RESID) {
;       const int col = tn * 256 + wc * 64 + l15;
;       const float* rb_ = (tm * 256 < M_P) ? r0 : (r1 - (size_t)M_P * DM);
; #pragma unroll
;       for (int i = 0; i < 8; ++i)
; #pragma unroll
;         for (int r = 0; r < 4; ++r) {
;           const size_t i0 = (size_t)(mrow + i * 16 + r) * DM + col;
;           const float x0 = rb_[i0], x1 = rb_[i0 + 16], x2 = rb_[i0 + 32], x3 = rb_[i0 + 48];
;           outf[i0] = x0 + acc[i][0][r]; outf[i0 + 16] = x1 + acc[i][1][r]; outf[i0 + 32] = x2 + acc[i][2][r]; outf[i0 + 48] = x3 + acc[i][3][r];
	v_mfma_f32_16x16x32_bf16 v[124:127], v[188:191], v[168:171], v[124:127]
	v_mfma_f32_16x16x32_bf16 v[120:123], v[188:191], v[176:179], v[120:123]
	v_mfma_f32_16x16x32_bf16 v[116:119], v[188:191], v[180:183], v[116:119]
	v_mfma_f32_16x16x32_bf16 v[112:115], v[188:191], v[184:187], v[112:115]
	v_mfma_f32_16x16x32_bf16 v[108:111], v[192:195], v[168:171], v[108:111]
	v_mfma_f32_16x16x32_bf16 v[104:107], v[192:195], v[176:179], v[104:107]
	v_mfma_f32_16x16x32_bf16 v[100:103], v[192:195], v[180:183], v[100:103]
	v_mfma_f32_16x16x32_bf16 v[96:99], v[192:195], v[184:187], v[96:99]
	v_mfma_f32_16x16x32_bf16 v[92:95], v[196:199], v[168:171], v[92:95]
	v_mfma_f32_16x16x32_bf16 v[88:91], v[196:199], v[176:179], v[88:91]
	v_mfma_f32_16x16x32_bf16 v[84:87], v[196:199], v[180:183], v[84:87]
	v_mfma_f32_16x16x32_bf16 v[80:83], v[196:199], v[184:187], v[80:83]
	v_mfma_f32_16x16x32_bf16 v[76:79], v[200:203], v[168:171], v[76:79]
	v_mfma_f32_16x16x32_bf16 v[72:75], v[200:203], v[176:179], v[72:75]
	v_mfma_f32_16x16x32_bf16 v[68:71], v[200:203], v[180:183], v[68:71]
	v_mfma_f32_16x16x32_bf16 v[64:67], v[200:203], v[184:187], v[64:67]
	v_mfma_f32_16x16x32_bf16 v[60:63], v[204:207], v[168:171], v[60:63]
	v_mfma_f32_16x16x32_bf16 v[56:59], v[204:207], v[176:179], v[56:59]
	v_mfma_f32_16x16x32_bf16 v[52:55], v[204:207], v[180:183], v[52:55]
	v_mfma_f32_16x16x32_bf16 v[48:51], v[204:207], v[184:187], v[48:51]
	v_mfma_f32_16x16x32_bf16 v[44:47], v[208:211], v[168:171], v[44:47]
	v_mfma_f32_16x16x32_bf16 v[40:43], v[208:211], v[176:179], v[40:43]
	v_mfma_f32_16x16x32_bf16 v[36:39], v[208:211], v[180:183], v[36:39]
	v_mfma_f32_16x16x32_bf16 v[32:35], v[208:211], v[184:187], v[32:35]
	v_mfma_f32_16x16x32_bf16 v[28:31], v[212:215], v[168:171], v[28:31]
	v_mfma_f32_16x16x32_bf16 v[24:27], v[212:215], v[176:179], v[24:27]
	v_mfma_f32_16x16x32_bf16 v[20:23], v[212:215], v[180:183], v[20:23]
	v_mfma_f32_16x16x32_bf16 v[16:19], v[212:215], v[184:187], v[16:19]
	v_mfma_f32_16x16x32_bf16 v[12:15], v[220:223], v[168:171], v[12:15]
	v_mfma_f32_16x16x32_bf16 v[8:11], v[220:223], v[176:179], v[8:11]
	v_mfma_f32_16x16x32_bf16 v[4:7], v[220:223], v[180:183], v[4:7]
	v_mfma_f32_16x16x32_bf16 v[0:3], v[220:223], v[184:187], v[0:3]
	s_nop 7
	s_nop 3
	v_mov_b32_e32 v224, v96
	v_mov_b32_e32 v225, v97
	v_mov_b32_e32 v226, v98
	v_mov_b32_e32 v227, v99
	v_mov_b32_e32 v172, v80
	v_mov_b32_e32 v80, v92
	v_mov_b32_e32 v92, v172
	v_mov_b32_e32 v172, v81
	v_mov_b32_e32 v81, v93
	v_mov_b32_e32 v93, v172
	v_mov_b32_e32 v172, v82
	v_mov_b32_e32 v82, v94
	v_mov_b32_e32 v94, v172
	v_mov_b32_e32 v172, v83
	v_mov_b32_e32 v83, v95
	v_mov_b32_e32 v95, v172
	v_mov_b32_e32 v172, v84
	v_mov_b32_e32 v84, v88
	v_mov_b32_e32 v88, v172
	v_mov_b32_e32 v172, v85
	v_mov_b32_e32 v85, v89
	v_mov_b32_e32 v89, v172
	v_mov_b32_e32 v172, v86
	v_mov_b32_e32 v86, v90
	v_mov_b32_e32 v90, v172
	v_mov_b32_e32 v172, v87
	v_mov_b32_e32 v87, v91
	v_mov_b32_e32 v91, v172
	v_mov_b32_e32 v172, v64
	v_mov_b32_e32 v64, v76
	v_mov_b32_e32 v76, v172
	v_mov_b32_e32 v172, v65
	v_mov_b32_e32 v65, v77
	v_mov_b32_e32 v77, v172
	v_mov_b32_e32 v172, v66
	v_mov_b32_e32 v66, v78
	v_mov_b32_e32 v78, v172
	v_mov_b32_e32 v172, v67
	v_mov_b32_e32 v67, v79
	v_mov_b32_e32 v79, v172
	v_mov_b32_e32 v172, v68
	v_mov_b32_e32 v68, v72
	v_mov_b32_e32 v72, v172
	v_mov_b32_e32 v172, v69
	v_mov_b32_e32 v69, v73
	v_mov_b32_e32 v73, v172
	v_mov_b32_e32 v172, v70
	v_mov_b32_e32 v70, v74
	v_mov_b32_e32 v74, v172
	v_mov_b32_e32 v172, v71
	v_mov_b32_e32 v71, v75
	v_mov_b32_e32 v75, v172
	v_mov_b32_e32 v172, v48
	v_mov_b32_e32 v48, v60
	v_mov_b32_e32 v60, v172
	v_mov_b32_e32 v172, v49
	v_mov_b32_e32 v49, v61
	v_mov_b32_e32 v61, v172
	v_mov_b32_e32 v172, v50
	v_mov_b32_e32 v50, v62
	v_mov_b32_e32 v62, v172
	v_mov_b32_e32 v172, v51
	v_mov_b32_e32 v51, v63
	v_mov_b32_e32 v63, v172
	v_mov_b32_e32 v172, v52
	v_mov_b32_e32 v52, v56
	v_mov_b32_e32 v56, v172
	v_mov_b32_e32 v172, v53
	v_mov_b32_e32 v53, v57
	v_mov_b32_e32 v57, v172
	v_mov_b32_e32 v172, v54
	v_mov_b32_e32 v54, v58
	v_mov_b32_e32 v58, v172
	v_mov_b32_e32 v172, v55
	v_mov_b32_e32 v55, v59
	v_mov_b32_e32 v59, v172
	v_mov_b32_e32 v172, v32
	v_mov_b32_e32 v32, v44
	v_mov_b32_e32 v44, v172
	v_mov_b32_e32 v172, v33
	v_mov_b32_e32 v33, v45
	v_mov_b32_e32 v45, v172
	v_mov_b32_e32 v172, v34
	v_mov_b32_e32 v34, v46
	v_mov_b32_e32 v46, v172
	v_mov_b32_e32 v172, v35
	v_mov_b32_e32 v35, v47
	v_mov_b32_e32 v47, v172
	v_mov_b32_e32 v172, v36
	v_mov_b32_e32 v36, v40
	v_mov_b32_e32 v40, v172
	v_mov_b32_e32 v172, v37
	v_mov_b32_e32 v37, v41
	v_mov_b32_e32 v41, v172
	v_mov_b32_e32 v172, v38
	v_mov_b32_e32 v38, v42
	v_mov_b32_e32 v42, v172
	v_mov_b32_e32 v172, v39
	v_mov_b32_e32 v39, v43
	v_mov_b32_e32 v43, v172
	v_mov_b32_e32 v172, v16
	v_mov_b32_e32 v16, v28
	v_mov_b32_e32 v28, v172
	v_mov_b32_e32 v172, v17
	v_mov_b32_e32 v17, v29
	v_mov_b32_e32 v29, v172
	v_mov_b32_e32 v172, v18
	v_mov_b32_e32 v18, v30
	v_mov_b32_e32 v30, v172
	v_mov_b32_e32 v172, v19
	v_mov_b32_e32 v19, v31
	v_mov_b32_e32 v31, v172
	v_mov_b32_e32 v172, v20
	v_mov_b32_e32 v20, v24
	v_mov_b32_e32 v24, v172
	v_mov_b32_e32 v172, v21
	v_mov_b32_e32 v21, v25
	v_mov_b32_e32 v25, v172
	v_mov_b32_e32 v172, v22
	v_mov_b32_e32 v22, v26
	v_mov_b32_e32 v26, v172
	v_mov_b32_e32 v172, v23
	v_mov_b32_e32 v23, v27
	v_mov_b32_e32 v27, v172
	v_mov_b32_e32 v172, v0
	v_mov_b32_e32 v0, v12
	v_mov_b32_e32 v12, v172
	v_mov_b32_e32 v172, v1
	v_mov_b32_e32 v1, v13
	v_mov_b32_e32 v13, v172
	v_mov_b32_e32 v172, v2
	v_mov_b32_e32 v2, v14
	v_mov_b32_e32 v14, v172
	v_mov_b32_e32 v172, v3
	v_mov_b32_e32 v3, v15
	v_mov_b32_e32 v15, v172
	v_mov_b32_e32 v172, v4
	v_mov_b32_e32 v4, v8
	v_mov_b32_e32 v8, v172
	v_mov_b32_e32 v172, v5
	v_mov_b32_e32 v5, v9
	v_mov_b32_e32 v9, v172
	v_mov_b32_e32 v172, v6
	v_mov_b32_e32 v6, v10
	v_mov_b32_e32 v10, v172
	v_mov_b32_e32 v172, v7
	v_mov_b32_e32 v7, v11
	v_mov_b32_e32 v11, v172
	v_add_u32_e32 v98, s39, v143
	v_or_b32_e32 v96, s40, v144
	v_ashrrev_i32_e32 v99, 31, v98
	v_ashrrev_i32_e32 v97, 31, v96
	v_lshlrev_b64 v[134:135], 10, v[98:99]
	v_lshl_add_u64 v[134:135], v[134:135], 0, v[96:97]
	v_lshl_add_u64 v[134:135], v[134:135], 2, s[22:23]
	global_load_dword v99, v[134:135], off
	global_load_dword v151, v[134:135], off offset:64
	global_load_dword v152, v[134:135], off offset:128
	global_load_dword v153, v[134:135], off offset:192
	v_or_b32_e32 v136, 1, v98
	v_ashrrev_i32_e32 v137, 31, v136
	v_lshlrev_b64 v[136:137], 10, v[136:137]
	v_lshl_add_u64 v[136:137], v[136:137], 0, v[96:97]
	v_lshl_add_u64 v[136:137], v[136:137], 2, s[22:23]
	s_add_i32 s14, s14, 1
	s_cmp_eq_u32 s14, s3
	s_waitcnt vmcnt(3)
; template <int EPI>
; DI void gemm_phase(const u16* __restrict__ A, int lda, const u16* __restrict__ Bt, int K, int N, u16* outb, int ldo,
;                    const float* r0, const float* r1, float* outf, char* lds, int bid, int nb) {
;     ...
; #pragma unroll
;       for (int i = 0; i < 8; ++i)
; #pragma unroll
;         for (int r = 0; r < 4; ++r) {
;           const size_t i0 = (size_t)(mrow + i * 16 + r) * DM + col;
;           const float x0 = rb_[i0], x1 = rb_[i0 + 16], x2 = rb_[i0 + 32], x3 = rb_[i0 + 48];
;           outf[i0] = x0 + acc[i][0][r]; outf[i0 + 16] = x1 + acc[i][1][r]; outf[i0 + 32] = x2 + acc[i][2][r]; outf[i0 + 48] = x3 + acc[i][3][r];
;         }
	v_add_f32_e32 v99, v124, v99
	s_waitcnt vmcnt(2)
	v_add_f32_e32 v120, v120, v151
	s_waitcnt vmcnt(1)
	v_add_f32_e32 v116, v116, v152
	s_waitcnt vmcnt(0)
	v_add_f32_e32 v112, v112, v153
	global_store_dword v[134:135], v99, off
	global_store_dword v[134:135], v120, off offset:64
	global_store_dword v[134:135], v116, off offset:128
	global_store_dword v[134:135], v112, off offset:192
	global_load_dword v99, v[136:137], off
	s_nop 0
	global_load_dword v112, v[136:137], off offset:64
	global_load_dword v116, v[136:137], off offset:128
	global_load_dword v120, v[136:137], off offset:192
	v_or_b32_e32 v134, 2, v98
	v_ashrrev_i32_e32 v135, 31, v134
	v_lshlrev_b64 v[134:135], 10, v[134:135]
	v_lshl_add_u64 v[134:135], v[134:135], 0, v[96:97]
	v_lshl_add_u64 v[134:135], v[134:135], 2, s[22:23]
	s_waitcnt vmcnt(3)
	v_add_f32_e32 v99, v125, v99
	s_waitcnt vmcnt(2)
	v_add_f32_e32 v112, v121, v112
	s_waitcnt vmcnt(1)
	v_add_f32_e32 v116, v117, v116
	s_waitcnt vmcnt(0)
	v_add_f32_e32 v113, v113, v120
	global_store_dword v[136:137], v99, off
	global_store_dword v[136:137], v112, off offset:64
	global_store_dword v[136:137], v116, off offset:128
	global_store_dword v[136:137], v113, off offset:192
	global_load_dword v99, v[134:135], off
	s_nop 0
	global_load_dword v116, v[134:135], off offset:64
	global_load_dword v117, v[134:135], off offset:128
	global_load_dword v120, v[134:135], off offset:192
	v_or_b32_e32 v112, 3, v98
	v_ashrrev_i32_e32 v113, 31, v112
	v_lshlrev_b64 v[112:113], 10, v[112:113]
	v_lshl_add_u64 v[112:113], v[112:113], 0, v[96:97]
	v_lshl_add_u64 v[112:113], v[112:113], 2, s[22:23]
	s_waitcnt vmcnt(3)
	v_add_f32_e32 v99, v126, v99
	s_waitcnt vmcnt(2)
	v_add_f32_e32 v116, v122, v116
	s_waitcnt vmcnt(1)
	v_add_f32_e32 v117, v118, v117
	s_waitcnt vmcnt(0)
	v_add_f32_e32 v114, v114, v120
	global_store_dword v[134:135], v99, off
	global_store_dword v[134:135], v116, off offset:64
	global_store_dword v[134:135], v117, off offset:128
	global_store_dword v[134:135], v114, off offset:192
	global_load_dword v99, v[112:113], off
	s_nop 0
	global_load_dword v114, v[112:113], off offset:64
	global_load_dword v118, v[112:113], off offset:128
	global_load_dword v120, v[112:113], off offset:192
	v_or_b32_e32 v116, 16, v98
	v_ashrrev_i32_e32 v117, 31, v116
	v_lshlrev_b64 v[116:117], 10, v[116:117]
	v_lshl_add_u64 v[116:117], v[116:117], 0, v[96:97]
	v_lshl_add_u64 v[116:117], v[116:117], 2, s[22:23]
	s_waitcnt vmcnt(3)
	v_add_f32_e32 v99, v127, v99
	s_waitcnt vmcnt(2)
	v_add_f32_e32 v114, v123, v114
	s_waitcnt vmcnt(1)
	v_add_f32_e32 v118, v119, v118
	s_waitcnt vmcnt(0)
	v_add_f32_e32 v115, v115, v120
	global_store_dword v[112:113], v99, off
	global_store_dword v[112:113], v114, off offset:64
	global_store_dword v[112:113], v118, off offset:128
	global_store_dword v[112:113], v115, off offset:192
	global_load_dword v99, v[116:117], off
	s_nop 0
	global_load_dword v114, v[116:117], off offset:64
	global_load_dword v115, v[116:117], off offset:128
	global_load_dword v118, v[116:117], off offset:192
	v_or_b32_e32 v112, 17, v98
	v_ashrrev_i32_e32 v113, 31, v112
	v_lshlrev_b64 v[112:113], 10, v[112:113]
	v_lshl_add_u64 v[112:113], v[112:113], 0, v[96:97]
	v_lshl_add_u64 v[112:113], v[112:113], 2, s[22:23]
	s_waitcnt vmcnt(3)
	v_add_f32_e32 v99, v108, v99
	s_waitcnt vmcnt(2)
	v_add_f32_e32 v104, v104, v114
	s_waitcnt vmcnt(1)
	v_add_f32_e32 v100, v100, v115
	s_waitcnt vmcnt(0)
	v_add_f32_e32 v108, v224, v118
	global_store_dword v[116:117], v99, off
	global_store_dword v[116:117], v104, off offset:64
	global_store_dword v[116:117], v100, off offset:128
	global_store_dword v[116:117], v108, off offset:192
	global_load_dword v99, v[112:113], off
	s_nop 0
	global_load_dword v100, v[112:113], off offset:64
	global_load_dword v104, v[112:113], off offset:128
	global_load_dword v108, v[112:113], off offset:192
	v_or_b32_e32 v114, 18, v98
	v_ashrrev_i32_e32 v115, 31, v114
	v_lshlrev_b64 v[114:115], 10, v[114:115]
	v_lshl_add_u64 v[114:115], v[114:115], 0, v[96:97]
	v_lshl_add_u64 v[114:115], v[114:115], 2, s[22:23]
	s_waitcnt vmcnt(3)
	v_add_f32_e32 v99, v109, v99
	s_waitcnt vmcnt(2)
	v_add_f32_e32 v100, v105, v100
	s_waitcnt vmcnt(1)
	v_add_f32_e32 v101, v101, v104
	s_waitcnt vmcnt(0)
	v_add_f32_e32 v104, v225, v108
	global_store_dword v[112:113], v99, off
	global_store_dword v[112:113], v100, off offset:64
	global_store_dword v[112:113], v101, off offset:128
	global_store_dword v[112:113], v104, off offset:192
	global_load_dword v99, v[114:115], off
	s_nop 0
	global_load_dword v104, v[114:115], off offset:64
	global_load_dword v105, v[114:115], off offset:128
	global_load_dword v108, v[114:115], off offset:192
	v_or_b32_e32 v100, 19, v98
	v_ashrrev_i32_e32 v101, 31, v100
	v_lshlrev_b64 v[100:101], 10, v[100:101]
	v_lshl_add_u64 v[100:101], v[100:101], 0, v[96:97]
	v_lshl_add_u64 v[100:101], v[100:101], 2, s[22:23]
	s_waitcnt vmcnt(3)
	v_add_f32_e32 v99, v110, v99
	s_waitcnt vmcnt(2)
	v_add_f32_e32 v104, v106, v104
	s_waitcnt vmcnt(1)
	v_add_f32_e32 v102, v102, v105
	s_waitcnt vmcnt(0)
	v_add_f32_e32 v105, v226, v108
	global_store_dword v[114:115], v99, off
	global_store_dword v[114:115], v104, off offset:64
	global_store_dword v[114:115], v102, off offset:128
	global_store_dword v[114:115], v105, off offset:192
	global_load_dword v99, v[100:101], off
	s_nop 0
	global_load_dword v102, v[100:101], off offset:64
	global_load_dword v106, v[100:101], off offset:128
	global_load_dword v108, v[100:101], off offset:192
	v_or_b32_e32 v104, 32, v98
	v_ashrrev_i32_e32 v105, 31, v104
	v_lshlrev_b64 v[104:105], 10, v[104:105]
	v_lshl_add_u64 v[104:105], v[104:105], 0, v[96:97]
	v_lshl_add_u64 v[104:105], v[104:105], 2, s[22:23]
	s_waitcnt vmcnt(3)
; template <int EPI>
; DI void gemm_phase(const u16* __restrict__ A, int lda, const u16* __restrict__ Bt, int K, int N, u16* outb, int ldo,
;                    const float* r0, const float* r1, float* outf, char* lds, int bid, int nb) {
;     ...
; #pragma unroll
;       for (int i = 0; i < 8; ++i)
; #pragma unroll
;         for (int r = 0; r < 4; ++r) {
;           const size_t i0 = (size_t)(mrow + i * 16 + r) * DM + col;
;           const float x0 = rb_[i0], x1 = rb_[i0 + 16], x2 = rb_[i0 + 32], x3 = rb_[i0 + 48];
;           outf[i0] = x0 + acc[i][0][r]; outf[i0 + 16] = x1 + acc[i][1][r]; outf[i0 + 32] = x2 + acc[i][2][r]; outf[i0 + 48] = x3 + acc[i][3][r];
;         }
	v_add_f32_e32 v99, v111, v99
	s_waitcnt vmcnt(2)
	v_add_f32_e32 v102, v107, v102
	s_waitcnt vmcnt(1)
	v_add_f32_e32 v103, v103, v106
	s_waitcnt vmcnt(0)
	v_add_f32_e32 v106, v227, v108
	global_store_dword v[100:101], v99, off
	global_store_dword v[100:101], v102, off offset:64
	global_store_dword v[100:101], v103, off offset:128
	global_store_dword v[100:101], v106, off offset:192
	global_load_dword v99, v[104:105], off
	s_nop 0
	global_load_dword v102, v[104:105], off offset:64
	global_load_dword v103, v[104:105], off offset:128
	global_load_dword v106, v[104:105], off offset:192
	v_or_b32_e32 v100, 33, v98
	v_ashrrev_i32_e32 v101, 31, v100
	v_lshlrev_b64 v[100:101], 10, v[100:101]
	v_lshl_add_u64 v[100:101], v[100:101], 0, v[96:97]
	v_lshl_add_u64 v[100:101], v[100:101], 2, s[22:23]
	s_waitcnt vmcnt(3)
	v_add_f32_e32 v80, v80, v99
	s_waitcnt vmcnt(2)
	v_add_f32_e32 v84, v84, v102
	s_waitcnt vmcnt(1)
	v_add_f32_e32 v88, v88, v103
	s_waitcnt vmcnt(0)
	v_add_f32_e32 v92, v92, v106
	global_store_dword v[104:105], v80, off
	global_store_dword v[104:105], v84, off offset:64
	global_store_dword v[104:105], v88, off offset:128
	global_store_dword v[104:105], v92, off offset:192
	global_load_dword v80, v[100:101], off
	s_nop 0
	global_load_dword v84, v[100:101], off offset:64
	global_load_dword v88, v[100:101], off offset:128
	global_load_dword v92, v[100:101], off offset:192
	v_or_b32_e32 v102, 34, v98
	v_ashrrev_i32_e32 v103, 31, v102
	v_lshlrev_b64 v[102:103], 10, v[102:103]
	v_lshl_add_u64 v[102:103], v[102:103], 0, v[96:97]
	v_lshl_add_u64 v[102:103], v[102:103], 2, s[22:23]
	s_waitcnt vmcnt(3)
	v_add_f32_e32 v80, v81, v80
	s_waitcnt vmcnt(2)
	v_add_f32_e32 v81, v85, v84
	s_waitcnt vmcnt(1)
	v_add_f32_e32 v84, v89, v88
	s_waitcnt vmcnt(0)
	v_add_f32_e32 v85, v93, v92
	global_store_dword v[100:101], v80, off
	global_store_dword v[100:101], v81, off offset:64
	global_store_dword v[100:101], v84, off offset:128
	global_store_dword v[100:101], v85, off offset:192
	global_load_dword v84, v[102:103], off
	s_nop 0
	global_load_dword v85, v[102:103], off offset:64
	global_load_dword v88, v[102:103], off offset:128
	global_load_dword v89, v[102:103], off offset:192
	v_or_b32_e32 v80, 35, v98
	v_ashrrev_i32_e32 v81, 31, v80
	v_lshlrev_b64 v[80:81], 10, v[80:81]
	v_lshl_add_u64 v[80:81], v[80:81], 0, v[96:97]
	v_lshl_add_u64 v[80:81], v[80:81], 2, s[22:23]
	s_waitcnt vmcnt(3)
	v_add_f32_e32 v82, v82, v84
	s_waitcnt vmcnt(2)
	v_add_f32_e32 v84, v86, v85
	s_waitcnt vmcnt(1)
	v_add_f32_e32 v85, v90, v88
	s_waitcnt vmcnt(0)
	v_add_f32_e32 v86, v94, v89
	global_store_dword v[102:103], v82, off
	global_store_dword v[102:103], v84, off offset:64
	global_store_dword v[102:103], v85, off offset:128
	global_store_dword v[102:103], v86, off offset:192
	global_load_dword v82, v[80:81], off
	s_nop 0
	global_load_dword v86, v[80:81], off offset:64
	global_load_dword v88, v[80:81], off offset:128
	global_load_dword v89, v[80:81], off offset:192
	v_or_b32_e32 v84, 48, v98
	v_ashrrev_i32_e32 v85, 31, v84
	v_lshlrev_b64 v[84:85], 10, v[84:85]
	v_lshl_add_u64 v[84:85], v[84:85], 0, v[96:97]
	v_lshl_add_u64 v[84:85], v[84:85], 2, s[22:23]
	s_waitcnt vmcnt(3)
	v_add_f32_e32 v82, v83, v82
	s_waitcnt vmcnt(2)
	v_add_f32_e32 v83, v87, v86
	s_waitcnt vmcnt(1)
	v_add_f32_e32 v86, v91, v88
	s_waitcnt vmcnt(0)
	v_add_f32_e32 v87, v95, v89
	global_store_dword v[80:81], v82, off
	global_store_dword v[80:81], v83, off offset:64
	global_store_dword v[80:81], v86, off offset:128
	global_store_dword v[80:81], v87, off offset:192
	global_load_dword v82, v[84:85], off
	s_nop 0
	global_load_dword v83, v[84:85], off offset:64
	global_load_dword v86, v[84:85], off offset:128
	global_load_dword v87, v[84:85], off offset:192
	v_or_b32_e32 v80, 49, v98
	v_ashrrev_i32_e32 v81, 31, v80
	v_lshlrev_b64 v[80:81], 10, v[80:81]
	v_lshl_add_u64 v[80:81], v[80:81], 0, v[96:97]
	v_lshl_add_u64 v[80:81], v[80:81], 2, s[22:23]
	s_waitcnt vmcnt(3)
	v_add_f32_e32 v64, v64, v82
	s_waitcnt vmcnt(2)
	v_add_f32_e32 v68, v68, v83
	s_waitcnt vmcnt(1)
	v_add_f32_e32 v72, v72, v86
	s_waitcnt vmcnt(0)
	v_add_f32_e32 v76, v76, v87
	global_store_dword v[84:85], v64, off
	global_store_dword v[84:85], v68, off offset:64
	global_store_dword v[84:85], v72, off offset:128
	global_store_dword v[84:85], v76, off offset:192
	global_load_dword v64, v[80:81], off
	s_nop 0
	global_load_dword v68, v[80:81], off offset:64
	global_load_dword v72, v[80:81], off offset:128
	global_load_dword v76, v[80:81], off offset:192
	v_or_b32_e32 v82, 50, v98
	v_ashrrev_i32_e32 v83, 31, v82
	v_lshlrev_b64 v[82:83], 10, v[82:83]
	v_lshl_add_u64 v[82:83], v[82:83], 0, v[96:97]
	v_lshl_add_u64 v[82:83], v[82:83], 2, s[22:23]
	s_waitcnt vmcnt(3)
	v_add_f32_e32 v64, v65, v64
	s_waitcnt vmcnt(2)
	v_add_f32_e32 v65, v69, v68
	s_waitcnt vmcnt(1)
	v_add_f32_e32 v68, v73, v72
	s_waitcnt vmcnt(0)
	v_add_f32_e32 v69, v77, v76
	global_store_dword v[80:81], v64, off
	global_store_dword v[80:81], v65, off offset:64
	global_store_dword v[80:81], v68, off offset:128
	global_store_dword v[80:81], v69, off offset:192
	global_load_dword v68, v[82:83], off
	s_nop 0
	global_load_dword v69, v[82:83], off offset:64
	global_load_dword v72, v[82:83], off offset:128
	global_load_dword v73, v[82:83], off offset:192
	v_or_b32_e32 v64, 51, v98
	v_ashrrev_i32_e32 v65, 31, v64
	v_lshlrev_b64 v[64:65], 10, v[64:65]
	v_lshl_add_u64 v[64:65], v[64:65], 0, v[96:97]
	v_lshl_add_u64 v[64:65], v[64:65], 2, s[22:23]
	s_waitcnt vmcnt(3)
	v_add_f32_e32 v66, v66, v68
	s_waitcnt vmcnt(2)
	v_add_f32_e32 v68, v70, v69
	s_waitcnt vmcnt(1)
	v_add_f32_e32 v69, v74, v72
	s_waitcnt vmcnt(0)
; template <int EPI>
; DI void gemm_phase(const u16* __restrict__ A, int lda, const u16* __restrict__ Bt, int K, int N, u16* outb, int ldo,
;                    const float* r0, const float* r1, float* outf, char* lds, int bid, int nb) {
;     ...
; #pragma unroll
;       for (int i = 0; i < 8; ++i)
; #pragma unroll
;         for (int r = 0; r < 4; ++r) {
;           const size_t i0 = (size_t)(mrow + i * 16 + r) * DM + col;
;           const float x0 = rb_[i0], x1 = rb_[i0 + 16], x2 = rb_[i0 + 32], x3 = rb_[i0 + 48];
;           outf[i0] = x0 + acc[i][0][r]; outf[i0 + 16] = x1 + acc[i][1][r]; outf[i0 + 32] = x2 + acc[i][2][r]; outf[i0 + 48] = x3 + acc[i][3][r];
;         }
	v_add_f32_e32 v70, v78, v73
	global_store_dword v[82:83], v66, off
	global_store_dword v[82:83], v68, off offset:64
	global_store_dword v[82:83], v69, off offset:128
	global_store_dword v[82:83], v70, off offset:192
	global_load_dword v66, v[64:65], off
	s_nop 0
	global_load_dword v70, v[64:65], off offset:64
	global_load_dword v72, v[64:65], off offset:128
	global_load_dword v73, v[64:65], off offset:192
	v_or_b32_e32 v68, 64, v98
	v_ashrrev_i32_e32 v69, 31, v68
	v_lshlrev_b64 v[68:69], 10, v[68:69]
	v_lshl_add_u64 v[68:69], v[68:69], 0, v[96:97]
	v_lshl_add_u64 v[68:69], v[68:69], 2, s[22:23]
	s_waitcnt vmcnt(3)
	v_add_f32_e32 v66, v67, v66
	s_waitcnt vmcnt(2)
	v_add_f32_e32 v67, v71, v70
	s_waitcnt vmcnt(1)
	v_add_f32_e32 v70, v75, v72
	s_waitcnt vmcnt(0)
	v_add_f32_e32 v71, v79, v73
	global_store_dword v[64:65], v66, off
	global_store_dword v[64:65], v67, off offset:64
	global_store_dword v[64:65], v70, off offset:128
	global_store_dword v[64:65], v71, off offset:192
	global_load_dword v66, v[68:69], off
	s_nop 0
	global_load_dword v67, v[68:69], off offset:64
	global_load_dword v70, v[68:69], off offset:128
	global_load_dword v71, v[68:69], off offset:192
	v_or_b32_e32 v64, 0x41, v98
	v_ashrrev_i32_e32 v65, 31, v64
	v_lshlrev_b64 v[64:65], 10, v[64:65]
	v_lshl_add_u64 v[64:65], v[64:65], 0, v[96:97]
	v_lshl_add_u64 v[64:65], v[64:65], 2, s[22:23]
	s_waitcnt vmcnt(3)
	v_add_f32_e32 v48, v48, v66
	s_waitcnt vmcnt(2)
	v_add_f32_e32 v52, v52, v67
	s_waitcnt vmcnt(1)
	v_add_f32_e32 v56, v56, v70
	s_waitcnt vmcnt(0)
	v_add_f32_e32 v60, v60, v71
	global_store_dword v[68:69], v48, off
	global_store_dword v[68:69], v52, off offset:64
	global_store_dword v[68:69], v56, off offset:128
	global_store_dword v[68:69], v60, off offset:192
	global_load_dword v48, v[64:65], off
	s_nop 0
	global_load_dword v52, v[64:65], off offset:64
	global_load_dword v56, v[64:65], off offset:128
	global_load_dword v60, v[64:65], off offset:192
	v_or_b32_e32 v66, 0x42, v98
	v_ashrrev_i32_e32 v67, 31, v66
	v_lshlrev_b64 v[66:67], 10, v[66:67]
	v_lshl_add_u64 v[66:67], v[66:67], 0, v[96:97]
	v_lshl_add_u64 v[66:67], v[66:67], 2, s[22:23]
	s_waitcnt vmcnt(3)
	v_add_f32_e32 v48, v49, v48
	s_waitcnt vmcnt(2)
	v_add_f32_e32 v49, v53, v52
	s_waitcnt vmcnt(1)
	v_add_f32_e32 v52, v57, v56
	s_waitcnt vmcnt(0)
	v_add_f32_e32 v53, v61, v60
	global_store_dword v[64:65], v48, off
	global_store_dword v[64:65], v49, off offset:64
	global_store_dword v[64:65], v52, off offset:128
	global_store_dword v[64:65], v53, off offset:192
	global_load_dword v52, v[66:67], off
	s_nop 0
	global_load_dword v53, v[66:67], off offset:64
	global_load_dword v56, v[66:67], off offset:128
	global_load_dword v57, v[66:67], off offset:192
	v_or_b32_e32 v48, 0x43, v98
	v_ashrrev_i32_e32 v49, 31, v48
	v_lshlrev_b64 v[48:49], 10, v[48:49]
	v_lshl_add_u64 v[48:49], v[48:49], 0, v[96:97]
	v_lshl_add_u64 v[48:49], v[48:49], 2, s[22:23]
	s_waitcnt vmcnt(3)
	v_add_f32_e32 v50, v50, v52
	s_waitcnt vmcnt(2)
	v_add_f32_e32 v52, v54, v53
	s_waitcnt vmcnt(1)
	v_add_f32_e32 v53, v58, v56
	s_waitcnt vmcnt(0)
	v_add_f32_e32 v54, v62, v57
	global_store_dword v[66:67], v50, off
	global_store_dword v[66:67], v52, off offset:64
	global_store_dword v[66:67], v53, off offset:128
	global_store_dword v[66:67], v54, off offset:192
	global_load_dword v50, v[48:49], off
	s_nop 0
	global_load_dword v54, v[48:49], off offset:64
	global_load_dword v56, v[48:49], off offset:128
	global_load_dword v57, v[48:49], off offset:192
	v_or_b32_e32 v52, 0x50, v98
	v_ashrrev_i32_e32 v53, 31, v52
	v_lshlrev_b64 v[52:53], 10, v[52:53]
	v_lshl_add_u64 v[52:53], v[52:53], 0, v[96:97]
	v_lshl_add_u64 v[52:53], v[52:53], 2, s[22:23]
	s_waitcnt vmcnt(3)
	v_add_f32_e32 v50, v51, v50
	s_waitcnt vmcnt(2)
	v_add_f32_e32 v51, v55, v54
	s_waitcnt vmcnt(1)
	v_add_f32_e32 v54, v59, v56
	s_waitcnt vmcnt(0)
	v_add_f32_e32 v55, v63, v57
	global_store_dword v[48:49], v50, off
	global_store_dword v[48:49], v51, off offset:64
	global_store_dword v[48:49], v54, off offset:128
	global_store_dword v[48:49], v55, off offset:192
	global_load_dword v50, v[52:53], off
	s_nop 0
	global_load_dword v51, v[52:53], off offset:64
	global_load_dword v54, v[52:53], off offset:128
	global_load_dword v55, v[52:53], off offset:192
	v_or_b32_e32 v48, 0x51, v98
	v_ashrrev_i32_e32 v49, 31, v48
	v_lshlrev_b64 v[48:49], 10, v[48:49]
	v_lshl_add_u64 v[48:49], v[48:49], 0, v[96:97]
	v_lshl_add_u64 v[48:49], v[48:49], 2, s[22:23]
	s_waitcnt vmcnt(3)
	v_add_f32_e32 v32, v32, v50
	s_waitcnt vmcnt(2)
	v_add_f32_e32 v36, v36, v51
	s_waitcnt vmcnt(1)
	v_add_f32_e32 v40, v40, v54
	s_waitcnt vmcnt(0)
	v_add_f32_e32 v44, v44, v55
	global_store_dword v[52:53], v32, off
	global_store_dword v[52:53], v36, off offset:64
	global_store_dword v[52:53], v40, off offset:128
	global_store_dword v[52:53], v44, off offset:192
	global_load_dword v32, v[48:49], off
	s_nop 0
	global_load_dword v36, v[48:49], off offset:64
	global_load_dword v40, v[48:49], off offset:128
	global_load_dword v44, v[48:49], off offset:192
	v_or_b32_e32 v50, 0x52, v98
	v_ashrrev_i32_e32 v51, 31, v50
	v_lshlrev_b64 v[50:51], 10, v[50:51]
	v_lshl_add_u64 v[50:51], v[50:51], 0, v[96:97]
	v_lshl_add_u64 v[50:51], v[50:51], 2, s[22:23]
	s_waitcnt vmcnt(3)
	v_add_f32_e32 v32, v33, v32
	s_waitcnt vmcnt(2)
	v_add_f32_e32 v33, v37, v36
	s_waitcnt vmcnt(1)
	v_add_f32_e32 v36, v41, v40
	s_waitcnt vmcnt(0)
; template <int EPI>
; DI void gemm_phase(const u16* __restrict__ A, int lda, const u16* __restrict__ Bt, int K, int N, u16* outb, int ldo,
;                    const float* r0, const float* r1, float* outf, char* lds, int bid, int nb) {
;     ...
; #pragma unroll
;       for (int i = 0; i < 8; ++i)
; #pragma unroll
;         for (int r = 0; r < 4; ++r) {
;           const size_t i0 = (size_t)(mrow + i * 16 + r) * DM + col;
;           const float x0 = rb_[i0], x1 = rb_[i0 + 16], x2 = rb_[i0 + 32], x3 = rb_[i0 + 48];
;           outf[i0] = x0 + acc[i][0][r]; outf[i0 + 16] = x1 + acc[i][1][r]; outf[i0 + 32] = x2 + acc[i][2][r]; outf[i0 + 48] = x3 + acc[i][3][r];
;         }
	v_add_f32_e32 v37, v45, v44
	global_store_dword v[48:49], v32, off
	global_store_dword v[48:49], v33, off offset:64
	global_store_dword v[48:49], v36, off offset:128
	global_store_dword v[48:49], v37, off offset:192
	global_load_dword v36, v[50:51], off
	s_nop 0
	global_load_dword v37, v[50:51], off offset:64
	global_load_dword v40, v[50:51], off offset:128
	global_load_dword v41, v[50:51], off offset:192
	v_or_b32_e32 v32, 0x53, v98
	v_ashrrev_i32_e32 v33, 31, v32
	v_lshlrev_b64 v[32:33], 10, v[32:33]
	v_lshl_add_u64 v[32:33], v[32:33], 0, v[96:97]
	v_lshl_add_u64 v[32:33], v[32:33], 2, s[22:23]
	s_waitcnt vmcnt(3)
	v_add_f32_e32 v34, v34, v36
	s_waitcnt vmcnt(2)
	v_add_f32_e32 v36, v38, v37
	s_waitcnt vmcnt(1)
	v_add_f32_e32 v37, v42, v40
	s_waitcnt vmcnt(0)
	v_add_f32_e32 v38, v46, v41
	global_store_dword v[50:51], v34, off
	global_store_dword v[50:51], v36, off offset:64
	global_store_dword v[50:51], v37, off offset:128
	global_store_dword v[50:51], v38, off offset:192
	global_load_dword v34, v[32:33], off
	s_nop 0
	global_load_dword v38, v[32:33], off offset:64
	global_load_dword v40, v[32:33], off offset:128
	global_load_dword v41, v[32:33], off offset:192
	v_or_b32_e32 v36, 0x60, v98
	v_ashrrev_i32_e32 v37, 31, v36
	v_lshlrev_b64 v[36:37], 10, v[36:37]
	v_lshl_add_u64 v[36:37], v[36:37], 0, v[96:97]
	v_lshl_add_u64 v[36:37], v[36:37], 2, s[22:23]
	s_waitcnt vmcnt(3)
	v_add_f32_e32 v34, v35, v34
	s_waitcnt vmcnt(2)
	v_add_f32_e32 v35, v39, v38
	s_waitcnt vmcnt(1)
	v_add_f32_e32 v38, v43, v40
	s_waitcnt vmcnt(0)
	v_add_f32_e32 v39, v47, v41
	global_store_dword v[32:33], v34, off
	global_store_dword v[32:33], v35, off offset:64
	global_store_dword v[32:33], v38, off offset:128
	global_store_dword v[32:33], v39, off offset:192
	global_load_dword v34, v[36:37], off
	s_nop 0
	global_load_dword v35, v[36:37], off offset:64
	global_load_dword v38, v[36:37], off offset:128
	global_load_dword v39, v[36:37], off offset:192
	v_or_b32_e32 v32, 0x61, v98
	v_ashrrev_i32_e32 v33, 31, v32
	v_lshlrev_b64 v[32:33], 10, v[32:33]
	v_lshl_add_u64 v[32:33], v[32:33], 0, v[96:97]
	v_lshl_add_u64 v[32:33], v[32:33], 2, s[22:23]
	s_waitcnt vmcnt(3)
	v_add_f32_e32 v16, v16, v34
	s_waitcnt vmcnt(2)
	v_add_f32_e32 v20, v20, v35
	s_waitcnt vmcnt(1)
	v_add_f32_e32 v24, v24, v38
	s_waitcnt vmcnt(0)
	v_add_f32_e32 v28, v28, v39
	global_store_dword v[36:37], v16, off
	global_store_dword v[36:37], v20, off offset:64
	global_store_dword v[36:37], v24, off offset:128
	global_store_dword v[36:37], v28, off offset:192
	global_load_dword v16, v[32:33], off
	s_nop 0
	global_load_dword v20, v[32:33], off offset:64
	global_load_dword v24, v[32:33], off offset:128
	global_load_dword v28, v[32:33], off offset:192
	v_or_b32_e32 v34, 0x62, v98
	v_ashrrev_i32_e32 v35, 31, v34
	v_lshlrev_b64 v[34:35], 10, v[34:35]
	v_lshl_add_u64 v[34:35], v[34:35], 0, v[96:97]
	v_lshl_add_u64 v[34:35], v[34:35], 2, s[22:23]
	s_waitcnt vmcnt(3)
	v_add_f32_e32 v16, v17, v16
	s_waitcnt vmcnt(2)
	v_add_f32_e32 v17, v21, v20
	s_waitcnt vmcnt(1)
	v_add_f32_e32 v20, v25, v24
	s_waitcnt vmcnt(0)
	v_add_f32_e32 v21, v29, v28
	global_store_dword v[32:33], v16, off
	global_store_dword v[32:33], v17, off offset:64
	global_store_dword v[32:33], v20, off offset:128
	global_store_dword v[32:33], v21, off offset:192
	global_load_dword v20, v[34:35], off
	s_nop 0
	global_load_dword v21, v[34:35], off offset:64
	global_load_dword v24, v[34:35], off offset:128
	global_load_dword v25, v[34:35], off offset:192
	v_or_b32_e32 v16, 0x63, v98
	v_ashrrev_i32_e32 v17, 31, v16
	v_lshlrev_b64 v[16:17], 10, v[16:17]
	v_lshl_add_u64 v[16:17], v[16:17], 0, v[96:97]
	v_lshl_add_u64 v[16:17], v[16:17], 2, s[22:23]
	s_waitcnt vmcnt(3)
	v_add_f32_e32 v18, v18, v20
	s_waitcnt vmcnt(2)
	v_add_f32_e32 v20, v22, v21
	s_waitcnt vmcnt(1)
	v_add_f32_e32 v21, v26, v24
	s_waitcnt vmcnt(0)
; template <int EPI>
; DI void gemm_phase(const u16* __restrict__ A, int lda, const u16* __restrict__ Bt, int K, int N, u16* outb, int ldo,
;                    const float* r0, const float* r1, float* outf, char* lds, int bid, int nb) {
;     ...
; #pragma unroll
;       for (int i = 0; i < 8; ++i)
; #pragma unroll
;         for (int r = 0; r < 4; ++r) {
;           const size_t i0 = (size_t)(mrow + i * 16 + r) * DM + col;
;           const float x0 = rb_[i0], x1 = rb_[i0 + 16], x2 = rb_[i0 + 32], x3 = rb_[i0 + 48];
;           outf[i0] = x0 + acc[i][0][r]; outf[i0 + 16] = x1 + acc[i][1][r]; outf[i0 + 32] = x2 + acc[i][2][r]; outf[i0 + 48] = x3 + acc[i][3][r];
;         }
	v_add_f32_e32 v22, v30, v25
	global_store_dword v[34:35], v18, off
	global_store_dword v[34:35], v20, off offset:64
	global_store_dword v[34:35], v21, off offset:128
	global_store_dword v[34:35], v22, off offset:192
	global_load_dword v18, v[16:17], off
	s_nop 0
	global_load_dword v22, v[16:17], off offset:64
	global_load_dword v24, v[16:17], off offset:128
	global_load_dword v25, v[16:17], off offset:192
	v_or_b32_e32 v20, 0x70, v98
	v_ashrrev_i32_e32 v21, 31, v20
	v_lshlrev_b64 v[20:21], 10, v[20:21]
	v_lshl_add_u64 v[20:21], v[20:21], 0, v[96:97]
	v_lshl_add_u64 v[20:21], v[20:21], 2, s[22:23]
	s_waitcnt vmcnt(3)
	v_add_f32_e32 v18, v19, v18
	s_waitcnt vmcnt(2)
	v_add_f32_e32 v19, v23, v22
	s_waitcnt vmcnt(1)
	v_add_f32_e32 v22, v27, v24
	s_waitcnt vmcnt(0)
	v_add_f32_e32 v23, v31, v25
	global_store_dword v[16:17], v18, off
	global_store_dword v[16:17], v19, off offset:64
	global_store_dword v[16:17], v22, off offset:128
	global_store_dword v[16:17], v23, off offset:192
	global_load_dword v18, v[20:21], off
	s_nop 0
	global_load_dword v19, v[20:21], off offset:64
	global_load_dword v22, v[20:21], off offset:128
	global_load_dword v23, v[20:21], off offset:192
	v_or_b32_e32 v16, 0x71, v98
	v_ashrrev_i32_e32 v17, 31, v16
	v_lshlrev_b64 v[16:17], 10, v[16:17]
	v_lshl_add_u64 v[16:17], v[16:17], 0, v[96:97]
	v_lshl_add_u64 v[16:17], v[16:17], 2, s[22:23]
	s_waitcnt vmcnt(3)
	v_add_f32_e32 v0, v0, v18
	s_waitcnt vmcnt(2)
	v_add_f32_e32 v4, v4, v19
	s_waitcnt vmcnt(1)
	v_add_f32_e32 v8, v8, v22
	s_waitcnt vmcnt(0)
	v_add_f32_e32 v12, v12, v23
	global_store_dword v[20:21], v0, off
	global_store_dword v[20:21], v4, off offset:64
	global_store_dword v[20:21], v8, off offset:128
	global_store_dword v[20:21], v12, off offset:192
	global_load_dword v0, v[16:17], off
	s_nop 0
	global_load_dword v4, v[16:17], off offset:64
	global_load_dword v8, v[16:17], off offset:128
	global_load_dword v12, v[16:17], off offset:192
	v_or_b32_e32 v18, 0x72, v98
	v_ashrrev_i32_e32 v19, 31, v18
	v_lshlrev_b64 v[18:19], 10, v[18:19]
	v_lshl_add_u64 v[18:19], v[18:19], 0, v[96:97]
	v_lshl_add_u64 v[18:19], v[18:19], 2, s[22:23]
	s_waitcnt vmcnt(3)
	v_add_f32_e32 v0, v1, v0
	s_waitcnt vmcnt(2)
	v_add_f32_e32 v1, v5, v4
	s_waitcnt vmcnt(1)
	v_add_f32_e32 v4, v9, v8
	s_waitcnt vmcnt(0)
	v_add_f32_e32 v5, v13, v12
	global_store_dword v[16:17], v0, off
	global_store_dword v[16:17], v1, off offset:64
	global_store_dword v[16:17], v4, off offset:128
	global_store_dword v[16:17], v5, off offset:192
	global_load_dword v4, v[18:19], off
	s_nop 0
	global_load_dword v5, v[18:19], off offset:64
	global_load_dword v8, v[18:19], off offset:128
	global_load_dword v9, v[18:19], off offset:192
	v_or_b32_e32 v0, 0x73, v98
	v_ashrrev_i32_e32 v1, 31, v0
	v_lshlrev_b64 v[0:1], 10, v[0:1]
	v_lshl_add_u64 v[0:1], v[0:1], 0, v[96:97]
	v_lshl_add_u64 v[0:1], v[0:1], 2, s[22:23]
	s_waitcnt vmcnt(3)
	v_add_f32_e32 v2, v2, v4
	s_waitcnt vmcnt(2)
	v_add_f32_e32 v4, v6, v5
	s_waitcnt vmcnt(1)
	v_add_f32_e32 v5, v10, v8
	s_waitcnt vmcnt(0)
	v_add_f32_e32 v6, v14, v9
	global_store_dword v[18:19], v2, off
	global_store_dword v[18:19], v4, off offset:64
	global_store_dword v[18:19], v5, off offset:128
	global_store_dword v[18:19], v6, off offset:192
	global_load_dword v2, v[0:1], off
	s_nop 0
	global_load_dword v4, v[0:1], off offset:64
	global_load_dword v5, v[0:1], off offset:128
	global_load_dword v6, v[0:1], off offset:192
	s_waitcnt vmcnt(3)
	v_add_f32_e32 v2, v3, v2
	s_waitcnt vmcnt(2)
	v_add_f32_e32 v3, v7, v4
	s_waitcnt vmcnt(1)
	v_add_f32_e32 v4, v11, v5
	s_waitcnt vmcnt(0)
	v_add_f32_e32 v5, v15, v6
	global_store_dword v[0:1], v2, off
	global_store_dword v[0:1], v3, off offset:64
	global_store_dword v[0:1], v4, off offset:128
	global_store_dword v[0:1], v5, off offset:192
	s_cbranch_scc0 .LBB0_1177

; #define G_LOAD(KT) do { _Pragma("unroll") for (int i = 0; i < 4; ++i) { ra[i] = *(const u32x4*)(Ag + (size_t)i * 64 * lda + (KT) * 64); rb[i] = *(const u32x4*)(Bg + (size_t)i * 64 * K + (KT) * 64); } } while (0)
; #define G_STORE(BUF) do { u16* ad = As + (BUF) * 256 * 64 + sto; u16* bd = Bs + (BUF) * 256 * 64 + sto; _Pragma("unroll") for (int i = 0; i < 4; ++i) { *(u32x4*)(ad + i * 64 * 64) = ra[i]; *(u32x4*)(bd + i * 64 * 64) = rb[i]; } } while (0)
; template <int EPI>
; DI void gemm_phase(const u16* __restrict__ A, int lda, const u16* __restrict__ Bt, int K, int N, u16* outb, int ldo,
;                    const float* r0, const float* r1, float* outf, char* lds, int bid, int nb) {
;     ...
;   for (int it = 0; it < nIter; ++it) {
;     int tm, tn;
;     if (swz) { const int st = xcd + 8 * it, sm = st / nSN, sn = st - sm * nSN; tm = sm * GM + jb / GN; tn = sn * GN + (jb % GN); }
;     else { const int t = bid + it * nb; tm = t / nN; tn = t - tm * nN; }
;     const u16* Ag = A + (size_t)(tm * 256 + lrow) * lda + lch * 8;
;     const u16* Bg = Bt + (size_t)(tn * 256 + lrow) * K + lch * 8;
;     f32x4 acc[8][4];
; #pragma unroll
;     for (int i = 0; i < 8; ++i)
; #pragma unroll
;       for (int j = 0; j < 4; ++j) acc[i][j] = (f32x4){0.f, 0.f, 0.f, 0.f};
;     u32x4 ra[4], rb[4];
;     ...
;     G_LOAD(0);
;     G_STORE(0);
;     __syncthreads();
.LBB0_1301:
	s_lshl_b32 s41, s41, 8
	v_or_b32_e32 v0, s41, v138
	v_ashrrev_i32_e32 v1, 31, v0
	v_lshlrev_b64 v[64:65], 11, v[0:1]
	v_lshl_or_b32 v0, s40, 8, v138
	v_ashrrev_i32_e32 v1, 31, v0
	v_lshlrev_b64 v[66:67], 11, v[0:1]
	v_lshl_add_u64 v[0:1], v[128:129], 0, v[64:65]
	v_add_co_u32_e32 v4, vcc, 0x20000, v0
	v_lshl_add_u64 v[2:3], v[130:131], 0, v[66:67]
	s_nop 0
	v_addc_co_u32_e32 v5, vcc, 0, v1, vcc
	v_add_co_u32_e32 v6, vcc, 0x20000, v2
	s_nop 1
	v_readfirstlane_b32 s98, v0
	v_readfirstlane_b32 s99, v1
	s_nop 1
	v_readfirstlane_b32 s100, v2
	v_readfirstlane_b32 s101, v3
	v_addc_co_u32_e32 v7, vcc, 0, v3, vcc
	v_add_co_u32_e32 v4, vcc, 0x40000, v0
	s_mov_b32 s42, 0
	s_nop 0
	v_addc_co_u32_e32 v5, vcc, 0, v1, vcc
	v_add_co_u32_e32 v6, vcc, 0x40000, v2
	s_mov_b64 s[10:11], 0
	s_nop 0
	v_addc_co_u32_e32 v7, vcc, 0, v3, vcc
	v_add_co_u32_e32 v0, vcc, 0x60000, v0
	v_addc_co_u32_e32 v1, vcc, 0, v1, vcc
	v_add_co_u32_e32 v2, vcc, 0x60000, v2
	v_lshl_add_u64 v[134:135], v[132:133], 0, v[66:67]
	s_nop 0
	v_addc_co_u32_e32 v3, vcc, 0, v3, vcc
	v_mov_b32_e32 v0, 0
	v_mov_b32_e32 v1, v0
	v_mov_b32_e32 v2, v0
	v_mov_b32_e32 v3, v0
	v_mov_b32_e32 v4, v0
	v_mov_b32_e32 v5, v0
	v_mov_b32_e32 v6, v0
	v_mov_b32_e32 v7, v0
	v_mov_b32_e32 v8, v0
	v_mov_b32_e32 v9, v0
	v_mov_b32_e32 v10, v0
	v_mov_b32_e32 v11, v0
	v_mov_b32_e32 v12, v0
	v_mov_b32_e32 v13, v0
	v_mov_b32_e32 v14, v0
	v_mov_b32_e32 v15, v0
	v_mov_b32_e32 v16, v0
	v_mov_b32_e32 v17, v0
	v_mov_b32_e32 v18, v0
	v_mov_b32_e32 v19, v0
	v_mov_b32_e32 v20, v0
	v_mov_b32_e32 v21, v0
	v_mov_b32_e32 v22, v0
	v_mov_b32_e32 v23, v0
	v_mov_b32_e32 v24, v0
	v_mov_b32_e32 v25, v0
	v_mov_b32_e32 v26, v0
	v_mov_b32_e32 v27, v0
	v_mov_b32_e32 v28, v0
	v_mov_b32_e32 v29, v0
	v_mov_b32_e32 v30, v0
	v_lshl_add_u64 v[136:137], v[132:133], 0, v[64:65]
	v_mov_b32_e32 v31, v0
	v_mov_b32_e32 v64, v0
	v_mov_b32_e32 v65, v0
	v_mov_b32_e32 v66, v0
	v_mov_b32_e32 v67, v0
	v_mov_b32_e32 v68, v0
	v_mov_b32_e32 v69, v0
	v_mov_b32_e32 v70, v0
	v_mov_b32_e32 v71, v0
	v_mov_b32_e32 v72, v0
	v_mov_b32_e32 v73, v0
	v_mov_b32_e32 v74, v0
	v_mov_b32_e32 v75, v0
	v_mov_b32_e32 v76, v0
	v_mov_b32_e32 v77, v0
	v_mov_b32_e32 v78, v0
	v_mov_b32_e32 v79, v0
	v_mov_b32_e32 v80, v0
	v_mov_b32_e32 v81, v0
	v_mov_b32_e32 v82, v0
	v_mov_b32_e32 v83, v0
	v_mov_b32_e32 v84, v0
	v_mov_b32_e32 v85, v0
	v_mov_b32_e32 v86, v0
	v_mov_b32_e32 v87, v0
	v_mov_b32_e32 v32, v0
	v_mov_b32_e32 v33, v0
	v_mov_b32_e32 v34, v0
	v_mov_b32_e32 v35, v0
	v_mov_b32_e32 v36, v0
	v_mov_b32_e32 v37, v0
	v_mov_b32_e32 v38, v0
	v_mov_b32_e32 v39, v0
	v_mov_b32_e32 v40, v0
	v_mov_b32_e32 v41, v0
	v_mov_b32_e32 v42, v0
	v_mov_b32_e32 v43, v0
	v_mov_b32_e32 v44, v0
	v_mov_b32_e32 v45, v0
	v_mov_b32_e32 v46, v0
	v_mov_b32_e32 v47, v0
	v_mov_b32_e32 v48, v0
	v_mov_b32_e32 v49, v0
	v_mov_b32_e32 v50, v0
	v_mov_b32_e32 v51, v0
	v_mov_b32_e32 v52, v0
	v_mov_b32_e32 v53, v0
	v_mov_b32_e32 v54, v0
	v_mov_b32_e32 v55, v0
	v_mov_b32_e32 v56, v0
	v_mov_b32_e32 v57, v0
	v_mov_b32_e32 v58, v0
	v_mov_b32_e32 v59, v0
	v_mov_b32_e32 v60, v0
	v_mov_b32_e32 v61, v0
	v_mov_b32_e32 v62, v0
	v_mov_b32_e32 v63, v0
	v_mov_b32_e32 v88, v0
	v_mov_b32_e32 v89, v0
	v_mov_b32_e32 v90, v0
	v_mov_b32_e32 v91, v0
	v_mov_b32_e32 v92, v0
	v_mov_b32_e32 v93, v0
	v_mov_b32_e32 v94, v0
	v_mov_b32_e32 v95, v0
	v_mov_b32_e32 v96, v0
	v_mov_b32_e32 v97, v0
	v_mov_b32_e32 v98, v0
	v_mov_b32_e32 v99, v0
	v_mov_b32_e32 v100, v0
	v_mov_b32_e32 v101, v0
	v_mov_b32_e32 v102, v0
	v_mov_b32_e32 v103, v0
	v_mov_b32_e32 v104, v0
	v_mov_b32_e32 v105, v0
	v_mov_b32_e32 v106, v0
	v_mov_b32_e32 v107, v0
	v_mov_b32_e32 v108, v0
	v_mov_b32_e32 v109, v0
	v_mov_b32_e32 v110, v0
	v_mov_b32_e32 v111, v0
	v_mov_b32_e32 v112, v0
	v_mov_b32_e32 v113, v0
	v_mov_b32_e32 v114, v0
	v_mov_b32_e32 v115, v0
	v_mov_b32_e32 v116, v0
	v_mov_b32_e32 v117, v0
	v_mov_b32_e32 v118, v0
	v_mov_b32_e32 v119, v0
	v_mov_b32_e32 v120, v0
	v_mov_b32_e32 v121, v0
	v_mov_b32_e32 v122, v0
	v_mov_b32_e32 v123, v0
	v_mov_b32_e32 v124, v0
	v_mov_b32_e32 v125, v0
	v_mov_b32_e32 v126, v0
	v_mov_b32_e32 v127, v0
	v_and_b32_e32 v229, 63, v174
	v_lshrrev_b32_e32 v230, 3, v229
	v_mov_b32_e32 v233, 0x800
	v_mul_u32_u24_e32 v224, v230, v233
	v_bfe_u32 v231, v174, 4, 2
	v_bfe_u32 v232, v174, 6, 1
	v_lshl_or_b32 v232, v232, 2, v231
	v_and_b32_e32 v233, 7, v174
	v_xor_b32_e32 v232, v232, v233
	v_lshl_add_u32 v224, v232, 4, v224
	v_and_b32_e32 v229, 15, v174
	v_bfe_u32 v230, v174, 1, 3
	v_xor_b32_e32 v230, v230, v231
	v_lshlrev_b32_e32 v230, 4, v230
	v_lshl_or_b32 v230, v229, 7, v230
	v_lshrrev_b32_e32 v229, 8, v174
	v_lshl_or_b32 v225, v229, 14, v230
	v_bfe_u32 v229, v174, 6, 2
	v_lshl_or_b32 v227, v229, 13, v230
	v_or_b32_e32 v227, 0x10000, v227
	v_xor_b32_e32 v226, 64, v225
	v_xor_b32_e32 v228, 64, v227
	v_readfirstlane_b32 s97, v174
	s_lshl_b32 s97, s97, 4
	s_mov_b32 s28, 14
	s_add_u32 s10, s98, 0x0
	s_addc_u32 s11, s99, 0
	s_add_u32 m0, s97, 0x0
	s_nop 0
	global_load_lds_dwordx4 v224, s[10:11]
	s_add_u32 s10, s100, 0x0
	s_addc_u32 s11, s101, 0
	s_add_u32 m0, s97, 0x10000
	s_nop 0
	global_load_lds_dwordx4 v224, s[10:11]
	s_add_u32 s10, s98, 0x20000
	s_addc_u32 s11, s99, 0
	s_add_u32 m0, s97, 0x2000
	s_nop 0
	global_load_lds_dwordx4 v224, s[10:11]
	s_add_u32 s10, s100, 0x20000
	s_addc_u32 s11, s101, 0
	s_add_u32 m0, s97, 0x12000
	s_nop 0
	global_load_lds_dwordx4 v224, s[10:11]
	s_add_u32 s10, s98, 0x40000
	s_addc_u32 s11, s99, 0
	s_add_u32 m0, s97, 0x4000
	s_nop 0
	global_load_lds_dwordx4 v224, s[10:11]
	s_add_u32 s10, s100, 0x40000
	s_addc_u32 s11, s101, 0
	s_add_u32 m0, s97, 0x14000
	s_nop 0
	global_load_lds_dwordx4 v224, s[10:11]
	s_add_u32 s10, s98, 0x60000
	s_addc_u32 s11, s99, 0
	s_add_u32 m0, s97, 0x6000
	s_nop 0
	global_load_lds_dwordx4 v224, s[10:11]
	s_add_u32 s10, s100, 0x60000
	s_addc_u32 s11, s101, 0
	s_add_u32 m0, s97, 0x16000
	s_nop 0
	global_load_lds_dwordx4 v224, s[10:11]
	s_add_u32 s10, s98, 0x80
	s_addc_u32 s11, s99, 0
	s_add_u32 m0, s97, 0x8000
	s_nop 0
	global_load_lds_dwordx4 v224, s[10:11]
	s_add_u32 s10, s100, 0x80
	s_addc_u32 s11, s101, 0
	s_add_u32 m0, s97, 0x18000
	s_nop 0
	global_load_lds_dwordx4 v224, s[10:11]
	s_add_u32 s10, s98, 0x20080
	s_addc_u32 s11, s99, 0
	s_add_u32 m0, s97, 0xa000
	s_nop 0
	global_load_lds_dwordx4 v224, s[10:11]
	s_add_u32 s10, s100, 0x20080
	s_addc_u32 s11, s101, 0
	s_add_u32 m0, s97, 0x1a000
	s_nop 0
	global_load_lds_dwordx4 v224, s[10:11]
	s_add_u32 s10, s98, 0x40080
	s_addc_u32 s11, s99, 0
	s_add_u32 m0, s97, 0xc000
	s_nop 0
	global_load_lds_dwordx4 v224, s[10:11]
	s_add_u32 s10, s100, 0x40080
	s_addc_u32 s11, s101, 0
	s_add_u32 m0, s97, 0x1c000
	s_nop 0
	global_load_lds_dwordx4 v224, s[10:11]
	s_add_u32 s10, s98, 0x60080
	s_addc_u32 s11, s99, 0
	s_add_u32 m0, s97, 0xe000
	s_nop 0
	global_load_lds_dwordx4 v224, s[10:11]
	s_add_u32 s10, s100, 0x60080
	s_addc_u32 s11, s101, 0
	s_add_u32 m0, s97, 0x1e000
	s_nop 0
	global_load_lds_dwordx4 v224, s[10:11]
	s_add_u32 s98, s98, 0x100
	s_addc_u32 s99, s99, 0
	s_add_u32 s100, s100, 0x100
	s_addc_u32 s101, s101, 0
	s_waitcnt vmcnt(8)
; #define G_LOAD(KT) do { _Pragma("unroll") for (int i = 0; i < 4; ++i) { ra[i] = *(const u32x4*)(Ag + (size_t)i * 64 * lda + (KT) * 64); rb[i] = *(const u32x4*)(Bg + (size_t)i * 64 * K + (KT) * 64); } } while (0)
; #define G_STORE(BUF) do { u16* ad = As + (BUF) * 256 * 64 + sto; u16* bd = Bs + (BUF) * 256 * 64 + sto; _Pragma("unroll") for (int i = 0; i < 4; ++i) { *(u32x4*)(ad + i * 64 * 64) = ra[i]; *(u32x4*)(bd + i * 64 * 64) = rb[i]; } } while (0)
; template <int EPI>
; DI void gemm_phase(const u16* __restrict__ A, int lda, const u16* __restrict__ Bt, int K, int N, u16* outb, int ldo,
;                    const float* r0, const float* r1, float* outf, char* lds, int bid, int nb) {
;     ...
;     G_LOAD(0);
;     G_STORE(0);
;     __syncthreads();
;     for (int kt = 0; kt < nk; ++kt) {
;       const int cur = kt & 1;
;       if (kt + 1 < nk) G_LOAD(kt + 1);
;       G_MMA(cur, fo0);
;       G_MMA(cur, fo1);
;       if (kt + 1 < nk) G_STORE(cur ^ 1);
;       __syncthreads();
	s_barrier
	ds_read_b128 v[152:155], v227 offset:0
	ds_read_b128 v[156:159], v227 offset:2048
	ds_read_b128 v[160:163], v227 offset:4096
	ds_read_b128 v[164:167], v227 offset:6144
	ds_read_b128 v[188:191], v225 offset:0
	ds_read_b128 v[192:195], v225 offset:2048
	ds_read_b128 v[196:199], v225 offset:4096
	ds_read_b128 v[200:203], v225 offset:6144
	ds_read_b128 v[204:207], v225 offset:8192
	ds_read_b128 v[208:211], v225 offset:10240
	ds_read_b128 v[212:215], v225 offset:12288
	ds_read_b128 v[216:219], v225 offset:14336
	v_xor_b32_e32 v225, 0x8000, v225
	v_xor_b32_e32 v227, 0x8000, v227
	s_waitcnt lgkmcnt(0)
.Lgm6_loop:
	s_waitcnt lgkmcnt(4)
	v_mfma_f32_16x16x32_bf16 v[124:127], v[188:191], v[152:155], v[124:127]
	v_mfma_f32_16x16x32_bf16 v[120:123], v[188:191], v[156:159], v[120:123]
	v_mfma_f32_16x16x32_bf16 v[116:119], v[188:191], v[160:163], v[116:119]
	v_mfma_f32_16x16x32_bf16 v[112:115], v[188:191], v[164:167], v[112:115]
	ds_read_b128 v[188:191], v226 offset:0
	ds_read_b128 v[168:171], v228 offset:0
	v_mfma_f32_16x16x32_bf16 v[108:111], v[192:195], v[152:155], v[108:111]
	v_mfma_f32_16x16x32_bf16 v[104:107], v[192:195], v[156:159], v[104:107]
	v_mfma_f32_16x16x32_bf16 v[100:103], v[192:195], v[160:163], v[100:103]
	v_mfma_f32_16x16x32_bf16 v[96:99], v[192:195], v[164:167], v[96:99]
	ds_read_b128 v[192:195], v226 offset:2048
	ds_read_b128 v[176:179], v228 offset:2048
	v_mfma_f32_16x16x32_bf16 v[92:95], v[196:199], v[152:155], v[92:95]
	v_mfma_f32_16x16x32_bf16 v[88:91], v[196:199], v[156:159], v[88:91]
	v_mfma_f32_16x16x32_bf16 v[84:87], v[196:199], v[160:163], v[84:87]
	v_mfma_f32_16x16x32_bf16 v[80:83], v[196:199], v[164:167], v[80:83]
	ds_read_b128 v[196:199], v226 offset:4096
	ds_read_b128 v[180:183], v228 offset:4096
	v_mfma_f32_16x16x32_bf16 v[76:79], v[200:203], v[152:155], v[76:79]
	v_mfma_f32_16x16x32_bf16 v[72:75], v[200:203], v[156:159], v[72:75]
	v_mfma_f32_16x16x32_bf16 v[68:71], v[200:203], v[160:163], v[68:71]
	v_mfma_f32_16x16x32_bf16 v[64:67], v[200:203], v[164:167], v[64:67]
	ds_read_b128 v[200:203], v226 offset:6144
	ds_read_b128 v[184:187], v228 offset:6144
	s_waitcnt lgkmcnt(11)
	v_mfma_f32_16x16x32_bf16 v[60:63], v[204:207], v[152:155], v[60:63]
	v_mfma_f32_16x16x32_bf16 v[56:59], v[204:207], v[156:159], v[56:59]
	v_mfma_f32_16x16x32_bf16 v[52:55], v[204:207], v[160:163], v[52:55]
	v_mfma_f32_16x16x32_bf16 v[48:51], v[204:207], v[164:167], v[48:51]
	ds_read_b128 v[204:207], v226 offset:8192
	ds_read_b128 v[220:223], v226 offset:14336
	s_waitcnt lgkmcnt(11)
	v_mfma_f32_16x16x32_bf16 v[44:47], v[208:211], v[152:155], v[44:47]
	v_mfma_f32_16x16x32_bf16 v[40:43], v[208:211], v[156:159], v[40:43]
	v_mfma_f32_16x16x32_bf16 v[36:39], v[208:211], v[160:163], v[36:39]
	v_mfma_f32_16x16x32_bf16 v[32:35], v[208:211], v[164:167], v[32:35]
	ds_read_b128 v[208:211], v226 offset:10240
	s_waitcnt lgkmcnt(11)
	v_mfma_f32_16x16x32_bf16 v[28:31], v[212:215], v[152:155], v[28:31]
	v_mfma_f32_16x16x32_bf16 v[24:27], v[212:215], v[156:159], v[24:27]
	v_mfma_f32_16x16x32_bf16 v[20:23], v[212:215], v[160:163], v[20:23]
	v_mfma_f32_16x16x32_bf16 v[16:19], v[212:215], v[164:167], v[16:19]
	ds_read_b128 v[212:215], v226 offset:12288
	v_mfma_f32_16x16x32_bf16 v[12:15], v[216:219], v[152:155], v[12:15]
	v_mfma_f32_16x16x32_bf16 v[8:11], v[216:219], v[156:159], v[8:11]
	v_mfma_f32_16x16x32_bf16 v[4:7], v[216:219], v[160:163], v[4:7]
	v_mfma_f32_16x16x32_bf16 v[0:3], v[216:219], v[164:167], v[0:3]
	s_waitcnt vmcnt(0) lgkmcnt(0)
	s_barrier
	v_mfma_f32_16x16x32_bf16 v[124:127], v[188:191], v[168:171], v[124:127]
	v_mfma_f32_16x16x32_bf16 v[120:123], v[188:191], v[176:179], v[120:123]
	v_mfma_f32_16x16x32_bf16 v[116:119], v[188:191], v[180:183], v[116:119]
	v_mfma_f32_16x16x32_bf16 v[112:115], v[188:191], v[184:187], v[112:115]
	ds_read_b128 v[188:191], v225 offset:0
	ds_read_b128 v[152:155], v227 offset:0
	s_add_u32 s10, s98, 0x0
	s_addc_u32 s11, s99, 0
	s_add_u32 m0, s97, 0x0
	s_nop 0
	global_load_lds_dwordx4 v224, s[10:11]
	v_mfma_f32_16x16x32_bf16 v[108:111], v[192:195], v[168:171], v[108:111]
	v_mfma_f32_16x16x32_bf16 v[104:107], v[192:195], v[176:179], v[104:107]
	v_mfma_f32_16x16x32_bf16 v[100:103], v[192:195], v[180:183], v[100:103]
	v_mfma_f32_16x16x32_bf16 v[96:99], v[192:195], v[184:187], v[96:99]
	ds_read_b128 v[192:195], v225 offset:2048
	ds_read_b128 v[156:159], v227 offset:2048
	s_add_u32 s10, s100, 0x0
	s_addc_u32 s11, s101, 0
	s_add_u32 m0, s97, 0x10000
	s_nop 0
	global_load_lds_dwordx4 v224, s[10:11]
	v_mfma_f32_16x16x32_bf16 v[92:95], v[196:199], v[168:171], v[92:95]
	v_mfma_f32_16x16x32_bf16 v[88:91], v[196:199], v[176:179], v[88:91]
	v_mfma_f32_16x16x32_bf16 v[84:87], v[196:199], v[180:183], v[84:87]
	v_mfma_f32_16x16x32_bf16 v[80:83], v[196:199], v[184:187], v[80:83]
	ds_read_b128 v[196:199], v225 offset:4096
	ds_read_b128 v[160:163], v227 offset:4096
	s_add_u32 s10, s98, 0x20000
	s_addc_u32 s11, s99, 0
	s_add_u32 m0, s97, 0x2000
	s_nop 0
	global_load_lds_dwordx4 v224, s[10:11]
	v_mfma_f32_16x16x32_bf16 v[76:79], v[200:203], v[168:171], v[76:79]
	v_mfma_f32_16x16x32_bf16 v[72:75], v[200:203], v[176:179], v[72:75]
	v_mfma_f32_16x16x32_bf16 v[68:71], v[200:203], v[180:183], v[68:71]
	v_mfma_f32_16x16x32_bf16 v[64:67], v[200:203], v[184:187], v[64:67]
	ds_read_b128 v[200:203], v225 offset:6144
	ds_read_b128 v[164:167], v227 offset:6144
	s_add_u32 s10, s100, 0x20000
	s_addc_u32 s11, s101, 0
	s_add_u32 m0, s97, 0x12000
	s_nop 0
	global_load_lds_dwordx4 v224, s[10:11]
	v_mfma_f32_16x16x32_bf16 v[60:63], v[204:207], v[168:171], v[60:63]
	v_mfma_f32_16x16x32_bf16 v[56:59], v[204:207], v[176:179], v[56:59]
; #define G_LOAD(KT) do { _Pragma("unroll") for (int i = 0; i < 4; ++i) { ra[i] = *(const u32x4*)(Ag + (size_t)i * 64 * lda + (KT) * 64); rb[i] = *(const u32x4*)(Bg + (size_t)i * 64 * K + (KT) * 64); } } while (0)
; #define G_STORE(BUF) do { u16* ad = As + (BUF) * 256 * 64 + sto; u16* bd = Bs + (BUF) * 256 * 64 + sto; _Pragma("unroll") for (int i = 0; i < 4; ++i) { *(u32x4*)(ad + i * 64 * 64) = ra[i]; *(u32x4*)(bd + i * 64 * 64) = rb[i]; } } while (0)
; template <int EPI>
; DI void gemm_phase(const u16* __restrict__ A, int lda, const u16* __restrict__ Bt, int K, int N, u16* outb, int ldo,
;                    const float* r0, const float* r1, float* outf, char* lds, int bid, int nb) {
;     ...
;     G_LOAD(0);
;     G_STORE(0);
;     __syncthreads();
;     for (int kt = 0; kt < nk; ++kt) {
;       const int cur = kt & 1;
;       if (kt + 1 < nk) G_LOAD(kt + 1);
;       G_MMA(cur, fo0);
;       G_MMA(cur, fo1);
;       if (kt + 1 < nk) G_STORE(cur ^ 1);
;       __syncthreads();
;     }
	v_mfma_f32_16x16x32_bf16 v[52:55], v[204:207], v[180:183], v[52:55]
	v_mfma_f32_16x16x32_bf16 v[48:51], v[204:207], v[184:187], v[48:51]
	ds_read_b128 v[204:207], v225 offset:8192
	ds_read_b128 v[216:219], v225 offset:14336
	s_add_u32 s10, s98, 0x40000
	s_addc_u32 s11, s99, 0
	s_add_u32 m0, s97, 0x4000
	s_nop 0
	global_load_lds_dwordx4 v224, s[10:11]
	v_mfma_f32_16x16x32_bf16 v[44:47], v[208:211], v[168:171], v[44:47]
	v_mfma_f32_16x16x32_bf16 v[40:43], v[208:211], v[176:179], v[40:43]
	v_mfma_f32_16x16x32_bf16 v[36:39], v[208:211], v[180:183], v[36:39]
	v_mfma_f32_16x16x32_bf16 v[32:35], v[208:211], v[184:187], v[32:35]
	ds_read_b128 v[208:211], v225 offset:10240
	s_add_u32 s10, s100, 0x40000
	s_addc_u32 s11, s101, 0
	s_add_u32 m0, s97, 0x14000
	s_nop 0
	global_load_lds_dwordx4 v224, s[10:11]
	v_mfma_f32_16x16x32_bf16 v[28:31], v[212:215], v[168:171], v[28:31]
	v_mfma_f32_16x16x32_bf16 v[24:27], v[212:215], v[176:179], v[24:27]
	v_mfma_f32_16x16x32_bf16 v[20:23], v[212:215], v[180:183], v[20:23]
	v_mfma_f32_16x16x32_bf16 v[16:19], v[212:215], v[184:187], v[16:19]
	ds_read_b128 v[212:215], v225 offset:12288
	s_add_u32 s10, s98, 0x60000
	s_addc_u32 s11, s99, 0
	s_add_u32 m0, s97, 0x6000
	s_nop 0
	global_load_lds_dwordx4 v224, s[10:11]
	v_mfma_f32_16x16x32_bf16 v[12:15], v[220:223], v[168:171], v[12:15]
	v_mfma_f32_16x16x32_bf16 v[8:11], v[220:223], v[176:179], v[8:11]
	v_mfma_f32_16x16x32_bf16 v[4:7], v[220:223], v[180:183], v[4:7]
	v_mfma_f32_16x16x32_bf16 v[0:3], v[220:223], v[184:187], v[0:3]
	s_add_u32 s10, s100, 0x60000
	s_addc_u32 s11, s101, 0
	s_add_u32 m0, s97, 0x16000
	s_nop 0
	global_load_lds_dwordx4 v224, s[10:11]
	v_xor_b32_e32 v225, 0x8000, v225
	v_xor_b32_e32 v227, 0x8000, v227
	v_xor_b32_e32 v226, 0x8000, v226
	v_xor_b32_e32 v228, 0x8000, v228
	s_xor_b32 s97, s97, 0x8000
	s_add_u32 s98, s98, 0x80
	s_addc_u32 s99, s99, 0
	s_add_u32 s100, s100, 0x80
	s_addc_u32 s101, s101, 0
	s_sub_u32 s28, s28, 1
	s_cmp_lg_u32 s28, 0
	s_cbranch_scc1 .Lgm6_loop
	s_waitcnt lgkmcnt(4)
	v_mfma_f32_16x16x32_bf16 v[124:127], v[188:191], v[152:155], v[124:127]
	v_mfma_f32_16x16x32_bf16 v[120:123], v[188:191], v[156:159], v[120:123]
	v_mfma_f32_16x16x32_bf16 v[116:119], v[188:191], v[160:163], v[116:119]
	v_mfma_f32_16x16x32_bf16 v[112:115], v[188:191], v[164:167], v[112:115]
	ds_read_b128 v[188:191], v226 offset:0
	ds_read_b128 v[168:171], v228 offset:0
	v_mfma_f32_16x16x32_bf16 v[108:111], v[192:195], v[152:155], v[108:111]
	v_mfma_f32_16x16x32_bf16 v[104:107], v[192:195], v[156:159], v[104:107]
	v_mfma_f32_16x16x32_bf16 v[100:103], v[192:195], v[160:163], v[100:103]
	v_mfma_f32_16x16x32_bf16 v[96:99], v[192:195], v[164:167], v[96:99]
	ds_read_b128 v[192:195], v226 offset:2048
	ds_read_b128 v[176:179], v228 offset:2048
	v_mfma_f32_16x16x32_bf16 v[92:95], v[196:199], v[152:155], v[92:95]
	v_mfma_f32_16x16x32_bf16 v[88:91], v[196:199], v[156:159], v[88:91]
	v_mfma_f32_16x16x32_bf16 v[84:87], v[196:199], v[160:163], v[84:87]
	v_mfma_f32_16x16x32_bf16 v[80:83], v[196:199], v[164:167], v[80:83]
	ds_read_b128 v[196:199], v226 offset:4096
	ds_read_b128 v[180:183], v228 offset:4096
	v_mfma_f32_16x16x32_bf16 v[76:79], v[200:203], v[152:155], v[76:79]
	v_mfma_f32_16x16x32_bf16 v[72:75], v[200:203], v[156:159], v[72:75]
	v_mfma_f32_16x16x32_bf16 v[68:71], v[200:203], v[160:163], v[68:71]
	v_mfma_f32_16x16x32_bf16 v[64:67], v[200:203], v[164:167], v[64:67]
	ds_read_b128 v[200:203], v226 offset:6144
	ds_read_b128 v[184:187], v228 offset:6144
	s_waitcnt lgkmcnt(11)
	v_mfma_f32_16x16x32_bf16 v[60:63], v[204:207], v[152:155], v[60:63]
	v_mfma_f32_16x16x32_bf16 v[56:59], v[204:207], v[156:159], v[56:59]
	v_mfma_f32_16x16x32_bf16 v[52:55], v[204:207], v[160:163], v[52:55]
	v_mfma_f32_16x16x32_bf16 v[48:51], v[204:207], v[164:167], v[48:51]
	ds_read_b128 v[204:207], v226 offset:8192
	ds_read_b128 v[220:223], v226 offset:14336
	s_waitcnt lgkmcnt(11)
	v_mfma_f32_16x16x32_bf16 v[44:47], v[208:211], v[152:155], v[44:47]
	v_mfma_f32_16x16x32_bf16 v[40:43], v[208:211], v[156:159], v[40:43]
	v_mfma_f32_16x16x32_bf16 v[36:39], v[208:211], v[160:163], v[36:39]
	v_mfma_f32_16x16x32_bf16 v[32:35], v[208:211], v[164:167], v[32:35]
	ds_read_b128 v[208:211], v226 offset:10240
	s_waitcnt lgkmcnt(11)
	v_mfma_f32_16x16x32_bf16 v[28:31], v[212:215], v[152:155], v[28:31]
	v_mfma_f32_16x16x32_bf16 v[24:27], v[212:215], v[156:159], v[24:27]
	v_mfma_f32_16x16x32_bf16 v[20:23], v[212:215], v[160:163], v[20:23]
	v_mfma_f32_16x16x32_bf16 v[16:19], v[212:215], v[164:167], v[16:19]
	ds_read_b128 v[212:215], v226 offset:12288
	v_mfma_f32_16x16x32_bf16 v[12:15], v[216:219], v[152:155], v[12:15]
	v_mfma_f32_16x16x32_bf16 v[8:11], v[216:219], v[156:159], v[8:11]
	v_mfma_f32_16x16x32_bf16 v[4:7], v[216:219], v[160:163], v[4:7]
	v_mfma_f32_16x16x32_bf16 v[0:3], v[216:219], v[164:167], v[0:3]
	s_waitcnt vmcnt(0) lgkmcnt(0)
	s_barrier
; #define G_LOAD(KT) do { _Pragma("unroll") for (int i = 0; i < 4; ++i) { ra[i] = *(const u32x4*)(Ag + (size_t)i * 64 * lda + (KT) * 64); rb[i] = *(const u32x4*)(Bg + (size_t)i * 64 * K + (KT) * 64); } } while (0)
; #define G_STORE(BUF) do { u16* ad = As + (BUF) * 256 * 64 + sto; u16* bd = Bs + (BUF) * 256 * 64 + sto; _Pragma("unroll") for (int i = 0; i < 4; ++i) { *(u32x4*)(ad + i * 64 * 64) = ra[i]; *(u32x4*)(bd + i * 64 * 64) = rb[i]; } } while (0)
; template <int EPI>
; DI void gemm_phase(const u16* __restrict__ A, int lda, const u16* __restrict__ Bt, int K, int N, u16* outb, int ldo,
;                    const float* r0, const float* r1, float* outf, char* lds, int bid, int nb) {
;     ...
;     G_LOAD(0);
;     G_STORE(0);
;     __syncthreads();
;     for (int kt = 0; kt < nk; ++kt) {
;       const int cur = kt & 1;
;       if (kt + 1 < nk) G_LOAD(kt + 1);
;       G_MMA(cur, fo0);
;       G_MMA(cur, fo1);
;       if (kt + 1 < nk) G_STORE(cur ^ 1);
;       __syncthreads();
;     }
	v_mfma_f32_16x16x32_bf16 v[124:127], v[188:191], v[168:171], v[124:127]
	v_mfma_f32_16x16x32_bf16 v[120:123], v[188:191], v[176:179], v[120:123]
	v_mfma_f32_16x16x32_bf16 v[116:119], v[188:191], v[180:183], v[116:119]
	v_mfma_f32_16x16x32_bf16 v[112:115], v[188:191], v[184:187], v[112:115]
	ds_read_b128 v[188:191], v225 offset:0
	ds_read_b128 v[152:155], v227 offset:0
	v_mfma_f32_16x16x32_bf16 v[108:111], v[192:195], v[168:171], v[108:111]
	v_mfma_f32_16x16x32_bf16 v[104:107], v[192:195], v[176:179], v[104:107]
	v_mfma_f32_16x16x32_bf16 v[100:103], v[192:195], v[180:183], v[100:103]
	v_mfma_f32_16x16x32_bf16 v[96:99], v[192:195], v[184:187], v[96:99]
	ds_read_b128 v[192:195], v225 offset:2048
	ds_read_b128 v[156:159], v227 offset:2048
	v_mfma_f32_16x16x32_bf16 v[92:95], v[196:199], v[168:171], v[92:95]
	v_mfma_f32_16x16x32_bf16 v[88:91], v[196:199], v[176:179], v[88:91]
	v_mfma_f32_16x16x32_bf16 v[84:87], v[196:199], v[180:183], v[84:87]
	v_mfma_f32_16x16x32_bf16 v[80:83], v[196:199], v[184:187], v[80:83]
	ds_read_b128 v[196:199], v225 offset:4096
	ds_read_b128 v[160:163], v227 offset:4096
	v_mfma_f32_16x16x32_bf16 v[76:79], v[200:203], v[168:171], v[76:79]
	v_mfma_f32_16x16x32_bf16 v[72:75], v[200:203], v[176:179], v[72:75]
	v_mfma_f32_16x16x32_bf16 v[68:71], v[200:203], v[180:183], v[68:71]
	v_mfma_f32_16x16x32_bf16 v[64:67], v[200:203], v[184:187], v[64:67]
	ds_read_b128 v[200:203], v225 offset:6144
	ds_read_b128 v[164:167], v227 offset:6144
	v_mfma_f32_16x16x32_bf16 v[60:63], v[204:207], v[168:171], v[60:63]
	v_mfma_f32_16x16x32_bf16 v[56:59], v[204:207], v[176:179], v[56:59]
	v_mfma_f32_16x16x32_bf16 v[52:55], v[204:207], v[180:183], v[52:55]
	v_mfma_f32_16x16x32_bf16 v[48:51], v[204:207], v[184:187], v[48:51]
	ds_read_b128 v[204:207], v225 offset:8192
	ds_read_b128 v[216:219], v225 offset:14336
	v_mfma_f32_16x16x32_bf16 v[44:47], v[208:211], v[168:171], v[44:47]
	v_mfma_f32_16x16x32_bf16 v[40:43], v[208:211], v[176:179], v[40:43]
	v_mfma_f32_16x16x32_bf16 v[36:39], v[208:211], v[180:183], v[36:39]
	v_mfma_f32_16x16x32_bf16 v[32:35], v[208:211], v[184:187], v[32:35]
	ds_read_b128 v[208:211], v225 offset:10240
	v_mfma_f32_16x16x32_bf16 v[28:31], v[212:215], v[168:171], v[28:31]
	v_mfma_f32_16x16x32_bf16 v[24:27], v[212:215], v[176:179], v[24:27]
	v_mfma_f32_16x16x32_bf16 v[20:23], v[212:215], v[180:183], v[20:23]
	v_mfma_f32_16x16x32_bf16 v[16:19], v[212:215], v[184:187], v[16:19]
	ds_read_b128 v[212:215], v225 offset:12288
	v_mfma_f32_16x16x32_bf16 v[12:15], v[220:223], v[168:171], v[12:15]
	v_mfma_f32_16x16x32_bf16 v[8:11], v[220:223], v[176:179], v[8:11]
	v_mfma_f32_16x16x32_bf16 v[4:7], v[220:223], v[180:183], v[4:7]
	v_mfma_f32_16x16x32_bf16 v[0:3], v[220:223], v[184:187], v[0:3]
	v_xor_b32_e32 v226, 0x8000, v226
	v_xor_b32_e32 v228, 0x8000, v228
	s_waitcnt lgkmcnt(4)
	v_mfma_f32_16x16x32_bf16 v[124:127], v[188:191], v[152:155], v[124:127]
	v_mfma_f32_16x16x32_bf16 v[120:123], v[188:191], v[156:159], v[120:123]
	v_mfma_f32_16x16x32_bf16 v[116:119], v[188:191], v[160:163], v[116:119]
	v_mfma_f32_16x16x32_bf16 v[112:115], v[188:191], v[164:167], v[112:115]
	ds_read_b128 v[188:191], v226 offset:0
	ds_read_b128 v[168:171], v228 offset:0
	v_mfma_f32_16x16x32_bf16 v[108:111], v[192:195], v[152:155], v[108:111]
	v_mfma_f32_16x16x32_bf16 v[104:107], v[192:195], v[156:159], v[104:107]
	v_mfma_f32_16x16x32_bf16 v[100:103], v[192:195], v[160:163], v[100:103]
	v_mfma_f32_16x16x32_bf16 v[96:99], v[192:195], v[164:167], v[96:99]
	ds_read_b128 v[192:195], v226 offset:2048
	ds_read_b128 v[176:179], v228 offset:2048
	v_mfma_f32_16x16x32_bf16 v[92:95], v[196:199], v[152:155], v[92:95]
	v_mfma_f32_16x16x32_bf16 v[88:91], v[196:199], v[156:159], v[88:91]
	v_mfma_f32_16x16x32_bf16 v[84:87], v[196:199], v[160:163], v[84:87]
	v_mfma_f32_16x16x32_bf16 v[80:83], v[196:199], v[164:167], v[80:83]
	ds_read_b128 v[196:199], v226 offset:4096
	ds_read_b128 v[180:183], v228 offset:4096
	v_mfma_f32_16x16x32_bf16 v[76:79], v[200:203], v[152:155], v[76:79]
	v_mfma_f32_16x16x32_bf16 v[72:75], v[200:203], v[156:159], v[72:75]
	v_mfma_f32_16x16x32_bf16 v[68:71], v[200:203], v[160:163], v[68:71]
	v_mfma_f32_16x16x32_bf16 v[64:67], v[200:203], v[164:167], v[64:67]
	ds_read_b128 v[200:203], v226 offset:6144
	ds_read_b128 v[184:187], v228 offset:6144
	s_waitcnt lgkmcnt(11)
	v_mfma_f32_16x16x32_bf16 v[60:63], v[204:207], v[152:155], v[60:63]
	v_mfma_f32_16x16x32_bf16 v[56:59], v[204:207], v[156:159], v[56:59]
	v_mfma_f32_16x16x32_bf16 v[52:55], v[204:207], v[160:163], v[52:55]
	v_mfma_f32_16x16x32_bf16 v[48:51], v[204:207], v[164:167], v[48:51]
	ds_read_b128 v[204:207], v226 offset:8192
	ds_read_b128 v[220:223], v226 offset:14336
	s_waitcnt lgkmcnt(11)
	v_mfma_f32_16x16x32_bf16 v[44:47], v[208:211], v[152:155], v[44:47]
	v_mfma_f32_16x16x32_bf16 v[40:43], v[208:211], v[156:159], v[40:43]
	v_mfma_f32_16x16x32_bf16 v[36:39], v[208:211], v[160:163], v[36:39]
	v_mfma_f32_16x16x32_bf16 v[32:35], v[208:211], v[164:167], v[32:35]
	ds_read_b128 v[208:211], v226 offset:10240
	s_waitcnt lgkmcnt(11)
	v_mfma_f32_16x16x32_bf16 v[28:31], v[212:215], v[152:155], v[28:31]
	v_mfma_f32_16x16x32_bf16 v[24:27], v[212:215], v[156:159], v[24:27]
	v_mfma_f32_16x16x32_bf16 v[20:23], v[212:215], v[160:163], v[20:23]
	v_mfma_f32_16x16x32_bf16 v[16:19], v[212:215], v[164:167], v[16:19]
	ds_read_b128 v[212:215], v226 offset:12288
	v_mfma_f32_16x16x32_bf16 v[12:15], v[216:219], v[152:155], v[12:15]
	v_mfma_f32_16x16x32_bf16 v[8:11], v[216:219], v[156:159], v[8:11]
	v_mfma_f32_16x16x32_bf16 v[4:7], v[216:219], v[160:163], v[4:7]
	v_mfma_f32_16x16x32_bf16 v[0:3], v[216:219], v[164:167], v[0:3]
	s_waitcnt vmcnt(0) lgkmcnt(0)
	s_barrier
; DI u16 f2bf(float a) { return (u16)(pk2(a, 0.f) & 0xffffu); }
; DI float sigmoidf_(float x) { return __builtin_amdgcn_rcpf(1.f + __builtin_amdgcn_exp2f(-1.4426950408889634f * x)); }
; #define G_LOAD(KT) do { _Pragma("unroll") for (int i = 0; i < 4; ++i) { ra[i] = *(const u32x4*)(Ag + (size_t)i * 64 * lda + (KT) * 64); rb[i] = *(const u32x4*)(Bg + (size_t)i * 64 * K + (KT) * 64); } } while (0)
; #define G_STORE(BUF) do { u16* ad = As + (BUF) * 256 * 64 + sto; u16* bd = Bs + (BUF) * 256 * 64 + sto; _Pragma("unroll") for (int i = 0; i < 4; ++i) { *(u32x4*)(ad + i * 64 * 64) = ra[i]; *(u32x4*)(bd + i * 64 * 64) = rb[i]; } } while (0)
; template <int EPI>
; DI void gemm_phase(const u16* __restrict__ A, int lda, const u16* __restrict__ Bt, int K, int N, u16* outb, int ldo,
;                    const float* r0, const float* r1, float* outf, char* lds, int bid, int nb) {
;     ...
;     G_LOAD(0);
;     G_STORE(0);
;     __syncthreads();
;     for (int kt = 0; kt < nk; ++kt) {
;       const int cur = kt & 1;
;       if (kt + 1 < nk) G_LOAD(kt + 1);
;       G_MMA(cur, fo0);
;       G_MMA(cur, fo1);
;       if (kt + 1 < nk) G_STORE(cur ^ 1);
;       __syncthreads();
;     ...
;       const int col = (tn * 4 + wc) * 32 + l15;
; #pragma unroll
;       for (int i = 0; i < 8; ++i)
; #pragma unroll
;         for (int r = 0; r < 4; ++r) {
;           const float g0 = acc[i][0][r], u0 = acc[i][2][r], g1 = acc[i][1][r], u1 = acc[i][3][r];
;           u16* o0 = outb + (size_t)(mrow + i * 16 + r) * ldo + col;
;           o0[0] = f2bf(g0 * sigmoidf_(g0) * u0); o0[16] = f2bf(g1 * sigmoidf_(g1) * u1);
;         }
	v_mfma_f32_16x16x32_bf16 v[124:127], v[188:191], v[168:171], v[124:127]
	v_mfma_f32_16x16x32_bf16 v[120:123], v[188:191], v[176:179], v[120:123]
	v_mfma_f32_16x16x32_bf16 v[116:119], v[188:191], v[180:183], v[116:119]
	v_mfma_f32_16x16x32_bf16 v[112:115], v[188:191], v[184:187], v[112:115]
	v_mfma_f32_16x16x32_bf16 v[108:111], v[192:195], v[168:171], v[108:111]
	v_mfma_f32_16x16x32_bf16 v[104:107], v[192:195], v[176:179], v[104:107]
	v_mfma_f32_16x16x32_bf16 v[100:103], v[192:195], v[180:183], v[100:103]
	v_mfma_f32_16x16x32_bf16 v[96:99], v[192:195], v[184:187], v[96:99]
	v_mfma_f32_16x16x32_bf16 v[92:95], v[196:199], v[168:171], v[92:95]
	v_mfma_f32_16x16x32_bf16 v[88:91], v[196:199], v[176:179], v[88:91]
	v_mfma_f32_16x16x32_bf16 v[84:87], v[196:199], v[180:183], v[84:87]
	v_mfma_f32_16x16x32_bf16 v[80:83], v[196:199], v[184:187], v[80:83]
	v_mfma_f32_16x16x32_bf16 v[76:79], v[200:203], v[168:171], v[76:79]
	v_mfma_f32_16x16x32_bf16 v[72:75], v[200:203], v[176:179], v[72:75]
	v_mfma_f32_16x16x32_bf16 v[68:71], v[200:203], v[180:183], v[68:71]
	v_mfma_f32_16x16x32_bf16 v[64:67], v[200:203], v[184:187], v[64:67]
	v_mfma_f32_16x16x32_bf16 v[60:63], v[204:207], v[168:171], v[60:63]
	v_mfma_f32_16x16x32_bf16 v[56:59], v[204:207], v[176:179], v[56:59]
	v_mfma_f32_16x16x32_bf16 v[52:55], v[204:207], v[180:183], v[52:55]
	v_mfma_f32_16x16x32_bf16 v[48:51], v[204:207], v[184:187], v[48:51]
	v_mfma_f32_16x16x32_bf16 v[44:47], v[208:211], v[168:171], v[44:47]
	v_mfma_f32_16x16x32_bf16 v[40:43], v[208:211], v[176:179], v[40:43]
	v_mfma_f32_16x16x32_bf16 v[36:39], v[208:211], v[180:183], v[36:39]
	v_mfma_f32_16x16x32_bf16 v[32:35], v[208:211], v[184:187], v[32:35]
	v_mfma_f32_16x16x32_bf16 v[28:31], v[212:215], v[168:171], v[28:31]
	v_mfma_f32_16x16x32_bf16 v[24:27], v[212:215], v[176:179], v[24:27]
	v_mfma_f32_16x16x32_bf16 v[20:23], v[212:215], v[180:183], v[20:23]
	v_mfma_f32_16x16x32_bf16 v[16:19], v[212:215], v[184:187], v[16:19]
	v_mfma_f32_16x16x32_bf16 v[12:15], v[220:223], v[168:171], v[12:15]
	v_mfma_f32_16x16x32_bf16 v[8:11], v[220:223], v[176:179], v[8:11]
	v_mfma_f32_16x16x32_bf16 v[4:7], v[220:223], v[180:183], v[4:7]
	v_mfma_f32_16x16x32_bf16 v[0:3], v[220:223], v[184:187], v[0:3]
	s_nop 7
	s_nop 3
	v_mov_b32_e32 v208, v96
	v_mov_b32_e32 v209, v97
	v_mov_b32_e32 v210, v98
	v_mov_b32_e32 v211, v99
	v_mov_b32_e32 v172, v80
	v_mov_b32_e32 v80, v88
	v_mov_b32_e32 v88, v84
	v_mov_b32_e32 v84, v172
	v_mov_b32_e32 v172, v81
	v_mov_b32_e32 v81, v89
	v_mov_b32_e32 v89, v85
	v_mov_b32_e32 v85, v172
	v_mov_b32_e32 v172, v82
	v_mov_b32_e32 v82, v90
	v_mov_b32_e32 v90, v86
	v_mov_b32_e32 v86, v172
	v_mov_b32_e32 v172, v83
	v_mov_b32_e32 v83, v91
	v_mov_b32_e32 v91, v87
	v_mov_b32_e32 v87, v172
	v_mov_b32_e32 v172, v64
	v_mov_b32_e32 v64, v72
	v_mov_b32_e32 v72, v68
	v_mov_b32_e32 v68, v172
	v_mov_b32_e32 v172, v65
	v_mov_b32_e32 v65, v73
	v_mov_b32_e32 v73, v69
	v_mov_b32_e32 v69, v172
	v_mov_b32_e32 v172, v66
	v_mov_b32_e32 v66, v74
	v_mov_b32_e32 v74, v70
	v_mov_b32_e32 v70, v172
	v_mov_b32_e32 v172, v67
	v_mov_b32_e32 v67, v75
	v_mov_b32_e32 v75, v71
	v_mov_b32_e32 v71, v172
	v_mov_b32_e32 v172, v48
	v_mov_b32_e32 v48, v56
	v_mov_b32_e32 v56, v52
	v_mov_b32_e32 v52, v172
	v_mov_b32_e32 v172, v49
	v_mov_b32_e32 v49, v57
	v_mov_b32_e32 v57, v53
	v_mov_b32_e32 v53, v172
	v_mov_b32_e32 v172, v50
	v_mov_b32_e32 v50, v58
	v_mov_b32_e32 v58, v54
	v_mov_b32_e32 v54, v172
	v_mov_b32_e32 v172, v51
	v_mov_b32_e32 v51, v59
	v_mov_b32_e32 v59, v55
	v_mov_b32_e32 v55, v172
	v_mov_b32_e32 v172, v32
	v_mov_b32_e32 v32, v40
	v_mov_b32_e32 v40, v36
	v_mov_b32_e32 v36, v172
	v_mov_b32_e32 v172, v33
	v_mov_b32_e32 v33, v41
	v_mov_b32_e32 v41, v37
	v_mov_b32_e32 v37, v172
	v_mov_b32_e32 v172, v34
	v_mov_b32_e32 v34, v42
	v_mov_b32_e32 v42, v38
	v_mov_b32_e32 v38, v172
	v_mov_b32_e32 v172, v35
	v_mov_b32_e32 v35, v43
	v_mov_b32_e32 v43, v39
	v_mov_b32_e32 v39, v172
	v_mov_b32_e32 v172, v16
	v_mov_b32_e32 v16, v24
	v_mov_b32_e32 v24, v20
	v_mov_b32_e32 v20, v172
	v_mov_b32_e32 v172, v17
	v_mov_b32_e32 v17, v25
	v_mov_b32_e32 v25, v21
	v_mov_b32_e32 v21, v172
	v_mov_b32_e32 v172, v18
	v_mov_b32_e32 v18, v26
	v_mov_b32_e32 v26, v22
	v_mov_b32_e32 v22, v172
	v_mov_b32_e32 v172, v19
	v_mov_b32_e32 v19, v27
	v_mov_b32_e32 v27, v23
	v_mov_b32_e32 v23, v172
	v_mov_b32_e32 v172, v0
	v_mov_b32_e32 v0, v8
	v_mov_b32_e32 v8, v4
	v_mov_b32_e32 v4, v172
	v_mov_b32_e32 v172, v1
	v_mov_b32_e32 v1, v9
	v_mov_b32_e32 v9, v5
	v_mov_b32_e32 v5, v172
	v_mov_b32_e32 v172, v2
	v_mov_b32_e32 v2, v10
	v_mov_b32_e32 v10, v6
	v_mov_b32_e32 v6, v172
	v_mov_b32_e32 v172, v3
	v_mov_b32_e32 v3, v11
	v_mov_b32_e32 v11, v7
	v_mov_b32_e32 v7, v172
	v_mul_f32_e32 v96, 0xbfb8aa3b, v124
	v_exp_f32_e32 v99, v96
	v_mul_f32_e32 v134, 0xbfb8aa3b, v120
	v_exp_f32_e32 v136, v134
	v_lshl_or_b32 v96, s40, 7, v148
	v_add_f32_e32 v99, 1.0, v99
	v_rcp_f32_e32 v99, v99
	v_ashrrev_i32_e32 v97, 31, v96
	v_add_u32_e32 v98, s41, v143
	v_lshl_add_u64 v[96:97], v[96:97], 1, s[8:9]
	v_mul_f32_e32 v99, v124, v99
	v_add_f32_e32 v124, 1.0, v136
	v_rcp_f32_e32 v124, v124
	v_mul_f32_e32 v99, v116, v99
	v_mad_i64_i32 v[134:135], s[10:11], v98, s39, v[96:97]
	v_cvt_pk_bf16_f32 v99, v99, s0
	global_store_short v[134:135], v99, off
	v_mul_f32_e32 v99, v120, v124
	v_mul_f32_e32 v99, v112, v99
	v_mul_f32_e32 v112, 0xbfb8aa3b, v125
	v_exp_f32_e32 v112, v112
	v_mul_f32_e32 v116, 0xbfb8aa3b, v121
	v_exp_f32_e32 v116, v116
	v_cvt_pk_bf16_f32 v99, v99, s0
	v_add_f32_e32 v112, 1.0, v112
	v_rcp_f32_e32 v112, v112
	global_store_short v[134:135], v99, off offset:32
	v_or_b32_e32 v99, 1, v98
	v_mad_i64_i32 v[134:135], s[10:11], v99, s39, v[96:97]
; DI u16 f2bf(float a) { return (u16)(pk2(a, 0.f) & 0xffffu); }
; DI float sigmoidf_(float x) { return __builtin_amdgcn_rcpf(1.f + __builtin_amdgcn_exp2f(-1.4426950408889634f * x)); }
; template <int EPI>
; DI void gemm_phase(const u16* __restrict__ A, int lda, const u16* __restrict__ Bt, int K, int N, u16* outb, int ldo,
;                    const float* r0, const float* r1, float* outf, char* lds, int bid, int nb) {
;     ...
;       const int col = (tn * 4 + wc) * 32 + l15;
; #pragma unroll
;       for (int i = 0; i < 8; ++i)
; #pragma unroll
;         for (int r = 0; r < 4; ++r) {
;           const float g0 = acc[i][0][r], u0 = acc[i][2][r], g1 = acc[i][1][r], u1 = acc[i][3][r];
;           u16* o0 = outb + (size_t)(mrow + i * 16 + r) * ldo + col;
;           o0[0] = f2bf(g0 * sigmoidf_(g0) * u0); o0[16] = f2bf(g1 * sigmoidf_(g1) * u1);
;         }
	v_mul_f32_e32 v99, v125, v112
	v_add_f32_e32 v112, 1.0, v116
	v_rcp_f32_e32 v112, v112
	v_mul_f32_e32 v99, v117, v99
	v_cvt_pk_bf16_f32 v99, v99, s0
	global_store_short v[134:135], v99, off
	v_mul_f32_e32 v99, v121, v112
	v_mul_f32_e32 v112, 0xbfb8aa3b, v126
	v_exp_f32_e32 v112, v112
	v_mul_f32_e32 v99, v113, v99
	v_cvt_pk_bf16_f32 v99, v99, s0
	global_store_short v[134:135], v99, off offset:32
	v_add_f32_e32 v112, 1.0, v112
	v_rcp_f32_e32 v116, v112
	v_mul_f32_e32 v112, 0xbfb8aa3b, v122
	v_exp_f32_e32 v117, v112
	v_or_b32_e32 v99, 2, v98
	v_mad_i64_i32 v[112:113], s[10:11], v99, s39, v[96:97]
	v_mul_f32_e32 v99, v126, v116
	v_add_f32_e32 v116, 1.0, v117
	v_rcp_f32_e32 v116, v116
	v_mul_f32_e32 v99, v118, v99
	v_cvt_pk_bf16_f32 v99, v99, s0
	global_store_short v[112:113], v99, off
	v_mul_f32_e32 v99, v122, v116
	v_mul_f32_e32 v99, v114, v99
	v_mul_f32_e32 v114, 0xbfb8aa3b, v127
	v_exp_f32_e32 v114, v114
	v_cvt_pk_bf16_f32 v99, v99, s0
	global_store_short v[112:113], v99, off offset:32
	v_or_b32_e32 v99, 3, v98
	v_add_f32_e32 v112, 1.0, v114
	v_rcp_f32_e32 v114, v112
	v_mul_f32_e32 v112, 0xbfb8aa3b, v123
	v_exp_f32_e32 v116, v112
	v_mad_i64_i32 v[112:113], s[10:11], v99, s39, v[96:97]
	v_mul_f32_e32 v99, v127, v114
	v_add_f32_e32 v114, 1.0, v116
	v_rcp_f32_e32 v114, v114
	v_mul_f32_e32 v99, v119, v99
	v_cvt_pk_bf16_f32 v99, v99, s0
	global_store_short v[112:113], v99, off
	v_mul_f32_e32 v99, v123, v114
	v_mul_f32_e32 v114, 0xbfb8aa3b, v108
	v_exp_f32_e32 v114, v114
	v_mul_f32_e32 v99, v115, v99
	v_cvt_pk_bf16_f32 v99, v99, s0
	global_store_short v[112:113], v99, off offset:32
	v_add_f32_e32 v112, 1.0, v114
	v_rcp_f32_e32 v114, v112
	v_mul_f32_e32 v112, 0xbfb8aa3b, v104
	v_exp_f32_e32 v115, v112
	v_or_b32_e32 v99, 16, v98
	v_mad_i64_i32 v[112:113], s[10:11], v99, s39, v[96:97]
	v_mul_f32_e32 v99, v108, v114
	v_add_f32_e32 v108, 1.0, v115
	v_mul_f32_e32 v99, v100, v99
	v_mul_f32_e32 v100, 0xbfb8aa3b, v109
	v_rcp_f32_e32 v108, v108
	v_exp_f32_e32 v100, v100
	v_cvt_pk_bf16_f32 v99, v99, s0
	global_store_short v[112:113], v99, off
	v_mul_f32_e32 v99, v104, v108
	v_add_f32_e32 v100, 1.0, v100
	v_mul_f32_e32 v104, 0xbfb8aa3b, v105
	v_rcp_f32_e32 v100, v100
	v_exp_f32_e32 v104, v104
	v_mul_f32_e32 v99, v208, v99
	v_cvt_pk_bf16_f32 v99, v99, s0
	global_store_short v[112:113], v99, off offset:32
	v_or_b32_e32 v99, 17, v98
	v_mad_i64_i32 v[112:113], s[10:11], v99, s39, v[96:97]
	v_mul_f32_e32 v99, v109, v100
	v_add_f32_e32 v100, 1.0, v104
	v_rcp_f32_e32 v100, v100
	v_mul_f32_e32 v99, v101, v99
	v_cvt_pk_bf16_f32 v99, v99, s0
	global_store_short v[112:113], v99, off
	v_mul_f32_e32 v99, v105, v100
	v_mul_f32_e32 v100, 0xbfb8aa3b, v110
	v_exp_f32_e32 v100, v100
	v_mul_f32_e32 v99, v209, v99
	v_cvt_pk_bf16_f32 v99, v99, s0
	global_store_short v[112:113], v99, off offset:32
	v_add_f32_e32 v100, 1.0, v100
	v_rcp_f32_e32 v104, v100
	v_mul_f32_e32 v100, 0xbfb8aa3b, v106
	v_exp_f32_e32 v105, v100
	v_or_b32_e32 v99, 18, v98
	v_mad_i64_i32 v[100:101], s[10:11], v99, s39, v[96:97]
	v_mul_f32_e32 v99, v110, v104
	v_add_f32_e32 v104, 1.0, v105
	v_rcp_f32_e32 v104, v104
	v_mul_f32_e32 v99, v102, v99
	v_mul_f32_e32 v102, 0xbfb8aa3b, v111
	v_cvt_pk_bf16_f32 v99, v99, s0
	v_exp_f32_e32 v102, v102
	global_store_short v[100:101], v99, off
	v_mul_f32_e32 v99, v106, v104
	v_mul_f32_e32 v99, v210, v99
	v_cvt_pk_bf16_f32 v99, v99, s0
	global_store_short v[100:101], v99, off offset:32
	v_add_f32_e32 v100, 1.0, v102
	v_rcp_f32_e32 v102, v100
	v_mul_f32_e32 v100, 0xbfb8aa3b, v107
	v_exp_f32_e32 v104, v100
	v_or_b32_e32 v99, 19, v98
	v_mad_i64_i32 v[100:101], s[10:11], v99, s39, v[96:97]
	v_mul_f32_e32 v99, v111, v102
	v_add_f32_e32 v102, 1.0, v104
	v_rcp_f32_e32 v102, v102
	v_mul_f32_e32 v99, v103, v99
	v_cvt_pk_bf16_f32 v99, v99, s0
	global_store_short v[100:101], v99, off
	v_mul_f32_e32 v99, v107, v102
	v_mul_f32_e32 v102, 0xbfb8aa3b, v92
	v_exp_f32_e32 v102, v102
	v_mul_f32_e32 v99, v211, v99
	v_cvt_pk_bf16_f32 v99, v99, s0
	global_store_short v[100:101], v99, off offset:32
	v_add_f32_e32 v100, 1.0, v102
	v_rcp_f32_e32 v102, v100
	v_mul_f32_e32 v100, 0xbfb8aa3b, v80
	v_exp_f32_e32 v103, v100
	v_or_b32_e32 v99, 32, v98
	v_mad_i64_i32 v[100:101], s[10:11], v99, s39, v[96:97]
	v_add_f32_e32 v99, 1.0, v103
	v_rcp_f32_e32 v99, v99
	v_mul_f32_e32 v92, v92, v102
	v_mul_f32_e32 v88, v88, v92
	v_cvt_pk_bf16_f32 v88, v88, s0
	v_mul_f32_e32 v80, v80, v99
	v_mul_f32_e32 v80, v84, v80
	v_mul_f32_e32 v84, 0xbfb8aa3b, v93
	v_exp_f32_e32 v84, v84
	global_store_short v[100:101], v88, off
	v_mul_f32_e32 v88, 0xbfb8aa3b, v81
	v_exp_f32_e32 v88, v88
	v_add_f32_e32 v84, 1.0, v84
	v_rcp_f32_e32 v84, v84
	v_cvt_pk_bf16_f32 v80, v80, s0
	global_store_short v[100:101], v80, off offset:32
	v_or_b32_e32 v80, 33, v98
	v_mad_i64_i32 v[100:101], s[10:11], v80, s39, v[96:97]
	v_mul_f32_e32 v80, v93, v84
	v_add_f32_e32 v84, 1.0, v88
	v_rcp_f32_e32 v84, v84
	v_mul_f32_e32 v80, v89, v80
	v_cvt_pk_bf16_f32 v80, v80, s0
	global_store_short v[100:101], v80, off
	v_mul_f32_e32 v80, v81, v84
	v_mul_f32_e32 v81, 0xbfb8aa3b, v94
	v_exp_f32_e32 v81, v81
	v_mul_f32_e32 v80, v85, v80
	v_cvt_pk_bf16_f32 v80, v80, s0
	global_store_short v[100:101], v80, off offset:32
	v_add_f32_e32 v81, 1.0, v81
	v_rcp_f32_e32 v84, v81
	v_mul_f32_e32 v81, 0xbfb8aa3b, v82
	v_exp_f32_e32 v85, v81
	v_or_b32_e32 v80, 34, v98
	v_mul_f32_e32 v84, v94, v84
	v_mul_f32_e32 v84, v90, v84
	v_add_f32_e32 v85, 1.0, v85
	v_rcp_f32_e32 v85, v85
	v_mad_i64_i32 v[80:81], s[10:11], v80, s39, v[96:97]
	v_cvt_pk_bf16_f32 v84, v84, s0
	global_store_short v[80:81], v84, off
	v_mul_f32_e32 v84, 0xbfb8aa3b, v95
	v_exp_f32_e32 v84, v84
	v_mul_f32_e32 v82, v82, v85
; DI u16 f2bf(float a) { return (u16)(pk2(a, 0.f) & 0xffffu); }
; DI float sigmoidf_(float x) { return __builtin_amdgcn_rcpf(1.f + __builtin_amdgcn_exp2f(-1.4426950408889634f * x)); }
; template <int EPI>
; DI void gemm_phase(const u16* __restrict__ A, int lda, const u16* __restrict__ Bt, int K, int N, u16* outb, int ldo,
;                    const float* r0, const float* r1, float* outf, char* lds, int bid, int nb) {
;     ...
;       const int col = (tn * 4 + wc) * 32 + l15;
; #pragma unroll
;       for (int i = 0; i < 8; ++i)
; #pragma unroll
;         for (int r = 0; r < 4; ++r) {
;           const float g0 = acc[i][0][r], u0 = acc[i][2][r], g1 = acc[i][1][r], u1 = acc[i][3][r];
;           u16* o0 = outb + (size_t)(mrow + i * 16 + r) * ldo + col;
;           o0[0] = f2bf(g0 * sigmoidf_(g0) * u0); o0[16] = f2bf(g1 * sigmoidf_(g1) * u1);
;         }
	v_mul_f32_e32 v82, v86, v82
	v_cvt_pk_bf16_f32 v82, v82, s0
	global_store_short v[80:81], v82, off offset:32
	v_add_f32_e32 v81, 1.0, v84
	v_rcp_f32_e32 v82, v81
	v_mul_f32_e32 v81, 0xbfb8aa3b, v83
	v_exp_f32_e32 v84, v81
	v_or_b32_e32 v80, 35, v98
	v_mul_f32_e32 v82, v95, v82
	v_mul_f32_e32 v82, v91, v82
	v_add_f32_e32 v84, 1.0, v84
	v_rcp_f32_e32 v84, v84
	v_mad_i64_i32 v[80:81], s[10:11], v80, s39, v[96:97]
	v_cvt_pk_bf16_f32 v82, v82, s0
	global_store_short v[80:81], v82, off
	v_mul_f32_e32 v82, v83, v84
	v_mul_f32_e32 v83, 0xbfb8aa3b, v76
	v_exp_f32_e32 v83, v83
	v_mul_f32_e32 v82, v87, v82
	v_cvt_pk_bf16_f32 v82, v82, s0
	global_store_short v[80:81], v82, off offset:32
	v_add_f32_e32 v81, 1.0, v83
	v_rcp_f32_e32 v82, v81
	v_mul_f32_e32 v81, 0xbfb8aa3b, v64
	v_exp_f32_e32 v83, v81
	v_or_b32_e32 v80, 48, v98
	v_mul_f32_e32 v76, v76, v82
	v_mul_f32_e32 v72, v72, v76
	v_add_f32_e32 v82, 1.0, v83
	v_rcp_f32_e32 v82, v82
	v_mad_i64_i32 v[80:81], s[10:11], v80, s39, v[96:97]
	v_cvt_pk_bf16_f32 v72, v72, s0
	v_mul_f32_e32 v64, v64, v82
	v_mul_f32_e32 v64, v68, v64
	v_mul_f32_e32 v68, 0xbfb8aa3b, v77
	v_exp_f32_e32 v68, v68
	global_store_short v[80:81], v72, off
	v_mul_f32_e32 v72, 0xbfb8aa3b, v65
	v_exp_f32_e32 v72, v72
	v_add_f32_e32 v68, 1.0, v68
	v_rcp_f32_e32 v68, v68
	v_cvt_pk_bf16_f32 v64, v64, s0
	global_store_short v[80:81], v64, off offset:32
	v_or_b32_e32 v64, 49, v98
	v_mad_i64_i32 v[80:81], s[10:11], v64, s39, v[96:97]
	v_mul_f32_e32 v64, v77, v68
	v_add_f32_e32 v68, 1.0, v72
	v_rcp_f32_e32 v68, v68
	v_mul_f32_e32 v64, v73, v64
	v_cvt_pk_bf16_f32 v64, v64, s0
	global_store_short v[80:81], v64, off
	v_mul_f32_e32 v64, v65, v68
	v_mul_f32_e32 v65, 0xbfb8aa3b, v78
	v_exp_f32_e32 v65, v65
	v_mul_f32_e32 v64, v69, v64
	v_cvt_pk_bf16_f32 v64, v64, s0
	global_store_short v[80:81], v64, off offset:32
	v_add_f32_e32 v65, 1.0, v65
	v_rcp_f32_e32 v68, v65
	v_mul_f32_e32 v65, 0xbfb8aa3b, v66
	v_exp_f32_e32 v69, v65
	v_or_b32_e32 v64, 50, v98
	v_mul_f32_e32 v68, v78, v68
	v_mul_f32_e32 v68, v74, v68
	v_add_f32_e32 v69, 1.0, v69
	v_rcp_f32_e32 v69, v69
	v_mad_i64_i32 v[64:65], s[10:11], v64, s39, v[96:97]
	v_cvt_pk_bf16_f32 v68, v68, s0
	global_store_short v[64:65], v68, off
	v_mul_f32_e32 v68, 0xbfb8aa3b, v79
	v_exp_f32_e32 v68, v68
	v_mul_f32_e32 v66, v66, v69
	v_mul_f32_e32 v66, v70, v66
	v_cvt_pk_bf16_f32 v66, v66, s0
	global_store_short v[64:65], v66, off offset:32
	v_add_f32_e32 v65, 1.0, v68
	v_rcp_f32_e32 v66, v65
	v_mul_f32_e32 v65, 0xbfb8aa3b, v67
	v_exp_f32_e32 v68, v65
	v_or_b32_e32 v64, 51, v98
	v_mul_f32_e32 v66, v79, v66
	v_mul_f32_e32 v66, v75, v66
	v_add_f32_e32 v68, 1.0, v68
	v_rcp_f32_e32 v68, v68
	v_mad_i64_i32 v[64:65], s[10:11], v64, s39, v[96:97]
	v_cvt_pk_bf16_f32 v66, v66, s0
	global_store_short v[64:65], v66, off
	v_mul_f32_e32 v66, v67, v68
	v_mul_f32_e32 v67, 0xbfb8aa3b, v60
	v_exp_f32_e32 v67, v67
	v_mul_f32_e32 v66, v71, v66
	v_cvt_pk_bf16_f32 v66, v66, s0
	global_store_short v[64:65], v66, off offset:32
	v_add_f32_e32 v65, 1.0, v67
	v_rcp_f32_e32 v66, v65
	v_mul_f32_e32 v65, 0xbfb8aa3b, v48
	v_exp_f32_e32 v67, v65
	v_or_b32_e32 v64, 64, v98
	v_mul_f32_e32 v60, v60, v66
	v_mul_f32_e32 v56, v56, v60
	v_add_f32_e32 v66, 1.0, v67
	v_rcp_f32_e32 v66, v66
	v_mad_i64_i32 v[64:65], s[10:11], v64, s39, v[96:97]
	v_cvt_pk_bf16_f32 v56, v56, s0
	v_mul_f32_e32 v48, v48, v66
	v_mul_f32_e32 v48, v52, v48
	v_mul_f32_e32 v52, 0xbfb8aa3b, v61
	v_exp_f32_e32 v52, v52
	global_store_short v[64:65], v56, off
	v_mul_f32_e32 v56, 0xbfb8aa3b, v49
	v_exp_f32_e32 v56, v56
	v_add_f32_e32 v52, 1.0, v52
	v_rcp_f32_e32 v52, v52
	v_cvt_pk_bf16_f32 v48, v48, s0
	global_store_short v[64:65], v48, off offset:32
	v_or_b32_e32 v48, 0x41, v98
	v_mad_i64_i32 v[64:65], s[10:11], v48, s39, v[96:97]
	v_mul_f32_e32 v48, v61, v52
	v_add_f32_e32 v52, 1.0, v56
	v_rcp_f32_e32 v52, v52
	v_mul_f32_e32 v48, v57, v48
	v_cvt_pk_bf16_f32 v48, v48, s0
	global_store_short v[64:65], v48, off
	v_mul_f32_e32 v48, v49, v52
	v_mul_f32_e32 v49, 0xbfb8aa3b, v62
	v_exp_f32_e32 v49, v49
	v_mul_f32_e32 v48, v53, v48
	v_cvt_pk_bf16_f32 v48, v48, s0
	global_store_short v[64:65], v48, off offset:32
	v_add_f32_e32 v49, 1.0, v49
	v_rcp_f32_e32 v52, v49
	v_mul_f32_e32 v49, 0xbfb8aa3b, v50
	v_exp_f32_e32 v53, v49
	v_or_b32_e32 v48, 0x42, v98
	v_mul_f32_e32 v52, v62, v52
	v_mul_f32_e32 v52, v58, v52
	v_add_f32_e32 v53, 1.0, v53
	v_rcp_f32_e32 v53, v53
	v_mad_i64_i32 v[48:49], s[10:11], v48, s39, v[96:97]
	v_cvt_pk_bf16_f32 v52, v52, s0
	global_store_short v[48:49], v52, off
	v_mul_f32_e32 v52, 0xbfb8aa3b, v63
	v_exp_f32_e32 v52, v52
	v_mul_f32_e32 v50, v50, v53
	v_mul_f32_e32 v50, v54, v50
	v_cvt_pk_bf16_f32 v50, v50, s0
	global_store_short v[48:49], v50, off offset:32
	v_add_f32_e32 v49, 1.0, v52
	v_rcp_f32_e32 v50, v49
	v_mul_f32_e32 v49, 0xbfb8aa3b, v51
	v_exp_f32_e32 v52, v49
	v_or_b32_e32 v48, 0x43, v98
	v_mul_f32_e32 v50, v63, v50
	v_mul_f32_e32 v50, v59, v50
	v_add_f32_e32 v52, 1.0, v52
	v_rcp_f32_e32 v52, v52
	v_mad_i64_i32 v[48:49], s[10:11], v48, s39, v[96:97]
	v_cvt_pk_bf16_f32 v50, v50, s0
	global_store_short v[48:49], v50, off
	v_mul_f32_e32 v50, v51, v52
	v_mul_f32_e32 v51, 0xbfb8aa3b, v44
	v_exp_f32_e32 v51, v51
	v_mul_f32_e32 v50, v55, v50
	v_cvt_pk_bf16_f32 v50, v50, s0
	global_store_short v[48:49], v50, off offset:32
	v_add_f32_e32 v49, 1.0, v51
	v_rcp_f32_e32 v50, v49
	v_mul_f32_e32 v49, 0xbfb8aa3b, v32
	v_exp_f32_e32 v51, v49
	v_or_b32_e32 v48, 0x50, v98
	v_mul_f32_e32 v44, v44, v50
	v_mul_f32_e32 v40, v40, v44
	v_add_f32_e32 v50, 1.0, v51
	v_rcp_f32_e32 v50, v50
	v_mad_i64_i32 v[48:49], s[10:11], v48, s39, v[96:97]
	v_cvt_pk_bf16_f32 v40, v40, s0
; DI u16 f2bf(float a) { return (u16)(pk2(a, 0.f) & 0xffffu); }
; DI float sigmoidf_(float x) { return __builtin_amdgcn_rcpf(1.f + __builtin_amdgcn_exp2f(-1.4426950408889634f * x)); }
; template <int EPI>
; DI void gemm_phase(const u16* __restrict__ A, int lda, const u16* __restrict__ Bt, int K, int N, u16* outb, int ldo,
;                    const float* r0, const float* r1, float* outf, char* lds, int bid, int nb) {
;     ...
;   for (int it = 0; it < nIter; ++it) {
;     ...
;       const int col = (tn * 4 + wc) * 32 + l15;
; #pragma unroll
;       for (int i = 0; i < 8; ++i)
; #pragma unroll
;         for (int r = 0; r < 4; ++r) {
;           const float g0 = acc[i][0][r], u0 = acc[i][2][r], g1 = acc[i][1][r], u1 = acc[i][3][r];
;           u16* o0 = outb + (size_t)(mrow + i * 16 + r) * ldo + col;
;           o0[0] = f2bf(g0 * sigmoidf_(g0) * u0); o0[16] = f2bf(g1 * sigmoidf_(g1) * u1);
;         }
	v_mul_f32_e32 v32, v32, v50
	v_mul_f32_e32 v32, v36, v32
	v_mul_f32_e32 v36, 0xbfb8aa3b, v45
	v_exp_f32_e32 v36, v36
	global_store_short v[48:49], v40, off
	v_mul_f32_e32 v40, 0xbfb8aa3b, v33
	v_exp_f32_e32 v40, v40
	v_add_f32_e32 v36, 1.0, v36
	v_rcp_f32_e32 v36, v36
	v_cvt_pk_bf16_f32 v32, v32, s0
	global_store_short v[48:49], v32, off offset:32
	v_or_b32_e32 v32, 0x51, v98
	v_mad_i64_i32 v[48:49], s[10:11], v32, s39, v[96:97]
	v_mul_f32_e32 v32, v45, v36
	v_add_f32_e32 v36, 1.0, v40
	v_rcp_f32_e32 v36, v36
	v_mul_f32_e32 v32, v41, v32
	v_cvt_pk_bf16_f32 v32, v32, s0
	global_store_short v[48:49], v32, off
	v_mul_f32_e32 v32, v33, v36
	v_mul_f32_e32 v33, 0xbfb8aa3b, v46
	v_exp_f32_e32 v33, v33
	v_mul_f32_e32 v32, v37, v32
	v_cvt_pk_bf16_f32 v32, v32, s0
	global_store_short v[48:49], v32, off offset:32
	v_add_f32_e32 v33, 1.0, v33
	v_rcp_f32_e32 v36, v33
	v_mul_f32_e32 v33, 0xbfb8aa3b, v34
	v_exp_f32_e32 v37, v33
	v_or_b32_e32 v32, 0x52, v98
	v_mul_f32_e32 v36, v46, v36
	v_mul_f32_e32 v36, v42, v36
	v_add_f32_e32 v37, 1.0, v37
	v_rcp_f32_e32 v37, v37
	v_mad_i64_i32 v[32:33], s[10:11], v32, s39, v[96:97]
	v_cvt_pk_bf16_f32 v36, v36, s0
	global_store_short v[32:33], v36, off
	v_mul_f32_e32 v36, 0xbfb8aa3b, v47
	v_exp_f32_e32 v36, v36
	v_mul_f32_e32 v34, v34, v37
	v_mul_f32_e32 v34, v38, v34
	v_cvt_pk_bf16_f32 v34, v34, s0
	global_store_short v[32:33], v34, off offset:32
	v_add_f32_e32 v33, 1.0, v36
	v_rcp_f32_e32 v34, v33
	v_mul_f32_e32 v33, 0xbfb8aa3b, v35
	v_exp_f32_e32 v36, v33
	v_or_b32_e32 v32, 0x53, v98
	v_mul_f32_e32 v34, v47, v34
	v_mul_f32_e32 v34, v43, v34
	v_add_f32_e32 v36, 1.0, v36
	v_rcp_f32_e32 v36, v36
	v_mad_i64_i32 v[32:33], s[10:11], v32, s39, v[96:97]
	v_cvt_pk_bf16_f32 v34, v34, s0
	global_store_short v[32:33], v34, off
	v_mul_f32_e32 v34, v35, v36
	v_mul_f32_e32 v35, 0xbfb8aa3b, v28
	v_exp_f32_e32 v35, v35
	v_mul_f32_e32 v34, v39, v34
	v_cvt_pk_bf16_f32 v34, v34, s0
	global_store_short v[32:33], v34, off offset:32
	v_add_f32_e32 v33, 1.0, v35
	v_rcp_f32_e32 v34, v33
	v_mul_f32_e32 v33, 0xbfb8aa3b, v16
	v_exp_f32_e32 v35, v33
	v_or_b32_e32 v32, 0x60, v98
	v_mul_f32_e32 v28, v28, v34
	v_mul_f32_e32 v24, v24, v28
	v_add_f32_e32 v34, 1.0, v35
	v_rcp_f32_e32 v34, v34
	v_mad_i64_i32 v[32:33], s[10:11], v32, s39, v[96:97]
	v_cvt_pk_bf16_f32 v24, v24, s0
	v_mul_f32_e32 v16, v16, v34
	v_mul_f32_e32 v16, v20, v16
	v_mul_f32_e32 v20, 0xbfb8aa3b, v29
	v_exp_f32_e32 v20, v20
	global_store_short v[32:33], v24, off
	v_mul_f32_e32 v24, 0xbfb8aa3b, v17
	v_exp_f32_e32 v24, v24
	v_add_f32_e32 v20, 1.0, v20
	v_rcp_f32_e32 v20, v20
	v_cvt_pk_bf16_f32 v16, v16, s0
	global_store_short v[32:33], v16, off offset:32
	v_or_b32_e32 v16, 0x61, v98
	v_mad_i64_i32 v[32:33], s[10:11], v16, s39, v[96:97]
	v_mul_f32_e32 v16, v29, v20
	v_add_f32_e32 v20, 1.0, v24
	v_rcp_f32_e32 v20, v20
	v_mul_f32_e32 v16, v25, v16
	v_cvt_pk_bf16_f32 v16, v16, s0
	global_store_short v[32:33], v16, off
	v_mul_f32_e32 v16, v17, v20
	v_mul_f32_e32 v17, 0xbfb8aa3b, v30
	v_exp_f32_e32 v17, v17
	v_mul_f32_e32 v16, v21, v16
	v_cvt_pk_bf16_f32 v16, v16, s0
	global_store_short v[32:33], v16, off offset:32
	v_add_f32_e32 v17, 1.0, v17
	v_rcp_f32_e32 v20, v17
	v_mul_f32_e32 v17, 0xbfb8aa3b, v18
	v_exp_f32_e32 v21, v17
	v_or_b32_e32 v16, 0x62, v98
	v_mul_f32_e32 v20, v30, v20
	v_mul_f32_e32 v20, v26, v20
	v_add_f32_e32 v21, 1.0, v21
	v_rcp_f32_e32 v21, v21
	v_mad_i64_i32 v[16:17], s[10:11], v16, s39, v[96:97]
	v_cvt_pk_bf16_f32 v20, v20, s0
	global_store_short v[16:17], v20, off
	v_mul_f32_e32 v20, 0xbfb8aa3b, v31
	v_exp_f32_e32 v20, v20
	v_mul_f32_e32 v18, v18, v21
	v_mul_f32_e32 v18, v22, v18
	v_cvt_pk_bf16_f32 v18, v18, s0
	global_store_short v[16:17], v18, off offset:32
	v_add_f32_e32 v17, 1.0, v20
	v_rcp_f32_e32 v18, v17
	v_mul_f32_e32 v17, 0xbfb8aa3b, v19
	v_exp_f32_e32 v20, v17
	v_or_b32_e32 v16, 0x63, v98
	v_mul_f32_e32 v18, v31, v18
	v_mul_f32_e32 v18, v27, v18
	v_add_f32_e32 v20, 1.0, v20
	v_rcp_f32_e32 v20, v20
	v_mad_i64_i32 v[16:17], s[10:11], v16, s39, v[96:97]
	v_cvt_pk_bf16_f32 v18, v18, s0
	global_store_short v[16:17], v18, off
	v_mul_f32_e32 v18, v19, v20
	v_mul_f32_e32 v19, 0xbfb8aa3b, v12
	v_exp_f32_e32 v19, v19
	v_mul_f32_e32 v18, v23, v18
	v_cvt_pk_bf16_f32 v18, v18, s0
	global_store_short v[16:17], v18, off offset:32
	v_add_f32_e32 v17, 1.0, v19
	v_rcp_f32_e32 v18, v17
	v_mul_f32_e32 v17, 0xbfb8aa3b, v0
	v_exp_f32_e32 v19, v17
	v_or_b32_e32 v16, 0x70, v98
	v_mul_f32_e32 v12, v12, v18
	v_mul_f32_e32 v8, v8, v12
	v_add_f32_e32 v18, 1.0, v19
	v_rcp_f32_e32 v18, v18
	v_mad_i64_i32 v[16:17], s[10:11], v16, s39, v[96:97]
	v_cvt_pk_bf16_f32 v8, v8, s0
	v_mul_f32_e32 v0, v0, v18
	v_mul_f32_e32 v0, v4, v0
	v_mul_f32_e32 v4, 0xbfb8aa3b, v13
	v_exp_f32_e32 v4, v4
	global_store_short v[16:17], v8, off
	v_mul_f32_e32 v8, 0xbfb8aa3b, v1
	v_exp_f32_e32 v8, v8
	v_add_f32_e32 v4, 1.0, v4
	v_rcp_f32_e32 v4, v4
	v_cvt_pk_bf16_f32 v0, v0, s0
	global_store_short v[16:17], v0, off offset:32
	v_or_b32_e32 v0, 0x71, v98
	v_mad_i64_i32 v[16:17], s[10:11], v0, s39, v[96:97]
	v_mul_f32_e32 v0, v13, v4
	v_add_f32_e32 v4, 1.0, v8
	v_rcp_f32_e32 v4, v4
	v_mul_f32_e32 v0, v9, v0
	v_cvt_pk_bf16_f32 v0, v0, s0
	global_store_short v[16:17], v0, off
	v_mul_f32_e32 v0, v1, v4
	v_mul_f32_e32 v1, 0xbfb8aa3b, v14
	v_exp_f32_e32 v1, v1
	v_mul_f32_e32 v0, v5, v0
	v_cvt_pk_bf16_f32 v0, v0, s0
	global_store_short v[16:17], v0, off offset:32
	v_add_f32_e32 v1, 1.0, v1
	v_rcp_f32_e32 v4, v1
	v_mul_f32_e32 v1, 0xbfb8aa3b, v2
	v_exp_f32_e32 v5, v1
	v_or_b32_e32 v0, 0x72, v98
	v_mul_f32_e32 v4, v14, v4
	v_mul_f32_e32 v4, v10, v4
	v_add_f32_e32 v5, 1.0, v5
	v_rcp_f32_e32 v5, v5
	v_mad_i64_i32 v[0:1], s[10:11], v0, s39, v[96:97]
	v_cvt_pk_bf16_f32 v4, v4, s0
	global_store_short v[0:1], v4, off
	v_mul_f32_e32 v4, 0xbfb8aa3b, v15
	v_exp_f32_e32 v4, v4
	v_mul_f32_e32 v2, v2, v5
	v_mul_f32_e32 v2, v6, v2
	v_cvt_pk_bf16_f32 v2, v2, s0
	global_store_short v[0:1], v2, off offset:32
	v_add_f32_e32 v1, 1.0, v4
	v_rcp_f32_e32 v2, v1
	v_mul_f32_e32 v1, 0xbfb8aa3b, v3
	v_exp_f32_e32 v4, v1
	v_or_b32_e32 v0, 0x73, v98
	v_mul_f32_e32 v2, v15, v2
	v_mul_f32_e32 v2, v11, v2
	v_add_f32_e32 v4, 1.0, v4
	v_rcp_f32_e32 v4, v4
	v_mad_i64_i32 v[0:1], s[10:11], v0, s39, v[96:97]
	v_cvt_pk_bf16_f32 v2, v2, s0
	global_store_short v[0:1], v2, off
	v_mul_f32_e32 v2, v3, v4
	v_mul_f32_e32 v2, v7, v2
	s_add_i32 s17, s17, 1
	v_cvt_pk_bf16_f32 v2, v2, s0
	s_cmp_eq_u32 s17, s3
	global_store_short v[0:1], v2, off offset:32
	s_cbranch_scc0 .LBB0_1297

; #define G_LOAD(KT) do { _Pragma("unroll") for (int i = 0; i < 4; ++i) { ra[i] = *(const u32x4*)(Ag + (size_t)i * 64 * lda + (KT) * 64); rb[i] = *(const u32x4*)(Bg + (size_t)i * 64 * K + (KT) * 64); } } while (0)
; #define G_STORE(BUF) do { u16* ad = As + (BUF) * 256 * 64 + sto; u16* bd = Bs + (BUF) * 256 * 64 + sto; _Pragma("unroll") for (int i = 0; i < 4; ++i) { *(u32x4*)(ad + i * 64 * 64) = ra[i]; *(u32x4*)(bd + i * 64 * 64) = rb[i]; } } while (0)
; template <int EPI>
; DI void gemm_phase(const u16* __restrict__ A, int lda, const u16* __restrict__ Bt, int K, int N, u16* outb, int ldo,
;                    const float* r0, const float* r1, float* outf, char* lds, int bid, int nb) {
;   const int tid = threadIdx.x, lane = tid & 63, wid = tid >> 6, wr = wid >> 2, wc = wid & 3, l15 = lane & 15, quad = lane >> 4;
;   u16* As = (u16*)lds; u16* Bs = As + 2 * 256 * 64;
;   const int nN = N >> 8, nM = M_TOT >> 8, nT = nM * nN, nk = K >> 6;
;   const int lrow = tid >> 3, lch = tid & 7;
;   const int sto = lrow * 64 + ((lch ^ ((lrow >> 1) & 7)) * 8);
;   const int fsw = (l15 >> 1) & 7;
;   const int fo0 = ((0 * 4 + quad) ^ fsw) * 8, fo1 = ((1 * 4 + quad) ^ fsw) * 8;
;   const bool swz = (nb == 256);
;   const int GN = (nN & 3) == 0 ? 4 : ((nN & 1) == 0 ? 2 : 1), GM = 32 / GN, nSN = nN / GN, nST = (nM / GM) * nSN;
;   const int xcd = bid & 7, jb = bid >> 3;
;   const int nIter = swz ? (nST - xcd + 7) / 8 : (nT - bid + nb - 1) / nb;
;   for (int it = 0; it < nIter; ++it) {
;     int tm, tn;
;     if (swz) { const int st = xcd + 8 * it, sm = st / nSN, sn = st - sm * nSN; tm = sm * GM + jb / GN; tn = sn * GN + (jb % GN); }
;     else { const int t = bid + it * nb; tm = t / nN; tn = t - tm * nN; }
;     const u16* Ag = A + (size_t)(tm * 256 + lrow) * lda + lch * 8;
;     const u16* Bg = Bt + (size_t)(tn * 256 + lrow) * K + lch * 8;
;     f32x4 acc[8][4];
; #pragma unroll
;     for (int i = 0; i < 8; ++i)
; #pragma unroll
;       for (int j = 0; j < 4; ++j) acc[i][j] = (f32x4){0.f, 0.f, 0.f, 0.f};
;     u32x4 ra[4], rb[4];
;     ...
;     G_LOAD(0);
;     G_STORE(0);
;     __syncthreads();
.LBB0_1363:
	s_lshl_b32 s37, s37, 8
	v_or_b32_e32 v60, s37, v138
	s_lshl_b32 s38, s38, 8
	v_mad_i64_i32 v[0:1], s[8:9], v60, s15, v[128:129]
	v_or_b32_e32 v61, s38, v138
	v_add_co_u32_e32 v4, vcc, 0x58000, v0
	v_mad_i64_i32 v[2:3], s[8:9], v61, s15, v[130:131]
	s_nop 0
	v_addc_co_u32_e32 v5, vcc, 0, v1, vcc
	v_add_co_u32_e32 v6, vcc, 0x58000, v2
	s_nop 1
	v_readfirstlane_b32 s98, v0
	v_readfirstlane_b32 s99, v1
	s_nop 1
	v_readfirstlane_b32 s100, v2
	v_readfirstlane_b32 s101, v3
	v_addc_co_u32_e32 v7, vcc, 0, v3, vcc
	v_add_co_u32_e32 v4, vcc, 0xb0000, v0
	s_mov_b32 s39, 0
	s_nop 0
	v_addc_co_u32_e32 v5, vcc, 0, v1, vcc
	v_add_co_u32_e32 v6, vcc, 0xb0000, v2
	s_mov_b64 s[8:9], 0
	s_nop 0
	v_addc_co_u32_e32 v7, vcc, 0, v3, vcc
	v_add_co_u32_e32 v0, vcc, 0x108000, v0
	v_addc_co_u32_e32 v1, vcc, 0, v1, vcc
	v_add_co_u32_e32 v2, vcc, 0x108000, v2
	v_mad_i64_i32 v[134:135], s[28:29], v60, s15, v[132:133]
	s_nop 0
	v_addc_co_u32_e32 v3, vcc, 0, v3, vcc
	v_mov_b32_e32 v0, 0
	v_mov_b32_e32 v1, v0
	v_mov_b32_e32 v2, v0
	v_mov_b32_e32 v3, v0
	v_mov_b32_e32 v4, v0
	v_mov_b32_e32 v5, v0
	v_mov_b32_e32 v6, v0
	v_mov_b32_e32 v7, v0
	v_mov_b32_e32 v8, v0
	v_mov_b32_e32 v9, v0
	v_mov_b32_e32 v10, v0
	v_mov_b32_e32 v11, v0
	v_mov_b32_e32 v12, v0
	v_mov_b32_e32 v13, v0
	v_mov_b32_e32 v14, v0
	v_mov_b32_e32 v15, v0
	v_mov_b32_e32 v16, v0
	v_mov_b32_e32 v17, v0
	v_mov_b32_e32 v18, v0
	v_mov_b32_e32 v19, v0
	v_mov_b32_e32 v20, v0
	v_mov_b32_e32 v21, v0
	v_mov_b32_e32 v22, v0
	v_mov_b32_e32 v23, v0
	v_mov_b32_e32 v24, v0
	v_mov_b32_e32 v25, v0
	v_mov_b32_e32 v26, v0
	v_mov_b32_e32 v27, v0
	v_mad_i64_i32 v[136:137], s[28:29], v61, s15, v[132:133]
	v_mov_b32_e32 v60, v0
	v_mov_b32_e32 v61, v0
	v_mov_b32_e32 v62, v0
	v_mov_b32_e32 v63, v0
	v_mov_b32_e32 v64, v0
	v_mov_b32_e32 v65, v0
	v_mov_b32_e32 v66, v0
	v_mov_b32_e32 v67, v0
	v_mov_b32_e32 v68, v0
	v_mov_b32_e32 v69, v0
	v_mov_b32_e32 v70, v0
	v_mov_b32_e32 v71, v0
	v_mov_b32_e32 v72, v0
	v_mov_b32_e32 v73, v0
	v_mov_b32_e32 v74, v0
	v_mov_b32_e32 v75, v0
	v_mov_b32_e32 v76, v0
	v_mov_b32_e32 v77, v0
	v_mov_b32_e32 v78, v0
	v_mov_b32_e32 v79, v0
	v_mov_b32_e32 v80, v0
	v_mov_b32_e32 v81, v0
	v_mov_b32_e32 v82, v0
	v_mov_b32_e32 v83, v0
	v_mov_b32_e32 v28, v0
	v_mov_b32_e32 v29, v0
	v_mov_b32_e32 v30, v0
	v_mov_b32_e32 v31, v0
	v_mov_b32_e32 v32, v0
	v_mov_b32_e32 v33, v0
	v_mov_b32_e32 v34, v0
	v_mov_b32_e32 v35, v0
	v_mov_b32_e32 v36, v0
	v_mov_b32_e32 v37, v0
	v_mov_b32_e32 v38, v0
	v_mov_b32_e32 v39, v0
	v_mov_b32_e32 v40, v0
	v_mov_b32_e32 v41, v0
	v_mov_b32_e32 v42, v0
	v_mov_b32_e32 v43, v0
	v_mov_b32_e32 v44, v0
	v_mov_b32_e32 v45, v0
	v_mov_b32_e32 v46, v0
	v_mov_b32_e32 v47, v0
	v_mov_b32_e32 v48, v0
	v_mov_b32_e32 v49, v0
	v_mov_b32_e32 v50, v0
	v_mov_b32_e32 v51, v0
	v_mov_b32_e32 v52, v0
	v_mov_b32_e32 v53, v0
	v_mov_b32_e32 v54, v0
	v_mov_b32_e32 v55, v0
	v_mov_b32_e32 v56, v0
	v_mov_b32_e32 v57, v0
	v_mov_b32_e32 v58, v0
	v_mov_b32_e32 v59, v0
	v_mov_b32_e32 v84, v0
	v_mov_b32_e32 v85, v0
	v_mov_b32_e32 v86, v0
	v_mov_b32_e32 v87, v0
	v_mov_b32_e32 v88, v0
	v_mov_b32_e32 v89, v0
	v_mov_b32_e32 v90, v0
	v_mov_b32_e32 v91, v0
	v_mov_b32_e32 v92, v0
	v_mov_b32_e32 v93, v0
	v_mov_b32_e32 v94, v0
	v_mov_b32_e32 v95, v0
	v_mov_b32_e32 v96, v0
	v_mov_b32_e32 v97, v0
	v_mov_b32_e32 v98, v0
	v_mov_b32_e32 v99, v0
	v_mov_b32_e32 v100, v0
	v_mov_b32_e32 v101, v0
	v_mov_b32_e32 v102, v0
	v_mov_b32_e32 v103, v0
	v_mov_b32_e32 v104, v0
	v_mov_b32_e32 v105, v0
	v_mov_b32_e32 v106, v0
	v_mov_b32_e32 v107, v0
	v_mov_b32_e32 v108, v0
	v_mov_b32_e32 v109, v0
	v_mov_b32_e32 v110, v0
	v_mov_b32_e32 v111, v0
	v_mov_b32_e32 v112, v0
	v_mov_b32_e32 v113, v0
	v_mov_b32_e32 v114, v0
	v_mov_b32_e32 v115, v0
	v_mov_b32_e32 v116, v0
	v_mov_b32_e32 v117, v0
	v_mov_b32_e32 v118, v0
	v_mov_b32_e32 v119, v0
	v_mov_b32_e32 v120, v0
	v_mov_b32_e32 v121, v0
	v_mov_b32_e32 v122, v0
	v_mov_b32_e32 v123, v0
	v_mov_b32_e32 v124, v0
	v_mov_b32_e32 v125, v0
	v_mov_b32_e32 v126, v0
	v_mov_b32_e32 v127, v0
	v_and_b32_e32 v229, 63, v174
	v_lshrrev_b32_e32 v230, 3, v229
	v_mov_b32_e32 v233, 0x1600
	v_mul_u32_u24_e32 v224, v230, v233
	v_bfe_u32 v231, v174, 4, 2
	v_bfe_u32 v232, v174, 6, 1
	v_lshl_or_b32 v232, v232, 2, v231
	v_and_b32_e32 v233, 7, v174
	v_xor_b32_e32 v232, v232, v233
	v_lshl_add_u32 v224, v232, 4, v224
	v_and_b32_e32 v229, 15, v174
	v_bfe_u32 v230, v174, 1, 3
	v_xor_b32_e32 v230, v230, v231
	v_lshlrev_b32_e32 v230, 4, v230
	v_lshl_or_b32 v230, v229, 7, v230
	v_lshrrev_b32_e32 v229, 8, v174
	v_lshl_or_b32 v225, v229, 14, v230
	v_bfe_u32 v229, v174, 6, 2
	v_lshl_or_b32 v227, v229, 13, v230
	v_or_b32_e32 v227, 0x10000, v227
	v_xor_b32_e32 v226, 64, v225
	v_xor_b32_e32 v228, 64, v227
	v_readfirstlane_b32 s97, v174
	s_lshl_b32 s97, s97, 4
	s_mov_b32 s28, 42
	s_add_u32 s8, s98, 0x0
	s_addc_u32 s9, s99, 0
	s_add_u32 m0, s97, 0x0
	s_nop 0
	global_load_lds_dwordx4 v224, s[8:9]
	s_add_u32 s8, s100, 0x0
	s_addc_u32 s9, s101, 0
	s_add_u32 m0, s97, 0x10000
	s_nop 0
	global_load_lds_dwordx4 v224, s[8:9]
	s_add_u32 s8, s98, 0x58000
	s_addc_u32 s9, s99, 0
	s_add_u32 m0, s97, 0x2000
	s_nop 0
	global_load_lds_dwordx4 v224, s[8:9]
	s_add_u32 s8, s100, 0x58000
	s_addc_u32 s9, s101, 0
	s_add_u32 m0, s97, 0x12000
	s_nop 0
	global_load_lds_dwordx4 v224, s[8:9]
	s_add_u32 s8, s98, 0xb0000
	s_addc_u32 s9, s99, 0
	s_add_u32 m0, s97, 0x4000
	s_nop 0
	global_load_lds_dwordx4 v224, s[8:9]
	s_add_u32 s8, s100, 0xb0000
	s_addc_u32 s9, s101, 0
	s_add_u32 m0, s97, 0x14000
	s_nop 0
	global_load_lds_dwordx4 v224, s[8:9]
	s_add_u32 s8, s98, 0x108000
	s_addc_u32 s9, s99, 0
	s_add_u32 m0, s97, 0x6000
	s_nop 0
	global_load_lds_dwordx4 v224, s[8:9]
	s_add_u32 s8, s100, 0x108000
	s_addc_u32 s9, s101, 0
	s_add_u32 m0, s97, 0x16000
	s_nop 0
	global_load_lds_dwordx4 v224, s[8:9]
	s_add_u32 s8, s98, 0x80
	s_addc_u32 s9, s99, 0
	s_add_u32 m0, s97, 0x8000
	s_nop 0
	global_load_lds_dwordx4 v224, s[8:9]
	s_add_u32 s8, s100, 0x80
	s_addc_u32 s9, s101, 0
	s_add_u32 m0, s97, 0x18000
	s_nop 0
	global_load_lds_dwordx4 v224, s[8:9]
	s_add_u32 s8, s98, 0x58080
	s_addc_u32 s9, s99, 0
	s_add_u32 m0, s97, 0xa000
	s_nop 0
	global_load_lds_dwordx4 v224, s[8:9]
	s_add_u32 s8, s100, 0x58080
	s_addc_u32 s9, s101, 0
	s_add_u32 m0, s97, 0x1a000
	s_nop 0
	global_load_lds_dwordx4 v224, s[8:9]
	s_add_u32 s8, s98, 0xb0080
	s_addc_u32 s9, s99, 0
	s_add_u32 m0, s97, 0xc000
	s_nop 0
	global_load_lds_dwordx4 v224, s[8:9]
	s_add_u32 s8, s100, 0xb0080
	s_addc_u32 s9, s101, 0
	s_add_u32 m0, s97, 0x1c000
	s_nop 0
	global_load_lds_dwordx4 v224, s[8:9]
	s_add_u32 s8, s98, 0x108080
	s_addc_u32 s9, s99, 0
	s_add_u32 m0, s97, 0xe000
	s_nop 0
	global_load_lds_dwordx4 v224, s[8:9]
	s_add_u32 s8, s100, 0x108080
	s_addc_u32 s9, s101, 0
	s_add_u32 m0, s97, 0x1e000
	s_nop 0
	global_load_lds_dwordx4 v224, s[8:9]
	s_add_u32 s98, s98, 0x100
	s_addc_u32 s99, s99, 0
	s_add_u32 s100, s100, 0x100
	s_addc_u32 s101, s101, 0
	s_waitcnt vmcnt(8)
	s_barrier
; #define G_LOAD(KT) do { _Pragma("unroll") for (int i = 0; i < 4; ++i) { ra[i] = *(const u32x4*)(Ag + (size_t)i * 64 * lda + (KT) * 64); rb[i] = *(const u32x4*)(Bg + (size_t)i * 64 * K + (KT) * 64); } } while (0)
; #define G_STORE(BUF) do { u16* ad = As + (BUF) * 256 * 64 + sto; u16* bd = Bs + (BUF) * 256 * 64 + sto; _Pragma("unroll") for (int i = 0; i < 4; ++i) { *(u32x4*)(ad + i * 64 * 64) = ra[i]; *(u32x4*)(bd + i * 64 * 64) = rb[i]; } } while (0)
; template <int EPI>
; DI void gemm_phase(const u16* __restrict__ A, int lda, const u16* __restrict__ Bt, int K, int N, u16* outb, int ldo,
;                    const float* r0, const float* r1, float* outf, char* lds, int bid, int nb) {
;     ...
;     G_LOAD(0);
;     G_STORE(0);
;     __syncthreads();
;     for (int kt = 0; kt < nk; ++kt) {
;       const int cur = kt & 1;
;       if (kt + 1 < nk) G_LOAD(kt + 1);
;       G_MMA(cur, fo0);
;       G_MMA(cur, fo1);
;       if (kt + 1 < nk) G_STORE(cur ^ 1);
;       __syncthreads();
;     }
	ds_read_b128 v[152:155], v227 offset:0
	ds_read_b128 v[156:159], v227 offset:2048
	ds_read_b128 v[160:163], v227 offset:4096
	ds_read_b128 v[164:167], v227 offset:6144
	ds_read_b128 v[188:191], v225 offset:0
	ds_read_b128 v[192:195], v225 offset:2048
	ds_read_b128 v[196:199], v225 offset:4096
	ds_read_b128 v[200:203], v225 offset:6144
	ds_read_b128 v[204:207], v225 offset:8192
	ds_read_b128 v[208:211], v225 offset:10240
	ds_read_b128 v[212:215], v225 offset:12288
	ds_read_b128 v[216:219], v225 offset:14336
	v_xor_b32_e32 v225, 0x8000, v225
	v_xor_b32_e32 v227, 0x8000, v227
	s_waitcnt lgkmcnt(0)
.Lgm7_loop:
	s_waitcnt lgkmcnt(4)
	v_mfma_f32_16x16x32_bf16 v[124:127], v[188:191], v[152:155], v[124:127]
	v_mfma_f32_16x16x32_bf16 v[120:123], v[188:191], v[156:159], v[120:123]
	v_mfma_f32_16x16x32_bf16 v[116:119], v[188:191], v[160:163], v[116:119]
	v_mfma_f32_16x16x32_bf16 v[112:115], v[188:191], v[164:167], v[112:115]
	ds_read_b128 v[188:191], v226 offset:0
	ds_read_b128 v[168:171], v228 offset:0
	v_mfma_f32_16x16x32_bf16 v[108:111], v[192:195], v[152:155], v[108:111]
	v_mfma_f32_16x16x32_bf16 v[104:107], v[192:195], v[156:159], v[104:107]
	v_mfma_f32_16x16x32_bf16 v[100:103], v[192:195], v[160:163], v[100:103]
	v_mfma_f32_16x16x32_bf16 v[96:99], v[192:195], v[164:167], v[96:99]
	ds_read_b128 v[192:195], v226 offset:2048
	ds_read_b128 v[176:179], v228 offset:2048
	v_mfma_f32_16x16x32_bf16 v[92:95], v[196:199], v[152:155], v[92:95]
	v_mfma_f32_16x16x32_bf16 v[88:91], v[196:199], v[156:159], v[88:91]
	v_mfma_f32_16x16x32_bf16 v[84:87], v[196:199], v[160:163], v[84:87]
	v_mfma_f32_16x16x32_bf16 v[80:83], v[196:199], v[164:167], v[80:83]
	ds_read_b128 v[196:199], v226 offset:4096
	ds_read_b128 v[180:183], v228 offset:4096
	v_mfma_f32_16x16x32_bf16 v[76:79], v[200:203], v[152:155], v[76:79]
	v_mfma_f32_16x16x32_bf16 v[72:75], v[200:203], v[156:159], v[72:75]
	v_mfma_f32_16x16x32_bf16 v[68:71], v[200:203], v[160:163], v[68:71]
	v_mfma_f32_16x16x32_bf16 v[64:67], v[200:203], v[164:167], v[64:67]
	ds_read_b128 v[200:203], v226 offset:6144
	ds_read_b128 v[184:187], v228 offset:6144
	s_waitcnt lgkmcnt(11)
	v_mfma_f32_16x16x32_bf16 v[60:63], v[204:207], v[152:155], v[60:63]
	v_mfma_f32_16x16x32_bf16 v[56:59], v[204:207], v[156:159], v[56:59]
	v_mfma_f32_16x16x32_bf16 v[52:55], v[204:207], v[160:163], v[52:55]
	v_mfma_f32_16x16x32_bf16 v[48:51], v[204:207], v[164:167], v[48:51]
	ds_read_b128 v[204:207], v226 offset:8192
	ds_read_b128 v[220:223], v226 offset:14336
	s_waitcnt lgkmcnt(11)
	v_mfma_f32_16x16x32_bf16 v[44:47], v[208:211], v[152:155], v[44:47]
	v_mfma_f32_16x16x32_bf16 v[40:43], v[208:211], v[156:159], v[40:43]
	v_mfma_f32_16x16x32_bf16 v[36:39], v[208:211], v[160:163], v[36:39]
	v_mfma_f32_16x16x32_bf16 v[32:35], v[208:211], v[164:167], v[32:35]
	ds_read_b128 v[208:211], v226 offset:10240
	s_waitcnt lgkmcnt(11)
	v_mfma_f32_16x16x32_bf16 v[28:31], v[212:215], v[152:155], v[28:31]
	v_mfma_f32_16x16x32_bf16 v[24:27], v[212:215], v[156:159], v[24:27]
	v_mfma_f32_16x16x32_bf16 v[20:23], v[212:215], v[160:163], v[20:23]
	v_mfma_f32_16x16x32_bf16 v[16:19], v[212:215], v[164:167], v[16:19]
	ds_read_b128 v[212:215], v226 offset:12288
	v_mfma_f32_16x16x32_bf16 v[12:15], v[216:219], v[152:155], v[12:15]
	v_mfma_f32_16x16x32_bf16 v[8:11], v[216:219], v[156:159], v[8:11]
	v_mfma_f32_16x16x32_bf16 v[4:7], v[216:219], v[160:163], v[4:7]
	v_mfma_f32_16x16x32_bf16 v[0:3], v[216:219], v[164:167], v[0:3]
	s_waitcnt vmcnt(0) lgkmcnt(0)
	s_barrier
	v_mfma_f32_16x16x32_bf16 v[124:127], v[188:191], v[168:171], v[124:127]
	v_mfma_f32_16x16x32_bf16 v[120:123], v[188:191], v[176:179], v[120:123]
	v_mfma_f32_16x16x32_bf16 v[116:119], v[188:191], v[180:183], v[116:119]
	v_mfma_f32_16x16x32_bf16 v[112:115], v[188:191], v[184:187], v[112:115]
	ds_read_b128 v[188:191], v225 offset:0
	ds_read_b128 v[152:155], v227 offset:0
	s_add_u32 s8, s98, 0x0
	s_addc_u32 s9, s99, 0
	s_add_u32 m0, s97, 0x0
	s_nop 0
	global_load_lds_dwordx4 v224, s[8:9]
	v_mfma_f32_16x16x32_bf16 v[108:111], v[192:195], v[168:171], v[108:111]
	v_mfma_f32_16x16x32_bf16 v[104:107], v[192:195], v[176:179], v[104:107]
	v_mfma_f32_16x16x32_bf16 v[100:103], v[192:195], v[180:183], v[100:103]
	v_mfma_f32_16x16x32_bf16 v[96:99], v[192:195], v[184:187], v[96:99]
	ds_read_b128 v[192:195], v225 offset:2048
	ds_read_b128 v[156:159], v227 offset:2048
	s_add_u32 s8, s100, 0x0
	s_addc_u32 s9, s101, 0
	s_add_u32 m0, s97, 0x10000
	s_nop 0
	global_load_lds_dwordx4 v224, s[8:9]
	v_mfma_f32_16x16x32_bf16 v[92:95], v[196:199], v[168:171], v[92:95]
	v_mfma_f32_16x16x32_bf16 v[88:91], v[196:199], v[176:179], v[88:91]
	v_mfma_f32_16x16x32_bf16 v[84:87], v[196:199], v[180:183], v[84:87]
	v_mfma_f32_16x16x32_bf16 v[80:83], v[196:199], v[184:187], v[80:83]
	ds_read_b128 v[196:199], v225 offset:4096
	ds_read_b128 v[160:163], v227 offset:4096
	s_add_u32 s8, s98, 0x58000
	s_addc_u32 s9, s99, 0
	s_add_u32 m0, s97, 0x2000
	s_nop 0
	global_load_lds_dwordx4 v224, s[8:9]
	v_mfma_f32_16x16x32_bf16 v[76:79], v[200:203], v[168:171], v[76:79]
	v_mfma_f32_16x16x32_bf16 v[72:75], v[200:203], v[176:179], v[72:75]
	v_mfma_f32_16x16x32_bf16 v[68:71], v[200:203], v[180:183], v[68:71]
	v_mfma_f32_16x16x32_bf16 v[64:67], v[200:203], v[184:187], v[64:67]
	ds_read_b128 v[200:203], v225 offset:6144
	ds_read_b128 v[164:167], v227 offset:6144
	s_add_u32 s8, s100, 0x58000
	s_addc_u32 s9, s101, 0
	s_add_u32 m0, s97, 0x12000
	s_nop 0
	global_load_lds_dwordx4 v224, s[8:9]
	v_mfma_f32_16x16x32_bf16 v[60:63], v[204:207], v[168:171], v[60:63]
	v_mfma_f32_16x16x32_bf16 v[56:59], v[204:207], v[176:179], v[56:59]
	v_mfma_f32_16x16x32_bf16 v[52:55], v[204:207], v[180:183], v[52:55]
; #define G_LOAD(KT) do { _Pragma("unroll") for (int i = 0; i < 4; ++i) { ra[i] = *(const u32x4*)(Ag + (size_t)i * 64 * lda + (KT) * 64); rb[i] = *(const u32x4*)(Bg + (size_t)i * 64 * K + (KT) * 64); } } while (0)
; #define G_STORE(BUF) do { u16* ad = As + (BUF) * 256 * 64 + sto; u16* bd = Bs + (BUF) * 256 * 64 + sto; _Pragma("unroll") for (int i = 0; i < 4; ++i) { *(u32x4*)(ad + i * 64 * 64) = ra[i]; *(u32x4*)(bd + i * 64 * 64) = rb[i]; } } while (0)
; template <int EPI>
; DI void gemm_phase(const u16* __restrict__ A, int lda, const u16* __restrict__ Bt, int K, int N, u16* outb, int ldo,
;                    const float* r0, const float* r1, float* outf, char* lds, int bid, int nb) {
;     ...
;     G_LOAD(0);
;     G_STORE(0);
;     __syncthreads();
;     for (int kt = 0; kt < nk; ++kt) {
;       const int cur = kt & 1;
;       if (kt + 1 < nk) G_LOAD(kt + 1);
;       G_MMA(cur, fo0);
;       G_MMA(cur, fo1);
;       if (kt + 1 < nk) G_STORE(cur ^ 1);
;       __syncthreads();
;     }
	v_mfma_f32_16x16x32_bf16 v[48:51], v[204:207], v[184:187], v[48:51]
	ds_read_b128 v[204:207], v225 offset:8192
	ds_read_b128 v[216:219], v225 offset:14336
	s_add_u32 s8, s98, 0xb0000
	s_addc_u32 s9, s99, 0
	s_add_u32 m0, s97, 0x4000
	s_nop 0
	global_load_lds_dwordx4 v224, s[8:9]
	v_mfma_f32_16x16x32_bf16 v[44:47], v[208:211], v[168:171], v[44:47]
	v_mfma_f32_16x16x32_bf16 v[40:43], v[208:211], v[176:179], v[40:43]
	v_mfma_f32_16x16x32_bf16 v[36:39], v[208:211], v[180:183], v[36:39]
	v_mfma_f32_16x16x32_bf16 v[32:35], v[208:211], v[184:187], v[32:35]
	ds_read_b128 v[208:211], v225 offset:10240
	s_add_u32 s8, s100, 0xb0000
	s_addc_u32 s9, s101, 0
	s_add_u32 m0, s97, 0x14000
	s_nop 0
	global_load_lds_dwordx4 v224, s[8:9]
	v_mfma_f32_16x16x32_bf16 v[28:31], v[212:215], v[168:171], v[28:31]
	v_mfma_f32_16x16x32_bf16 v[24:27], v[212:215], v[176:179], v[24:27]
	v_mfma_f32_16x16x32_bf16 v[20:23], v[212:215], v[180:183], v[20:23]
	v_mfma_f32_16x16x32_bf16 v[16:19], v[212:215], v[184:187], v[16:19]
	ds_read_b128 v[212:215], v225 offset:12288
	s_add_u32 s8, s98, 0x108000
	s_addc_u32 s9, s99, 0
	s_add_u32 m0, s97, 0x6000
	s_nop 0
	global_load_lds_dwordx4 v224, s[8:9]
	v_mfma_f32_16x16x32_bf16 v[12:15], v[220:223], v[168:171], v[12:15]
	v_mfma_f32_16x16x32_bf16 v[8:11], v[220:223], v[176:179], v[8:11]
	v_mfma_f32_16x16x32_bf16 v[4:7], v[220:223], v[180:183], v[4:7]
	v_mfma_f32_16x16x32_bf16 v[0:3], v[220:223], v[184:187], v[0:3]
	s_add_u32 s8, s100, 0x108000
	s_addc_u32 s9, s101, 0
	s_add_u32 m0, s97, 0x16000
	s_nop 0
	global_load_lds_dwordx4 v224, s[8:9]
	v_xor_b32_e32 v225, 0x8000, v225
	v_xor_b32_e32 v227, 0x8000, v227
	v_xor_b32_e32 v226, 0x8000, v226
	v_xor_b32_e32 v228, 0x8000, v228
	s_xor_b32 s97, s97, 0x8000
	s_add_u32 s98, s98, 0x80
	s_addc_u32 s99, s99, 0
	s_add_u32 s100, s100, 0x80
	s_addc_u32 s101, s101, 0
	s_sub_u32 s28, s28, 1
	s_cmp_lg_u32 s28, 0
	s_cbranch_scc1 .Lgm7_loop
	s_waitcnt lgkmcnt(4)
	v_mfma_f32_16x16x32_bf16 v[124:127], v[188:191], v[152:155], v[124:127]
	v_mfma_f32_16x16x32_bf16 v[120:123], v[188:191], v[156:159], v[120:123]
	v_mfma_f32_16x16x32_bf16 v[116:119], v[188:191], v[160:163], v[116:119]
	v_mfma_f32_16x16x32_bf16 v[112:115], v[188:191], v[164:167], v[112:115]
	ds_read_b128 v[188:191], v226 offset:0
	ds_read_b128 v[168:171], v228 offset:0
	v_mfma_f32_16x16x32_bf16 v[108:111], v[192:195], v[152:155], v[108:111]
	v_mfma_f32_16x16x32_bf16 v[104:107], v[192:195], v[156:159], v[104:107]
	v_mfma_f32_16x16x32_bf16 v[100:103], v[192:195], v[160:163], v[100:103]
	v_mfma_f32_16x16x32_bf16 v[96:99], v[192:195], v[164:167], v[96:99]
	ds_read_b128 v[192:195], v226 offset:2048
	ds_read_b128 v[176:179], v228 offset:2048
	v_mfma_f32_16x16x32_bf16 v[92:95], v[196:199], v[152:155], v[92:95]
	v_mfma_f32_16x16x32_bf16 v[88:91], v[196:199], v[156:159], v[88:91]
	v_mfma_f32_16x16x32_bf16 v[84:87], v[196:199], v[160:163], v[84:87]
	v_mfma_f32_16x16x32_bf16 v[80:83], v[196:199], v[164:167], v[80:83]
	ds_read_b128 v[196:199], v226 offset:4096
	ds_read_b128 v[180:183], v228 offset:4096
	v_mfma_f32_16x16x32_bf16 v[76:79], v[200:203], v[152:155], v[76:79]
	v_mfma_f32_16x16x32_bf16 v[72:75], v[200:203], v[156:159], v[72:75]
	v_mfma_f32_16x16x32_bf16 v[68:71], v[200:203], v[160:163], v[68:71]
	v_mfma_f32_16x16x32_bf16 v[64:67], v[200:203], v[164:167], v[64:67]
	ds_read_b128 v[200:203], v226 offset:6144
	ds_read_b128 v[184:187], v228 offset:6144
	s_waitcnt lgkmcnt(11)
	v_mfma_f32_16x16x32_bf16 v[60:63], v[204:207], v[152:155], v[60:63]
	v_mfma_f32_16x16x32_bf16 v[56:59], v[204:207], v[156:159], v[56:59]
	v_mfma_f32_16x16x32_bf16 v[52:55], v[204:207], v[160:163], v[52:55]
	v_mfma_f32_16x16x32_bf16 v[48:51], v[204:207], v[164:167], v[48:51]
	ds_read_b128 v[204:207], v226 offset:8192
	ds_read_b128 v[220:223], v226 offset:14336
	s_waitcnt lgkmcnt(11)
	v_mfma_f32_16x16x32_bf16 v[44:47], v[208:211], v[152:155], v[44:47]
	v_mfma_f32_16x16x32_bf16 v[40:43], v[208:211], v[156:159], v[40:43]
	v_mfma_f32_16x16x32_bf16 v[36:39], v[208:211], v[160:163], v[36:39]
	v_mfma_f32_16x16x32_bf16 v[32:35], v[208:211], v[164:167], v[32:35]
	ds_read_b128 v[208:211], v226 offset:10240
	s_waitcnt lgkmcnt(11)
	v_mfma_f32_16x16x32_bf16 v[28:31], v[212:215], v[152:155], v[28:31]
	v_mfma_f32_16x16x32_bf16 v[24:27], v[212:215], v[156:159], v[24:27]
	v_mfma_f32_16x16x32_bf16 v[20:23], v[212:215], v[160:163], v[20:23]
	v_mfma_f32_16x16x32_bf16 v[16:19], v[212:215], v[164:167], v[16:19]
	ds_read_b128 v[212:215], v226 offset:12288
	v_mfma_f32_16x16x32_bf16 v[12:15], v[216:219], v[152:155], v[12:15]
	v_mfma_f32_16x16x32_bf16 v[8:11], v[216:219], v[156:159], v[8:11]
	v_mfma_f32_16x16x32_bf16 v[4:7], v[216:219], v[160:163], v[4:7]
	v_mfma_f32_16x16x32_bf16 v[0:3], v[216:219], v[164:167], v[0:3]
	s_waitcnt vmcnt(0) lgkmcnt(0)
	s_barrier
; #define G_LOAD(KT) do { _Pragma("unroll") for (int i = 0; i < 4; ++i) { ra[i] = *(const u32x4*)(Ag + (size_t)i * 64 * lda + (KT) * 64); rb[i] = *(const u32x4*)(Bg + (size_t)i * 64 * K + (KT) * 64); } } while (0)
; #define G_STORE(BUF) do { u16* ad = As + (BUF) * 256 * 64 + sto; u16* bd = Bs + (BUF) * 256 * 64 + sto; _Pragma("unroll") for (int i = 0; i < 4; ++i) { *(u32x4*)(ad + i * 64 * 64) = ra[i]; *(u32x4*)(bd + i * 64 * 64) = rb[i]; } } while (0)
; template <int EPI>
; DI void gemm_phase(const u16* __restrict__ A, int lda, const u16* __restrict__ Bt, int K, int N, u16* outb, int ldo,
;                    const float* r0, const float* r1, float* outf, char* lds, int bid, int nb) {
;     ...
;     G_LOAD(0);
;     G_STORE(0);
;     __syncthreads();
;     for (int kt = 0; kt < nk; ++kt) {
;       const int cur = kt & 1;
;       if (kt + 1 < nk) G_LOAD(kt + 1);
;       G_MMA(cur, fo0);
;       G_MMA(cur, fo1);
;       if (kt + 1 < nk) G_STORE(cur ^ 1);
;       __syncthreads();
;     }
	v_mfma_f32_16x16x32_bf16 v[124:127], v[188:191], v[168:171], v[124:127]
	v_mfma_f32_16x16x32_bf16 v[120:123], v[188:191], v[176:179], v[120:123]
	v_mfma_f32_16x16x32_bf16 v[116:119], v[188:191], v[180:183], v[116:119]
	v_mfma_f32_16x16x32_bf16 v[112:115], v[188:191], v[184:187], v[112:115]
	ds_read_b128 v[188:191], v225 offset:0
	ds_read_b128 v[152:155], v227 offset:0
	v_mfma_f32_16x16x32_bf16 v[108:111], v[192:195], v[168:171], v[108:111]
	v_mfma_f32_16x16x32_bf16 v[104:107], v[192:195], v[176:179], v[104:107]
	v_mfma_f32_16x16x32_bf16 v[100:103], v[192:195], v[180:183], v[100:103]
	v_mfma_f32_16x16x32_bf16 v[96:99], v[192:195], v[184:187], v[96:99]
	ds_read_b128 v[192:195], v225 offset:2048
	ds_read_b128 v[156:159], v227 offset:2048
	v_mfma_f32_16x16x32_bf16 v[92:95], v[196:199], v[168:171], v[92:95]
	v_mfma_f32_16x16x32_bf16 v[88:91], v[196:199], v[176:179], v[88:91]
	v_mfma_f32_16x16x32_bf16 v[84:87], v[196:199], v[180:183], v[84:87]
	v_mfma_f32_16x16x32_bf16 v[80:83], v[196:199], v[184:187], v[80:83]
	ds_read_b128 v[196:199], v225 offset:4096
	ds_read_b128 v[160:163], v227 offset:4096
	v_mfma_f32_16x16x32_bf16 v[76:79], v[200:203], v[168:171], v[76:79]
	v_mfma_f32_16x16x32_bf16 v[72:75], v[200:203], v[176:179], v[72:75]
	v_mfma_f32_16x16x32_bf16 v[68:71], v[200:203], v[180:183], v[68:71]
	v_mfma_f32_16x16x32_bf16 v[64:67], v[200:203], v[184:187], v[64:67]
	ds_read_b128 v[200:203], v225 offset:6144
	ds_read_b128 v[164:167], v227 offset:6144
	v_mfma_f32_16x16x32_bf16 v[60:63], v[204:207], v[168:171], v[60:63]
	v_mfma_f32_16x16x32_bf16 v[56:59], v[204:207], v[176:179], v[56:59]
	v_mfma_f32_16x16x32_bf16 v[52:55], v[204:207], v[180:183], v[52:55]
	v_mfma_f32_16x16x32_bf16 v[48:51], v[204:207], v[184:187], v[48:51]
	ds_read_b128 v[204:207], v225 offset:8192
	ds_read_b128 v[216:219], v225 offset:14336
	v_mfma_f32_16x16x32_bf16 v[44:47], v[208:211], v[168:171], v[44:47]
	v_mfma_f32_16x16x32_bf16 v[40:43], v[208:211], v[176:179], v[40:43]
	v_mfma_f32_16x16x32_bf16 v[36:39], v[208:211], v[180:183], v[36:39]
	v_mfma_f32_16x16x32_bf16 v[32:35], v[208:211], v[184:187], v[32:35]
	ds_read_b128 v[208:211], v225 offset:10240
	v_mfma_f32_16x16x32_bf16 v[28:31], v[212:215], v[168:171], v[28:31]
	v_mfma_f32_16x16x32_bf16 v[24:27], v[212:215], v[176:179], v[24:27]
	v_mfma_f32_16x16x32_bf16 v[20:23], v[212:215], v[180:183], v[20:23]
	v_mfma_f32_16x16x32_bf16 v[16:19], v[212:215], v[184:187], v[16:19]
	ds_read_b128 v[212:215], v225 offset:12288
	v_mfma_f32_16x16x32_bf16 v[12:15], v[220:223], v[168:171], v[12:15]
	v_mfma_f32_16x16x32_bf16 v[8:11], v[220:223], v[176:179], v[8:11]
	v_mfma_f32_16x16x32_bf16 v[4:7], v[220:223], v[180:183], v[4:7]
	v_mfma_f32_16x16x32_bf16 v[0:3], v[220:223], v[184:187], v[0:3]
	v_xor_b32_e32 v226, 0x8000, v226
	v_xor_b32_e32 v228, 0x8000, v228
	s_waitcnt lgkmcnt(4)
	v_mfma_f32_16x16x32_bf16 v[124:127], v[188:191], v[152:155], v[124:127]
	v_mfma_f32_16x16x32_bf16 v[120:123], v[188:191], v[156:159], v[120:123]
	v_mfma_f32_16x16x32_bf16 v[116:119], v[188:191], v[160:163], v[116:119]
	v_mfma_f32_16x16x32_bf16 v[112:115], v[188:191], v[164:167], v[112:115]
	ds_read_b128 v[188:191], v226 offset:0
	ds_read_b128 v[168:171], v228 offset:0
	v_mfma_f32_16x16x32_bf16 v[108:111], v[192:195], v[152:155], v[108:111]
	v_mfma_f32_16x16x32_bf16 v[104:107], v[192:195], v[156:159], v[104:107]
	v_mfma_f32_16x16x32_bf16 v[100:103], v[192:195], v[160:163], v[100:103]
	v_mfma_f32_16x16x32_bf16 v[96:99], v[192:195], v[164:167], v[96:99]
	ds_read_b128 v[192:195], v226 offset:2048
	ds_read_b128 v[176:179], v228 offset:2048
	v_mfma_f32_16x16x32_bf16 v[92:95], v[196:199], v[152:155], v[92:95]
	v_mfma_f32_16x16x32_bf16 v[88:91], v[196:199], v[156:159], v[88:91]
	v_mfma_f32_16x16x32_bf16 v[84:87], v[196:199], v[160:163], v[84:87]
	v_mfma_f32_16x16x32_bf16 v[80:83], v[196:199], v[164:167], v[80:83]
	ds_read_b128 v[196:199], v226 offset:4096
	ds_read_b128 v[180:183], v228 offset:4096
	v_mfma_f32_16x16x32_bf16 v[76:79], v[200:203], v[152:155], v[76:79]
	v_mfma_f32_16x16x32_bf16 v[72:75], v[200:203], v[156:159], v[72:75]
	v_mfma_f32_16x16x32_bf16 v[68:71], v[200:203], v[160:163], v[68:71]
	v_mfma_f32_16x16x32_bf16 v[64:67], v[200:203], v[164:167], v[64:67]
	ds_read_b128 v[200:203], v226 offset:6144
	ds_read_b128 v[184:187], v228 offset:6144
	s_waitcnt lgkmcnt(11)
	v_mfma_f32_16x16x32_bf16 v[60:63], v[204:207], v[152:155], v[60:63]
	v_mfma_f32_16x16x32_bf16 v[56:59], v[204:207], v[156:159], v[56:59]
	v_mfma_f32_16x16x32_bf16 v[52:55], v[204:207], v[160:163], v[52:55]
	v_mfma_f32_16x16x32_bf16 v[48:51], v[204:207], v[164:167], v[48:51]
	ds_read_b128 v[204:207], v226 offset:8192
	ds_read_b128 v[220:223], v226 offset:14336
	s_waitcnt lgkmcnt(11)
	v_mfma_f32_16x16x32_bf16 v[44:47], v[208:211], v[152:155], v[44:47]
	v_mfma_f32_16x16x32_bf16 v[40:43], v[208:211], v[156:159], v[40:43]
	v_mfma_f32_16x16x32_bf16 v[36:39], v[208:211], v[160:163], v[36:39]
	v_mfma_f32_16x16x32_bf16 v[32:35], v[208:211], v[164:167], v[32:35]
	ds_read_b128 v[208:211], v226 offset:10240
	s_waitcnt lgkmcnt(11)
	v_mfma_f32_16x16x32_bf16 v[28:31], v[212:215], v[152:155], v[28:31]
	v_mfma_f32_16x16x32_bf16 v[24:27], v[212:215], v[156:159], v[24:27]
	v_mfma_f32_16x16x32_bf16 v[20:23], v[212:215], v[160:163], v[20:23]
	v_mfma_f32_16x16x32_bf16 v[16:19], v[212:215], v[164:167], v[16:19]
	ds_read_b128 v[212:215], v226 offset:12288
	v_mfma_f32_16x16x32_bf16 v[12:15], v[216:219], v[152:155], v[12:15]
	v_mfma_f32_16x16x32_bf16 v[8:11], v[216:219], v[156:159], v[8:11]
	v_mfma_f32_16x16x32_bf16 v[4:7], v[216:219], v[160:163], v[4:7]
	v_mfma_f32_16x16x32_bf16 v[0:3], v[216:219], v[164:167], v[0:3]
	s_waitcnt vmcnt(0) lgkmcnt(0)
	s_barrier
; #define G_LOAD(KT) do { _Pragma("unroll") for (int i = 0; i < 4; ++i) { ra[i] = *(const u32x4*)(Ag + (size_t)i * 64 * lda + (KT) * 64); rb[i] = *(const u32x4*)(Bg + (size_t)i * 64 * K + (KT) * 64); } } while (0)
; #define G_STORE(BUF) do { u16* ad = As + (BUF) * 256 * 64 + sto; u16* bd = Bs + (BUF) * 256 * 64 + sto; _Pragma("unroll") for (int i = 0; i < 4; ++i) { *(u32x4*)(ad + i * 64 * 64) = ra[i]; *(u32x4*)(bd + i * 64 * 64) = rb[i]; } } while (0)
; template <int EPI>
; DI void gemm_phase(const u16* __restrict__ A, int lda, const u16* __restrict__ Bt, int K, int N, u16* outb, int ldo,
;                    const float* r0, const float* r1, float* outf, char* lds, int bid, int nb) {
;     ...
;     G_LOAD(0);
;     G_STORE(0);
;     __syncthreads();
;     for (int kt = 0; kt < nk; ++kt) {
;       const int cur = kt & 1;
;       if (kt + 1 < nk) G_LOAD(kt + 1);
;       G_MMA(cur, fo0);
;       G_MMA(cur, fo1);
;       if (kt + 1 < nk) G_STORE(cur ^ 1);
;       __syncthreads();
;     ...
;     } else if constexpr (EPI == EPI_RESID) {
;       const int col = tn * 256 + wc * 64 + l15;
;       const float* rb_ = (tm * 256 < M_P) ? r0 : (r1 - (size_t)M_P * DM);
; #pragma unroll
;       for (int i = 0; i < 8; ++i)
; #pragma unroll
;         for (int r = 0; r < 4; ++r) {
;           const size_t i0 = (size_t)(mrow + i * 16 + r) * DM + col;
;           const float x0 = rb_[i0], x1 = rb_[i0 + 16], x2 = rb_[i0 + 32], x3 = rb_[i0 + 48];
;           outf[i0] = x0 + acc[i][0][r]; outf[i0 + 16] = x1 + acc[i][1][r]; outf[i0 + 32] = x2 + acc[i][2][r]; outf[i0 + 48] = x3 + acc[i][3][r];
;         }
	v_mfma_f32_16x16x32_bf16 v[124:127], v[188:191], v[168:171], v[124:127]
	v_mfma_f32_16x16x32_bf16 v[120:123], v[188:191], v[176:179], v[120:123]
	v_mfma_f32_16x16x32_bf16 v[116:119], v[188:191], v[180:183], v[116:119]
	v_mfma_f32_16x16x32_bf16 v[112:115], v[188:191], v[184:187], v[112:115]
	v_mfma_f32_16x16x32_bf16 v[108:111], v[192:195], v[168:171], v[108:111]
	v_mfma_f32_16x16x32_bf16 v[104:107], v[192:195], v[176:179], v[104:107]
	v_mfma_f32_16x16x32_bf16 v[100:103], v[192:195], v[180:183], v[100:103]
	v_mfma_f32_16x16x32_bf16 v[96:99], v[192:195], v[184:187], v[96:99]
	v_mfma_f32_16x16x32_bf16 v[92:95], v[196:199], v[168:171], v[92:95]
	v_mfma_f32_16x16x32_bf16 v[88:91], v[196:199], v[176:179], v[88:91]
	v_mfma_f32_16x16x32_bf16 v[84:87], v[196:199], v[180:183], v[84:87]
	v_mfma_f32_16x16x32_bf16 v[80:83], v[196:199], v[184:187], v[80:83]
	v_mfma_f32_16x16x32_bf16 v[76:79], v[200:203], v[168:171], v[76:79]
	v_mfma_f32_16x16x32_bf16 v[72:75], v[200:203], v[176:179], v[72:75]
	v_mfma_f32_16x16x32_bf16 v[68:71], v[200:203], v[180:183], v[68:71]
	v_mfma_f32_16x16x32_bf16 v[64:67], v[200:203], v[184:187], v[64:67]
	v_mfma_f32_16x16x32_bf16 v[60:63], v[204:207], v[168:171], v[60:63]
	v_mfma_f32_16x16x32_bf16 v[56:59], v[204:207], v[176:179], v[56:59]
	v_mfma_f32_16x16x32_bf16 v[52:55], v[204:207], v[180:183], v[52:55]
	v_mfma_f32_16x16x32_bf16 v[48:51], v[204:207], v[184:187], v[48:51]
	v_mfma_f32_16x16x32_bf16 v[44:47], v[208:211], v[168:171], v[44:47]
	v_mfma_f32_16x16x32_bf16 v[40:43], v[208:211], v[176:179], v[40:43]
	v_mfma_f32_16x16x32_bf16 v[36:39], v[208:211], v[180:183], v[36:39]
	v_mfma_f32_16x16x32_bf16 v[32:35], v[208:211], v[184:187], v[32:35]
	v_mfma_f32_16x16x32_bf16 v[28:31], v[212:215], v[168:171], v[28:31]
	v_mfma_f32_16x16x32_bf16 v[24:27], v[212:215], v[176:179], v[24:27]
	v_mfma_f32_16x16x32_bf16 v[20:23], v[212:215], v[180:183], v[20:23]
	v_mfma_f32_16x16x32_bf16 v[16:19], v[212:215], v[184:187], v[16:19]
	v_mfma_f32_16x16x32_bf16 v[12:15], v[220:223], v[168:171], v[12:15]
	v_mfma_f32_16x16x32_bf16 v[8:11], v[220:223], v[176:179], v[8:11]
	v_mfma_f32_16x16x32_bf16 v[4:7], v[220:223], v[180:183], v[4:7]
	v_mfma_f32_16x16x32_bf16 v[0:3], v[220:223], v[184:187], v[0:3]
	s_nop 7
	s_nop 3
	v_mov_b32_e32 v224, v96
	v_mov_b32_e32 v225, v97
	v_mov_b32_e32 v226, v98
	v_mov_b32_e32 v227, v99
	v_mov_b32_e32 v172, v80
	v_mov_b32_e32 v80, v92
	v_mov_b32_e32 v92, v172
	v_mov_b32_e32 v172, v81
	v_mov_b32_e32 v81, v93
	v_mov_b32_e32 v93, v172
	v_mov_b32_e32 v172, v82
	v_mov_b32_e32 v82, v94
	v_mov_b32_e32 v94, v172
	v_mov_b32_e32 v172, v83
	v_mov_b32_e32 v83, v95
	v_mov_b32_e32 v95, v172
	v_mov_b32_e32 v172, v84
	v_mov_b32_e32 v84, v88
	v_mov_b32_e32 v88, v172
	v_mov_b32_e32 v172, v85
	v_mov_b32_e32 v85, v89
	v_mov_b32_e32 v89, v172
	v_mov_b32_e32 v172, v86
	v_mov_b32_e32 v86, v90
	v_mov_b32_e32 v90, v172
	v_mov_b32_e32 v172, v87
	v_mov_b32_e32 v87, v91
	v_mov_b32_e32 v91, v172
	v_mov_b32_e32 v172, v64
	v_mov_b32_e32 v64, v76
	v_mov_b32_e32 v76, v172
	v_mov_b32_e32 v172, v65
	v_mov_b32_e32 v65, v77
	v_mov_b32_e32 v77, v172
	v_mov_b32_e32 v172, v66
	v_mov_b32_e32 v66, v78
	v_mov_b32_e32 v78, v172
	v_mov_b32_e32 v172, v67
	v_mov_b32_e32 v67, v79
	v_mov_b32_e32 v79, v172
	v_mov_b32_e32 v172, v68
	v_mov_b32_e32 v68, v72
	v_mov_b32_e32 v72, v172
	v_mov_b32_e32 v172, v69
	v_mov_b32_e32 v69, v73
	v_mov_b32_e32 v73, v172
	v_mov_b32_e32 v172, v70
	v_mov_b32_e32 v70, v74
	v_mov_b32_e32 v74, v172
	v_mov_b32_e32 v172, v71
	v_mov_b32_e32 v71, v75
	v_mov_b32_e32 v75, v172
	v_mov_b32_e32 v172, v48
	v_mov_b32_e32 v48, v60
	v_mov_b32_e32 v60, v172
	v_mov_b32_e32 v172, v49
	v_mov_b32_e32 v49, v61
	v_mov_b32_e32 v61, v172
	v_mov_b32_e32 v172, v50
	v_mov_b32_e32 v50, v62
	v_mov_b32_e32 v62, v172
	v_mov_b32_e32 v172, v51
	v_mov_b32_e32 v51, v63
	v_mov_b32_e32 v63, v172
	v_mov_b32_e32 v172, v52
	v_mov_b32_e32 v52, v56
	v_mov_b32_e32 v56, v172
	v_mov_b32_e32 v172, v53
	v_mov_b32_e32 v53, v57
	v_mov_b32_e32 v57, v172
	v_mov_b32_e32 v172, v54
	v_mov_b32_e32 v54, v58
	v_mov_b32_e32 v58, v172
	v_mov_b32_e32 v172, v55
	v_mov_b32_e32 v55, v59
	v_mov_b32_e32 v59, v172
	v_mov_b32_e32 v172, v32
	v_mov_b32_e32 v32, v44
	v_mov_b32_e32 v44, v172
	v_mov_b32_e32 v172, v33
	v_mov_b32_e32 v33, v45
	v_mov_b32_e32 v45, v172
	v_mov_b32_e32 v172, v34
	v_mov_b32_e32 v34, v46
	v_mov_b32_e32 v46, v172
	v_mov_b32_e32 v172, v35
	v_mov_b32_e32 v35, v47
	v_mov_b32_e32 v47, v172
	v_mov_b32_e32 v172, v36
	v_mov_b32_e32 v36, v40
	v_mov_b32_e32 v40, v172
	v_mov_b32_e32 v172, v37
	v_mov_b32_e32 v37, v41
	v_mov_b32_e32 v41, v172
	v_mov_b32_e32 v172, v38
	v_mov_b32_e32 v38, v42
	v_mov_b32_e32 v42, v172
	v_mov_b32_e32 v172, v39
	v_mov_b32_e32 v39, v43
	v_mov_b32_e32 v43, v172
	v_mov_b32_e32 v172, v16
	v_mov_b32_e32 v16, v28
	v_mov_b32_e32 v28, v172
	v_mov_b32_e32 v172, v17
	v_mov_b32_e32 v17, v29
	v_mov_b32_e32 v29, v172
	v_mov_b32_e32 v172, v18
	v_mov_b32_e32 v18, v30
	v_mov_b32_e32 v30, v172
	v_mov_b32_e32 v172, v19
	v_mov_b32_e32 v19, v31
	v_mov_b32_e32 v31, v172
	v_mov_b32_e32 v172, v20
	v_mov_b32_e32 v20, v24
	v_mov_b32_e32 v24, v172
	v_mov_b32_e32 v172, v21
	v_mov_b32_e32 v21, v25
	v_mov_b32_e32 v25, v172
	v_mov_b32_e32 v172, v22
	v_mov_b32_e32 v22, v26
	v_mov_b32_e32 v26, v172
	v_mov_b32_e32 v172, v23
	v_mov_b32_e32 v23, v27
	v_mov_b32_e32 v27, v172
	v_mov_b32_e32 v172, v0
	v_mov_b32_e32 v0, v12
	v_mov_b32_e32 v12, v172
	v_mov_b32_e32 v172, v1
	v_mov_b32_e32 v1, v13
	v_mov_b32_e32 v13, v172
	v_mov_b32_e32 v172, v2
	v_mov_b32_e32 v2, v14
	v_mov_b32_e32 v14, v172
	v_mov_b32_e32 v172, v3
	v_mov_b32_e32 v3, v15
	v_mov_b32_e32 v15, v172
	v_mov_b32_e32 v172, v4
	v_mov_b32_e32 v4, v8
	v_mov_b32_e32 v8, v172
	v_mov_b32_e32 v172, v5
	v_mov_b32_e32 v5, v9
	v_mov_b32_e32 v9, v172
	v_mov_b32_e32 v172, v6
	v_mov_b32_e32 v6, v10
	v_mov_b32_e32 v10, v172
	v_mov_b32_e32 v172, v7
	v_mov_b32_e32 v7, v11
	v_mov_b32_e32 v11, v172
	v_add_u32_e32 v98, s37, v143
	v_or_b32_e32 v96, s38, v144
	v_ashrrev_i32_e32 v99, 31, v98
	v_ashrrev_i32_e32 v97, 31, v96
	v_lshlrev_b64 v[134:135], 10, v[98:99]
	v_lshl_add_u64 v[134:135], v[134:135], 0, v[96:97]
	v_lshl_add_u64 v[134:135], v[134:135], 2, s[22:23]
	global_load_dword v99, v[134:135], off
	global_load_dword v151, v[134:135], off offset:64
	global_load_dword v152, v[134:135], off offset:128
	global_load_dword v153, v[134:135], off offset:192
	v_or_b32_e32 v136, 1, v98
	v_ashrrev_i32_e32 v137, 31, v136
	v_lshlrev_b64 v[136:137], 10, v[136:137]
	v_lshl_add_u64 v[136:137], v[136:137], 0, v[96:97]
	v_lshl_add_u64 v[136:137], v[136:137], 2, s[22:23]
	s_add_i32 s14, s14, 1
	s_cmp_eq_u32 s14, s3
	s_waitcnt vmcnt(3)
; template <int EPI>
; DI void gemm_phase(const u16* __restrict__ A, int lda, const u16* __restrict__ Bt, int K, int N, u16* outb, int ldo,
;                    const float* r0, const float* r1, float* outf, char* lds, int bid, int nb) {
;     ...
;     } else if constexpr (EPI == EPI_RESID) {
;       const int col = tn * 256 + wc * 64 + l15;
;       const float* rb_ = (tm * 256 < M_P) ? r0 : (r1 - (size_t)M_P * DM);
; #pragma unroll
;       for (int i = 0; i < 8; ++i)
; #pragma unroll
;         for (int r = 0; r < 4; ++r) {
;           const size_t i0 = (size_t)(mrow + i * 16 + r) * DM + col;
;           const float x0 = rb_[i0], x1 = rb_[i0 + 16], x2 = rb_[i0 + 32], x3 = rb_[i0 + 48];
;           outf[i0] = x0 + acc[i][0][r]; outf[i0 + 16] = x1 + acc[i][1][r]; outf[i0 + 32] = x2 + acc[i][2][r]; outf[i0 + 48] = x3 + acc[i][3][r];
;         }
	v_add_f32_e32 v99, v124, v99
	s_waitcnt vmcnt(2)
	v_add_f32_e32 v120, v120, v151
	s_waitcnt vmcnt(1)
	v_add_f32_e32 v116, v116, v152
	s_waitcnt vmcnt(0)
	v_add_f32_e32 v112, v112, v153
	global_store_dword v[134:135], v99, off
	global_store_dword v[134:135], v120, off offset:64
	global_store_dword v[134:135], v116, off offset:128
	global_store_dword v[134:135], v112, off offset:192
	global_load_dword v99, v[136:137], off
	s_nop 0
	global_load_dword v112, v[136:137], off offset:64
	global_load_dword v116, v[136:137], off offset:128
	global_load_dword v120, v[136:137], off offset:192
	v_or_b32_e32 v134, 2, v98
	v_ashrrev_i32_e32 v135, 31, v134
	v_lshlrev_b64 v[134:135], 10, v[134:135]
	v_lshl_add_u64 v[134:135], v[134:135], 0, v[96:97]
	v_lshl_add_u64 v[134:135], v[134:135], 2, s[22:23]
	s_waitcnt vmcnt(3)
	v_add_f32_e32 v99, v125, v99
	s_waitcnt vmcnt(2)
	v_add_f32_e32 v112, v121, v112
	s_waitcnt vmcnt(1)
	v_add_f32_e32 v116, v117, v116
	s_waitcnt vmcnt(0)
	v_add_f32_e32 v113, v113, v120
	global_store_dword v[136:137], v99, off
	global_store_dword v[136:137], v112, off offset:64
	global_store_dword v[136:137], v116, off offset:128
	global_store_dword v[136:137], v113, off offset:192
	global_load_dword v99, v[134:135], off
	s_nop 0
	global_load_dword v116, v[134:135], off offset:64
	global_load_dword v117, v[134:135], off offset:128
	global_load_dword v120, v[134:135], off offset:192
	v_or_b32_e32 v112, 3, v98
	v_ashrrev_i32_e32 v113, 31, v112
	v_lshlrev_b64 v[112:113], 10, v[112:113]
	v_lshl_add_u64 v[112:113], v[112:113], 0, v[96:97]
	v_lshl_add_u64 v[112:113], v[112:113], 2, s[22:23]
	s_waitcnt vmcnt(3)
	v_add_f32_e32 v99, v126, v99
	s_waitcnt vmcnt(2)
	v_add_f32_e32 v116, v122, v116
	s_waitcnt vmcnt(1)
	v_add_f32_e32 v117, v118, v117
	s_waitcnt vmcnt(0)
	v_add_f32_e32 v114, v114, v120
	global_store_dword v[134:135], v99, off
	global_store_dword v[134:135], v116, off offset:64
	global_store_dword v[134:135], v117, off offset:128
	global_store_dword v[134:135], v114, off offset:192
	global_load_dword v99, v[112:113], off
	s_nop 0
	global_load_dword v114, v[112:113], off offset:64
	global_load_dword v118, v[112:113], off offset:128
	global_load_dword v120, v[112:113], off offset:192
	v_or_b32_e32 v116, 16, v98
	v_ashrrev_i32_e32 v117, 31, v116
	v_lshlrev_b64 v[116:117], 10, v[116:117]
	v_lshl_add_u64 v[116:117], v[116:117], 0, v[96:97]
	v_lshl_add_u64 v[116:117], v[116:117], 2, s[22:23]
	s_waitcnt vmcnt(3)
	v_add_f32_e32 v99, v127, v99
	s_waitcnt vmcnt(2)
	v_add_f32_e32 v114, v123, v114
	s_waitcnt vmcnt(1)
	v_add_f32_e32 v118, v119, v118
	s_waitcnt vmcnt(0)
	v_add_f32_e32 v115, v115, v120
	global_store_dword v[112:113], v99, off
	global_store_dword v[112:113], v114, off offset:64
	global_store_dword v[112:113], v118, off offset:128
	global_store_dword v[112:113], v115, off offset:192
	global_load_dword v99, v[116:117], off
	s_nop 0
	global_load_dword v114, v[116:117], off offset:64
	global_load_dword v115, v[116:117], off offset:128
	global_load_dword v118, v[116:117], off offset:192
	v_or_b32_e32 v112, 17, v98
	v_ashrrev_i32_e32 v113, 31, v112
	v_lshlrev_b64 v[112:113], 10, v[112:113]
	v_lshl_add_u64 v[112:113], v[112:113], 0, v[96:97]
	v_lshl_add_u64 v[112:113], v[112:113], 2, s[22:23]
	s_waitcnt vmcnt(3)
	v_add_f32_e32 v99, v108, v99
	s_waitcnt vmcnt(2)
	v_add_f32_e32 v104, v104, v114
	s_waitcnt vmcnt(1)
	v_add_f32_e32 v100, v100, v115
	s_waitcnt vmcnt(0)
	v_add_f32_e32 v108, v224, v118
	global_store_dword v[116:117], v99, off
	global_store_dword v[116:117], v104, off offset:64
	global_store_dword v[116:117], v100, off offset:128
	global_store_dword v[116:117], v108, off offset:192
	global_load_dword v99, v[112:113], off
	s_nop 0
	global_load_dword v100, v[112:113], off offset:64
	global_load_dword v104, v[112:113], off offset:128
	global_load_dword v108, v[112:113], off offset:192
	v_or_b32_e32 v114, 18, v98
	v_ashrrev_i32_e32 v115, 31, v114
	v_lshlrev_b64 v[114:115], 10, v[114:115]
	v_lshl_add_u64 v[114:115], v[114:115], 0, v[96:97]
	v_lshl_add_u64 v[114:115], v[114:115], 2, s[22:23]
	s_waitcnt vmcnt(3)
	v_add_f32_e32 v99, v109, v99
	s_waitcnt vmcnt(2)
	v_add_f32_e32 v100, v105, v100
	s_waitcnt vmcnt(1)
	v_add_f32_e32 v101, v101, v104
	s_waitcnt vmcnt(0)
	v_add_f32_e32 v104, v225, v108
	global_store_dword v[112:113], v99, off
	global_store_dword v[112:113], v100, off offset:64
	global_store_dword v[112:113], v101, off offset:128
	global_store_dword v[112:113], v104, off offset:192
	global_load_dword v99, v[114:115], off
	s_nop 0
	global_load_dword v104, v[114:115], off offset:64
	global_load_dword v105, v[114:115], off offset:128
	global_load_dword v108, v[114:115], off offset:192
	v_or_b32_e32 v100, 19, v98
	v_ashrrev_i32_e32 v101, 31, v100
	v_lshlrev_b64 v[100:101], 10, v[100:101]
	v_lshl_add_u64 v[100:101], v[100:101], 0, v[96:97]
	v_lshl_add_u64 v[100:101], v[100:101], 2, s[22:23]
	s_waitcnt vmcnt(3)
	v_add_f32_e32 v99, v110, v99
	s_waitcnt vmcnt(2)
	v_add_f32_e32 v104, v106, v104
	s_waitcnt vmcnt(1)
	v_add_f32_e32 v102, v102, v105
	s_waitcnt vmcnt(0)
	v_add_f32_e32 v105, v226, v108
	global_store_dword v[114:115], v99, off
	global_store_dword v[114:115], v104, off offset:64
	global_store_dword v[114:115], v102, off offset:128
	global_store_dword v[114:115], v105, off offset:192
	global_load_dword v99, v[100:101], off
	s_nop 0
	global_load_dword v102, v[100:101], off offset:64
	global_load_dword v106, v[100:101], off offset:128
	global_load_dword v108, v[100:101], off offset:192
	v_or_b32_e32 v104, 32, v98
	v_ashrrev_i32_e32 v105, 31, v104
	v_lshlrev_b64 v[104:105], 10, v[104:105]
	v_lshl_add_u64 v[104:105], v[104:105], 0, v[96:97]
	v_lshl_add_u64 v[104:105], v[104:105], 2, s[22:23]
	s_waitcnt vmcnt(3)
; template <int EPI>
; DI void gemm_phase(const u16* __restrict__ A, int lda, const u16* __restrict__ Bt, int K, int N, u16* outb, int ldo,
;                    const float* r0, const float* r1, float* outf, char* lds, int bid, int nb) {
;     ...
;     } else if constexpr (EPI == EPI_RESID) {
;       const int col = tn * 256 + wc * 64 + l15;
;       const float* rb_ = (tm * 256 < M_P) ? r0 : (r1 - (size_t)M_P * DM);
; #pragma unroll
;       for (int i = 0; i < 8; ++i)
; #pragma unroll
;         for (int r = 0; r < 4; ++r) {
;           const size_t i0 = (size_t)(mrow + i * 16 + r) * DM + col;
;           const float x0 = rb_[i0], x1 = rb_[i0 + 16], x2 = rb_[i0 + 32], x3 = rb_[i0 + 48];
;           outf[i0] = x0 + acc[i][0][r]; outf[i0 + 16] = x1 + acc[i][1][r]; outf[i0 + 32] = x2 + acc[i][2][r]; outf[i0 + 48] = x3 + acc[i][3][r];
;         }
	v_add_f32_e32 v99, v111, v99
	s_waitcnt vmcnt(2)
	v_add_f32_e32 v102, v107, v102
	s_waitcnt vmcnt(1)
	v_add_f32_e32 v103, v103, v106
	s_waitcnt vmcnt(0)
	v_add_f32_e32 v106, v227, v108
	global_store_dword v[100:101], v99, off
	global_store_dword v[100:101], v102, off offset:64
	global_store_dword v[100:101], v103, off offset:128
	global_store_dword v[100:101], v106, off offset:192
	global_load_dword v99, v[104:105], off
	s_nop 0
	global_load_dword v102, v[104:105], off offset:64
	global_load_dword v103, v[104:105], off offset:128
	global_load_dword v106, v[104:105], off offset:192
	v_or_b32_e32 v100, 33, v98
	v_ashrrev_i32_e32 v101, 31, v100
	v_lshlrev_b64 v[100:101], 10, v[100:101]
	v_lshl_add_u64 v[100:101], v[100:101], 0, v[96:97]
	v_lshl_add_u64 v[100:101], v[100:101], 2, s[22:23]
	s_waitcnt vmcnt(3)
	v_add_f32_e32 v80, v80, v99
	s_waitcnt vmcnt(2)
	v_add_f32_e32 v84, v84, v102
	s_waitcnt vmcnt(1)
	v_add_f32_e32 v88, v88, v103
	s_waitcnt vmcnt(0)
	v_add_f32_e32 v92, v92, v106
	global_store_dword v[104:105], v80, off
	global_store_dword v[104:105], v84, off offset:64
	global_store_dword v[104:105], v88, off offset:128
	global_store_dword v[104:105], v92, off offset:192
	global_load_dword v80, v[100:101], off
	s_nop 0
	global_load_dword v84, v[100:101], off offset:64
	global_load_dword v88, v[100:101], off offset:128
	global_load_dword v92, v[100:101], off offset:192
	v_or_b32_e32 v102, 34, v98
	v_ashrrev_i32_e32 v103, 31, v102
	v_lshlrev_b64 v[102:103], 10, v[102:103]
	v_lshl_add_u64 v[102:103], v[102:103], 0, v[96:97]
	v_lshl_add_u64 v[102:103], v[102:103], 2, s[22:23]
	s_waitcnt vmcnt(3)
	v_add_f32_e32 v80, v81, v80
	s_waitcnt vmcnt(2)
	v_add_f32_e32 v81, v85, v84
	s_waitcnt vmcnt(1)
	v_add_f32_e32 v84, v89, v88
	s_waitcnt vmcnt(0)
	v_add_f32_e32 v85, v93, v92
	global_store_dword v[100:101], v80, off
	global_store_dword v[100:101], v81, off offset:64
	global_store_dword v[100:101], v84, off offset:128
	global_store_dword v[100:101], v85, off offset:192
	global_load_dword v84, v[102:103], off
	s_nop 0
	global_load_dword v85, v[102:103], off offset:64
	global_load_dword v88, v[102:103], off offset:128
	global_load_dword v89, v[102:103], off offset:192
	v_or_b32_e32 v80, 35, v98
	v_ashrrev_i32_e32 v81, 31, v80
	v_lshlrev_b64 v[80:81], 10, v[80:81]
	v_lshl_add_u64 v[80:81], v[80:81], 0, v[96:97]
	v_lshl_add_u64 v[80:81], v[80:81], 2, s[22:23]
	s_waitcnt vmcnt(3)
	v_add_f32_e32 v82, v82, v84
	s_waitcnt vmcnt(2)
	v_add_f32_e32 v84, v86, v85
	s_waitcnt vmcnt(1)
	v_add_f32_e32 v85, v90, v88
	s_waitcnt vmcnt(0)
	v_add_f32_e32 v86, v94, v89
	global_store_dword v[102:103], v82, off
	global_store_dword v[102:103], v84, off offset:64
	global_store_dword v[102:103], v85, off offset:128
	global_store_dword v[102:103], v86, off offset:192
	global_load_dword v82, v[80:81], off
	s_nop 0
	global_load_dword v86, v[80:81], off offset:64
	global_load_dword v88, v[80:81], off offset:128
	global_load_dword v89, v[80:81], off offset:192
	v_or_b32_e32 v84, 48, v98
	v_ashrrev_i32_e32 v85, 31, v84
	v_lshlrev_b64 v[84:85], 10, v[84:85]
	v_lshl_add_u64 v[84:85], v[84:85], 0, v[96:97]
	v_lshl_add_u64 v[84:85], v[84:85], 2, s[22:23]
	s_waitcnt vmcnt(3)
	v_add_f32_e32 v82, v83, v82
	s_waitcnt vmcnt(2)
	v_add_f32_e32 v83, v87, v86
	s_waitcnt vmcnt(1)
	v_add_f32_e32 v86, v91, v88
	s_waitcnt vmcnt(0)
	v_add_f32_e32 v87, v95, v89
	global_store_dword v[80:81], v82, off
	global_store_dword v[80:81], v83, off offset:64
	global_store_dword v[80:81], v86, off offset:128
	global_store_dword v[80:81], v87, off offset:192
	global_load_dword v82, v[84:85], off
	s_nop 0
	global_load_dword v83, v[84:85], off offset:64
	global_load_dword v86, v[84:85], off offset:128
	global_load_dword v87, v[84:85], off offset:192
	v_or_b32_e32 v80, 49, v98
	v_ashrrev_i32_e32 v81, 31, v80
	v_lshlrev_b64 v[80:81], 10, v[80:81]
	v_lshl_add_u64 v[80:81], v[80:81], 0, v[96:97]
	v_lshl_add_u64 v[80:81], v[80:81], 2, s[22:23]
	s_waitcnt vmcnt(3)
	v_add_f32_e32 v64, v64, v82
	s_waitcnt vmcnt(2)
	v_add_f32_e32 v68, v68, v83
	s_waitcnt vmcnt(1)
	v_add_f32_e32 v72, v72, v86
	s_waitcnt vmcnt(0)
	v_add_f32_e32 v76, v76, v87
	global_store_dword v[84:85], v64, off
	global_store_dword v[84:85], v68, off offset:64
	global_store_dword v[84:85], v72, off offset:128
	global_store_dword v[84:85], v76, off offset:192
	global_load_dword v64, v[80:81], off
	s_nop 0
	global_load_dword v68, v[80:81], off offset:64
	global_load_dword v72, v[80:81], off offset:128
	global_load_dword v76, v[80:81], off offset:192
	v_or_b32_e32 v82, 50, v98
	v_ashrrev_i32_e32 v83, 31, v82
	v_lshlrev_b64 v[82:83], 10, v[82:83]
	v_lshl_add_u64 v[82:83], v[82:83], 0, v[96:97]
	v_lshl_add_u64 v[82:83], v[82:83], 2, s[22:23]
	s_waitcnt vmcnt(3)
	v_add_f32_e32 v64, v65, v64
	s_waitcnt vmcnt(2)
	v_add_f32_e32 v65, v69, v68
	s_waitcnt vmcnt(1)
	v_add_f32_e32 v68, v73, v72
	s_waitcnt vmcnt(0)
	v_add_f32_e32 v69, v77, v76
	global_store_dword v[80:81], v64, off
	global_store_dword v[80:81], v65, off offset:64
	global_store_dword v[80:81], v68, off offset:128
	global_store_dword v[80:81], v69, off offset:192
	global_load_dword v68, v[82:83], off
	s_nop 0
	global_load_dword v69, v[82:83], off offset:64
	global_load_dword v72, v[82:83], off offset:128
	global_load_dword v73, v[82:83], off offset:192
	v_or_b32_e32 v64, 51, v98
	v_ashrrev_i32_e32 v65, 31, v64
	v_lshlrev_b64 v[64:65], 10, v[64:65]
	v_lshl_add_u64 v[64:65], v[64:65], 0, v[96:97]
	v_lshl_add_u64 v[64:65], v[64:65], 2, s[22:23]
	s_waitcnt vmcnt(3)
	v_add_f32_e32 v66, v66, v68
	s_waitcnt vmcnt(2)
	v_add_f32_e32 v68, v70, v69
	s_waitcnt vmcnt(1)
	v_add_f32_e32 v69, v74, v72
	s_waitcnt vmcnt(0)
; template <int EPI>
; DI void gemm_phase(const u16* __restrict__ A, int lda, const u16* __restrict__ Bt, int K, int N, u16* outb, int ldo,
;                    const float* r0, const float* r1, float* outf, char* lds, int bid, int nb) {
;     ...
;     } else if constexpr (EPI == EPI_RESID) {
;       const int col = tn * 256 + wc * 64 + l15;
;       const float* rb_ = (tm * 256 < M_P) ? r0 : (r1 - (size_t)M_P * DM);
; #pragma unroll
;       for (int i = 0; i < 8; ++i)
; #pragma unroll
;         for (int r = 0; r < 4; ++r) {
;           const size_t i0 = (size_t)(mrow + i * 16 + r) * DM + col;
;           const float x0 = rb_[i0], x1 = rb_[i0 + 16], x2 = rb_[i0 + 32], x3 = rb_[i0 + 48];
;           outf[i0] = x0 + acc[i][0][r]; outf[i0 + 16] = x1 + acc[i][1][r]; outf[i0 + 32] = x2 + acc[i][2][r]; outf[i0 + 48] = x3 + acc[i][3][r];
;         }
	v_add_f32_e32 v70, v78, v73
	global_store_dword v[82:83], v66, off
	global_store_dword v[82:83], v68, off offset:64
	global_store_dword v[82:83], v69, off offset:128
	global_store_dword v[82:83], v70, off offset:192
	global_load_dword v66, v[64:65], off
	s_nop 0
	global_load_dword v70, v[64:65], off offset:64
	global_load_dword v72, v[64:65], off offset:128
	global_load_dword v73, v[64:65], off offset:192
	v_or_b32_e32 v68, 64, v98
	v_ashrrev_i32_e32 v69, 31, v68
	v_lshlrev_b64 v[68:69], 10, v[68:69]
	v_lshl_add_u64 v[68:69], v[68:69], 0, v[96:97]
	v_lshl_add_u64 v[68:69], v[68:69], 2, s[22:23]
	s_waitcnt vmcnt(3)
	v_add_f32_e32 v66, v67, v66
	s_waitcnt vmcnt(2)
	v_add_f32_e32 v67, v71, v70
	s_waitcnt vmcnt(1)
	v_add_f32_e32 v70, v75, v72
	s_waitcnt vmcnt(0)
	v_add_f32_e32 v71, v79, v73
	global_store_dword v[64:65], v66, off
	global_store_dword v[64:65], v67, off offset:64
	global_store_dword v[64:65], v70, off offset:128
	global_store_dword v[64:65], v71, off offset:192
	global_load_dword v66, v[68:69], off
	s_nop 0
	global_load_dword v67, v[68:69], off offset:64
	global_load_dword v70, v[68:69], off offset:128
	global_load_dword v71, v[68:69], off offset:192
	v_or_b32_e32 v64, 0x41, v98
	v_ashrrev_i32_e32 v65, 31, v64
	v_lshlrev_b64 v[64:65], 10, v[64:65]
	v_lshl_add_u64 v[64:65], v[64:65], 0, v[96:97]
	v_lshl_add_u64 v[64:65], v[64:65], 2, s[22:23]
	s_waitcnt vmcnt(3)
	v_add_f32_e32 v48, v48, v66
	s_waitcnt vmcnt(2)
	v_add_f32_e32 v52, v52, v67
	s_waitcnt vmcnt(1)
	v_add_f32_e32 v56, v56, v70
	s_waitcnt vmcnt(0)
	v_add_f32_e32 v60, v60, v71
	global_store_dword v[68:69], v48, off
	global_store_dword v[68:69], v52, off offset:64
	global_store_dword v[68:69], v56, off offset:128
	global_store_dword v[68:69], v60, off offset:192
	global_load_dword v48, v[64:65], off
	s_nop 0
	global_load_dword v52, v[64:65], off offset:64
	global_load_dword v56, v[64:65], off offset:128
	global_load_dword v60, v[64:65], off offset:192
	v_or_b32_e32 v66, 0x42, v98
	v_ashrrev_i32_e32 v67, 31, v66
	v_lshlrev_b64 v[66:67], 10, v[66:67]
	v_lshl_add_u64 v[66:67], v[66:67], 0, v[96:97]
	v_lshl_add_u64 v[66:67], v[66:67], 2, s[22:23]
	s_waitcnt vmcnt(3)
	v_add_f32_e32 v48, v49, v48
	s_waitcnt vmcnt(2)
	v_add_f32_e32 v49, v53, v52
	s_waitcnt vmcnt(1)
	v_add_f32_e32 v52, v57, v56
	s_waitcnt vmcnt(0)
	v_add_f32_e32 v53, v61, v60
	global_store_dword v[64:65], v48, off
	global_store_dword v[64:65], v49, off offset:64
	global_store_dword v[64:65], v52, off offset:128
	global_store_dword v[64:65], v53, off offset:192
	global_load_dword v52, v[66:67], off
	s_nop 0
	global_load_dword v53, v[66:67], off offset:64
	global_load_dword v56, v[66:67], off offset:128
	global_load_dword v57, v[66:67], off offset:192
	v_or_b32_e32 v48, 0x43, v98
	v_ashrrev_i32_e32 v49, 31, v48
	v_lshlrev_b64 v[48:49], 10, v[48:49]
	v_lshl_add_u64 v[48:49], v[48:49], 0, v[96:97]
	v_lshl_add_u64 v[48:49], v[48:49], 2, s[22:23]
	s_waitcnt vmcnt(3)
	v_add_f32_e32 v50, v50, v52
	s_waitcnt vmcnt(2)
	v_add_f32_e32 v52, v54, v53
	s_waitcnt vmcnt(1)
	v_add_f32_e32 v53, v58, v56
	s_waitcnt vmcnt(0)
	v_add_f32_e32 v54, v62, v57
	global_store_dword v[66:67], v50, off
	global_store_dword v[66:67], v52, off offset:64
	global_store_dword v[66:67], v53, off offset:128
	global_store_dword v[66:67], v54, off offset:192
	global_load_dword v50, v[48:49], off
	s_nop 0
	global_load_dword v54, v[48:49], off offset:64
	global_load_dword v56, v[48:49], off offset:128
	global_load_dword v57, v[48:49], off offset:192
	v_or_b32_e32 v52, 0x50, v98
	v_ashrrev_i32_e32 v53, 31, v52
	v_lshlrev_b64 v[52:53], 10, v[52:53]
	v_lshl_add_u64 v[52:53], v[52:53], 0, v[96:97]
	v_lshl_add_u64 v[52:53], v[52:53], 2, s[22:23]
	s_waitcnt vmcnt(3)
	v_add_f32_e32 v50, v51, v50
	s_waitcnt vmcnt(2)
	v_add_f32_e32 v51, v55, v54
	s_waitcnt vmcnt(1)
	v_add_f32_e32 v54, v59, v56
	s_waitcnt vmcnt(0)
	v_add_f32_e32 v55, v63, v57
	global_store_dword v[48:49], v50, off
	global_store_dword v[48:49], v51, off offset:64
	global_store_dword v[48:49], v54, off offset:128
	global_store_dword v[48:49], v55, off offset:192
	global_load_dword v50, v[52:53], off
	s_nop 0
	global_load_dword v51, v[52:53], off offset:64
	global_load_dword v54, v[52:53], off offset:128
	global_load_dword v55, v[52:53], off offset:192
	v_or_b32_e32 v48, 0x51, v98
	v_ashrrev_i32_e32 v49, 31, v48
	v_lshlrev_b64 v[48:49], 10, v[48:49]
	v_lshl_add_u64 v[48:49], v[48:49], 0, v[96:97]
	v_lshl_add_u64 v[48:49], v[48:49], 2, s[22:23]
	s_waitcnt vmcnt(3)
	v_add_f32_e32 v32, v32, v50
	s_waitcnt vmcnt(2)
	v_add_f32_e32 v36, v36, v51
	s_waitcnt vmcnt(1)
	v_add_f32_e32 v40, v40, v54
	s_waitcnt vmcnt(0)
	v_add_f32_e32 v44, v44, v55
	global_store_dword v[52:53], v32, off
	global_store_dword v[52:53], v36, off offset:64
	global_store_dword v[52:53], v40, off offset:128
	global_store_dword v[52:53], v44, off offset:192
	global_load_dword v32, v[48:49], off
	s_nop 0
	global_load_dword v36, v[48:49], off offset:64
	global_load_dword v40, v[48:49], off offset:128
	global_load_dword v44, v[48:49], off offset:192
	v_or_b32_e32 v50, 0x52, v98
	v_ashrrev_i32_e32 v51, 31, v50
	v_lshlrev_b64 v[50:51], 10, v[50:51]
	v_lshl_add_u64 v[50:51], v[50:51], 0, v[96:97]
	v_lshl_add_u64 v[50:51], v[50:51], 2, s[22:23]
	s_waitcnt vmcnt(3)
	v_add_f32_e32 v32, v33, v32
	s_waitcnt vmcnt(2)
	v_add_f32_e32 v33, v37, v36
	s_waitcnt vmcnt(1)
	v_add_f32_e32 v36, v41, v40
	s_waitcnt vmcnt(0)
; template <int EPI>
; DI void gemm_phase(const u16* __restrict__ A, int lda, const u16* __restrict__ Bt, int K, int N, u16* outb, int ldo,
;                    const float* r0, const float* r1, float* outf, char* lds, int bid, int nb) {
;     ...
;     } else if constexpr (EPI == EPI_RESID) {
;       const int col = tn * 256 + wc * 64 + l15;
;       const float* rb_ = (tm * 256 < M_P) ? r0 : (r1 - (size_t)M_P * DM);
; #pragma unroll
;       for (int i = 0; i < 8; ++i)
; #pragma unroll
;         for (int r = 0; r < 4; ++r) {
;           const size_t i0 = (size_t)(mrow + i * 16 + r) * DM + col;
;           const float x0 = rb_[i0], x1 = rb_[i0 + 16], x2 = rb_[i0 + 32], x3 = rb_[i0 + 48];
;           outf[i0] = x0 + acc[i][0][r]; outf[i0 + 16] = x1 + acc[i][1][r]; outf[i0 + 32] = x2 + acc[i][2][r]; outf[i0 + 48] = x3 + acc[i][3][r];
;         }
	v_add_f32_e32 v37, v45, v44
	global_store_dword v[48:49], v32, off
	global_store_dword v[48:49], v33, off offset:64
	global_store_dword v[48:49], v36, off offset:128
	global_store_dword v[48:49], v37, off offset:192
	global_load_dword v36, v[50:51], off
	s_nop 0
	global_load_dword v37, v[50:51], off offset:64
	global_load_dword v40, v[50:51], off offset:128
	global_load_dword v41, v[50:51], off offset:192
	v_or_b32_e32 v32, 0x53, v98
	v_ashrrev_i32_e32 v33, 31, v32
	v_lshlrev_b64 v[32:33], 10, v[32:33]
	v_lshl_add_u64 v[32:33], v[32:33], 0, v[96:97]
	v_lshl_add_u64 v[32:33], v[32:33], 2, s[22:23]
	s_waitcnt vmcnt(3)
	v_add_f32_e32 v34, v34, v36
	s_waitcnt vmcnt(2)
	v_add_f32_e32 v36, v38, v37
	s_waitcnt vmcnt(1)
	v_add_f32_e32 v37, v42, v40
	s_waitcnt vmcnt(0)
	v_add_f32_e32 v38, v46, v41
	global_store_dword v[50:51], v34, off
	global_store_dword v[50:51], v36, off offset:64
	global_store_dword v[50:51], v37, off offset:128
	global_store_dword v[50:51], v38, off offset:192
	global_load_dword v34, v[32:33], off
	s_nop 0
	global_load_dword v38, v[32:33], off offset:64
	global_load_dword v40, v[32:33], off offset:128
	global_load_dword v41, v[32:33], off offset:192
	v_or_b32_e32 v36, 0x60, v98
	v_ashrrev_i32_e32 v37, 31, v36
	v_lshlrev_b64 v[36:37], 10, v[36:37]
	v_lshl_add_u64 v[36:37], v[36:37], 0, v[96:97]
	v_lshl_add_u64 v[36:37], v[36:37], 2, s[22:23]
	s_waitcnt vmcnt(3)
	v_add_f32_e32 v34, v35, v34
	s_waitcnt vmcnt(2)
	v_add_f32_e32 v35, v39, v38
	s_waitcnt vmcnt(1)
	v_add_f32_e32 v38, v43, v40
	s_waitcnt vmcnt(0)
	v_add_f32_e32 v39, v47, v41
	global_store_dword v[32:33], v34, off
	global_store_dword v[32:33], v35, off offset:64
	global_store_dword v[32:33], v38, off offset:128
	global_store_dword v[32:33], v39, off offset:192
	global_load_dword v34, v[36:37], off
	s_nop 0
	global_load_dword v35, v[36:37], off offset:64
	global_load_dword v38, v[36:37], off offset:128
	global_load_dword v39, v[36:37], off offset:192
	v_or_b32_e32 v32, 0x61, v98
	v_ashrrev_i32_e32 v33, 31, v32
	v_lshlrev_b64 v[32:33], 10, v[32:33]
	v_lshl_add_u64 v[32:33], v[32:33], 0, v[96:97]
	v_lshl_add_u64 v[32:33], v[32:33], 2, s[22:23]
	s_waitcnt vmcnt(3)
	v_add_f32_e32 v16, v16, v34
	s_waitcnt vmcnt(2)
	v_add_f32_e32 v20, v20, v35
	s_waitcnt vmcnt(1)
	v_add_f32_e32 v24, v24, v38
	s_waitcnt vmcnt(0)
	v_add_f32_e32 v28, v28, v39
	global_store_dword v[36:37], v16, off
	global_store_dword v[36:37], v20, off offset:64
	global_store_dword v[36:37], v24, off offset:128
	global_store_dword v[36:37], v28, off offset:192
	global_load_dword v16, v[32:33], off
	s_nop 0
	global_load_dword v20, v[32:33], off offset:64
	global_load_dword v24, v[32:33], off offset:128
	global_load_dword v28, v[32:33], off offset:192
	v_or_b32_e32 v34, 0x62, v98
	v_ashrrev_i32_e32 v35, 31, v34
	v_lshlrev_b64 v[34:35], 10, v[34:35]
	v_lshl_add_u64 v[34:35], v[34:35], 0, v[96:97]
	v_lshl_add_u64 v[34:35], v[34:35], 2, s[22:23]
	s_waitcnt vmcnt(3)
	v_add_f32_e32 v16, v17, v16
	s_waitcnt vmcnt(2)
	v_add_f32_e32 v17, v21, v20
	s_waitcnt vmcnt(1)
	v_add_f32_e32 v20, v25, v24
	s_waitcnt vmcnt(0)
	v_add_f32_e32 v21, v29, v28
	global_store_dword v[32:33], v16, off
	global_store_dword v[32:33], v17, off offset:64
	global_store_dword v[32:33], v20, off offset:128
	global_store_dword v[32:33], v21, off offset:192
	global_load_dword v20, v[34:35], off
	s_nop 0
	global_load_dword v21, v[34:35], off offset:64
	global_load_dword v24, v[34:35], off offset:128
	global_load_dword v25, v[34:35], off offset:192
	v_or_b32_e32 v16, 0x63, v98
	v_ashrrev_i32_e32 v17, 31, v16
	v_lshlrev_b64 v[16:17], 10, v[16:17]
	v_lshl_add_u64 v[16:17], v[16:17], 0, v[96:97]
	v_lshl_add_u64 v[16:17], v[16:17], 2, s[22:23]
	s_waitcnt vmcnt(3)
	v_add_f32_e32 v18, v18, v20
	s_waitcnt vmcnt(2)
	v_add_f32_e32 v20, v22, v21
	s_waitcnt vmcnt(1)
	v_add_f32_e32 v21, v26, v24
	s_waitcnt vmcnt(0)
; template <int EPI>
; DI void gemm_phase(const u16* __restrict__ A, int lda, const u16* __restrict__ Bt, int K, int N, u16* outb, int ldo,
;                    const float* r0, const float* r1, float* outf, char* lds, int bid, int nb) {
;     ...
;   for (int it = 0; it < nIter; ++it) {
;     ...
;     } else if constexpr (EPI == EPI_RESID) {
;       const int col = tn * 256 + wc * 64 + l15;
;       const float* rb_ = (tm * 256 < M_P) ? r0 : (r1 - (size_t)M_P * DM);
; #pragma unroll
;       for (int i = 0; i < 8; ++i)
; #pragma unroll
;         for (int r = 0; r < 4; ++r) {
;           const size_t i0 = (size_t)(mrow + i * 16 + r) * DM + col;
;           const float x0 = rb_[i0], x1 = rb_[i0 + 16], x2 = rb_[i0 + 32], x3 = rb_[i0 + 48];
;           outf[i0] = x0 + acc[i][0][r]; outf[i0 + 16] = x1 + acc[i][1][r]; outf[i0 + 32] = x2 + acc[i][2][r]; outf[i0 + 48] = x3 + acc[i][3][r];
;         }
	v_add_f32_e32 v22, v30, v25
	global_store_dword v[34:35], v18, off
	global_store_dword v[34:35], v20, off offset:64
	global_store_dword v[34:35], v21, off offset:128
	global_store_dword v[34:35], v22, off offset:192
	global_load_dword v18, v[16:17], off
	s_nop 0
	global_load_dword v22, v[16:17], off offset:64
	global_load_dword v24, v[16:17], off offset:128
	global_load_dword v25, v[16:17], off offset:192
	v_or_b32_e32 v20, 0x70, v98
	v_ashrrev_i32_e32 v21, 31, v20
	v_lshlrev_b64 v[20:21], 10, v[20:21]
	v_lshl_add_u64 v[20:21], v[20:21], 0, v[96:97]
	v_lshl_add_u64 v[20:21], v[20:21], 2, s[22:23]
	s_waitcnt vmcnt(3)
	v_add_f32_e32 v18, v19, v18
	s_waitcnt vmcnt(2)
	v_add_f32_e32 v19, v23, v22
	s_waitcnt vmcnt(1)
	v_add_f32_e32 v22, v27, v24
	s_waitcnt vmcnt(0)
	v_add_f32_e32 v23, v31, v25
	global_store_dword v[16:17], v18, off
	global_store_dword v[16:17], v19, off offset:64
	global_store_dword v[16:17], v22, off offset:128
	global_store_dword v[16:17], v23, off offset:192
	global_load_dword v18, v[20:21], off
	s_nop 0
	global_load_dword v19, v[20:21], off offset:64
	global_load_dword v22, v[20:21], off offset:128
	global_load_dword v23, v[20:21], off offset:192
	v_or_b32_e32 v16, 0x71, v98
	v_ashrrev_i32_e32 v17, 31, v16
	v_lshlrev_b64 v[16:17], 10, v[16:17]
	v_lshl_add_u64 v[16:17], v[16:17], 0, v[96:97]
	v_lshl_add_u64 v[16:17], v[16:17], 2, s[22:23]
	s_waitcnt vmcnt(3)
	v_add_f32_e32 v0, v0, v18
	s_waitcnt vmcnt(2)
	v_add_f32_e32 v4, v4, v19
	s_waitcnt vmcnt(1)
	v_add_f32_e32 v8, v8, v22
	s_waitcnt vmcnt(0)
	v_add_f32_e32 v12, v12, v23
	global_store_dword v[20:21], v0, off
	global_store_dword v[20:21], v4, off offset:64
	global_store_dword v[20:21], v8, off offset:128
	global_store_dword v[20:21], v12, off offset:192
	global_load_dword v0, v[16:17], off
	s_nop 0
	global_load_dword v4, v[16:17], off offset:64
	global_load_dword v8, v[16:17], off offset:128
	global_load_dword v12, v[16:17], off offset:192
	v_or_b32_e32 v18, 0x72, v98
	v_ashrrev_i32_e32 v19, 31, v18
	v_lshlrev_b64 v[18:19], 10, v[18:19]
	v_lshl_add_u64 v[18:19], v[18:19], 0, v[96:97]
	v_lshl_add_u64 v[18:19], v[18:19], 2, s[22:23]
	s_waitcnt vmcnt(3)
	v_add_f32_e32 v0, v1, v0
	s_waitcnt vmcnt(2)
	v_add_f32_e32 v1, v5, v4
	s_waitcnt vmcnt(1)
	v_add_f32_e32 v4, v9, v8
	s_waitcnt vmcnt(0)
	v_add_f32_e32 v5, v13, v12
	global_store_dword v[16:17], v0, off
	global_store_dword v[16:17], v1, off offset:64
	global_store_dword v[16:17], v4, off offset:128
	global_store_dword v[16:17], v5, off offset:192
	global_load_dword v4, v[18:19], off
	s_nop 0
	global_load_dword v5, v[18:19], off offset:64
	global_load_dword v8, v[18:19], off offset:128
	global_load_dword v9, v[18:19], off offset:192
	v_or_b32_e32 v0, 0x73, v98
	v_ashrrev_i32_e32 v1, 31, v0
	v_lshlrev_b64 v[0:1], 10, v[0:1]
	v_lshl_add_u64 v[0:1], v[0:1], 0, v[96:97]
	v_lshl_add_u64 v[0:1], v[0:1], 2, s[22:23]
	s_waitcnt vmcnt(3)
	v_add_f32_e32 v2, v2, v4
	s_waitcnt vmcnt(2)
	v_add_f32_e32 v4, v6, v5
	s_waitcnt vmcnt(1)
	v_add_f32_e32 v5, v10, v8
	s_waitcnt vmcnt(0)
	v_add_f32_e32 v6, v14, v9
	global_store_dword v[18:19], v2, off
	global_store_dword v[18:19], v4, off offset:64
	global_store_dword v[18:19], v5, off offset:128
	global_store_dword v[18:19], v6, off offset:192
	global_load_dword v2, v[0:1], off
	s_nop 0
	global_load_dword v4, v[0:1], off offset:64
	global_load_dword v5, v[0:1], off offset:128
	global_load_dword v6, v[0:1], off offset:192
	s_waitcnt vmcnt(3)
	v_add_f32_e32 v2, v3, v2
	s_waitcnt vmcnt(2)
	v_add_f32_e32 v3, v7, v4
	s_waitcnt vmcnt(1)
	v_add_f32_e32 v4, v11, v5
	s_waitcnt vmcnt(0)
	v_add_f32_e32 v5, v15, v6
	global_store_dword v[0:1], v2, off
	global_store_dword v[0:1], v3, off offset:64
	global_store_dword v[0:1], v4, off offset:128
	global_store_dword v[0:1], v5, off offset:192
	s_cbranch_scc0 .LBB0_1359

; __global__ void __launch_bounds__(512, 2) mega(Params p, int ph_lo, int ph_hi) {
;   __shared__ __attribute__((aligned(16))) char lds_all[LDS_BYTES];
	.amdhsa_kernel _Z4mega6Paramsii
		.amdhsa_group_segment_fixed_size 153616
		.amdhsa_private_segment_fixed_size 0
		.amdhsa_kernarg_size 464
		.amdhsa_user_sgpr_count 2
		.amdhsa_user_sgpr_dispatch_ptr 0
		.amdhsa_user_sgpr_queue_ptr 0
		.amdhsa_user_sgpr_kernarg_segment_ptr 1
		.amdhsa_user_sgpr_dispatch_id 0
		.amdhsa_user_sgpr_kernarg_preload_length 0
		.amdhsa_user_sgpr_kernarg_preload_offset 0
		.amdhsa_user_sgpr_private_segment_size 0
		.amdhsa_uses_dynamic_stack 0
		.amdhsa_enable_private_segment 0
		.amdhsa_system_sgpr_workgroup_id_x 1
		.amdhsa_system_sgpr_workgroup_id_y 0
		.amdhsa_system_sgpr_workgroup_id_z 0
		.amdhsa_system_sgpr_workgroup_info 0
		.amdhsa_system_vgpr_workitem_id 2
		.amdhsa_next_free_vgpr 249
		.amdhsa_next_free_sgpr 102
		.amdhsa_accum_offset 252
		.amdhsa_reserve_vcc 1
		.amdhsa_float_round_mode_32 0
		.amdhsa_float_round_mode_16_64 0
		.amdhsa_float_denorm_mode_32 3
		.amdhsa_float_denorm_mode_16_64 3
		.amdhsa_dx10_clamp 1
		.amdhsa_ieee_mode 1
		.amdhsa_fp16_overflow 0
		.amdhsa_tg_split 0
		.amdhsa_exception_fp_ieee_invalid_op 0
		.amdhsa_exception_fp_denorm_src 0
		.amdhsa_exception_fp_ieee_div_zero 0
		.amdhsa_exception_fp_ieee_overflow 0
		.amdhsa_exception_fp_ieee_underflow 0
		.amdhsa_exception_fp_ieee_inexact 0
		.amdhsa_exception_int_div_zero 0
	.end_amdhsa_kernel

; __global__ void __launch_bounds__(512, 2) mega(Params p, int ph_lo, int ph_hi) {
;   __shared__ __attribute__((aligned(16))) char lds_all[LDS_BYTES];
amdhsa.kernels:
  - .agpr_count:     0
    .args:
      - .offset:         0
        .size:           200
        .value_kind:     by_value
      - .offset:         200
        .size:           4
        .value_kind:     by_value
      - .offset:         204
        .size:           4
        .value_kind:     by_value
      - .offset:         208
        .size:           4
        .value_kind:     hidden_block_count_x
      - .offset:         212
        .size:           4
        .value_kind:     hidden_block_count_y
      - .offset:         216
        .size:           4
        .value_kind:     hidden_block_count_z
      - .offset:         220
        .size:           2
        .value_kind:     hidden_group_size_x
      - .offset:         222
        .size:           2
        .value_kind:     hidden_group_size_y
      - .offset:         224
        .size:           2
        .value_kind:     hidden_group_size_z
      - .offset:         226
        .size:           2
        .value_kind:     hidden_remainder_x
      - .offset:         228
        .size:           2
        .value_kind:     hidden_remainder_y
      - .offset:         230
        .size:           2
        .value_kind:     hidden_remainder_z
      - .offset:         248
        .size:           8
        .value_kind:     hidden_global_offset_x
      - .offset:         256
        .size:           8
        .value_kind:     hidden_global_offset_y
      - .offset:         264
        .size:           8
        .value_kind:     hidden_global_offset_z
      - .offset:         272
        .size:           2
        .value_kind:     hidden_grid_dims
      - .offset:         296
        .size:           8
        .value_kind:     hidden_multigrid_sync_arg
    .group_segment_fixed_size: 153616
    .kernarg_segment_align: 8
    .kernarg_segment_size: 464
    .language:       OpenCL C
    .language_version:
      - 2
      - 0
    .max_flat_workgroup_size: 512
    .name:           _Z4mega6Paramsii
    .private_segment_fixed_size: 0
    .sgpr_count:     108
    .sgpr_spill_count: 2
    .symbol:         _Z4mega6Paramsii.kd
    .uniform_work_group_size: 1
    .uses_dynamic_stack: false
    .vgpr_count:     249
    .vgpr_spill_count: 0
    .wavefront_size: 64
